# hand-written top-k indexer scoring: LDS-DMA double-buffered key chunks (swizzled source), same bf16 MFMA / f32 math order
# speedup vs baseline: 1.1237x; 1.0273x over previous
; __global__ void __launch_bounds__(NTHREADS) mega(Params p) {
;     ...
;   grid.sync();
;   const XcdBarrier xb = xcd_barrier_post(p.bar, xst);
;   for (int l = 0; l < 4; ++l) {
;     for (int rep = 0; rep < REP_P1; ++rep) {
;       for (int j = blockIdx.x; j < 66 * 48; j += gridDim.x) inproj_tile(p, l, j / 48, j % 48, lds);
.LBB0_99:
	s_mov_b64 s[8:9], 0
	v_readlane_b32 s64, v240, 5
	v_readlane_b32 s65, v240, 6
	v_readlane_b32 s66, v240, 7
	v_readlane_b32 s67, v240, 8
	v_readlane_b32 s74, v240, 15
	v_readlane_b32 s75, v240, 16

; DI int map_in(int n) {
;   if (n < 512) return n;
;   if (n < 1024) return n;
;   if (n < 1536) return 1544 + (n - 1024);
;   if (n < 1792) return 2056 + (n - 1536);
;   if (n < 1920) return 2312 + (n - 1792);
;   if (n < 2432) return 2472 + (n - 1920);
;   if (n < 2944) return 2984 + (n - 2432);
;   if (n < 3072) return 3496 + (n - 2944);
;   if (n < 3200) return 3624 + (n - 3072);
;   if (n < 3712) return 3752 + (n - 3200);
;   if (n < 4224) return 4336 + (n - 3712);
;   if (n < 4736) return 4848 + (n - 4224);
;   if (n < 4864) return 5360 + (n - 4736);
;   if (n < 5376) return 5616 + (n - 4864);
;   if (n < 5408) return 2440 + (n - 5376);
;   if (n < 5472) return 4264 + (n - 5408);
;   if (n < 5480) return 1536 + (n - 5472);
;   if (n < 5488) return 4328 + (n - 5480);
;   if (n < 5504) return -1;
;   if (n < 6016) return 1024 + (n - 5504);
;   return 5488 + (n - 6016);
; }
.LBB0_210:
	s_andn2_saveexec_b64 s[24:25], s[24:25]
	v_add_u32_e32 v10, 0xfffffb80, v12
	s_or_b64 exec, exec, s[24:25]
	v_readlane_b32 s64, v240, 5
	v_readlane_b32 s65, v240, 6
	v_readlane_b32 s66, v240, 7
	v_readlane_b32 s67, v240, 8
	v_readlane_b32 s74, v240, 15
	v_readlane_b32 s75, v240, 16

; template <bool SWAP, class Epi>
; DI void gemm_tile(const u16* __restrict__ A, int lda, const u16* __restrict__ Bw, int ldb, int K, char* lds, Epi epi) {
;     ...
;   gload(0, ra0, rb0);
;   lstore(0, ra0, rb0);
;   gload(1, ra1, rb1);
;   __syncthreads();
;   for (int kt = 0; kt < nk; kt += 2) {
;     if (kt + 2 < nk) gload(kt + 2, ra0, rb0);
;     compute(0);
;     lstore(1, ra1, rb1);
;     __syncthreads();
;     if (kt + 3 < nk) gload(kt + 3, ra1, rb1);
;     compute(1);
;     if (kt + 2 < nk) lstore(0, ra0, rb0);
;     __syncthreads();
; DI void inproj_tile(const Params& p, int l, int mt, int nt, char* lds) {
;     ...
;   } else {
;     u16* vt; int nv, c0;
;     if (nt < 47) { vt = p.VtA; nv = 512; c0 = (nt - 43) * 128; } else { vt = p.VtD; nv = 128; c0 = 0; }
;     gemm_tile<false>(A, DM, Bw, DM, DM, lds, [&](int mi, int ni, const f32x16& a) {
;       const int b = m0 / PP, t0 = m0 - b * PP + wm * 64 + mi * 32;
;       const int col = c0 + wn * 64 + ni * 32 + r;
;       store_transposed(vt + ((size_t)b * nv + col) * PP + t0, a, h, nullptr);
.LBB0_324:
	s_mul_hi_u32 s0, s25, 0x5555556
	s_mul_i32 s1, s0, 48
	s_sub_i32 s1, s25, s1
	s_mul_i32 s2, s0, 43
	s_lshr_b32 s2, s2, 8
	s_add_i32 s3, s0, s2
	s_add_i32 s3, s3, 4
	s_mul_i32 s4, s3, 43
	s_lshr_b32 s4, s4, 8
	s_mul_i32 s4, s4, 6
	s_sub_i32 s3, s3, s4
	s_lshl_b32 s3, s3, 3
	s_add_i32 s3, s1, s3
	s_cmp_ge_u32 s3, 48
	s_cselect_b32 s4, 48, 0
	s_sub_i32 s3, s3, s4
	s_mov_b32 s101, s25
	s_sub_i32 s25, s25, s1
	s_add_i32 s25, s25, s3
	s_lshl_b32 s24, s25, 1
	s_lshl_b32 s23, s25, 7
	s_mul_hi_i32 s0, s25, 0x2aaaaaab
	s_lshr_b32 s1, s0, 31
	s_ashr_i32 s26, s0, 3
	s_add_i32 s26, s26, s1
	s_lshl_b32 s4, s26, 8
	s_mul_i32 s0, s26, 0xffffffd0
	s_ashr_i32 s5, s4, 31
	s_add_i32 s2, s25, s0
	s_lshl_b64 s[0:1], s[4:5], 11
	v_readlane_b32 s78, v241, 26
	v_readlane_b32 s79, v241, 27
	s_add_u32 s6, s78, s0
	s_addc_u32 s7, s79, s1
	s_ashr_i32 s3, s2, 31
	s_lshl_b64 s[0:1], s[2:3], 18
	s_add_u32 s8, s18, s0
	v_mov_b32_e32 v1, v152
	s_addc_u32 s9, s19, s1
	s_cmp_gt_i32 s2, 41
	v_and_b32_e32 v107, 31, v1
	v_bfe_u32 v106, v1, 5, 1
	v_bfe_u32 v108, v1, 6, 2
	v_ashrrev_i32_e32 v0, 8, v1
	s_mov_b64 s[0:1], -1
	s_cbranch_scc0 .LBB0_358
	s_cmp_lg_u32 s2, 42
	s_cbranch_scc0 .LBB0_327
	v_mov_b32_e32 v30, v152
	s_mov_b32 s0, 0x40000
	v_ashrrev_i32_e32 v28, 3, v30
	v_ashrrev_i32_e32 v29, 31, v28
	s_waitcnt vmcnt(3)
	v_lshlrev_b64 v[4:5], 11, v[28:29]
	v_lshlrev_b32_e32 v2, 4, v30
	v_lshl_add_u64 v[6:7], s[6:7], 0, v[4:5]
	v_and_b32_e32 v2, 0x70, v2
	v_lshl_add_u64 v[70:71], v[6:7], 0, v[2:3]
	v_add_co_u32_e32 v72, vcc, s60, v70
	v_lshl_add_u64 v[4:5], s[8:9], 0, v[4:5]
	s_nop 0
	v_addc_co_u32_e32 v73, vcc, 0, v71, vcc
	v_add_co_u32_e32 v74, vcc, s0, v70
	s_mov_b32 s0, 0x60000
	s_nop 0
	v_addc_co_u32_e32 v75, vcc, 0, v71, vcc
	v_add_co_u32_e32 v76, vcc, s0, v70
	v_lshl_add_u64 v[68:69], v[4:5], 0, v[2:3]
	s_nop 0
	v_addc_co_u32_e32 v77, vcc, 0, v71, vcc
	global_load_dwordx4 v[4:7], v[70:71], off
	global_load_dwordx4 v[8:11], v[72:73], off
	global_load_dwordx4 v[12:15], v[74:75], off
	global_load_dwordx4 v[16:19], v[76:77], off
	global_load_dwordx4 v[20:23], v[68:69], off
	v_add_co_u32_e32 v78, vcc, s60, v68
	v_and_b32_e32 v29, 31, v30
	s_nop 0
	v_addc_co_u32_e32 v79, vcc, 0, v69, vcc
	global_load_dwordx4 v[24:27], v[78:79], off
	global_load_dwordx4 v[94:97], v[70:71], off offset:128
	global_load_dwordx4 v[98:101], v[68:69], off offset:128
	global_load_dwordx4 v[102:105], v[72:73], off offset:128
	global_load_dwordx4 v[110:113], v[74:75], off offset:128
	global_load_dwordx4 v[114:117], v[76:77], off offset:128
	global_load_dwordx4 v[118:121], v[78:79], off offset:128
	v_and_b32_e32 v31, 0xdf, v30
	v_lshrrev_b32_e32 v32, 1, v30
	v_lshrrev_b32_e32 v30, 2, v30
	s_mov_b32 s0, 0xfffffc0
	v_and_b32_e32 v85, 16, v32
	v_mul_u32_u24_e32 v83, 0x90, v31
	v_and_or_b32 v29, v30, s0, v29
	v_mad_u64_u32 v[86:87], s[0:1], v28, s57, v[2:3]
	v_add3_u32 v2, v83, v85, 0
	v_add_u32_e32 v80, 0, v86
	v_mul_lo_u32 v92, v29, s57
	v_add_u32_e32 v109, v92, v85
	v_add_u32_e32 v84, 0, v109
	v_or_b32_e32 v150, 32, v85
	v_add3_u32 v82, v83, v150, 0
	v_add_u32_e32 v151, v92, v150
	v_add_u32_e32 v87, 0, v151
	v_or_b32_e32 v153, 64, v85
	v_add3_u32 v81, v83, v153, 0
	v_or_b32_e32 v162, 0x60, v85
	v_add3_u32 v83, v83, v162, 0
	v_add_u32_e32 v163, v92, v162
	v_add_u32_e32 v93, 0, v163
	v_readlane_b32 s0, v238, 25
	s_cmp_lt_u32 s2, 47
	v_readlane_b32 s64, v240, 1
	v_readlane_b32 s82, v241, 30
	v_readlane_b32 s83, v241, 31
	v_readlane_b32 s65, v240, 2
	s_mul_i32 s3, s26, 0xffffe800
	s_mul_hi_i32 s5, s25, 0xa57eb503
	v_readlane_b32 s66, v240, 3
	v_readlane_b32 s67, v240, 4
	s_waitcnt vmcnt(11)
	ds_write_b128 v80, v[4:7]
	s_waitcnt vmcnt(7)
	ds_write_b128 v80, v[20:23] offset:36864
	ds_write_b128 v80, v[8:11] offset:9216
	ds_write_b128 v80, v[12:15] offset:18432
	ds_write_b128 v80, v[16:19] offset:27648
	s_waitcnt vmcnt(6)
	ds_write_b128 v80, v[24:27] offset:46080
	s_waitcnt lgkmcnt(0)
	s_barrier
	ds_read_b128 v[4:7], v2
	ds_read_b128 v[8:11], v84 offset:36864
	ds_read_b128 v[88:91], v2 offset:32
	ds_read_b128 v[12:15], v2 offset:4608
	ds_read_b128 v[16:19], v84 offset:41472
	ds_read_b128 v[122:125], v84 offset:36960
	ds_read_b128 v[138:141], v82 offset:4608
	ds_read_b128 v[142:145], v81 offset:4608
	s_waitcnt lgkmcnt(6)
	v_mfma_f32_32x32x16_bf16 v[52:67], v[4:7], v[8:11], 0
	ds_read_b128 v[126:129], v84 offset:36896
	ds_read_b128 v[130:133], v84 offset:36928
	ds_read_b128 v[134:137], v87 offset:41472
	s_waitcnt lgkmcnt(7)
	v_mfma_f32_32x32x16_bf16 v[20:35], v[12:15], v[8:11], 0
	s_waitcnt lgkmcnt(6)
	v_mfma_f32_32x32x16_bf16 v[36:51], v[4:7], v[16:19], 0
	v_mfma_f32_32x32x16_bf16 v[4:19], v[12:15], v[16:19], 0
	s_waitcnt lgkmcnt(2)
	v_mfma_f32_32x32x16_bf16 v[52:67], v[88:91], v[126:129], v[52:67]
	v_mfma_f32_32x32x16_bf16 v[20:35], v[138:141], v[126:129], v[20:35]
	ds_read_b128 v[126:129], v2 offset:64
	s_waitcnt lgkmcnt(1)
	v_mfma_f32_32x32x16_bf16 v[36:51], v[88:91], v[134:137], v[36:51]
	v_add_u32_e32 v88, v92, v153
	v_add_u32_e32 v90, 0, v88
	v_add_u32_e32 v89, s0, v86
	v_add_u32_e32 v91, s59, v86
	v_add_u32_e32 v88, s59, v88
	s_cselect_b64 s[0:1], -1, 0
	s_and_b64 s[10:11], s[0:1], exec
	v_mfma_f32_32x32x16_bf16 v[4:19], v[138:141], v[134:137], v[4:19]
	ds_read_b128 v[138:141], v90 offset:41472
	ds_read_b128 v[134:137], v2 offset:96
	s_cselect_b32 s11, s83, s65
	s_cselect_b32 s10, s82, s64
	s_add_i32 s3, s23, s3
	s_addk_i32 s3, 0xea80
	s_and_b64 s[12:13], s[0:1], exec
	s_waitcnt lgkmcnt(2)
; template <bool SWAP, class Epi>
; DI void gemm_tile(const u16* __restrict__ A, int lda, const u16* __restrict__ Bw, int ldb, int K, char* lds, Epi epi) {
;     ...
;   for (int kt = 0; kt < nk; kt += 2) {
;     if (kt + 2 < nk) gload(kt + 2, ra0, rb0);
;     compute(0);
;     lstore(1, ra1, rb1);
;     __syncthreads();
;     if (kt + 3 < nk) gload(kt + 3, ra1, rb1);
;     compute(1);
;     if (kt + 2 < nk) lstore(0, ra0, rb0);
;     __syncthreads();
	v_mfma_f32_32x32x16_bf16 v[52:67], v[126:129], v[130:133], v[52:67]
	s_cselect_b32 s3, s3, 0
	s_add_i32 s5, s5, s25
	s_lshr_b32 s12, s5, 31
	s_ashr_i32 s5, s5, 10
	s_add_i32 s12, s5, s12
	s_mul_i32 s5, s12, 0xffffdf00
	s_add_i32 s5, s5, s4
	v_mfma_f32_32x32x16_bf16 v[20:35], v[142:145], v[130:133], v[20:35]
	ds_read_b128 v[130:133], v83 offset:4608
	s_ashr_i32 s13, s12, 31
	s_and_b64 s[0:1], s[0:1], exec
	s_cselect_b32 s0, 9, 7
	s_lshl_b64 s[0:1], s[12:13], s0
	s_movk_i32 s12, 0x4200
	s_waitcnt lgkmcnt(2)
	v_mfma_f32_32x32x16_bf16 v[36:51], v[126:129], v[138:141], v[36:51]
	ds_read_b128 v[126:129], v93 offset:41472
	v_mfma_f32_32x32x16_bf16 v[4:19], v[142:145], v[138:141], v[4:19]
	s_waitcnt lgkmcnt(2)
	v_mfma_f32_32x32x16_bf16 v[52:67], v[134:137], v[122:125], v[52:67]
	s_waitcnt lgkmcnt(0)
	v_mfma_f32_32x32x16_bf16 v[36:51], v[134:137], v[126:129], v[36:51]
	v_mfma_f32_32x32x16_bf16 v[20:35], v[130:133], v[122:125], v[20:35]
	global_load_dwordx4 v[122:125], v[70:71], off offset:256
	global_load_dwordx4 v[134:137], v[72:73], off offset:256
	global_load_dwordx4 v[138:141], v[74:75], off offset:256
	global_load_dwordx4 v[142:145], v[76:77], off offset:256
	global_load_dwordx4 v[146:149], v[68:69], off offset:256
	global_load_dwordx4 v[158:161], v[78:79], off offset:256
	s_waitcnt vmcnt(11)
	ds_write_b128 v80, v[94:97] offset:55296
	s_waitcnt vmcnt(9)
	ds_write_b128 v80, v[102:105] offset:64512
	s_waitcnt vmcnt(8)
	ds_write_b128 v89, v[110:113] offset:18432
	s_waitcnt vmcnt(7)
	ds_write_b128 v89, v[114:117] offset:27648
	ds_write_b128 v91, v[98:101]
	s_waitcnt vmcnt(6)
	ds_write_b128 v91, v[118:121] offset:9216
	s_waitcnt lgkmcnt(0)
	s_barrier
	ds_read_b128 v[98:101], v2 offset:55296
	v_add_u32_e32 v96, s59, v109
	v_add_u32_e32 v95, 0x1200, v92
	ds_read_b128 v[102:105], v96
	v_add3_u32 v97, v95, v85, s59
	ds_read_b128 v[110:113], v97
	ds_read_b128 v[114:117], v2 offset:55328
	v_mfma_f32_32x32x16_bf16 v[4:19], v[130:133], v[126:129], v[4:19]
	v_add_u32_e32 v85, s59, v151
	v_add3_u32 v86, v95, v150, s59
	v_add3_u32 v92, v95, v153, s59
	v_add_u32_e32 v94, s59, v163
	v_add3_u32 v95, v95, v162, s59
	s_waitcnt lgkmcnt(2)
	v_mfma_f32_32x32x16_bf16 v[52:67], v[98:101], v[102:105], v[52:67]
	s_waitcnt lgkmcnt(1)
	v_mfma_f32_32x32x16_bf16 v[36:51], v[98:101], v[110:113], v[36:51]
	ds_read_b128 v[98:101], v2 offset:59904
	ds_read_b128 v[118:121], v82 offset:59904
	s_waitcnt lgkmcnt(1)
	v_mfma_f32_32x32x16_bf16 v[20:35], v[98:101], v[102:105], v[20:35]
	ds_read_b128 v[102:105], v86
	v_mfma_f32_32x32x16_bf16 v[4:19], v[98:101], v[110:113], v[4:19]
	ds_read_b128 v[98:101], v85
	s_waitcnt lgkmcnt(0)
	v_mfma_f32_32x32x16_bf16 v[52:67], v[114:117], v[98:101], v[52:67]
	v_mfma_f32_32x32x16_bf16 v[20:35], v[118:121], v[98:101], v[20:35]
	ds_read_b128 v[98:101], v2 offset:55360
	v_mfma_f32_32x32x16_bf16 v[36:51], v[114:117], v[102:105], v[36:51]
	v_mfma_f32_32x32x16_bf16 v[4:19], v[118:121], v[102:105], v[4:19]
	ds_read_b128 v[102:105], v88
	ds_read_b128 v[110:113], v92
	ds_read_b128 v[114:117], v2 offset:55392
	s_waitcnt lgkmcnt(2)
	v_mfma_f32_32x32x16_bf16 v[52:67], v[98:101], v[102:105], v[52:67]
	s_waitcnt lgkmcnt(1)
	v_mfma_f32_32x32x16_bf16 v[36:51], v[98:101], v[110:113], v[36:51]
	ds_read_b128 v[98:101], v81 offset:59904
	ds_read_b128 v[118:121], v83 offset:59904
	s_waitcnt lgkmcnt(1)
	v_mfma_f32_32x32x16_bf16 v[20:35], v[98:101], v[102:105], v[20:35]
	ds_read_b128 v[102:105], v95
	v_mfma_f32_32x32x16_bf16 v[4:19], v[98:101], v[110:113], v[4:19]
	ds_read_b128 v[98:101], v94
	s_waitcnt lgkmcnt(0)
	v_mfma_f32_32x32x16_bf16 v[52:67], v[114:117], v[98:101], v[52:67]
	v_mfma_f32_32x32x16_bf16 v[36:51], v[114:117], v[102:105], v[36:51]
	v_mfma_f32_32x32x16_bf16 v[20:35], v[118:121], v[98:101], v[20:35]
	global_load_dwordx4 v[98:101], v[70:71], off offset:384
	global_load_dwordx4 v[110:113], v[72:73], off offset:384
	global_load_dwordx4 v[114:117], v[74:75], off offset:384
	global_load_dwordx4 v[126:129], v[76:77], off offset:384
	global_load_dwordx4 v[130:133], v[68:69], off offset:384
	global_load_dwordx4 v[162:165], v[78:79], off offset:384
	s_waitcnt vmcnt(11)
	ds_write_b128 v80, v[122:125]
	s_waitcnt vmcnt(10)
	ds_write_b128 v80, v[134:137] offset:9216
	s_waitcnt vmcnt(9)
	ds_write_b128 v80, v[138:141] offset:18432
	s_waitcnt vmcnt(8)
	ds_write_b128 v80, v[142:145] offset:27648
	s_waitcnt vmcnt(7)
	ds_write_b128 v80, v[146:149] offset:36864
	s_waitcnt vmcnt(6)
	ds_write_b128 v80, v[158:161] offset:46080
	s_waitcnt lgkmcnt(0)
	s_barrier
; template <bool SWAP, class Epi>
; DI void gemm_tile(const u16* __restrict__ A, int lda, const u16* __restrict__ Bw, int ldb, int K, char* lds, Epi epi) {
;     ...
;   for (int kt = 0; kt < nk; kt += 2) {
;     if (kt + 2 < nk) gload(kt + 2, ra0, rb0);
;     compute(0);
;     lstore(1, ra1, rb1);
;     __syncthreads();
;     if (kt + 3 < nk) gload(kt + 3, ra1, rb1);
;     compute(1);
;     if (kt + 2 < nk) lstore(0, ra0, rb0);
;     __syncthreads();
	v_mfma_f32_32x32x16_bf16 v[4:19], v[118:121], v[102:105], v[4:19]
	ds_read_b128 v[102:105], v2
	ds_read_b128 v[118:121], v84 offset:36864
	ds_read_b128 v[122:125], v2 offset:32
	ds_read_b128 v[134:137], v2 offset:4608
	ds_read_b128 v[138:141], v84 offset:41472
	ds_read_b128 v[142:145], v84 offset:36960
	s_waitcnt lgkmcnt(4)
	v_mfma_f32_32x32x16_bf16 v[52:67], v[102:105], v[118:121], v[52:67]
	s_waitcnt lgkmcnt(1)
	v_mfma_f32_32x32x16_bf16 v[36:51], v[102:105], v[138:141], v[36:51]
	v_mfma_f32_32x32x16_bf16 v[20:35], v[134:137], v[118:121], v[20:35]
	ds_read_b128 v[102:105], v84 offset:36896
	ds_read_b128 v[118:121], v84 offset:36928
	v_mfma_f32_32x32x16_bf16 v[4:19], v[134:137], v[138:141], v[4:19]
	ds_read_b128 v[134:137], v87 offset:41472
	ds_read_b128 v[138:141], v82 offset:4608
	s_waitcnt lgkmcnt(3)
	v_mfma_f32_32x32x16_bf16 v[52:67], v[122:125], v[102:105], v[52:67]
	s_waitcnt lgkmcnt(1)
	v_mfma_f32_32x32x16_bf16 v[36:51], v[122:125], v[134:137], v[36:51]
	s_waitcnt lgkmcnt(0)
	v_mfma_f32_32x32x16_bf16 v[20:35], v[138:141], v[102:105], v[20:35]
	ds_read_b128 v[102:105], v2 offset:64
	ds_read_b128 v[122:125], v2 offset:96
	v_mfma_f32_32x32x16_bf16 v[4:19], v[138:141], v[134:137], v[4:19]
	ds_read_b128 v[134:137], v90 offset:41472
	ds_read_b128 v[138:141], v81 offset:4608
	s_waitcnt lgkmcnt(3)
	v_mfma_f32_32x32x16_bf16 v[52:67], v[102:105], v[118:121], v[52:67]
	s_waitcnt lgkmcnt(1)
	v_mfma_f32_32x32x16_bf16 v[36:51], v[102:105], v[134:137], v[36:51]
	s_waitcnt lgkmcnt(0)
	v_mfma_f32_32x32x16_bf16 v[20:35], v[138:141], v[118:121], v[20:35]
	ds_read_b128 v[102:105], v93 offset:41472
	ds_read_b128 v[118:121], v83 offset:4608
	v_mfma_f32_32x32x16_bf16 v[4:19], v[138:141], v[134:137], v[4:19]
	v_mfma_f32_32x32x16_bf16 v[52:67], v[122:125], v[142:145], v[52:67]
	s_waitcnt lgkmcnt(1)
	v_mfma_f32_32x32x16_bf16 v[36:51], v[122:125], v[102:105], v[36:51]
	s_waitcnt lgkmcnt(0)
	v_mfma_f32_32x32x16_bf16 v[20:35], v[118:121], v[142:145], v[20:35]
	global_load_dwordx4 v[122:125], v[70:71], off offset:512
	global_load_dwordx4 v[134:137], v[72:73], off offset:512
	global_load_dwordx4 v[138:141], v[74:75], off offset:512
	global_load_dwordx4 v[142:145], v[76:77], off offset:512
	global_load_dwordx4 v[146:149], v[68:69], off offset:512
	global_load_dwordx4 v[158:161], v[78:79], off offset:512
	s_waitcnt vmcnt(11)
	ds_write_b128 v80, v[98:101] offset:55296
	s_waitcnt vmcnt(10)
	ds_write_b128 v80, v[110:113] offset:64512
	s_waitcnt vmcnt(9)
	ds_write_b128 v89, v[114:117] offset:18432
	s_waitcnt vmcnt(8)
	ds_write_b128 v89, v[126:129] offset:27648
	s_waitcnt vmcnt(7)
	ds_write_b128 v91, v[130:133]
	s_waitcnt vmcnt(6)
	ds_write_b128 v91, v[162:165] offset:9216
	s_waitcnt lgkmcnt(0)
	s_barrier
	v_mfma_f32_32x32x16_bf16 v[4:19], v[118:121], v[102:105], v[4:19]
	ds_read_b128 v[98:101], v2 offset:55296
	ds_read_b128 v[102:105], v96
	ds_read_b128 v[110:113], v97
	ds_read_b128 v[114:117], v2 offset:55328
	s_waitcnt lgkmcnt(2)
	v_mfma_f32_32x32x16_bf16 v[52:67], v[98:101], v[102:105], v[52:67]
	s_waitcnt lgkmcnt(1)
	v_mfma_f32_32x32x16_bf16 v[36:51], v[98:101], v[110:113], v[36:51]
	ds_read_b128 v[98:101], v2 offset:59904
	ds_read_b128 v[118:121], v82 offset:59904
	s_waitcnt lgkmcnt(1)
	v_mfma_f32_32x32x16_bf16 v[20:35], v[98:101], v[102:105], v[20:35]
	v_mfma_f32_32x32x16_bf16 v[4:19], v[98:101], v[110:113], v[4:19]
	ds_read_b128 v[98:101], v85
	ds_read_b128 v[102:105], v86
	s_waitcnt lgkmcnt(1)
	v_mfma_f32_32x32x16_bf16 v[52:67], v[114:117], v[98:101], v[52:67]
	s_waitcnt lgkmcnt(0)
	v_mfma_f32_32x32x16_bf16 v[36:51], v[114:117], v[102:105], v[36:51]
	v_mfma_f32_32x32x16_bf16 v[20:35], v[118:121], v[98:101], v[20:35]
	v_mfma_f32_32x32x16_bf16 v[4:19], v[118:121], v[102:105], v[4:19]
	ds_read_b128 v[98:101], v2 offset:55360
	ds_read_b128 v[102:105], v88
	ds_read_b128 v[110:113], v92
	ds_read_b128 v[114:117], v2 offset:55392
	s_waitcnt lgkmcnt(2)
	v_mfma_f32_32x32x16_bf16 v[52:67], v[98:101], v[102:105], v[52:67]
	s_waitcnt lgkmcnt(1)
	v_mfma_f32_32x32x16_bf16 v[36:51], v[98:101], v[110:113], v[36:51]
	ds_read_b128 v[98:101], v81 offset:59904
	ds_read_b128 v[118:121], v83 offset:59904
	s_waitcnt lgkmcnt(1)
	v_mfma_f32_32x32x16_bf16 v[20:35], v[98:101], v[102:105], v[20:35]
	v_mfma_f32_32x32x16_bf16 v[4:19], v[98:101], v[110:113], v[4:19]
	ds_read_b128 v[98:101], v94
	ds_read_b128 v[102:105], v95
	s_waitcnt lgkmcnt(1)
	v_mfma_f32_32x32x16_bf16 v[52:67], v[114:117], v[98:101], v[52:67]
	s_waitcnt lgkmcnt(0)
	v_mfma_f32_32x32x16_bf16 v[36:51], v[114:117], v[102:105], v[36:51]
	v_mfma_f32_32x32x16_bf16 v[20:35], v[118:121], v[98:101], v[20:35]
	global_load_dwordx4 v[98:101], v[70:71], off offset:640
	global_load_dwordx4 v[110:113], v[72:73], off offset:640
	global_load_dwordx4 v[114:117], v[74:75], off offset:640
	global_load_dwordx4 v[126:129], v[76:77], off offset:640
	global_load_dwordx4 v[130:133], v[68:69], off offset:640
	global_load_dwordx4 v[162:165], v[78:79], off offset:640
	s_waitcnt vmcnt(11)
	ds_write_b128 v80, v[122:125]
	s_waitcnt vmcnt(10)
	ds_write_b128 v80, v[134:137] offset:9216
	s_waitcnt vmcnt(9)
	ds_write_b128 v80, v[138:141] offset:18432
	s_waitcnt vmcnt(8)
	ds_write_b128 v80, v[142:145] offset:27648
	s_waitcnt vmcnt(7)
	ds_write_b128 v80, v[146:149] offset:36864
	s_waitcnt vmcnt(6)
	ds_write_b128 v80, v[158:161] offset:46080
	s_waitcnt lgkmcnt(0)
	s_barrier
; template <bool SWAP, class Epi>
; DI void gemm_tile(const u16* __restrict__ A, int lda, const u16* __restrict__ Bw, int ldb, int K, char* lds, Epi epi) {
;     ...
;   for (int kt = 0; kt < nk; kt += 2) {
;     if (kt + 2 < nk) gload(kt + 2, ra0, rb0);
;     compute(0);
;     lstore(1, ra1, rb1);
;     __syncthreads();
;     if (kt + 3 < nk) gload(kt + 3, ra1, rb1);
;     compute(1);
;     if (kt + 2 < nk) lstore(0, ra0, rb0);
;     __syncthreads();
	v_mfma_f32_32x32x16_bf16 v[4:19], v[118:121], v[102:105], v[4:19]
	ds_read_b128 v[102:105], v2
	ds_read_b128 v[118:121], v84 offset:36864
	ds_read_b128 v[122:125], v2 offset:32
	ds_read_b128 v[134:137], v2 offset:4608
	ds_read_b128 v[138:141], v84 offset:41472
	ds_read_b128 v[142:145], v84 offset:36960
	s_waitcnt lgkmcnt(4)
	v_mfma_f32_32x32x16_bf16 v[52:67], v[102:105], v[118:121], v[52:67]
	s_waitcnt lgkmcnt(1)
	v_mfma_f32_32x32x16_bf16 v[36:51], v[102:105], v[138:141], v[36:51]
	v_mfma_f32_32x32x16_bf16 v[20:35], v[134:137], v[118:121], v[20:35]
	ds_read_b128 v[102:105], v84 offset:36896
	ds_read_b128 v[118:121], v84 offset:36928
	v_mfma_f32_32x32x16_bf16 v[4:19], v[134:137], v[138:141], v[4:19]
	ds_read_b128 v[134:137], v87 offset:41472
	ds_read_b128 v[138:141], v82 offset:4608
	s_waitcnt lgkmcnt(3)
	v_mfma_f32_32x32x16_bf16 v[52:67], v[122:125], v[102:105], v[52:67]
	s_waitcnt lgkmcnt(1)
	v_mfma_f32_32x32x16_bf16 v[36:51], v[122:125], v[134:137], v[36:51]
	s_waitcnt lgkmcnt(0)
	v_mfma_f32_32x32x16_bf16 v[20:35], v[138:141], v[102:105], v[20:35]
	ds_read_b128 v[102:105], v2 offset:64
	ds_read_b128 v[122:125], v2 offset:96
	v_mfma_f32_32x32x16_bf16 v[4:19], v[138:141], v[134:137], v[4:19]
	ds_read_b128 v[134:137], v90 offset:41472
	ds_read_b128 v[138:141], v81 offset:4608
	s_waitcnt lgkmcnt(3)
	v_mfma_f32_32x32x16_bf16 v[52:67], v[102:105], v[118:121], v[52:67]
	s_waitcnt lgkmcnt(1)
	v_mfma_f32_32x32x16_bf16 v[36:51], v[102:105], v[134:137], v[36:51]
	s_waitcnt lgkmcnt(0)
	v_mfma_f32_32x32x16_bf16 v[20:35], v[138:141], v[118:121], v[20:35]
	ds_read_b128 v[102:105], v93 offset:41472
	ds_read_b128 v[118:121], v83 offset:4608
	v_mfma_f32_32x32x16_bf16 v[4:19], v[138:141], v[134:137], v[4:19]
	v_mfma_f32_32x32x16_bf16 v[52:67], v[122:125], v[142:145], v[52:67]
	s_waitcnt lgkmcnt(1)
	v_mfma_f32_32x32x16_bf16 v[36:51], v[122:125], v[102:105], v[36:51]
	s_waitcnt lgkmcnt(0)
	v_mfma_f32_32x32x16_bf16 v[20:35], v[118:121], v[142:145], v[20:35]
	global_load_dwordx4 v[122:125], v[70:71], off offset:768
	global_load_dwordx4 v[134:137], v[72:73], off offset:768
	global_load_dwordx4 v[138:141], v[74:75], off offset:768
	global_load_dwordx4 v[142:145], v[76:77], off offset:768
	global_load_dwordx4 v[146:149], v[68:69], off offset:768
	global_load_dwordx4 v[158:161], v[78:79], off offset:768
	s_waitcnt vmcnt(11)
	ds_write_b128 v80, v[98:101] offset:55296
	s_waitcnt vmcnt(10)
	ds_write_b128 v80, v[110:113] offset:64512
	s_waitcnt vmcnt(9)
	ds_write_b128 v89, v[114:117] offset:18432
	s_waitcnt vmcnt(8)
	ds_write_b128 v89, v[126:129] offset:27648
	s_waitcnt vmcnt(7)
	ds_write_b128 v91, v[130:133]
	s_waitcnt vmcnt(6)
	ds_write_b128 v91, v[162:165] offset:9216
	s_waitcnt lgkmcnt(0)
	s_barrier
	v_mfma_f32_32x32x16_bf16 v[4:19], v[118:121], v[102:105], v[4:19]
	ds_read_b128 v[98:101], v2 offset:55296
	ds_read_b128 v[102:105], v96
	ds_read_b128 v[110:113], v97
	ds_read_b128 v[114:117], v2 offset:55328
	s_waitcnt lgkmcnt(2)
	v_mfma_f32_32x32x16_bf16 v[52:67], v[98:101], v[102:105], v[52:67]
	s_waitcnt lgkmcnt(1)
	v_mfma_f32_32x32x16_bf16 v[36:51], v[98:101], v[110:113], v[36:51]
	ds_read_b128 v[98:101], v2 offset:59904
	ds_read_b128 v[118:121], v82 offset:59904
	s_waitcnt lgkmcnt(1)
	v_mfma_f32_32x32x16_bf16 v[20:35], v[98:101], v[102:105], v[20:35]
	v_mfma_f32_32x32x16_bf16 v[4:19], v[98:101], v[110:113], v[4:19]
	ds_read_b128 v[98:101], v85
	ds_read_b128 v[102:105], v86
	s_waitcnt lgkmcnt(1)
	v_mfma_f32_32x32x16_bf16 v[52:67], v[114:117], v[98:101], v[52:67]
	s_waitcnt lgkmcnt(0)
	v_mfma_f32_32x32x16_bf16 v[36:51], v[114:117], v[102:105], v[36:51]
	v_mfma_f32_32x32x16_bf16 v[20:35], v[118:121], v[98:101], v[20:35]
	v_mfma_f32_32x32x16_bf16 v[4:19], v[118:121], v[102:105], v[4:19]
	ds_read_b128 v[98:101], v2 offset:55360
	ds_read_b128 v[102:105], v88
	ds_read_b128 v[110:113], v92
	ds_read_b128 v[114:117], v2 offset:55392
	s_waitcnt lgkmcnt(2)
	v_mfma_f32_32x32x16_bf16 v[52:67], v[98:101], v[102:105], v[52:67]
	s_waitcnt lgkmcnt(1)
	v_mfma_f32_32x32x16_bf16 v[36:51], v[98:101], v[110:113], v[36:51]
	ds_read_b128 v[98:101], v81 offset:59904
	ds_read_b128 v[118:121], v83 offset:59904
	s_waitcnt lgkmcnt(1)
	v_mfma_f32_32x32x16_bf16 v[20:35], v[98:101], v[102:105], v[20:35]
	v_mfma_f32_32x32x16_bf16 v[4:19], v[98:101], v[110:113], v[4:19]
	ds_read_b128 v[98:101], v94
	ds_read_b128 v[102:105], v95
	s_waitcnt lgkmcnt(1)
	v_mfma_f32_32x32x16_bf16 v[52:67], v[114:117], v[98:101], v[52:67]
	s_waitcnt lgkmcnt(0)
	v_mfma_f32_32x32x16_bf16 v[36:51], v[114:117], v[102:105], v[36:51]
	v_mfma_f32_32x32x16_bf16 v[20:35], v[118:121], v[98:101], v[20:35]
	global_load_dwordx4 v[98:101], v[70:71], off offset:896
	global_load_dwordx4 v[110:113], v[72:73], off offset:896
	global_load_dwordx4 v[114:117], v[74:75], off offset:896
	global_load_dwordx4 v[126:129], v[76:77], off offset:896
	global_load_dwordx4 v[130:133], v[68:69], off offset:896
	global_load_dwordx4 v[162:165], v[78:79], off offset:896
	s_waitcnt vmcnt(11)
	ds_write_b128 v80, v[122:125]
	s_waitcnt vmcnt(10)
	ds_write_b128 v80, v[134:137] offset:9216
	s_waitcnt vmcnt(9)
	ds_write_b128 v80, v[138:141] offset:18432
	s_waitcnt vmcnt(8)
	ds_write_b128 v80, v[142:145] offset:27648
	s_waitcnt vmcnt(7)
	ds_write_b128 v80, v[146:149] offset:36864
	s_waitcnt vmcnt(6)
	ds_write_b128 v80, v[158:161] offset:46080
	s_waitcnt lgkmcnt(0)
	s_barrier
; template <bool SWAP, class Epi>
; DI void gemm_tile(const u16* __restrict__ A, int lda, const u16* __restrict__ Bw, int ldb, int K, char* lds, Epi epi) {
;     ...
;   for (int kt = 0; kt < nk; kt += 2) {
;     if (kt + 2 < nk) gload(kt + 2, ra0, rb0);
;     compute(0);
;     lstore(1, ra1, rb1);
;     __syncthreads();
;     if (kt + 3 < nk) gload(kt + 3, ra1, rb1);
;     compute(1);
;     if (kt + 2 < nk) lstore(0, ra0, rb0);
;     __syncthreads();
	v_mfma_f32_32x32x16_bf16 v[4:19], v[118:121], v[102:105], v[4:19]
	ds_read_b128 v[102:105], v2
	ds_read_b128 v[118:121], v84 offset:36864
	ds_read_b128 v[122:125], v2 offset:32
	ds_read_b128 v[134:137], v2 offset:4608
	ds_read_b128 v[138:141], v84 offset:41472
	ds_read_b128 v[142:145], v84 offset:36960
	s_waitcnt lgkmcnt(4)
	v_mfma_f32_32x32x16_bf16 v[52:67], v[102:105], v[118:121], v[52:67]
	s_waitcnt lgkmcnt(1)
	v_mfma_f32_32x32x16_bf16 v[36:51], v[102:105], v[138:141], v[36:51]
	v_mfma_f32_32x32x16_bf16 v[20:35], v[134:137], v[118:121], v[20:35]
	ds_read_b128 v[102:105], v84 offset:36896
	ds_read_b128 v[118:121], v84 offset:36928
	v_mfma_f32_32x32x16_bf16 v[4:19], v[134:137], v[138:141], v[4:19]
	ds_read_b128 v[134:137], v87 offset:41472
	ds_read_b128 v[138:141], v82 offset:4608
	s_waitcnt lgkmcnt(3)
	v_mfma_f32_32x32x16_bf16 v[52:67], v[122:125], v[102:105], v[52:67]
	s_waitcnt lgkmcnt(1)
	v_mfma_f32_32x32x16_bf16 v[36:51], v[122:125], v[134:137], v[36:51]
	s_waitcnt lgkmcnt(0)
	v_mfma_f32_32x32x16_bf16 v[20:35], v[138:141], v[102:105], v[20:35]
	ds_read_b128 v[102:105], v2 offset:64
	ds_read_b128 v[122:125], v2 offset:96
	v_mfma_f32_32x32x16_bf16 v[4:19], v[138:141], v[134:137], v[4:19]
	ds_read_b128 v[134:137], v90 offset:41472
	ds_read_b128 v[138:141], v81 offset:4608
	s_waitcnt lgkmcnt(3)
	v_mfma_f32_32x32x16_bf16 v[52:67], v[102:105], v[118:121], v[52:67]
	s_waitcnt lgkmcnt(1)
	v_mfma_f32_32x32x16_bf16 v[36:51], v[102:105], v[134:137], v[36:51]
	s_waitcnt lgkmcnt(0)
	v_mfma_f32_32x32x16_bf16 v[20:35], v[138:141], v[118:121], v[20:35]
	ds_read_b128 v[102:105], v93 offset:41472
	ds_read_b128 v[118:121], v83 offset:4608
	v_mfma_f32_32x32x16_bf16 v[4:19], v[138:141], v[134:137], v[4:19]
	v_mfma_f32_32x32x16_bf16 v[52:67], v[122:125], v[142:145], v[52:67]
	s_waitcnt lgkmcnt(1)
	v_mfma_f32_32x32x16_bf16 v[36:51], v[122:125], v[102:105], v[36:51]
	s_waitcnt lgkmcnt(0)
	v_mfma_f32_32x32x16_bf16 v[20:35], v[118:121], v[142:145], v[20:35]
	global_load_dwordx4 v[122:125], v[70:71], off offset:1024
	global_load_dwordx4 v[134:137], v[72:73], off offset:1024
	global_load_dwordx4 v[138:141], v[74:75], off offset:1024
	global_load_dwordx4 v[142:145], v[76:77], off offset:1024
	global_load_dwordx4 v[146:149], v[68:69], off offset:1024
	global_load_dwordx4 v[158:161], v[78:79], off offset:1024
	s_waitcnt vmcnt(11)
	ds_write_b128 v80, v[98:101] offset:55296
	s_waitcnt vmcnt(10)
	ds_write_b128 v80, v[110:113] offset:64512
	s_waitcnt vmcnt(9)
	ds_write_b128 v89, v[114:117] offset:18432
	s_waitcnt vmcnt(8)
	ds_write_b128 v89, v[126:129] offset:27648
	s_waitcnt vmcnt(7)
	ds_write_b128 v91, v[130:133]
	s_waitcnt vmcnt(6)
	ds_write_b128 v91, v[162:165] offset:9216
	s_waitcnt lgkmcnt(0)
	s_barrier
	v_mfma_f32_32x32x16_bf16 v[4:19], v[118:121], v[102:105], v[4:19]
	ds_read_b128 v[98:101], v2 offset:55296
	ds_read_b128 v[102:105], v96
	ds_read_b128 v[110:113], v97
	ds_read_b128 v[114:117], v2 offset:55328
	s_waitcnt lgkmcnt(2)
	v_mfma_f32_32x32x16_bf16 v[52:67], v[98:101], v[102:105], v[52:67]
	s_waitcnt lgkmcnt(1)
	v_mfma_f32_32x32x16_bf16 v[36:51], v[98:101], v[110:113], v[36:51]
	ds_read_b128 v[98:101], v2 offset:59904
	ds_read_b128 v[118:121], v82 offset:59904
	s_waitcnt lgkmcnt(1)
	v_mfma_f32_32x32x16_bf16 v[20:35], v[98:101], v[102:105], v[20:35]
	v_mfma_f32_32x32x16_bf16 v[4:19], v[98:101], v[110:113], v[4:19]
	ds_read_b128 v[98:101], v85
	ds_read_b128 v[102:105], v86
	s_waitcnt lgkmcnt(1)
	v_mfma_f32_32x32x16_bf16 v[52:67], v[114:117], v[98:101], v[52:67]
	s_waitcnt lgkmcnt(0)
	v_mfma_f32_32x32x16_bf16 v[36:51], v[114:117], v[102:105], v[36:51]
	v_mfma_f32_32x32x16_bf16 v[20:35], v[118:121], v[98:101], v[20:35]
	v_mfma_f32_32x32x16_bf16 v[4:19], v[118:121], v[102:105], v[4:19]
	ds_read_b128 v[98:101], v2 offset:55360
	ds_read_b128 v[102:105], v88
	ds_read_b128 v[110:113], v92
	ds_read_b128 v[114:117], v2 offset:55392
	s_waitcnt lgkmcnt(2)
	v_mfma_f32_32x32x16_bf16 v[52:67], v[98:101], v[102:105], v[52:67]
	s_waitcnt lgkmcnt(1)
	v_mfma_f32_32x32x16_bf16 v[36:51], v[98:101], v[110:113], v[36:51]
	ds_read_b128 v[98:101], v81 offset:59904
	ds_read_b128 v[118:121], v83 offset:59904
	s_waitcnt lgkmcnt(1)
	v_mfma_f32_32x32x16_bf16 v[20:35], v[98:101], v[102:105], v[20:35]
	v_mfma_f32_32x32x16_bf16 v[4:19], v[98:101], v[110:113], v[4:19]
	ds_read_b128 v[98:101], v94
	ds_read_b128 v[102:105], v95
	s_waitcnt lgkmcnt(1)
	v_mfma_f32_32x32x16_bf16 v[52:67], v[114:117], v[98:101], v[52:67]
	s_waitcnt lgkmcnt(0)
	v_mfma_f32_32x32x16_bf16 v[36:51], v[114:117], v[102:105], v[36:51]
	v_mfma_f32_32x32x16_bf16 v[20:35], v[118:121], v[98:101], v[20:35]
	global_load_dwordx4 v[98:101], v[70:71], off offset:1152
	global_load_dwordx4 v[110:113], v[72:73], off offset:1152
	global_load_dwordx4 v[114:117], v[74:75], off offset:1152
	global_load_dwordx4 v[126:129], v[76:77], off offset:1152
	global_load_dwordx4 v[130:133], v[68:69], off offset:1152
	global_load_dwordx4 v[162:165], v[78:79], off offset:1152
	s_waitcnt vmcnt(11)
	ds_write_b128 v80, v[122:125]
	s_waitcnt vmcnt(10)
	ds_write_b128 v80, v[134:137] offset:9216
	s_waitcnt vmcnt(9)
	ds_write_b128 v80, v[138:141] offset:18432
	s_waitcnt vmcnt(8)
	ds_write_b128 v80, v[142:145] offset:27648
	s_waitcnt vmcnt(7)
	ds_write_b128 v80, v[146:149] offset:36864
	s_waitcnt vmcnt(6)
	ds_write_b128 v80, v[158:161] offset:46080
	s_waitcnt lgkmcnt(0)
	s_barrier
; template <bool SWAP, class Epi>
; DI void gemm_tile(const u16* __restrict__ A, int lda, const u16* __restrict__ Bw, int ldb, int K, char* lds, Epi epi) {
;     ...
;   for (int kt = 0; kt < nk; kt += 2) {
;     if (kt + 2 < nk) gload(kt + 2, ra0, rb0);
;     compute(0);
;     lstore(1, ra1, rb1);
;     __syncthreads();
;     if (kt + 3 < nk) gload(kt + 3, ra1, rb1);
;     compute(1);
;     if (kt + 2 < nk) lstore(0, ra0, rb0);
;     __syncthreads();
	v_mfma_f32_32x32x16_bf16 v[4:19], v[118:121], v[102:105], v[4:19]
	ds_read_b128 v[102:105], v2
	ds_read_b128 v[118:121], v84 offset:36864
	ds_read_b128 v[122:125], v2 offset:32
	ds_read_b128 v[134:137], v2 offset:4608
	ds_read_b128 v[138:141], v84 offset:41472
	ds_read_b128 v[142:145], v84 offset:36960
	s_waitcnt lgkmcnt(4)
	v_mfma_f32_32x32x16_bf16 v[52:67], v[102:105], v[118:121], v[52:67]
	s_waitcnt lgkmcnt(1)
	v_mfma_f32_32x32x16_bf16 v[36:51], v[102:105], v[138:141], v[36:51]
	v_mfma_f32_32x32x16_bf16 v[20:35], v[134:137], v[118:121], v[20:35]
	ds_read_b128 v[102:105], v84 offset:36896
	ds_read_b128 v[118:121], v84 offset:36928
	v_mfma_f32_32x32x16_bf16 v[4:19], v[134:137], v[138:141], v[4:19]
	ds_read_b128 v[134:137], v87 offset:41472
	ds_read_b128 v[138:141], v82 offset:4608
	s_waitcnt lgkmcnt(3)
	v_mfma_f32_32x32x16_bf16 v[52:67], v[122:125], v[102:105], v[52:67]
	s_waitcnt lgkmcnt(1)
	v_mfma_f32_32x32x16_bf16 v[36:51], v[122:125], v[134:137], v[36:51]
	s_waitcnt lgkmcnt(0)
	v_mfma_f32_32x32x16_bf16 v[20:35], v[138:141], v[102:105], v[20:35]
	ds_read_b128 v[102:105], v2 offset:64
	ds_read_b128 v[122:125], v2 offset:96
	v_mfma_f32_32x32x16_bf16 v[4:19], v[138:141], v[134:137], v[4:19]
	ds_read_b128 v[134:137], v90 offset:41472
	ds_read_b128 v[138:141], v81 offset:4608
	s_waitcnt lgkmcnt(3)
	v_mfma_f32_32x32x16_bf16 v[52:67], v[102:105], v[118:121], v[52:67]
	s_waitcnt lgkmcnt(1)
	v_mfma_f32_32x32x16_bf16 v[36:51], v[102:105], v[134:137], v[36:51]
	s_waitcnt lgkmcnt(0)
	v_mfma_f32_32x32x16_bf16 v[20:35], v[138:141], v[118:121], v[20:35]
	ds_read_b128 v[102:105], v93 offset:41472
	ds_read_b128 v[118:121], v83 offset:4608
	v_mfma_f32_32x32x16_bf16 v[4:19], v[138:141], v[134:137], v[4:19]
	v_mfma_f32_32x32x16_bf16 v[52:67], v[122:125], v[142:145], v[52:67]
	s_waitcnt lgkmcnt(1)
	v_mfma_f32_32x32x16_bf16 v[36:51], v[122:125], v[102:105], v[36:51]
	s_waitcnt lgkmcnt(0)
	v_mfma_f32_32x32x16_bf16 v[20:35], v[118:121], v[142:145], v[20:35]
	global_load_dwordx4 v[122:125], v[70:71], off offset:1280
	global_load_dwordx4 v[134:137], v[72:73], off offset:1280
	global_load_dwordx4 v[138:141], v[74:75], off offset:1280
	global_load_dwordx4 v[142:145], v[76:77], off offset:1280
	global_load_dwordx4 v[146:149], v[68:69], off offset:1280
	global_load_dwordx4 v[158:161], v[78:79], off offset:1280
	s_waitcnt vmcnt(11)
	ds_write_b128 v80, v[98:101] offset:55296
	s_waitcnt vmcnt(10)
	ds_write_b128 v80, v[110:113] offset:64512
	s_waitcnt vmcnt(9)
	ds_write_b128 v89, v[114:117] offset:18432
	s_waitcnt vmcnt(8)
	ds_write_b128 v89, v[126:129] offset:27648
	s_waitcnt vmcnt(7)
	ds_write_b128 v91, v[130:133]
	s_waitcnt vmcnt(6)
	ds_write_b128 v91, v[162:165] offset:9216
	s_waitcnt lgkmcnt(0)
	s_barrier
	v_mfma_f32_32x32x16_bf16 v[4:19], v[118:121], v[102:105], v[4:19]
	ds_read_b128 v[98:101], v2 offset:55296
	ds_read_b128 v[102:105], v96
	ds_read_b128 v[110:113], v97
	ds_read_b128 v[114:117], v2 offset:55328
	s_waitcnt lgkmcnt(2)
	v_mfma_f32_32x32x16_bf16 v[52:67], v[98:101], v[102:105], v[52:67]
	s_waitcnt lgkmcnt(1)
	v_mfma_f32_32x32x16_bf16 v[36:51], v[98:101], v[110:113], v[36:51]
	ds_read_b128 v[98:101], v2 offset:59904
	ds_read_b128 v[118:121], v82 offset:59904
	s_waitcnt lgkmcnt(1)
	v_mfma_f32_32x32x16_bf16 v[20:35], v[98:101], v[102:105], v[20:35]
	v_mfma_f32_32x32x16_bf16 v[4:19], v[98:101], v[110:113], v[4:19]
	ds_read_b128 v[98:101], v85
	ds_read_b128 v[102:105], v86
	s_waitcnt lgkmcnt(1)
	v_mfma_f32_32x32x16_bf16 v[52:67], v[114:117], v[98:101], v[52:67]
	s_waitcnt lgkmcnt(0)
	v_mfma_f32_32x32x16_bf16 v[36:51], v[114:117], v[102:105], v[36:51]
	v_mfma_f32_32x32x16_bf16 v[20:35], v[118:121], v[98:101], v[20:35]
	v_mfma_f32_32x32x16_bf16 v[4:19], v[118:121], v[102:105], v[4:19]
	ds_read_b128 v[98:101], v2 offset:55360
	ds_read_b128 v[102:105], v88
	ds_read_b128 v[110:113], v92
	ds_read_b128 v[114:117], v2 offset:55392
	s_waitcnt lgkmcnt(2)
	v_mfma_f32_32x32x16_bf16 v[52:67], v[98:101], v[102:105], v[52:67]
	s_waitcnt lgkmcnt(1)
	v_mfma_f32_32x32x16_bf16 v[36:51], v[98:101], v[110:113], v[36:51]
	ds_read_b128 v[98:101], v81 offset:59904
	ds_read_b128 v[118:121], v83 offset:59904
	s_waitcnt lgkmcnt(1)
	v_mfma_f32_32x32x16_bf16 v[20:35], v[98:101], v[102:105], v[20:35]
	v_mfma_f32_32x32x16_bf16 v[4:19], v[98:101], v[110:113], v[4:19]
	ds_read_b128 v[98:101], v94
	ds_read_b128 v[102:105], v95
	s_waitcnt lgkmcnt(1)
	v_mfma_f32_32x32x16_bf16 v[52:67], v[114:117], v[98:101], v[52:67]
	s_waitcnt lgkmcnt(0)
	v_mfma_f32_32x32x16_bf16 v[36:51], v[114:117], v[102:105], v[36:51]
	v_mfma_f32_32x32x16_bf16 v[20:35], v[118:121], v[98:101], v[20:35]
	global_load_dwordx4 v[98:101], v[70:71], off offset:1408
	global_load_dwordx4 v[110:113], v[72:73], off offset:1408
	global_load_dwordx4 v[114:117], v[74:75], off offset:1408
	global_load_dwordx4 v[126:129], v[76:77], off offset:1408
	global_load_dwordx4 v[130:133], v[68:69], off offset:1408
	global_load_dwordx4 v[162:165], v[78:79], off offset:1408
	s_waitcnt vmcnt(11)
	ds_write_b128 v80, v[122:125]
	s_waitcnt vmcnt(10)
	ds_write_b128 v80, v[134:137] offset:9216
	s_waitcnt vmcnt(9)
	ds_write_b128 v80, v[138:141] offset:18432
	s_waitcnt vmcnt(8)
	ds_write_b128 v80, v[142:145] offset:27648
	s_waitcnt vmcnt(7)
	ds_write_b128 v80, v[146:149] offset:36864
	s_waitcnt vmcnt(6)
	ds_write_b128 v80, v[158:161] offset:46080
	s_waitcnt lgkmcnt(0)
	s_barrier
; template <bool SWAP, class Epi>
; DI void gemm_tile(const u16* __restrict__ A, int lda, const u16* __restrict__ Bw, int ldb, int K, char* lds, Epi epi) {
;     ...
;   for (int kt = 0; kt < nk; kt += 2) {
;     if (kt + 2 < nk) gload(kt + 2, ra0, rb0);
;     compute(0);
;     lstore(1, ra1, rb1);
;     __syncthreads();
;     if (kt + 3 < nk) gload(kt + 3, ra1, rb1);
;     compute(1);
;     if (kt + 2 < nk) lstore(0, ra0, rb0);
;     __syncthreads();
	v_mfma_f32_32x32x16_bf16 v[4:19], v[118:121], v[102:105], v[4:19]
	ds_read_b128 v[102:105], v2
	ds_read_b128 v[118:121], v84 offset:36864
	ds_read_b128 v[122:125], v2 offset:32
	ds_read_b128 v[134:137], v2 offset:4608
	ds_read_b128 v[138:141], v84 offset:41472
	ds_read_b128 v[142:145], v84 offset:36960
	s_waitcnt lgkmcnt(4)
	v_mfma_f32_32x32x16_bf16 v[52:67], v[102:105], v[118:121], v[52:67]
	s_waitcnt lgkmcnt(1)
	v_mfma_f32_32x32x16_bf16 v[36:51], v[102:105], v[138:141], v[36:51]
	v_mfma_f32_32x32x16_bf16 v[20:35], v[134:137], v[118:121], v[20:35]
	ds_read_b128 v[102:105], v84 offset:36896
	ds_read_b128 v[118:121], v84 offset:36928
	v_mfma_f32_32x32x16_bf16 v[4:19], v[134:137], v[138:141], v[4:19]
	ds_read_b128 v[134:137], v87 offset:41472
	ds_read_b128 v[138:141], v82 offset:4608
	s_waitcnt lgkmcnt(3)
	v_mfma_f32_32x32x16_bf16 v[52:67], v[122:125], v[102:105], v[52:67]
	s_waitcnt lgkmcnt(1)
	v_mfma_f32_32x32x16_bf16 v[36:51], v[122:125], v[134:137], v[36:51]
	s_waitcnt lgkmcnt(0)
	v_mfma_f32_32x32x16_bf16 v[20:35], v[138:141], v[102:105], v[20:35]
	ds_read_b128 v[102:105], v2 offset:64
	ds_read_b128 v[122:125], v2 offset:96
	v_mfma_f32_32x32x16_bf16 v[4:19], v[138:141], v[134:137], v[4:19]
	ds_read_b128 v[134:137], v90 offset:41472
	ds_read_b128 v[138:141], v81 offset:4608
	s_waitcnt lgkmcnt(3)
	v_mfma_f32_32x32x16_bf16 v[52:67], v[102:105], v[118:121], v[52:67]
	s_waitcnt lgkmcnt(1)
	v_mfma_f32_32x32x16_bf16 v[36:51], v[102:105], v[134:137], v[36:51]
	s_waitcnt lgkmcnt(0)
	v_mfma_f32_32x32x16_bf16 v[20:35], v[138:141], v[118:121], v[20:35]
	ds_read_b128 v[102:105], v93 offset:41472
	ds_read_b128 v[118:121], v83 offset:4608
	v_mfma_f32_32x32x16_bf16 v[4:19], v[138:141], v[134:137], v[4:19]
	v_mfma_f32_32x32x16_bf16 v[52:67], v[122:125], v[142:145], v[52:67]
	s_waitcnt lgkmcnt(1)
	v_mfma_f32_32x32x16_bf16 v[36:51], v[122:125], v[102:105], v[36:51]
	s_waitcnt lgkmcnt(0)
	v_mfma_f32_32x32x16_bf16 v[20:35], v[118:121], v[142:145], v[20:35]
	global_load_dwordx4 v[122:125], v[70:71], off offset:1536
	global_load_dwordx4 v[134:137], v[72:73], off offset:1536
	global_load_dwordx4 v[138:141], v[74:75], off offset:1536
	global_load_dwordx4 v[142:145], v[76:77], off offset:1536
	global_load_dwordx4 v[146:149], v[68:69], off offset:1536
	global_load_dwordx4 v[158:161], v[78:79], off offset:1536
	s_waitcnt vmcnt(11)
	ds_write_b128 v80, v[98:101] offset:55296
	s_waitcnt vmcnt(10)
	ds_write_b128 v80, v[110:113] offset:64512
	s_waitcnt vmcnt(9)
	ds_write_b128 v89, v[114:117] offset:18432
	s_waitcnt vmcnt(8)
	ds_write_b128 v89, v[126:129] offset:27648
	s_waitcnt vmcnt(7)
	ds_write_b128 v91, v[130:133]
	s_waitcnt vmcnt(6)
	ds_write_b128 v91, v[162:165] offset:9216
	s_waitcnt lgkmcnt(0)
	s_barrier
	v_mfma_f32_32x32x16_bf16 v[4:19], v[118:121], v[102:105], v[4:19]
	ds_read_b128 v[98:101], v2 offset:55296
	ds_read_b128 v[102:105], v96
	ds_read_b128 v[110:113], v97
	ds_read_b128 v[114:117], v2 offset:55328
	s_waitcnt lgkmcnt(2)
	v_mfma_f32_32x32x16_bf16 v[52:67], v[98:101], v[102:105], v[52:67]
	s_waitcnt lgkmcnt(1)
	v_mfma_f32_32x32x16_bf16 v[36:51], v[98:101], v[110:113], v[36:51]
	ds_read_b128 v[98:101], v2 offset:59904
	ds_read_b128 v[118:121], v82 offset:59904
	s_waitcnt lgkmcnt(1)
	v_mfma_f32_32x32x16_bf16 v[20:35], v[98:101], v[102:105], v[20:35]
	v_mfma_f32_32x32x16_bf16 v[4:19], v[98:101], v[110:113], v[4:19]
	ds_read_b128 v[98:101], v85
	ds_read_b128 v[102:105], v86
	s_waitcnt lgkmcnt(1)
	v_mfma_f32_32x32x16_bf16 v[52:67], v[114:117], v[98:101], v[52:67]
	s_waitcnt lgkmcnt(0)
	v_mfma_f32_32x32x16_bf16 v[36:51], v[114:117], v[102:105], v[36:51]
	v_mfma_f32_32x32x16_bf16 v[20:35], v[118:121], v[98:101], v[20:35]
	v_mfma_f32_32x32x16_bf16 v[4:19], v[118:121], v[102:105], v[4:19]
	ds_read_b128 v[98:101], v2 offset:55360
	ds_read_b128 v[102:105], v88
	ds_read_b128 v[110:113], v92
	ds_read_b128 v[114:117], v2 offset:55392
	s_waitcnt lgkmcnt(2)
	v_mfma_f32_32x32x16_bf16 v[52:67], v[98:101], v[102:105], v[52:67]
	s_waitcnt lgkmcnt(1)
	v_mfma_f32_32x32x16_bf16 v[36:51], v[98:101], v[110:113], v[36:51]
	ds_read_b128 v[98:101], v81 offset:59904
	ds_read_b128 v[118:121], v83 offset:59904
	s_waitcnt lgkmcnt(1)
	v_mfma_f32_32x32x16_bf16 v[20:35], v[98:101], v[102:105], v[20:35]
	v_mfma_f32_32x32x16_bf16 v[4:19], v[98:101], v[110:113], v[4:19]
	ds_read_b128 v[98:101], v94
	ds_read_b128 v[102:105], v95
	s_waitcnt lgkmcnt(1)
	v_mfma_f32_32x32x16_bf16 v[52:67], v[114:117], v[98:101], v[52:67]
	s_waitcnt lgkmcnt(0)
	v_mfma_f32_32x32x16_bf16 v[36:51], v[114:117], v[102:105], v[36:51]
	v_mfma_f32_32x32x16_bf16 v[20:35], v[118:121], v[98:101], v[20:35]
	global_load_dwordx4 v[98:101], v[70:71], off offset:1664
	global_load_dwordx4 v[110:113], v[72:73], off offset:1664
	global_load_dwordx4 v[114:117], v[74:75], off offset:1664
	global_load_dwordx4 v[126:129], v[76:77], off offset:1664
	global_load_dwordx4 v[130:133], v[68:69], off offset:1664
	global_load_dwordx4 v[162:165], v[78:79], off offset:1664
	s_waitcnt vmcnt(11)
	ds_write_b128 v80, v[122:125]
	s_waitcnt vmcnt(10)
	ds_write_b128 v80, v[134:137] offset:9216
	s_waitcnt vmcnt(9)
	ds_write_b128 v80, v[138:141] offset:18432
	s_waitcnt vmcnt(8)
	ds_write_b128 v80, v[142:145] offset:27648
	s_waitcnt vmcnt(7)
	ds_write_b128 v80, v[146:149] offset:36864
	s_waitcnt vmcnt(6)
	ds_write_b128 v80, v[158:161] offset:46080
	s_waitcnt lgkmcnt(0)
	s_barrier
; template <bool SWAP, class Epi>
; DI void gemm_tile(const u16* __restrict__ A, int lda, const u16* __restrict__ Bw, int ldb, int K, char* lds, Epi epi) {
;     ...
;   for (int kt = 0; kt < nk; kt += 2) {
;     if (kt + 2 < nk) gload(kt + 2, ra0, rb0);
;     compute(0);
;     lstore(1, ra1, rb1);
;     __syncthreads();
;     if (kt + 3 < nk) gload(kt + 3, ra1, rb1);
;     compute(1);
;     if (kt + 2 < nk) lstore(0, ra0, rb0);
;     __syncthreads();
	v_mfma_f32_32x32x16_bf16 v[4:19], v[118:121], v[102:105], v[4:19]
	ds_read_b128 v[102:105], v2
	ds_read_b128 v[118:121], v84 offset:36864
	ds_read_b128 v[122:125], v2 offset:32
	ds_read_b128 v[134:137], v2 offset:4608
	ds_read_b128 v[138:141], v84 offset:41472
	ds_read_b128 v[142:145], v84 offset:36960
	s_waitcnt lgkmcnt(4)
	v_mfma_f32_32x32x16_bf16 v[52:67], v[102:105], v[118:121], v[52:67]
	s_waitcnt lgkmcnt(1)
	v_mfma_f32_32x32x16_bf16 v[36:51], v[102:105], v[138:141], v[36:51]
	v_mfma_f32_32x32x16_bf16 v[20:35], v[134:137], v[118:121], v[20:35]
	ds_read_b128 v[102:105], v84 offset:36896
	ds_read_b128 v[118:121], v84 offset:36928
	v_mfma_f32_32x32x16_bf16 v[4:19], v[134:137], v[138:141], v[4:19]
	ds_read_b128 v[134:137], v87 offset:41472
	ds_read_b128 v[138:141], v82 offset:4608
	s_waitcnt lgkmcnt(3)
	v_mfma_f32_32x32x16_bf16 v[52:67], v[122:125], v[102:105], v[52:67]
	s_waitcnt lgkmcnt(1)
	v_mfma_f32_32x32x16_bf16 v[36:51], v[122:125], v[134:137], v[36:51]
	s_waitcnt lgkmcnt(0)
	v_mfma_f32_32x32x16_bf16 v[20:35], v[138:141], v[102:105], v[20:35]
	ds_read_b128 v[102:105], v2 offset:64
	ds_read_b128 v[122:125], v2 offset:96
	v_mfma_f32_32x32x16_bf16 v[4:19], v[138:141], v[134:137], v[4:19]
	ds_read_b128 v[134:137], v90 offset:41472
	ds_read_b128 v[138:141], v81 offset:4608
	s_waitcnt lgkmcnt(3)
	v_mfma_f32_32x32x16_bf16 v[52:67], v[102:105], v[118:121], v[52:67]
	s_waitcnt lgkmcnt(1)
	v_mfma_f32_32x32x16_bf16 v[36:51], v[102:105], v[134:137], v[36:51]
	s_waitcnt lgkmcnt(0)
	v_mfma_f32_32x32x16_bf16 v[20:35], v[138:141], v[118:121], v[20:35]
	ds_read_b128 v[102:105], v93 offset:41472
	ds_read_b128 v[118:121], v83 offset:4608
	v_mfma_f32_32x32x16_bf16 v[4:19], v[138:141], v[134:137], v[4:19]
	v_mfma_f32_32x32x16_bf16 v[52:67], v[122:125], v[142:145], v[52:67]
	s_waitcnt lgkmcnt(1)
	v_mfma_f32_32x32x16_bf16 v[36:51], v[122:125], v[102:105], v[36:51]
	s_waitcnt lgkmcnt(0)
	v_mfma_f32_32x32x16_bf16 v[20:35], v[118:121], v[142:145], v[20:35]
	global_load_dwordx4 v[122:125], v[70:71], off offset:1792
	global_load_dwordx4 v[134:137], v[72:73], off offset:1792
	global_load_dwordx4 v[138:141], v[74:75], off offset:1792
	global_load_dwordx4 v[142:145], v[76:77], off offset:1792
	global_load_dwordx4 v[146:149], v[68:69], off offset:1792
	global_load_dwordx4 v[158:161], v[78:79], off offset:1792
	s_waitcnt vmcnt(11)
	ds_write_b128 v80, v[98:101] offset:55296
	s_waitcnt vmcnt(10)
	ds_write_b128 v80, v[110:113] offset:64512
	s_waitcnt vmcnt(9)
	ds_write_b128 v89, v[114:117] offset:18432
	s_waitcnt vmcnt(8)
	ds_write_b128 v89, v[126:129] offset:27648
	s_waitcnt vmcnt(7)
	ds_write_b128 v91, v[130:133]
	s_waitcnt vmcnt(6)
	ds_write_b128 v91, v[162:165] offset:9216
	s_waitcnt lgkmcnt(0)
	s_barrier
	v_mfma_f32_32x32x16_bf16 v[4:19], v[118:121], v[102:105], v[4:19]
	ds_read_b128 v[98:101], v2 offset:55296
	ds_read_b128 v[102:105], v96
	ds_read_b128 v[110:113], v97
	ds_read_b128 v[114:117], v2 offset:55328
	s_waitcnt lgkmcnt(2)
	v_mfma_f32_32x32x16_bf16 v[52:67], v[98:101], v[102:105], v[52:67]
	s_waitcnt lgkmcnt(1)
	v_mfma_f32_32x32x16_bf16 v[36:51], v[98:101], v[110:113], v[36:51]
	ds_read_b128 v[98:101], v2 offset:59904
	ds_read_b128 v[118:121], v82 offset:59904
	s_waitcnt lgkmcnt(1)
	v_mfma_f32_32x32x16_bf16 v[20:35], v[98:101], v[102:105], v[20:35]
	v_mfma_f32_32x32x16_bf16 v[4:19], v[98:101], v[110:113], v[4:19]
	ds_read_b128 v[98:101], v85
	ds_read_b128 v[102:105], v86
	s_waitcnt lgkmcnt(1)
	v_mfma_f32_32x32x16_bf16 v[52:67], v[114:117], v[98:101], v[52:67]
	s_waitcnt lgkmcnt(0)
	v_mfma_f32_32x32x16_bf16 v[36:51], v[114:117], v[102:105], v[36:51]
	v_mfma_f32_32x32x16_bf16 v[20:35], v[118:121], v[98:101], v[20:35]
	v_mfma_f32_32x32x16_bf16 v[4:19], v[118:121], v[102:105], v[4:19]
	ds_read_b128 v[98:101], v2 offset:55360
	ds_read_b128 v[102:105], v88
	ds_read_b128 v[110:113], v92
	ds_read_b128 v[114:117], v2 offset:55392
	s_waitcnt lgkmcnt(2)
	v_mfma_f32_32x32x16_bf16 v[52:67], v[98:101], v[102:105], v[52:67]
	s_waitcnt lgkmcnt(1)
	v_mfma_f32_32x32x16_bf16 v[36:51], v[98:101], v[110:113], v[36:51]
	ds_read_b128 v[98:101], v81 offset:59904
	ds_read_b128 v[118:121], v83 offset:59904
	s_waitcnt lgkmcnt(1)
	v_mfma_f32_32x32x16_bf16 v[20:35], v[98:101], v[102:105], v[20:35]
	v_mfma_f32_32x32x16_bf16 v[4:19], v[98:101], v[110:113], v[4:19]
	ds_read_b128 v[98:101], v94
	ds_read_b128 v[102:105], v95
	s_waitcnt lgkmcnt(1)
	v_mfma_f32_32x32x16_bf16 v[52:67], v[114:117], v[98:101], v[52:67]
	s_waitcnt lgkmcnt(0)
	v_mfma_f32_32x32x16_bf16 v[36:51], v[114:117], v[102:105], v[36:51]
	v_mfma_f32_32x32x16_bf16 v[20:35], v[118:121], v[98:101], v[20:35]
	global_load_dwordx4 v[98:101], v[70:71], off offset:1920
	s_nop 0
	global_load_dwordx4 v[70:73], v[72:73], off offset:1920
	s_nop 0
	global_load_dwordx4 v[110:113], v[74:75], off offset:1920
	s_nop 0
	global_load_dwordx4 v[74:77], v[76:77], off offset:1920
	s_nop 0
	global_load_dwordx4 v[114:117], v[68:69], off offset:1920
	global_load_dwordx4 v[126:129], v[78:79], off offset:1920
	s_waitcnt vmcnt(11)
	ds_write_b128 v80, v[122:125]
	s_waitcnt vmcnt(10)
	ds_write_b128 v80, v[134:137] offset:9216
	s_waitcnt vmcnt(9)
	ds_write_b128 v80, v[138:141] offset:18432
	s_waitcnt vmcnt(8)
	ds_write_b128 v80, v[142:145] offset:27648
	s_waitcnt vmcnt(7)
	ds_write_b128 v80, v[146:149] offset:36864
	s_waitcnt vmcnt(6)
	ds_write_b128 v80, v[158:161] offset:46080
	s_waitcnt lgkmcnt(0)
	s_barrier
; DI unsigned pk2(float a, float b) { f32x2 v = {a, b}; return __builtin_bit_cast(unsigned, __builtin_convertvector(v, bf2_t)); }
; template <bool SWAP, class Epi>
; DI void gemm_tile(const u16* __restrict__ A, int lda, const u16* __restrict__ Bw, int ldb, int K, char* lds, Epi epi) {
;     ...
;   for (int kt = 0; kt < nk; kt += 2) {
;     if (kt + 2 < nk) gload(kt + 2, ra0, rb0);
;     compute(0);
;     lstore(1, ra1, rb1);
;     __syncthreads();
;     if (kt + 3 < nk) gload(kt + 3, ra1, rb1);
;     compute(1);
;     if (kt + 2 < nk) lstore(0, ra0, rb0);
;     __syncthreads();
;   }
; #pragma unroll
;   for (int mi = 0; mi < 2; ++mi)
; #pragma unroll
;     for (int ni = 0; ni < 2; ++ni) epi(mi, ni, acc[mi][ni]);
; DI void store_transposed(u16* dst, const f32x16& a, int h, const float* rs  ) {
; #pragma unroll
;   for (int g = 0; g < 4; ++g) {
;     float s0 = 1.f, s1 = 1.f, s2 = 1.f, s3 = 1.f;
;     if (rs) { f32x4 sv = *(const f32x4*)(rs + 8 * g + 4 * h); s0 = sv[0]; s1 = sv[1]; s2 = sv[2]; s3 = sv[3]; }
;     u32x2 v = {pk2(a[4 * g] * s0, a[4 * g + 1] * s1), pk2(a[4 * g + 2] * s2, a[4 * g + 3] * s3)};
;     *(u32x2*)(dst + 8 * g + 4 * h) = v;
;   }
; }
	v_mfma_f32_32x32x16_bf16 v[4:19], v[118:121], v[102:105], v[4:19]
	ds_read_b128 v[102:105], v2
	ds_read_b128 v[118:121], v84 offset:36864
	ds_read_b128 v[122:125], v2 offset:32
	ds_read_b128 v[130:133], v2 offset:4608
	ds_read_b128 v[134:137], v84 offset:41472
	ds_read_b128 v[138:141], v84 offset:36960
	s_waitcnt lgkmcnt(4)
	v_mfma_f32_32x32x16_bf16 v[52:67], v[102:105], v[118:121], v[52:67]
	s_waitcnt lgkmcnt(1)
	v_mfma_f32_32x32x16_bf16 v[36:51], v[102:105], v[134:137], v[36:51]
	v_mfma_f32_32x32x16_bf16 v[20:35], v[130:133], v[118:121], v[20:35]
	ds_read_b128 v[102:105], v84 offset:36896
	ds_read_b128 v[118:121], v84 offset:36928
	v_mfma_f32_32x32x16_bf16 v[4:19], v[130:133], v[134:137], v[4:19]
	ds_read_b128 v[130:133], v87 offset:41472
	ds_read_b128 v[134:137], v82 offset:4608
	s_waitcnt lgkmcnt(3)
	v_mfma_f32_32x32x16_bf16 v[52:67], v[122:125], v[102:105], v[52:67]
	s_waitcnt lgkmcnt(1)
	v_mfma_f32_32x32x16_bf16 v[36:51], v[122:125], v[130:133], v[36:51]
	s_waitcnt lgkmcnt(0)
	v_mfma_f32_32x32x16_bf16 v[20:35], v[134:137], v[102:105], v[20:35]
	ds_read_b128 v[102:105], v2 offset:64
	ds_read_b128 v[122:125], v2 offset:96
	s_waitcnt lgkmcnt(1)
	v_mfma_f32_32x32x16_bf16 v[52:67], v[102:105], v[118:121], v[52:67]
	v_mfma_f32_32x32x16_bf16 v[4:19], v[134:137], v[130:133], v[4:19]
	ds_read_b128 v[130:133], v90 offset:41472
	ds_read_b128 v[134:137], v81 offset:4608
	s_waitcnt lgkmcnt(1)
	v_mfma_f32_32x32x16_bf16 v[36:51], v[102:105], v[130:133], v[36:51]
	v_mfma_f32_32x32x16_bf16 v[52:67], v[122:125], v[138:141], v[52:67]
	s_waitcnt lgkmcnt(0)
	v_mfma_f32_32x32x16_bf16 v[20:35], v[134:137], v[118:121], v[20:35]
	ds_read_b128 v[102:105], v93 offset:41472
	ds_read_b128 v[118:121], v83 offset:4608
	s_waitcnt vmcnt(5)
	ds_write_b128 v80, v[98:101] offset:55296
	s_waitcnt vmcnt(4)
	ds_write_b128 v80, v[70:73] offset:64512
	s_waitcnt vmcnt(3)
	ds_write_b128 v89, v[110:113] offset:18432
	s_waitcnt vmcnt(2)
	ds_write_b128 v89, v[74:77] offset:27648
	s_waitcnt vmcnt(1)
	ds_write_b128 v91, v[114:117]
	s_waitcnt vmcnt(0)
	ds_write_b128 v91, v[126:129] offset:9216
	s_waitcnt lgkmcnt(0)
	s_barrier
	ds_read_b128 v[68:71], v2 offset:55296
	ds_read_b128 v[72:75], v96
	ds_read_b128 v[76:79], v97
	ds_read_b128 v[96:99], v2 offset:55328
	v_mfma_f32_32x32x16_bf16 v[4:19], v[134:137], v[130:133], v[4:19]
	v_mfma_f32_32x32x16_bf16 v[36:51], v[122:125], v[102:105], v[36:51]
	s_waitcnt lgkmcnt(2)
	v_mfma_f32_32x32x16_bf16 v[52:67], v[68:71], v[72:75], v[52:67]
	v_mfma_f32_32x32x16_bf16 v[20:35], v[118:121], v[138:141], v[20:35]
	v_mfma_f32_32x32x16_bf16 v[4:19], v[118:121], v[102:105], v[4:19]
	ds_read_b128 v[100:103], v2 offset:59904
	s_waitcnt lgkmcnt(2)
	v_mfma_f32_32x32x16_bf16 v[36:51], v[68:71], v[76:79], v[36:51]
	ds_read_b128 v[68:71], v82 offset:59904
	ds_read_b128 v[110:113], v85
	ds_read_b128 v[84:87], v86
	ds_read_b128 v[88:91], v88
	ds_read_b128 v[114:117], v92
	ds_read_b128 v[118:121], v2 offset:55360
	ds_read_b128 v[122:125], v2 offset:55392
	s_waitcnt lgkmcnt(5)
	v_mfma_f32_32x32x16_bf16 v[52:67], v[96:99], v[110:113], v[52:67]
	s_waitcnt lgkmcnt(1)
	v_mfma_f32_32x32x16_bf16 v[52:67], v[118:121], v[88:91], v[52:67]
	v_mfma_f32_32x32x16_bf16 v[20:35], v[100:103], v[72:75], v[20:35]
	ds_read_b128 v[72:75], v81 offset:59904
	ds_read_b128 v[80:83], v83 offset:59904
	ds_read_b128 v[126:129], v94
	ds_read_b128 v[92:95], v95
	s_waitcnt lgkmcnt(0)
	s_barrier
	v_mfma_f32_32x32x16_bf16 v[36:51], v[96:99], v[84:87], v[36:51]
	v_mov_b64_e32 v[96:97], s[10:11]
	v_mfma_f32_32x32x16_bf16 v[4:19], v[100:103], v[76:79], v[4:19]
	v_lshlrev_b32_e32 v101, 6, v0
	v_add_u32_e32 v2, s3, v101
	v_or_b32_e32 v78, v2, v107
	v_lshlrev_b32_e32 v100, 6, v108
	v_ashrrev_i32_e32 v79, 31, v78
	v_or_b32_e32 v76, s5, v100
	v_lshl_add_u64 v[78:79], s[0:1], 0, v[78:79]
	v_mfma_f32_32x32x16_bf16 v[52:67], v[122:125], v[126:129], v[52:67]
	v_mad_u64_u32 v[98:99], s[10:11], v78, s12, v[96:97]
	v_ashrrev_i32_e32 v77, 31, v76
	v_mad_i32_i24 v99, v79, s12, v99
	v_lshlrev_b64 v[76:77], 1, v[76:77]
	v_lshl_add_u64 v[78:79], v[98:99], 0, v[76:77]
	v_lshlrev_b32_e32 v2, 3, v106
	v_mfma_f32_32x32x16_bf16 v[20:35], v[68:71], v[110:113], v[20:35]
	v_lshl_add_u64 v[78:79], v[78:79], 0, v[2:3]
	s_nop 3
	v_cvt_pk_bf16_f32 v52, v52, v53
	v_cvt_pk_bf16_f32 v53, v54, v55
	global_store_dwordx2 v[78:79], v[52:53], off
	v_cvt_pk_bf16_f32 v52, v56, v57
	v_cvt_pk_bf16_f32 v53, v58, v59
	global_store_dwordx2 v[78:79], v[52:53], off offset:16
	v_mfma_f32_32x32x16_bf16 v[36:51], v[118:121], v[114:117], v[36:51]
	v_cvt_pk_bf16_f32 v52, v60, v61
	v_cvt_pk_bf16_f32 v53, v62, v63
	global_store_dwordx2 v[78:79], v[52:53], off offset:32
	v_cvt_pk_bf16_f32 v52, v64, v65
	v_cvt_pk_bf16_f32 v53, v66, v67
	global_store_dwordx2 v[78:79], v[52:53], off offset:48
	v_or_b32_e32 v52, s3, v107
	v_mfma_f32_32x32x16_bf16 v[4:19], v[68:71], v[84:87], v[4:19]
	v_add3_u32 v52, v101, v52, 32
	v_ashrrev_i32_e32 v53, 31, v52
	v_lshl_add_u64 v[52:53], s[0:1], 0, v[52:53]
	v_mad_u64_u32 v[54:55], s[0:1], v52, s12, v[96:97]
	v_mad_i32_i24 v55, v53, s12, v55
	v_lshl_add_u64 v[52:53], v[54:55], 0, v[76:77]
	v_mfma_f32_32x32x16_bf16 v[36:51], v[122:125], v[92:95], v[36:51]
	v_lshl_add_u64 v[52:53], v[52:53], 0, v[2:3]
	s_add_i32 s5, s5, 32
	s_mov_b64 s[0:1], 0
	v_mfma_f32_32x32x16_bf16 v[20:35], v[72:75], v[88:91], v[20:35]
	s_nop 7
	v_cvt_pk_bf16_f32 v36, v36, v37
	v_cvt_pk_bf16_f32 v37, v38, v39
	global_store_dwordx2 v[52:53], v[36:37], off
	v_cvt_pk_bf16_f32 v36, v40, v41
	v_cvt_pk_bf16_f32 v37, v42, v43
	global_store_dwordx2 v[52:53], v[36:37], off offset:16
	v_cvt_pk_bf16_f32 v36, v44, v45
	v_mfma_f32_32x32x16_bf16 v[4:19], v[72:75], v[114:117], v[4:19]
; template <bool SWAP, class Epi>
; DI void gemm_tile(const u16* __restrict__ A, int lda, const u16* __restrict__ Bw, int ldb, int K, char* lds, Epi epi) {
;     ...
;   const int lrow = tid >> 3, lkc = tid & 7;
;   u32x4 ra0[4], rb0[2], ra1[4], rb1[2];
;   const u16* ap = A + (size_t)lrow * lda + lkc * 8;
;   const u16* bp = Bw + (size_t)lrow * ldb + lkc * 8;
;   const int nk = K >> 6;
;   auto gload = [&](int kt, u32x4* ra, u32x4* rb) {
; #pragma unroll
;     for (int j = 0; j < 4; ++j) ra[j] = *(const u32x4*)(ap + (size_t)(64 * j) * lda + kt * 64);
; #pragma unroll
;     for (int j = 0; j < 2; ++j) rb[j] = *(const u32x4*)(bp + (size_t)(64 * j) * ldb + kt * 64);
;   };
;   auto lstore = [&](int st, const u32x4* ra, const u32x4* rb) {
;     char* base = lds + st * GEMM_STAGE;
; #pragma unroll
;     for (int j = 0; j < 4; ++j) *(u32x4*)(base + ((lrow + 64 * j) * 72 + lkc * 8) * 2) = ra[j];
; #pragma unroll
;     for (int j = 0; j < 2; ++j) *(u32x4*)(base + 36864 + ((lrow + 64 * j) * 72 + lkc * 8) * 2) = rb[j];
;   };
;   auto compute = [&](int st) {
;     const char* as = lds + st * GEMM_STAGE;
;     const char* bs = as + 36864;
; #pragma unroll
;     for (int ks = 0; ks < 4; ++ks) {
;       bf16x8 af[2], bfr[2];
; #pragma unroll
;       for (int mi = 0; mi < 2; ++mi) af[mi] = *(const bf16x8*)(as + ((wm * 64 + mi * 32 + r) * 72 + ks * 16 + 8 * h) * 2);
; #pragma unroll
;       for (int ni = 0; ni < 2; ++ni) bfr[ni] = *(const bf16x8*)(bs + ((wn * 64 + ni * 32 + r) * 72 + ks * 16 + 8 * h) * 2);
; #pragma unroll
;       for (int mi = 0; mi < 2; ++mi)
; #pragma unroll
;         for (int ni = 0; ni < 2; ++ni) {
;           if (SWAP) acc[mi][ni] = MFMA32(bfr[ni], af[mi], acc[mi][ni]);
;           else acc[mi][ni] = MFMA32(af[mi], bfr[ni], acc[mi][ni]);
;         }
;     }
;   };
;   gload(0, ra0, rb0);
;   lstore(0, ra0, rb0);
;   gload(1, ra1, rb1);
;   __syncthreads();
; DI void store_transposed(u16* dst, const f32x16& a, int h, const float* rs  ) {
; #pragma unroll
;   for (int g = 0; g < 4; ++g) {
;     float s0 = 1.f, s1 = 1.f, s2 = 1.f, s3 = 1.f;
;     if (rs) { f32x4 sv = *(const f32x4*)(rs + 8 * g + 4 * h); s0 = sv[0]; s1 = sv[1]; s2 = sv[2]; s3 = sv[3]; }
;     u32x2 v = {pk2(a[4 * g] * s0, a[4 * g + 1] * s1), pk2(a[4 * g + 2] * s2, a[4 * g + 3] * s3)};
;     *(u32x2*)(dst + 8 * g + 4 * h) = v;
;   }
	v_cvt_pk_bf16_f32 v37, v46, v47
	global_store_dwordx2 v[52:53], v[36:37], off offset:32
	v_cvt_pk_bf16_f32 v36, v48, v49
	v_cvt_pk_bf16_f32 v37, v50, v51
	global_store_dwordx2 v[52:53], v[36:37], off offset:48
	v_or_b32_e32 v36, s5, v100
	v_ashrrev_i32_e32 v37, 31, v36
	v_mfma_f32_32x32x16_bf16 v[20:35], v[80:83], v[126:129], v[20:35]
	v_lshlrev_b64 v[36:37], 1, v[36:37]
	v_lshl_add_u64 v[38:39], v[98:99], 0, v[36:37]
	v_lshl_add_u64 v[38:39], v[38:39], 0, v[2:3]
	v_mfma_f32_32x32x16_bf16 v[4:19], v[80:83], v[92:95], v[4:19]
	s_nop 7
	v_cvt_pk_bf16_f32 v20, v20, v21
	v_cvt_pk_bf16_f32 v21, v22, v23
	global_store_dwordx2 v[38:39], v[20:21], off
	v_cvt_pk_bf16_f32 v20, v24, v25
	v_cvt_pk_bf16_f32 v21, v26, v27
	global_store_dwordx2 v[38:39], v[20:21], off offset:16
	v_cvt_pk_bf16_f32 v20, v28, v29
	v_cvt_pk_bf16_f32 v21, v30, v31
	global_store_dwordx2 v[38:39], v[20:21], off offset:32
	v_cvt_pk_bf16_f32 v20, v32, v33
	v_cvt_pk_bf16_f32 v21, v34, v35
	global_store_dwordx2 v[38:39], v[20:21], off offset:48
	v_lshl_add_u64 v[20:21], v[54:55], 0, v[36:37]
	v_lshl_add_u64 v[20:21], v[20:21], 0, v[2:3]
	v_cvt_pk_bf16_f32 v4, v4, v5
	v_cvt_pk_bf16_f32 v5, v6, v7
	global_store_dwordx2 v[20:21], v[4:5], off
	v_cvt_pk_bf16_f32 v4, v8, v9
	v_cvt_pk_bf16_f32 v5, v10, v11
	global_store_dwordx2 v[20:21], v[4:5], off offset:16
	v_cvt_pk_bf16_f32 v4, v12, v13
	v_cvt_pk_bf16_f32 v5, v14, v15
	global_store_dwordx2 v[20:21], v[4:5], off offset:32
	v_cvt_pk_bf16_f32 v4, v16, v17
	v_cvt_pk_bf16_f32 v5, v18, v19
	global_store_dwordx2 v[20:21], v[4:5], off offset:48
.LBB0_327:
	s_andn2_b64 vcc, exec, s[0:1]
	s_cbranch_vccnz .LBB0_357
	v_mov_b32_e32 v30, v152
	s_mov_b32 s0, 0xfffffc0
	v_ashrrev_i32_e32 v28, 3, v30
	v_ashrrev_i32_e32 v29, 31, v28
	s_waitcnt vmcnt(3)
	v_lshlrev_b64 v[4:5], 11, v[28:29]
	v_lshlrev_b32_e32 v2, 4, v30
	v_lshl_add_u64 v[6:7], s[6:7], 0, v[4:5]
	v_and_b32_e32 v2, 0x70, v2
	v_lshl_add_u64 v[94:95], v[6:7], 0, v[2:3]
	v_add_co_u32_e32 v96, vcc, 0x20000, v94
	v_lshl_add_u64 v[4:5], s[8:9], 0, v[4:5]
	s_nop 0
	v_addc_co_u32_e32 v97, vcc, 0, v95, vcc
	v_add_co_u32_e32 v98, vcc, 0x40000, v94
	v_lshl_add_u64 v[92:93], v[4:5], 0, v[2:3]
	s_nop 0
	v_addc_co_u32_e32 v99, vcc, 0, v95, vcc
	v_add_co_u32_e32 v100, vcc, 0x60000, v94
	global_load_dwordx4 v[4:7], v[94:95], off
	global_load_dwordx4 v[8:11], v[96:97], off
	v_addc_co_u32_e32 v101, vcc, 0, v95, vcc
	global_load_dwordx4 v[12:15], v[98:99], off
	global_load_dwordx4 v[16:19], v[100:101], off
	global_load_dwordx4 v[20:23], v[92:93], off
	v_add_co_u32_e32 v102, vcc, s60, v92
	v_and_b32_e32 v29, 31, v30
	s_nop 0
	v_addc_co_u32_e32 v103, vcc, 0, v93, vcc
	global_load_dwordx4 v[24:27], v[102:103], off
	global_load_dwordx4 v[84:87], v[94:95], off offset:128
	global_load_dwordx4 v[68:71], v[92:93], off offset:128
	global_load_dwordx4 v[88:91], v[96:97], off offset:128
	global_load_dwordx4 v[76:79], v[98:99], off offset:128
	global_load_dwordx4 v[80:83], v[100:101], off offset:128
	global_load_dwordx4 v[72:75], v[102:103], off offset:128
	v_lshrrev_b32_e32 v32, 2, v30
	v_lshrrev_b32_e32 v31, 1, v30
	v_and_or_b32 v29, v32, s0, v29
	v_and_b32_e32 v136, 16, v31
	v_mul_lo_u32 v137, v29, s57
	v_mad_u64_u32 v[104:105], s[0:1], v28, s57, v[2:3]
	v_add_u32_e32 v128, v137, v136
	v_add_u32_e32 v105, 0, v104
	v_add_u32_e32 v111, 0, v128
	v_and_b32_e32 v2, 0xdf, v30
	v_mul_u32_u24_e32 v112, 0x90, v2
	v_add3_u32 v2, v112, v136, 0
	v_or_b32_e32 v138, 32, v136
	v_add_u32_e32 v139, v137, v138
	v_add_u32_e32 v113, 0, v139
	v_add3_u32 v110, v112, v138, 0
	v_or_b32_e32 v140, 64, v136
	v_add_u32_e32 v141, v137, v140
	v_add3_u32 v109, v112, v140, 0
	v_or_b32_e32 v142, 0x60, v136
	v_add_u32_e32 v143, v137, v142
	v_add3_u32 v112, v112, v142, 0
	v_readlane_b32 s0, v238, 25
	v_cmp_lt_i32_e32 vcc, 0, v0
	s_mov_b64 s[10:11], 0
	s_mov_b64 s[14:15], 0
	s_waitcnt vmcnt(11)
	ds_write_b128 v105, v[4:7]
	s_waitcnt vmcnt(7)
	ds_write_b128 v105, v[20:23] offset:36864
	ds_write_b128 v105, v[8:11] offset:9216
	ds_write_b128 v105, v[12:15] offset:18432
	ds_write_b128 v105, v[16:19] offset:27648
	s_waitcnt vmcnt(6)
	ds_write_b128 v105, v[24:27] offset:46080
	s_waitcnt lgkmcnt(0)
	s_barrier
	ds_read_b128 v[4:7], v111 offset:36864
	ds_read_b128 v[8:11], v2
	ds_read_b128 v[12:15], v111 offset:41472
	s_waitcnt lgkmcnt(1)
	v_mfma_f32_32x32x16_bf16 v[52:67], v[4:7], v[8:11], 0
	s_waitcnt lgkmcnt(0)
	v_mfma_f32_32x32x16_bf16 v[36:51], v[12:15], v[8:11], 0
	ds_read_b128 v[8:11], v2 offset:4608
	ds_read_b128 v[114:117], v111 offset:36896
	ds_read_b128 v[118:121], v2 offset:32
	ds_read_b128 v[122:125], v113 offset:41472
	s_waitcnt lgkmcnt(3)
	v_mfma_f32_32x32x16_bf16 v[20:35], v[4:7], v[8:11], 0
	v_mfma_f32_32x32x16_bf16 v[4:19], v[12:15], v[8:11], 0
	s_waitcnt lgkmcnt(1)
	v_mfma_f32_32x32x16_bf16 v[52:67], v[114:117], v[118:121], v[52:67]
	s_waitcnt lgkmcnt(0)
	v_mfma_f32_32x32x16_bf16 v[36:51], v[122:125], v[118:121], v[36:51]
	ds_read_b128 v[118:121], v110 offset:4608
	s_waitcnt lgkmcnt(0)
	v_mfma_f32_32x32x16_bf16 v[20:35], v[114:117], v[118:121], v[20:35]
	v_add_u32_e32 v114, 0, v141
	v_add_u32_e32 v115, 0, v143
	v_mfma_f32_32x32x16_bf16 v[4:19], v[122:125], v[118:121], v[4:19]
	ds_read_b128 v[116:119], v111 offset:36928
	ds_read_b128 v[120:123], v2 offset:64
	ds_read_b128 v[124:127], v114 offset:41472
	s_waitcnt lgkmcnt(1)
	v_mfma_f32_32x32x16_bf16 v[52:67], v[116:119], v[120:123], v[52:67]
	s_waitcnt lgkmcnt(0)
	v_mfma_f32_32x32x16_bf16 v[36:51], v[124:127], v[120:123], v[36:51]
	ds_read_b128 v[120:123], v109 offset:4608
	s_waitcnt lgkmcnt(0)
; #define MFMA32(a, b, c) __builtin_amdgcn_mfma_f32_32x32x16_bf16((a), (b), (c), 0, 0, 0)
; template <bool SWAP, class Epi>
; DI void gemm_tile(const u16* __restrict__ A, int lda, const u16* __restrict__ Bw, int ldb, int K, char* lds, Epi epi) {
;     ...
;   auto compute = [&](int st) {
;     const char* as = lds + st * GEMM_STAGE;
;     const char* bs = as + 36864;
; #pragma unroll
;     for (int ks = 0; ks < 4; ++ks) {
;       bf16x8 af[2], bfr[2];
; #pragma unroll
;       for (int mi = 0; mi < 2; ++mi) af[mi] = *(const bf16x8*)(as + ((wm * 64 + mi * 32 + r) * 72 + ks * 16 + 8 * h) * 2);
; #pragma unroll
;       for (int ni = 0; ni < 2; ++ni) bfr[ni] = *(const bf16x8*)(bs + ((wn * 64 + ni * 32 + r) * 72 + ks * 16 + 8 * h) * 2);
; #pragma unroll
;       for (int mi = 0; mi < 2; ++mi)
; #pragma unroll
;         for (int ni = 0; ni < 2; ++ni) {
;           if (SWAP) acc[mi][ni] = MFMA32(bfr[ni], af[mi], acc[mi][ni]);
;           else acc[mi][ni] = MFMA32(af[mi], bfr[ni], acc[mi][ni]);
;         }
;     }
;   };
;   gload(0, ra0, rb0);
;   lstore(0, ra0, rb0);
;   gload(1, ra1, rb1);
;   __syncthreads();
;   for (int kt = 0; kt < nk; kt += 2) {
;     if (kt + 2 < nk) gload(kt + 2, ra0, rb0);
;     compute(0);
;     lstore(1, ra1, rb1);
;     __syncthreads();
;     if (kt + 3 < nk) gload(kt + 3, ra1, rb1);
;     compute(1);
;     if (kt + 2 < nk) lstore(0, ra0, rb0);
;     __syncthreads();
	v_mfma_f32_32x32x16_bf16 v[20:35], v[116:119], v[120:123], v[20:35]
	v_mfma_f32_32x32x16_bf16 v[4:19], v[124:127], v[120:123], v[4:19]
	ds_read_b128 v[116:119], v111 offset:36960
	ds_read_b128 v[120:123], v2 offset:96
	ds_read_b128 v[124:127], v115 offset:41472
	s_waitcnt lgkmcnt(1)
	v_mfma_f32_32x32x16_bf16 v[52:67], v[116:119], v[120:123], v[52:67]
	s_waitcnt lgkmcnt(0)
	v_mfma_f32_32x32x16_bf16 v[36:51], v[124:127], v[120:123], v[36:51]
	ds_read_b128 v[120:123], v112 offset:4608
	s_waitcnt lgkmcnt(0)
	v_mfma_f32_32x32x16_bf16 v[20:35], v[116:119], v[120:123], v[20:35]
	v_add_u32_e32 v117, s0, v104
	v_add_u32_e32 v116, s59, v104
	v_add_u32_e32 v104, s59, v128
	global_load_dwordx4 v[128:131], v[94:95], off offset:256
	global_load_dwordx4 v[132:135], v[96:97], off offset:256
	v_mfma_f32_32x32x16_bf16 v[4:19], v[124:127], v[120:123], v[4:19]
	global_load_dwordx4 v[118:121], v[98:99], off offset:256
	global_load_dwordx4 v[122:125], v[100:101], off offset:256
	v_add_u32_e32 v126, 0x1200, v137
	s_waitcnt vmcnt(9)
	ds_write_b128 v105, v[84:87] offset:55296
	global_load_dwordx4 v[84:87], v[92:93], off offset:256
	s_waitcnt vmcnt(8)
	ds_write_b128 v105, v[88:91] offset:64512
	global_load_dwordx4 v[88:91], v[102:103], off offset:256
	s_waitcnt vmcnt(8)
	ds_write_b128 v117, v[76:79] offset:18432
	s_waitcnt vmcnt(7)
	ds_write_b128 v117, v[80:83] offset:27648
	ds_write_b128 v116, v[68:71]
	s_waitcnt vmcnt(6)
	ds_write_b128 v116, v[72:75] offset:9216
	v_add3_u32 v68, v126, v136, s59
	s_waitcnt lgkmcnt(0)
	s_barrier
	ds_read_b128 v[70:73], v104
	ds_read_b128 v[74:77], v2 offset:55296
	ds_read_b128 v[78:81], v68
	s_waitcnt lgkmcnt(1)
	v_mfma_f32_32x32x16_bf16 v[52:67], v[70:73], v[74:77], v[52:67]
	v_add3_u32 v69, v126, v140, s59
	s_waitcnt lgkmcnt(0)
	v_mfma_f32_32x32x16_bf16 v[36:51], v[78:81], v[74:77], v[36:51]
	ds_read_b128 v[74:77], v2 offset:59904
	s_waitcnt lgkmcnt(0)
	v_mfma_f32_32x32x16_bf16 v[20:35], v[70:73], v[74:77], v[20:35]
	v_add_u32_e32 v70, s59, v139
	v_add3_u32 v71, v126, v138, s59
	v_mfma_f32_32x32x16_bf16 v[4:19], v[78:81], v[74:77], v[4:19]
	ds_read_b128 v[72:75], v70
	ds_read_b128 v[76:79], v2 offset:55328
	ds_read_b128 v[80:83], v71
	s_waitcnt lgkmcnt(1)
	v_mfma_f32_32x32x16_bf16 v[52:67], v[72:75], v[76:79], v[52:67]
	s_waitcnt lgkmcnt(0)
	v_mfma_f32_32x32x16_bf16 v[36:51], v[80:83], v[76:79], v[36:51]
	ds_read_b128 v[76:79], v110 offset:59904
	s_waitcnt lgkmcnt(0)
	v_mfma_f32_32x32x16_bf16 v[20:35], v[72:75], v[76:79], v[20:35]
	v_add_u32_e32 v72, s59, v141
	v_add_u32_e32 v73, s59, v143
	v_mfma_f32_32x32x16_bf16 v[4:19], v[80:83], v[76:79], v[4:19]
	ds_read_b128 v[74:77], v72
	ds_read_b128 v[78:81], v2 offset:55360
	ds_read_b128 v[136:139], v69
	s_waitcnt lgkmcnt(1)
	v_mfma_f32_32x32x16_bf16 v[52:67], v[74:77], v[78:81], v[52:67]
	s_waitcnt lgkmcnt(0)
	v_mfma_f32_32x32x16_bf16 v[36:51], v[136:139], v[78:81], v[36:51]
	ds_read_b128 v[78:81], v109 offset:59904
	s_waitcnt lgkmcnt(0)
	v_mfma_f32_32x32x16_bf16 v[20:35], v[74:77], v[78:81], v[20:35]
	v_add3_u32 v74, v126, v142, s59
	v_mfma_f32_32x32x16_bf16 v[4:19], v[136:139], v[78:81], v[4:19]
	ds_read_b128 v[76:79], v73
	ds_read_b128 v[80:83], v2 offset:55392
	ds_read_b128 v[136:139], v74
	s_waitcnt lgkmcnt(1)
	v_mfma_f32_32x32x16_bf16 v[52:67], v[76:79], v[80:83], v[52:67]
	s_waitcnt lgkmcnt(0)
	v_mfma_f32_32x32x16_bf16 v[36:51], v[136:139], v[80:83], v[36:51]
	ds_read_b128 v[80:83], v112 offset:59904
	s_waitcnt lgkmcnt(0)
	v_mfma_f32_32x32x16_bf16 v[20:35], v[76:79], v[80:83], v[20:35]
	global_load_dwordx4 v[76:79], v[94:95], off offset:384
	global_load_dwordx4 v[140:143], v[96:97], off offset:384
	global_load_dwordx4 v[144:147], v[98:99], off offset:384
	v_mfma_f32_32x32x16_bf16 v[4:19], v[136:139], v[80:83], v[4:19]
	global_load_dwordx4 v[80:83], v[100:101], off offset:384
	global_load_dwordx4 v[136:139], v[92:93], off offset:384
	s_waitcnt vmcnt(10)
	ds_write_b128 v105, v[128:131]
	global_load_dwordx4 v[126:129], v[102:103], off offset:384
	s_waitcnt vmcnt(10)
	ds_write_b128 v105, v[132:135] offset:9216
	s_waitcnt vmcnt(9)
	ds_write_b128 v105, v[118:121] offset:18432
	s_waitcnt vmcnt(8)
	ds_write_b128 v105, v[122:125] offset:27648
	s_waitcnt vmcnt(7)
	ds_write_b128 v105, v[84:87] offset:36864
	s_waitcnt vmcnt(6)
	ds_write_b128 v105, v[88:91] offset:46080
	s_waitcnt lgkmcnt(0)
	s_barrier
; #define MFMA32(a, b, c) __builtin_amdgcn_mfma_f32_32x32x16_bf16((a), (b), (c), 0, 0, 0)
; template <bool SWAP, class Epi>
; DI void gemm_tile(const u16* __restrict__ A, int lda, const u16* __restrict__ Bw, int ldb, int K, char* lds, Epi epi) {
;     ...
;   auto compute = [&](int st) {
;     const char* as = lds + st * GEMM_STAGE;
;     const char* bs = as + 36864;
; #pragma unroll
;     for (int ks = 0; ks < 4; ++ks) {
;       bf16x8 af[2], bfr[2];
; #pragma unroll
;       for (int mi = 0; mi < 2; ++mi) af[mi] = *(const bf16x8*)(as + ((wm * 64 + mi * 32 + r) * 72 + ks * 16 + 8 * h) * 2);
; #pragma unroll
;       for (int ni = 0; ni < 2; ++ni) bfr[ni] = *(const bf16x8*)(bs + ((wn * 64 + ni * 32 + r) * 72 + ks * 16 + 8 * h) * 2);
; #pragma unroll
;       for (int mi = 0; mi < 2; ++mi)
; #pragma unroll
;         for (int ni = 0; ni < 2; ++ni) {
;           if (SWAP) acc[mi][ni] = MFMA32(bfr[ni], af[mi], acc[mi][ni]);
;           else acc[mi][ni] = MFMA32(af[mi], bfr[ni], acc[mi][ni]);
;         }
;     }
;   };
;   gload(0, ra0, rb0);
;   lstore(0, ra0, rb0);
;   gload(1, ra1, rb1);
;   __syncthreads();
;   for (int kt = 0; kt < nk; kt += 2) {
;     if (kt + 2 < nk) gload(kt + 2, ra0, rb0);
;     compute(0);
;     lstore(1, ra1, rb1);
;     __syncthreads();
;     if (kt + 3 < nk) gload(kt + 3, ra1, rb1);
;     compute(1);
;     if (kt + 2 < nk) lstore(0, ra0, rb0);
;     __syncthreads();
	ds_read_b128 v[84:87], v111 offset:36864
	ds_read_b128 v[88:91], v2
	ds_read_b128 v[118:121], v111 offset:41472
	s_waitcnt lgkmcnt(1)
	v_mfma_f32_32x32x16_bf16 v[52:67], v[84:87], v[88:91], v[52:67]
	s_waitcnt lgkmcnt(0)
	v_mfma_f32_32x32x16_bf16 v[36:51], v[118:121], v[88:91], v[36:51]
	ds_read_b128 v[88:91], v2 offset:4608
	s_waitcnt lgkmcnt(0)
	v_mfma_f32_32x32x16_bf16 v[20:35], v[84:87], v[88:91], v[20:35]
	v_mfma_f32_32x32x16_bf16 v[4:19], v[118:121], v[88:91], v[4:19]
	ds_read_b128 v[84:87], v111 offset:36896
	ds_read_b128 v[88:91], v2 offset:32
	ds_read_b128 v[118:121], v113 offset:41472
	s_waitcnt lgkmcnt(1)
	v_mfma_f32_32x32x16_bf16 v[52:67], v[84:87], v[88:91], v[52:67]
	s_waitcnt lgkmcnt(0)
	v_mfma_f32_32x32x16_bf16 v[36:51], v[118:121], v[88:91], v[36:51]
	ds_read_b128 v[88:91], v110 offset:4608
	s_waitcnt lgkmcnt(0)
	v_mfma_f32_32x32x16_bf16 v[20:35], v[84:87], v[88:91], v[20:35]
	v_mfma_f32_32x32x16_bf16 v[4:19], v[118:121], v[88:91], v[4:19]
	ds_read_b128 v[84:87], v111 offset:36928
	ds_read_b128 v[88:91], v2 offset:64
	ds_read_b128 v[118:121], v114 offset:41472
	s_waitcnt lgkmcnt(1)
	v_mfma_f32_32x32x16_bf16 v[52:67], v[84:87], v[88:91], v[52:67]
	s_waitcnt lgkmcnt(0)
	v_mfma_f32_32x32x16_bf16 v[36:51], v[118:121], v[88:91], v[36:51]
	ds_read_b128 v[88:91], v109 offset:4608
	s_waitcnt lgkmcnt(0)
	v_mfma_f32_32x32x16_bf16 v[20:35], v[84:87], v[88:91], v[20:35]
	v_mfma_f32_32x32x16_bf16 v[4:19], v[118:121], v[88:91], v[4:19]
	ds_read_b128 v[84:87], v111 offset:36960
	ds_read_b128 v[88:91], v2 offset:96
	ds_read_b128 v[118:121], v115 offset:41472
	s_waitcnt lgkmcnt(1)
	v_mfma_f32_32x32x16_bf16 v[52:67], v[84:87], v[88:91], v[52:67]
	s_waitcnt lgkmcnt(0)
	v_mfma_f32_32x32x16_bf16 v[36:51], v[118:121], v[88:91], v[36:51]
	ds_read_b128 v[88:91], v112 offset:4608
	s_waitcnt lgkmcnt(0)
	v_mfma_f32_32x32x16_bf16 v[20:35], v[84:87], v[88:91], v[20:35]
	global_load_dwordx4 v[84:87], v[94:95], off offset:512
	global_load_dwordx4 v[122:125], v[96:97], off offset:512
	global_load_dwordx4 v[130:133], v[98:99], off offset:512
	v_mfma_f32_32x32x16_bf16 v[4:19], v[118:121], v[88:91], v[4:19]
	global_load_dwordx4 v[88:91], v[100:101], off offset:512
	global_load_dwordx4 v[118:121], v[92:93], off offset:512
	s_waitcnt vmcnt(10)
	ds_write_b128 v105, v[76:79] offset:55296
	global_load_dwordx4 v[76:79], v[102:103], off offset:512
	s_waitcnt vmcnt(10)
	ds_write_b128 v105, v[140:143] offset:64512
	s_waitcnt vmcnt(9)
	ds_write_b128 v117, v[144:147] offset:18432
	s_waitcnt vmcnt(8)
	ds_write_b128 v117, v[80:83] offset:27648
	s_waitcnt vmcnt(7)
	ds_write_b128 v116, v[136:139]
	s_waitcnt vmcnt(6)
	ds_write_b128 v116, v[126:129] offset:9216
	s_waitcnt lgkmcnt(0)
	s_barrier
	ds_read_b128 v[80:83], v104
	ds_read_b128 v[126:129], v2 offset:55296
	ds_read_b128 v[134:137], v68
	s_waitcnt lgkmcnt(1)
	v_mfma_f32_32x32x16_bf16 v[52:67], v[80:83], v[126:129], v[52:67]
	s_waitcnt lgkmcnt(0)
	v_mfma_f32_32x32x16_bf16 v[36:51], v[134:137], v[126:129], v[36:51]
	ds_read_b128 v[126:129], v2 offset:59904
	s_waitcnt lgkmcnt(0)
	v_mfma_f32_32x32x16_bf16 v[20:35], v[80:83], v[126:129], v[20:35]
	v_mfma_f32_32x32x16_bf16 v[4:19], v[134:137], v[126:129], v[4:19]
	ds_read_b128 v[80:83], v70
	ds_read_b128 v[126:129], v2 offset:55328
	ds_read_b128 v[134:137], v71
	s_waitcnt lgkmcnt(1)
	v_mfma_f32_32x32x16_bf16 v[52:67], v[80:83], v[126:129], v[52:67]
	s_waitcnt lgkmcnt(0)
	v_mfma_f32_32x32x16_bf16 v[36:51], v[134:137], v[126:129], v[36:51]
	ds_read_b128 v[126:129], v110 offset:59904
	s_waitcnt lgkmcnt(0)
	v_mfma_f32_32x32x16_bf16 v[20:35], v[80:83], v[126:129], v[20:35]
	v_mfma_f32_32x32x16_bf16 v[4:19], v[134:137], v[126:129], v[4:19]
	ds_read_b128 v[80:83], v72
	ds_read_b128 v[126:129], v2 offset:55360
	ds_read_b128 v[134:137], v69
	s_waitcnt lgkmcnt(1)
	v_mfma_f32_32x32x16_bf16 v[52:67], v[80:83], v[126:129], v[52:67]
	s_waitcnt lgkmcnt(0)
	v_mfma_f32_32x32x16_bf16 v[36:51], v[134:137], v[126:129], v[36:51]
	ds_read_b128 v[126:129], v109 offset:59904
	s_waitcnt lgkmcnt(0)
	v_mfma_f32_32x32x16_bf16 v[20:35], v[80:83], v[126:129], v[20:35]
	v_mfma_f32_32x32x16_bf16 v[4:19], v[134:137], v[126:129], v[4:19]
	ds_read_b128 v[80:83], v73
	ds_read_b128 v[126:129], v2 offset:55392
	ds_read_b128 v[134:137], v74
	s_waitcnt lgkmcnt(1)
	v_mfma_f32_32x32x16_bf16 v[52:67], v[80:83], v[126:129], v[52:67]
	s_waitcnt lgkmcnt(0)
	v_mfma_f32_32x32x16_bf16 v[36:51], v[134:137], v[126:129], v[36:51]
	ds_read_b128 v[126:129], v112 offset:59904
	s_waitcnt lgkmcnt(0)
	v_mfma_f32_32x32x16_bf16 v[20:35], v[80:83], v[126:129], v[20:35]
	global_load_dwordx4 v[80:83], v[94:95], off offset:640
	global_load_dwordx4 v[138:141], v[96:97], off offset:640
	global_load_dwordx4 v[142:145], v[98:99], off offset:640
	v_mfma_f32_32x32x16_bf16 v[4:19], v[134:137], v[126:129], v[4:19]
	global_load_dwordx4 v[126:129], v[100:101], off offset:640
	global_load_dwordx4 v[134:137], v[92:93], off offset:640
	s_waitcnt vmcnt(10)
	ds_write_b128 v105, v[84:87]
	global_load_dwordx4 v[84:87], v[102:103], off offset:640
	s_waitcnt vmcnt(10)
	ds_write_b128 v105, v[122:125] offset:9216
	s_waitcnt vmcnt(9)
	ds_write_b128 v105, v[130:133] offset:18432
	s_waitcnt vmcnt(8)
	ds_write_b128 v105, v[88:91] offset:27648
	s_waitcnt vmcnt(7)
	ds_write_b128 v105, v[118:121] offset:36864
	s_waitcnt vmcnt(6)
	ds_write_b128 v105, v[76:79] offset:46080
	s_waitcnt lgkmcnt(0)
	s_barrier
; #define MFMA32(a, b, c) __builtin_amdgcn_mfma_f32_32x32x16_bf16((a), (b), (c), 0, 0, 0)
; template <bool SWAP, class Epi>
; DI void gemm_tile(const u16* __restrict__ A, int lda, const u16* __restrict__ Bw, int ldb, int K, char* lds, Epi epi) {
;     ...
;   auto compute = [&](int st) {
;     const char* as = lds + st * GEMM_STAGE;
;     const char* bs = as + 36864;
; #pragma unroll
;     for (int ks = 0; ks < 4; ++ks) {
;       bf16x8 af[2], bfr[2];
; #pragma unroll
;       for (int mi = 0; mi < 2; ++mi) af[mi] = *(const bf16x8*)(as + ((wm * 64 + mi * 32 + r) * 72 + ks * 16 + 8 * h) * 2);
; #pragma unroll
;       for (int ni = 0; ni < 2; ++ni) bfr[ni] = *(const bf16x8*)(bs + ((wn * 64 + ni * 32 + r) * 72 + ks * 16 + 8 * h) * 2);
; #pragma unroll
;       for (int mi = 0; mi < 2; ++mi)
; #pragma unroll
;         for (int ni = 0; ni < 2; ++ni) {
;           if (SWAP) acc[mi][ni] = MFMA32(bfr[ni], af[mi], acc[mi][ni]);
;           else acc[mi][ni] = MFMA32(af[mi], bfr[ni], acc[mi][ni]);
;         }
;     }
;   };
;   gload(0, ra0, rb0);
;   lstore(0, ra0, rb0);
;   gload(1, ra1, rb1);
;   __syncthreads();
;   for (int kt = 0; kt < nk; kt += 2) {
;     if (kt + 2 < nk) gload(kt + 2, ra0, rb0);
;     compute(0);
;     lstore(1, ra1, rb1);
;     __syncthreads();
;     if (kt + 3 < nk) gload(kt + 3, ra1, rb1);
;     compute(1);
;     if (kt + 2 < nk) lstore(0, ra0, rb0);
;     __syncthreads();
	ds_read_b128 v[76:79], v111 offset:36864
	ds_read_b128 v[88:91], v2
	ds_read_b128 v[118:121], v111 offset:41472
	s_waitcnt lgkmcnt(1)
	v_mfma_f32_32x32x16_bf16 v[52:67], v[76:79], v[88:91], v[52:67]
	s_waitcnt lgkmcnt(0)
	v_mfma_f32_32x32x16_bf16 v[36:51], v[118:121], v[88:91], v[36:51]
	ds_read_b128 v[88:91], v2 offset:4608
	s_waitcnt lgkmcnt(0)
	v_mfma_f32_32x32x16_bf16 v[20:35], v[76:79], v[88:91], v[20:35]
	v_mfma_f32_32x32x16_bf16 v[4:19], v[118:121], v[88:91], v[4:19]
	ds_read_b128 v[76:79], v111 offset:36896
	ds_read_b128 v[88:91], v2 offset:32
	ds_read_b128 v[118:121], v113 offset:41472
	s_waitcnt lgkmcnt(1)
	v_mfma_f32_32x32x16_bf16 v[52:67], v[76:79], v[88:91], v[52:67]
	s_waitcnt lgkmcnt(0)
	v_mfma_f32_32x32x16_bf16 v[36:51], v[118:121], v[88:91], v[36:51]
	ds_read_b128 v[88:91], v110 offset:4608
	s_waitcnt lgkmcnt(0)
	v_mfma_f32_32x32x16_bf16 v[20:35], v[76:79], v[88:91], v[20:35]
	v_mfma_f32_32x32x16_bf16 v[4:19], v[118:121], v[88:91], v[4:19]
	ds_read_b128 v[76:79], v111 offset:36928
	ds_read_b128 v[88:91], v2 offset:64
	ds_read_b128 v[118:121], v114 offset:41472
	s_waitcnt lgkmcnt(1)
	v_mfma_f32_32x32x16_bf16 v[52:67], v[76:79], v[88:91], v[52:67]
	s_waitcnt lgkmcnt(0)
	v_mfma_f32_32x32x16_bf16 v[36:51], v[118:121], v[88:91], v[36:51]
	ds_read_b128 v[88:91], v109 offset:4608
	s_waitcnt lgkmcnt(0)
	v_mfma_f32_32x32x16_bf16 v[20:35], v[76:79], v[88:91], v[20:35]
	v_mfma_f32_32x32x16_bf16 v[4:19], v[118:121], v[88:91], v[4:19]
	ds_read_b128 v[76:79], v111 offset:36960
	ds_read_b128 v[88:91], v2 offset:96
	ds_read_b128 v[118:121], v115 offset:41472
	s_waitcnt lgkmcnt(1)
	v_mfma_f32_32x32x16_bf16 v[52:67], v[76:79], v[88:91], v[52:67]
	s_waitcnt lgkmcnt(0)
	v_mfma_f32_32x32x16_bf16 v[36:51], v[118:121], v[88:91], v[36:51]
	ds_read_b128 v[88:91], v112 offset:4608
	s_waitcnt lgkmcnt(0)
	v_mfma_f32_32x32x16_bf16 v[20:35], v[76:79], v[88:91], v[20:35]
	global_load_dwordx4 v[76:79], v[94:95], off offset:768
	global_load_dwordx4 v[122:125], v[96:97], off offset:768
	global_load_dwordx4 v[130:133], v[98:99], off offset:768
	v_mfma_f32_32x32x16_bf16 v[4:19], v[118:121], v[88:91], v[4:19]
	global_load_dwordx4 v[88:91], v[100:101], off offset:768
	global_load_dwordx4 v[118:121], v[92:93], off offset:768
	s_waitcnt vmcnt(10)
	ds_write_b128 v105, v[80:83] offset:55296
	global_load_dwordx4 v[80:83], v[102:103], off offset:768
	s_waitcnt vmcnt(10)
	ds_write_b128 v105, v[138:141] offset:64512
	s_waitcnt vmcnt(9)
	ds_write_b128 v117, v[142:145] offset:18432
	s_waitcnt vmcnt(8)
	ds_write_b128 v117, v[126:129] offset:27648
	s_waitcnt vmcnt(7)
	ds_write_b128 v116, v[134:137]
	s_waitcnt vmcnt(6)
	ds_write_b128 v116, v[84:87] offset:9216
	s_waitcnt lgkmcnt(0)
	s_barrier
	ds_read_b128 v[84:87], v104
	ds_read_b128 v[126:129], v2 offset:55296
	ds_read_b128 v[134:137], v68
	s_waitcnt lgkmcnt(1)
	v_mfma_f32_32x32x16_bf16 v[52:67], v[84:87], v[126:129], v[52:67]
	s_waitcnt lgkmcnt(0)
	v_mfma_f32_32x32x16_bf16 v[36:51], v[134:137], v[126:129], v[36:51]
	ds_read_b128 v[126:129], v2 offset:59904
	s_waitcnt lgkmcnt(0)
	v_mfma_f32_32x32x16_bf16 v[20:35], v[84:87], v[126:129], v[20:35]
	v_mfma_f32_32x32x16_bf16 v[4:19], v[134:137], v[126:129], v[4:19]
	ds_read_b128 v[84:87], v70
	ds_read_b128 v[126:129], v2 offset:55328
	ds_read_b128 v[134:137], v71
	s_waitcnt lgkmcnt(1)
	v_mfma_f32_32x32x16_bf16 v[52:67], v[84:87], v[126:129], v[52:67]
	s_waitcnt lgkmcnt(0)
	v_mfma_f32_32x32x16_bf16 v[36:51], v[134:137], v[126:129], v[36:51]
	ds_read_b128 v[126:129], v110 offset:59904
	s_waitcnt lgkmcnt(0)
	v_mfma_f32_32x32x16_bf16 v[20:35], v[84:87], v[126:129], v[20:35]
	v_mfma_f32_32x32x16_bf16 v[4:19], v[134:137], v[126:129], v[4:19]
	ds_read_b128 v[84:87], v72
	ds_read_b128 v[126:129], v2 offset:55360
	ds_read_b128 v[134:137], v69
	s_waitcnt lgkmcnt(1)
	v_mfma_f32_32x32x16_bf16 v[52:67], v[84:87], v[126:129], v[52:67]
	s_waitcnt lgkmcnt(0)
	v_mfma_f32_32x32x16_bf16 v[36:51], v[134:137], v[126:129], v[36:51]
	ds_read_b128 v[126:129], v109 offset:59904
	s_waitcnt lgkmcnt(0)
	v_mfma_f32_32x32x16_bf16 v[20:35], v[84:87], v[126:129], v[20:35]
	v_mfma_f32_32x32x16_bf16 v[4:19], v[134:137], v[126:129], v[4:19]
	ds_read_b128 v[84:87], v73
	ds_read_b128 v[126:129], v2 offset:55392
	ds_read_b128 v[134:137], v74
	s_waitcnt lgkmcnt(1)
	v_mfma_f32_32x32x16_bf16 v[52:67], v[84:87], v[126:129], v[52:67]
	s_waitcnt lgkmcnt(0)
	v_mfma_f32_32x32x16_bf16 v[36:51], v[134:137], v[126:129], v[36:51]
	ds_read_b128 v[126:129], v112 offset:59904
	s_waitcnt lgkmcnt(0)
	v_mfma_f32_32x32x16_bf16 v[20:35], v[84:87], v[126:129], v[20:35]
	global_load_dwordx4 v[84:87], v[94:95], off offset:896
	global_load_dwordx4 v[138:141], v[96:97], off offset:896
	global_load_dwordx4 v[142:145], v[98:99], off offset:896
	v_mfma_f32_32x32x16_bf16 v[4:19], v[134:137], v[126:129], v[4:19]
	global_load_dwordx4 v[126:129], v[100:101], off offset:896
	global_load_dwordx4 v[134:137], v[92:93], off offset:896
	s_waitcnt vmcnt(10)
	ds_write_b128 v105, v[76:79]
	global_load_dwordx4 v[76:79], v[102:103], off offset:896
	s_waitcnt vmcnt(10)
	ds_write_b128 v105, v[122:125] offset:9216
	s_waitcnt vmcnt(9)
	ds_write_b128 v105, v[130:133] offset:18432
	s_waitcnt vmcnt(8)
	ds_write_b128 v105, v[88:91] offset:27648
	s_waitcnt vmcnt(7)
	ds_write_b128 v105, v[118:121] offset:36864
	s_waitcnt vmcnt(6)
	ds_write_b128 v105, v[80:83] offset:46080
	s_waitcnt lgkmcnt(0)
	s_barrier
; #define MFMA32(a, b, c) __builtin_amdgcn_mfma_f32_32x32x16_bf16((a), (b), (c), 0, 0, 0)
; template <bool SWAP, class Epi>
; DI void gemm_tile(const u16* __restrict__ A, int lda, const u16* __restrict__ Bw, int ldb, int K, char* lds, Epi epi) {
;     ...
;   auto compute = [&](int st) {
;     const char* as = lds + st * GEMM_STAGE;
;     const char* bs = as + 36864;
; #pragma unroll
;     for (int ks = 0; ks < 4; ++ks) {
;       bf16x8 af[2], bfr[2];
; #pragma unroll
;       for (int mi = 0; mi < 2; ++mi) af[mi] = *(const bf16x8*)(as + ((wm * 64 + mi * 32 + r) * 72 + ks * 16 + 8 * h) * 2);
; #pragma unroll
;       for (int ni = 0; ni < 2; ++ni) bfr[ni] = *(const bf16x8*)(bs + ((wn * 64 + ni * 32 + r) * 72 + ks * 16 + 8 * h) * 2);
; #pragma unroll
;       for (int mi = 0; mi < 2; ++mi)
; #pragma unroll
;         for (int ni = 0; ni < 2; ++ni) {
;           if (SWAP) acc[mi][ni] = MFMA32(bfr[ni], af[mi], acc[mi][ni]);
;           else acc[mi][ni] = MFMA32(af[mi], bfr[ni], acc[mi][ni]);
;         }
;     }
;   };
;   gload(0, ra0, rb0);
;   lstore(0, ra0, rb0);
;   gload(1, ra1, rb1);
;   __syncthreads();
;   for (int kt = 0; kt < nk; kt += 2) {
;     if (kt + 2 < nk) gload(kt + 2, ra0, rb0);
;     compute(0);
;     lstore(1, ra1, rb1);
;     __syncthreads();
;     if (kt + 3 < nk) gload(kt + 3, ra1, rb1);
;     compute(1);
;     if (kt + 2 < nk) lstore(0, ra0, rb0);
;     __syncthreads();
	ds_read_b128 v[80:83], v111 offset:36864
	ds_read_b128 v[88:91], v2
	ds_read_b128 v[118:121], v111 offset:41472
	s_waitcnt lgkmcnt(1)
	v_mfma_f32_32x32x16_bf16 v[52:67], v[80:83], v[88:91], v[52:67]
	s_waitcnt lgkmcnt(0)
	v_mfma_f32_32x32x16_bf16 v[36:51], v[118:121], v[88:91], v[36:51]
	ds_read_b128 v[88:91], v2 offset:4608
	s_waitcnt lgkmcnt(0)
	v_mfma_f32_32x32x16_bf16 v[20:35], v[80:83], v[88:91], v[20:35]
	v_mfma_f32_32x32x16_bf16 v[4:19], v[118:121], v[88:91], v[4:19]
	ds_read_b128 v[80:83], v111 offset:36896
	ds_read_b128 v[88:91], v2 offset:32
	ds_read_b128 v[118:121], v113 offset:41472
	s_waitcnt lgkmcnt(1)
	v_mfma_f32_32x32x16_bf16 v[52:67], v[80:83], v[88:91], v[52:67]
	s_waitcnt lgkmcnt(0)
	v_mfma_f32_32x32x16_bf16 v[36:51], v[118:121], v[88:91], v[36:51]
	ds_read_b128 v[88:91], v110 offset:4608
	s_waitcnt lgkmcnt(0)
	v_mfma_f32_32x32x16_bf16 v[20:35], v[80:83], v[88:91], v[20:35]
	v_mfma_f32_32x32x16_bf16 v[4:19], v[118:121], v[88:91], v[4:19]
	ds_read_b128 v[80:83], v111 offset:36928
	ds_read_b128 v[88:91], v2 offset:64
	ds_read_b128 v[118:121], v114 offset:41472
	s_waitcnt lgkmcnt(1)
	v_mfma_f32_32x32x16_bf16 v[52:67], v[80:83], v[88:91], v[52:67]
	s_waitcnt lgkmcnt(0)
	v_mfma_f32_32x32x16_bf16 v[36:51], v[118:121], v[88:91], v[36:51]
	ds_read_b128 v[88:91], v109 offset:4608
	s_waitcnt lgkmcnt(0)
	v_mfma_f32_32x32x16_bf16 v[20:35], v[80:83], v[88:91], v[20:35]
	v_mfma_f32_32x32x16_bf16 v[4:19], v[118:121], v[88:91], v[4:19]
	ds_read_b128 v[80:83], v111 offset:36960
	ds_read_b128 v[88:91], v2 offset:96
	ds_read_b128 v[118:121], v115 offset:41472
	s_waitcnt lgkmcnt(1)
	v_mfma_f32_32x32x16_bf16 v[52:67], v[80:83], v[88:91], v[52:67]
	s_waitcnt lgkmcnt(0)
	v_mfma_f32_32x32x16_bf16 v[36:51], v[118:121], v[88:91], v[36:51]
	ds_read_b128 v[88:91], v112 offset:4608
	s_waitcnt lgkmcnt(0)
	v_mfma_f32_32x32x16_bf16 v[20:35], v[80:83], v[88:91], v[20:35]
	global_load_dwordx4 v[80:83], v[94:95], off offset:1024
	global_load_dwordx4 v[122:125], v[96:97], off offset:1024
	global_load_dwordx4 v[130:133], v[98:99], off offset:1024
	v_mfma_f32_32x32x16_bf16 v[4:19], v[118:121], v[88:91], v[4:19]
	global_load_dwordx4 v[88:91], v[100:101], off offset:1024
	global_load_dwordx4 v[118:121], v[92:93], off offset:1024
	s_waitcnt vmcnt(10)
	ds_write_b128 v105, v[84:87] offset:55296
	global_load_dwordx4 v[84:87], v[102:103], off offset:1024
	s_waitcnt vmcnt(10)
	ds_write_b128 v105, v[138:141] offset:64512
	s_waitcnt vmcnt(9)
	ds_write_b128 v117, v[142:145] offset:18432
	s_waitcnt vmcnt(8)
	ds_write_b128 v117, v[126:129] offset:27648
	s_waitcnt vmcnt(7)
	ds_write_b128 v116, v[134:137]
	s_waitcnt vmcnt(6)
	ds_write_b128 v116, v[76:79] offset:9216
	s_waitcnt lgkmcnt(0)
	s_barrier
	ds_read_b128 v[76:79], v104
	ds_read_b128 v[126:129], v2 offset:55296
	ds_read_b128 v[134:137], v68
	s_waitcnt lgkmcnt(1)
	v_mfma_f32_32x32x16_bf16 v[52:67], v[76:79], v[126:129], v[52:67]
	s_waitcnt lgkmcnt(0)
	v_mfma_f32_32x32x16_bf16 v[36:51], v[134:137], v[126:129], v[36:51]
	ds_read_b128 v[126:129], v2 offset:59904
	s_waitcnt lgkmcnt(0)
	v_mfma_f32_32x32x16_bf16 v[20:35], v[76:79], v[126:129], v[20:35]
	v_mfma_f32_32x32x16_bf16 v[4:19], v[134:137], v[126:129], v[4:19]
	ds_read_b128 v[76:79], v70
	ds_read_b128 v[126:129], v2 offset:55328
	ds_read_b128 v[134:137], v71
	s_waitcnt lgkmcnt(1)
	v_mfma_f32_32x32x16_bf16 v[52:67], v[76:79], v[126:129], v[52:67]
	s_waitcnt lgkmcnt(0)
	v_mfma_f32_32x32x16_bf16 v[36:51], v[134:137], v[126:129], v[36:51]
	ds_read_b128 v[126:129], v110 offset:59904
	s_waitcnt lgkmcnt(0)
	v_mfma_f32_32x32x16_bf16 v[20:35], v[76:79], v[126:129], v[20:35]
	v_mfma_f32_32x32x16_bf16 v[4:19], v[134:137], v[126:129], v[4:19]
	ds_read_b128 v[76:79], v72
	ds_read_b128 v[126:129], v2 offset:55360
	ds_read_b128 v[134:137], v69
	s_waitcnt lgkmcnt(1)
	v_mfma_f32_32x32x16_bf16 v[52:67], v[76:79], v[126:129], v[52:67]
	s_waitcnt lgkmcnt(0)
	v_mfma_f32_32x32x16_bf16 v[36:51], v[134:137], v[126:129], v[36:51]
	ds_read_b128 v[126:129], v109 offset:59904
	s_waitcnt lgkmcnt(0)
	v_mfma_f32_32x32x16_bf16 v[20:35], v[76:79], v[126:129], v[20:35]
	v_mfma_f32_32x32x16_bf16 v[4:19], v[134:137], v[126:129], v[4:19]
	ds_read_b128 v[76:79], v73
	ds_read_b128 v[126:129], v2 offset:55392
	ds_read_b128 v[134:137], v74
	s_waitcnt lgkmcnt(1)
	v_mfma_f32_32x32x16_bf16 v[52:67], v[76:79], v[126:129], v[52:67]
	s_waitcnt lgkmcnt(0)
	v_mfma_f32_32x32x16_bf16 v[36:51], v[134:137], v[126:129], v[36:51]
	ds_read_b128 v[126:129], v112 offset:59904
	s_waitcnt lgkmcnt(0)
	v_mfma_f32_32x32x16_bf16 v[20:35], v[76:79], v[126:129], v[20:35]
	global_load_dwordx4 v[76:79], v[94:95], off offset:1152
	global_load_dwordx4 v[138:141], v[96:97], off offset:1152
	global_load_dwordx4 v[142:145], v[98:99], off offset:1152
	v_mfma_f32_32x32x16_bf16 v[4:19], v[134:137], v[126:129], v[4:19]
	global_load_dwordx4 v[126:129], v[100:101], off offset:1152
	global_load_dwordx4 v[134:137], v[92:93], off offset:1152
	s_waitcnt vmcnt(10)
	ds_write_b128 v105, v[80:83]
	global_load_dwordx4 v[80:83], v[102:103], off offset:1152
	s_waitcnt vmcnt(10)
	ds_write_b128 v105, v[122:125] offset:9216
	s_waitcnt vmcnt(9)
	ds_write_b128 v105, v[130:133] offset:18432
	s_waitcnt vmcnt(8)
	ds_write_b128 v105, v[88:91] offset:27648
	s_waitcnt vmcnt(7)
	ds_write_b128 v105, v[118:121] offset:36864
	s_waitcnt vmcnt(6)
	ds_write_b128 v105, v[84:87] offset:46080
	s_waitcnt lgkmcnt(0)
	s_barrier
; #define MFMA32(a, b, c) __builtin_amdgcn_mfma_f32_32x32x16_bf16((a), (b), (c), 0, 0, 0)
; template <bool SWAP, class Epi>
; DI void gemm_tile(const u16* __restrict__ A, int lda, const u16* __restrict__ Bw, int ldb, int K, char* lds, Epi epi) {
;     ...
;   auto compute = [&](int st) {
;     const char* as = lds + st * GEMM_STAGE;
;     const char* bs = as + 36864;
; #pragma unroll
;     for (int ks = 0; ks < 4; ++ks) {
;       bf16x8 af[2], bfr[2];
; #pragma unroll
;       for (int mi = 0; mi < 2; ++mi) af[mi] = *(const bf16x8*)(as + ((wm * 64 + mi * 32 + r) * 72 + ks * 16 + 8 * h) * 2);
; #pragma unroll
;       for (int ni = 0; ni < 2; ++ni) bfr[ni] = *(const bf16x8*)(bs + ((wn * 64 + ni * 32 + r) * 72 + ks * 16 + 8 * h) * 2);
; #pragma unroll
;       for (int mi = 0; mi < 2; ++mi)
; #pragma unroll
;         for (int ni = 0; ni < 2; ++ni) {
;           if (SWAP) acc[mi][ni] = MFMA32(bfr[ni], af[mi], acc[mi][ni]);
;           else acc[mi][ni] = MFMA32(af[mi], bfr[ni], acc[mi][ni]);
;         }
;     }
;   };
;   gload(0, ra0, rb0);
;   lstore(0, ra0, rb0);
;   gload(1, ra1, rb1);
;   __syncthreads();
;   for (int kt = 0; kt < nk; kt += 2) {
;     if (kt + 2 < nk) gload(kt + 2, ra0, rb0);
;     compute(0);
;     lstore(1, ra1, rb1);
;     __syncthreads();
;     if (kt + 3 < nk) gload(kt + 3, ra1, rb1);
;     compute(1);
;     if (kt + 2 < nk) lstore(0, ra0, rb0);
;     __syncthreads();
	ds_read_b128 v[84:87], v111 offset:36864
	ds_read_b128 v[88:91], v2
	ds_read_b128 v[118:121], v111 offset:41472
	s_waitcnt lgkmcnt(1)
	v_mfma_f32_32x32x16_bf16 v[52:67], v[84:87], v[88:91], v[52:67]
	s_waitcnt lgkmcnt(0)
	v_mfma_f32_32x32x16_bf16 v[36:51], v[118:121], v[88:91], v[36:51]
	ds_read_b128 v[88:91], v2 offset:4608
	s_waitcnt lgkmcnt(0)
	v_mfma_f32_32x32x16_bf16 v[20:35], v[84:87], v[88:91], v[20:35]
	v_mfma_f32_32x32x16_bf16 v[4:19], v[118:121], v[88:91], v[4:19]
	ds_read_b128 v[84:87], v111 offset:36896
	ds_read_b128 v[88:91], v2 offset:32
	ds_read_b128 v[118:121], v113 offset:41472
	s_waitcnt lgkmcnt(1)
	v_mfma_f32_32x32x16_bf16 v[52:67], v[84:87], v[88:91], v[52:67]
	s_waitcnt lgkmcnt(0)
	v_mfma_f32_32x32x16_bf16 v[36:51], v[118:121], v[88:91], v[36:51]
	ds_read_b128 v[88:91], v110 offset:4608
	s_waitcnt lgkmcnt(0)
	v_mfma_f32_32x32x16_bf16 v[20:35], v[84:87], v[88:91], v[20:35]
	v_mfma_f32_32x32x16_bf16 v[4:19], v[118:121], v[88:91], v[4:19]
	ds_read_b128 v[84:87], v111 offset:36928
	ds_read_b128 v[88:91], v2 offset:64
	ds_read_b128 v[118:121], v114 offset:41472
	s_waitcnt lgkmcnt(1)
	v_mfma_f32_32x32x16_bf16 v[52:67], v[84:87], v[88:91], v[52:67]
	s_waitcnt lgkmcnt(0)
	v_mfma_f32_32x32x16_bf16 v[36:51], v[118:121], v[88:91], v[36:51]
	ds_read_b128 v[88:91], v109 offset:4608
	s_waitcnt lgkmcnt(0)
	v_mfma_f32_32x32x16_bf16 v[20:35], v[84:87], v[88:91], v[20:35]
	v_mfma_f32_32x32x16_bf16 v[4:19], v[118:121], v[88:91], v[4:19]
	ds_read_b128 v[84:87], v111 offset:36960
	ds_read_b128 v[88:91], v2 offset:96
	ds_read_b128 v[118:121], v115 offset:41472
	s_waitcnt lgkmcnt(1)
	v_mfma_f32_32x32x16_bf16 v[52:67], v[84:87], v[88:91], v[52:67]
	s_waitcnt lgkmcnt(0)
	v_mfma_f32_32x32x16_bf16 v[36:51], v[118:121], v[88:91], v[36:51]
	ds_read_b128 v[88:91], v112 offset:4608
	s_waitcnt lgkmcnt(0)
	v_mfma_f32_32x32x16_bf16 v[20:35], v[84:87], v[88:91], v[20:35]
	global_load_dwordx4 v[84:87], v[94:95], off offset:1280
	global_load_dwordx4 v[122:125], v[96:97], off offset:1280
	global_load_dwordx4 v[130:133], v[98:99], off offset:1280
	v_mfma_f32_32x32x16_bf16 v[4:19], v[118:121], v[88:91], v[4:19]
	global_load_dwordx4 v[88:91], v[100:101], off offset:1280
	global_load_dwordx4 v[118:121], v[92:93], off offset:1280
	s_waitcnt vmcnt(10)
	ds_write_b128 v105, v[76:79] offset:55296
	global_load_dwordx4 v[76:79], v[102:103], off offset:1280
	s_waitcnt vmcnt(10)
	ds_write_b128 v105, v[138:141] offset:64512
	s_waitcnt vmcnt(9)
	ds_write_b128 v117, v[142:145] offset:18432
	s_waitcnt vmcnt(8)
	ds_write_b128 v117, v[126:129] offset:27648
	s_waitcnt vmcnt(7)
	ds_write_b128 v116, v[134:137]
	s_waitcnt vmcnt(6)
	ds_write_b128 v116, v[80:83] offset:9216
	s_waitcnt lgkmcnt(0)
	s_barrier
	ds_read_b128 v[80:83], v104
	ds_read_b128 v[126:129], v2 offset:55296
	ds_read_b128 v[134:137], v68
	s_waitcnt lgkmcnt(1)
	v_mfma_f32_32x32x16_bf16 v[52:67], v[80:83], v[126:129], v[52:67]
	s_waitcnt lgkmcnt(0)
	v_mfma_f32_32x32x16_bf16 v[36:51], v[134:137], v[126:129], v[36:51]
	ds_read_b128 v[126:129], v2 offset:59904
	s_waitcnt lgkmcnt(0)
	v_mfma_f32_32x32x16_bf16 v[20:35], v[80:83], v[126:129], v[20:35]
	v_mfma_f32_32x32x16_bf16 v[4:19], v[134:137], v[126:129], v[4:19]
	ds_read_b128 v[80:83], v70
	ds_read_b128 v[126:129], v2 offset:55328
	ds_read_b128 v[134:137], v71
	s_waitcnt lgkmcnt(1)
	v_mfma_f32_32x32x16_bf16 v[52:67], v[80:83], v[126:129], v[52:67]
	s_waitcnt lgkmcnt(0)
	v_mfma_f32_32x32x16_bf16 v[36:51], v[134:137], v[126:129], v[36:51]
	ds_read_b128 v[126:129], v110 offset:59904
	s_waitcnt lgkmcnt(0)
	v_mfma_f32_32x32x16_bf16 v[20:35], v[80:83], v[126:129], v[20:35]
	v_mfma_f32_32x32x16_bf16 v[4:19], v[134:137], v[126:129], v[4:19]
	ds_read_b128 v[80:83], v72
	ds_read_b128 v[126:129], v2 offset:55360
	ds_read_b128 v[134:137], v69
	s_waitcnt lgkmcnt(1)
	v_mfma_f32_32x32x16_bf16 v[52:67], v[80:83], v[126:129], v[52:67]
	s_waitcnt lgkmcnt(0)
	v_mfma_f32_32x32x16_bf16 v[36:51], v[134:137], v[126:129], v[36:51]
	ds_read_b128 v[126:129], v109 offset:59904
	s_waitcnt lgkmcnt(0)
	v_mfma_f32_32x32x16_bf16 v[20:35], v[80:83], v[126:129], v[20:35]
	v_mfma_f32_32x32x16_bf16 v[4:19], v[134:137], v[126:129], v[4:19]
	ds_read_b128 v[80:83], v73
	ds_read_b128 v[126:129], v2 offset:55392
	ds_read_b128 v[134:137], v74
	s_waitcnt lgkmcnt(1)
	v_mfma_f32_32x32x16_bf16 v[52:67], v[80:83], v[126:129], v[52:67]
	s_waitcnt lgkmcnt(0)
	v_mfma_f32_32x32x16_bf16 v[36:51], v[134:137], v[126:129], v[36:51]
	ds_read_b128 v[126:129], v112 offset:59904
	s_waitcnt lgkmcnt(0)
	v_mfma_f32_32x32x16_bf16 v[20:35], v[80:83], v[126:129], v[20:35]
	global_load_dwordx4 v[80:83], v[94:95], off offset:1408
	global_load_dwordx4 v[138:141], v[96:97], off offset:1408
	global_load_dwordx4 v[142:145], v[98:99], off offset:1408
	v_mfma_f32_32x32x16_bf16 v[4:19], v[134:137], v[126:129], v[4:19]
	global_load_dwordx4 v[126:129], v[100:101], off offset:1408
	global_load_dwordx4 v[134:137], v[92:93], off offset:1408
	s_waitcnt vmcnt(10)
	ds_write_b128 v105, v[84:87]
	global_load_dwordx4 v[84:87], v[102:103], off offset:1408
	s_waitcnt vmcnt(10)
	ds_write_b128 v105, v[122:125] offset:9216
	s_waitcnt vmcnt(9)
	ds_write_b128 v105, v[130:133] offset:18432
	s_waitcnt vmcnt(8)
	ds_write_b128 v105, v[88:91] offset:27648
	s_waitcnt vmcnt(7)
	ds_write_b128 v105, v[118:121] offset:36864
	s_waitcnt vmcnt(6)
	ds_write_b128 v105, v[76:79] offset:46080
	s_waitcnt lgkmcnt(0)
	s_barrier
; #define MFMA32(a, b, c) __builtin_amdgcn_mfma_f32_32x32x16_bf16((a), (b), (c), 0, 0, 0)
; template <bool SWAP, class Epi>
; DI void gemm_tile(const u16* __restrict__ A, int lda, const u16* __restrict__ Bw, int ldb, int K, char* lds, Epi epi) {
;     ...
;   auto compute = [&](int st) {
;     const char* as = lds + st * GEMM_STAGE;
;     const char* bs = as + 36864;
; #pragma unroll
;     for (int ks = 0; ks < 4; ++ks) {
;       bf16x8 af[2], bfr[2];
; #pragma unroll
;       for (int mi = 0; mi < 2; ++mi) af[mi] = *(const bf16x8*)(as + ((wm * 64 + mi * 32 + r) * 72 + ks * 16 + 8 * h) * 2);
; #pragma unroll
;       for (int ni = 0; ni < 2; ++ni) bfr[ni] = *(const bf16x8*)(bs + ((wn * 64 + ni * 32 + r) * 72 + ks * 16 + 8 * h) * 2);
; #pragma unroll
;       for (int mi = 0; mi < 2; ++mi)
; #pragma unroll
;         for (int ni = 0; ni < 2; ++ni) {
;           if (SWAP) acc[mi][ni] = MFMA32(bfr[ni], af[mi], acc[mi][ni]);
;           else acc[mi][ni] = MFMA32(af[mi], bfr[ni], acc[mi][ni]);
;         }
;     }
;   };
;   gload(0, ra0, rb0);
;   lstore(0, ra0, rb0);
;   gload(1, ra1, rb1);
;   __syncthreads();
;   for (int kt = 0; kt < nk; kt += 2) {
;     if (kt + 2 < nk) gload(kt + 2, ra0, rb0);
;     compute(0);
;     lstore(1, ra1, rb1);
;     __syncthreads();
;     if (kt + 3 < nk) gload(kt + 3, ra1, rb1);
;     compute(1);
;     if (kt + 2 < nk) lstore(0, ra0, rb0);
;     __syncthreads();
	ds_read_b128 v[76:79], v111 offset:36864
	ds_read_b128 v[88:91], v2
	ds_read_b128 v[118:121], v111 offset:41472
	s_waitcnt lgkmcnt(1)
	v_mfma_f32_32x32x16_bf16 v[52:67], v[76:79], v[88:91], v[52:67]
	s_waitcnt lgkmcnt(0)
	v_mfma_f32_32x32x16_bf16 v[36:51], v[118:121], v[88:91], v[36:51]
	ds_read_b128 v[88:91], v2 offset:4608
	s_waitcnt lgkmcnt(0)
	v_mfma_f32_32x32x16_bf16 v[20:35], v[76:79], v[88:91], v[20:35]
	v_mfma_f32_32x32x16_bf16 v[4:19], v[118:121], v[88:91], v[4:19]
	ds_read_b128 v[76:79], v111 offset:36896
	ds_read_b128 v[88:91], v2 offset:32
	ds_read_b128 v[118:121], v113 offset:41472
	s_waitcnt lgkmcnt(1)
	v_mfma_f32_32x32x16_bf16 v[52:67], v[76:79], v[88:91], v[52:67]
	s_waitcnt lgkmcnt(0)
	v_mfma_f32_32x32x16_bf16 v[36:51], v[118:121], v[88:91], v[36:51]
	ds_read_b128 v[88:91], v110 offset:4608
	s_waitcnt lgkmcnt(0)
	v_mfma_f32_32x32x16_bf16 v[20:35], v[76:79], v[88:91], v[20:35]
	v_mfma_f32_32x32x16_bf16 v[4:19], v[118:121], v[88:91], v[4:19]
	ds_read_b128 v[76:79], v111 offset:36928
	ds_read_b128 v[88:91], v2 offset:64
	ds_read_b128 v[118:121], v114 offset:41472
	s_waitcnt lgkmcnt(1)
	v_mfma_f32_32x32x16_bf16 v[52:67], v[76:79], v[88:91], v[52:67]
	s_waitcnt lgkmcnt(0)
	v_mfma_f32_32x32x16_bf16 v[36:51], v[118:121], v[88:91], v[36:51]
	ds_read_b128 v[88:91], v109 offset:4608
	s_waitcnt lgkmcnt(0)
	v_mfma_f32_32x32x16_bf16 v[20:35], v[76:79], v[88:91], v[20:35]
	v_mfma_f32_32x32x16_bf16 v[4:19], v[118:121], v[88:91], v[4:19]
	ds_read_b128 v[76:79], v111 offset:36960
	ds_read_b128 v[88:91], v2 offset:96
	ds_read_b128 v[118:121], v115 offset:41472
	s_waitcnt lgkmcnt(1)
	v_mfma_f32_32x32x16_bf16 v[52:67], v[76:79], v[88:91], v[52:67]
	s_waitcnt lgkmcnt(0)
	v_mfma_f32_32x32x16_bf16 v[36:51], v[118:121], v[88:91], v[36:51]
	ds_read_b128 v[88:91], v112 offset:4608
	s_waitcnt lgkmcnt(0)
	v_mfma_f32_32x32x16_bf16 v[20:35], v[76:79], v[88:91], v[20:35]
	global_load_dwordx4 v[76:79], v[94:95], off offset:1536
	global_load_dwordx4 v[122:125], v[96:97], off offset:1536
	global_load_dwordx4 v[130:133], v[98:99], off offset:1536
	v_mfma_f32_32x32x16_bf16 v[4:19], v[118:121], v[88:91], v[4:19]
	global_load_dwordx4 v[88:91], v[100:101], off offset:1536
	global_load_dwordx4 v[118:121], v[92:93], off offset:1536
	s_waitcnt vmcnt(10)
	ds_write_b128 v105, v[80:83] offset:55296
	global_load_dwordx4 v[80:83], v[102:103], off offset:1536
	s_waitcnt vmcnt(10)
	ds_write_b128 v105, v[138:141] offset:64512
	s_waitcnt vmcnt(9)
	ds_write_b128 v117, v[142:145] offset:18432
	s_waitcnt vmcnt(8)
	ds_write_b128 v117, v[126:129] offset:27648
	s_waitcnt vmcnt(7)
	ds_write_b128 v116, v[134:137]
	s_waitcnt vmcnt(6)
	ds_write_b128 v116, v[84:87] offset:9216
	s_waitcnt lgkmcnt(0)
	s_barrier
	ds_read_b128 v[84:87], v104
	ds_read_b128 v[126:129], v2 offset:55296
	ds_read_b128 v[134:137], v68
	s_waitcnt lgkmcnt(1)
	v_mfma_f32_32x32x16_bf16 v[52:67], v[84:87], v[126:129], v[52:67]
	s_waitcnt lgkmcnt(0)
	v_mfma_f32_32x32x16_bf16 v[36:51], v[134:137], v[126:129], v[36:51]
	ds_read_b128 v[126:129], v2 offset:59904
	s_waitcnt lgkmcnt(0)
	v_mfma_f32_32x32x16_bf16 v[20:35], v[84:87], v[126:129], v[20:35]
	v_mfma_f32_32x32x16_bf16 v[4:19], v[134:137], v[126:129], v[4:19]
	ds_read_b128 v[84:87], v70
	ds_read_b128 v[126:129], v2 offset:55328
	ds_read_b128 v[134:137], v71
	s_waitcnt lgkmcnt(1)
	v_mfma_f32_32x32x16_bf16 v[52:67], v[84:87], v[126:129], v[52:67]
	s_waitcnt lgkmcnt(0)
	v_mfma_f32_32x32x16_bf16 v[36:51], v[134:137], v[126:129], v[36:51]
	ds_read_b128 v[126:129], v110 offset:59904
	s_waitcnt lgkmcnt(0)
	v_mfma_f32_32x32x16_bf16 v[20:35], v[84:87], v[126:129], v[20:35]
	v_mfma_f32_32x32x16_bf16 v[4:19], v[134:137], v[126:129], v[4:19]
	ds_read_b128 v[84:87], v72
	ds_read_b128 v[126:129], v2 offset:55360
	ds_read_b128 v[134:137], v69
	s_waitcnt lgkmcnt(1)
	v_mfma_f32_32x32x16_bf16 v[52:67], v[84:87], v[126:129], v[52:67]
	s_waitcnt lgkmcnt(0)
	v_mfma_f32_32x32x16_bf16 v[36:51], v[134:137], v[126:129], v[36:51]
	ds_read_b128 v[126:129], v109 offset:59904
	s_waitcnt lgkmcnt(0)
	v_mfma_f32_32x32x16_bf16 v[20:35], v[84:87], v[126:129], v[20:35]
	v_mfma_f32_32x32x16_bf16 v[4:19], v[134:137], v[126:129], v[4:19]
	ds_read_b128 v[84:87], v73
	ds_read_b128 v[126:129], v2 offset:55392
	ds_read_b128 v[134:137], v74
	s_waitcnt lgkmcnt(1)
	v_mfma_f32_32x32x16_bf16 v[52:67], v[84:87], v[126:129], v[52:67]
	s_waitcnt lgkmcnt(0)
	v_mfma_f32_32x32x16_bf16 v[36:51], v[134:137], v[126:129], v[36:51]
	ds_read_b128 v[126:129], v112 offset:59904
	s_waitcnt lgkmcnt(0)
	v_mfma_f32_32x32x16_bf16 v[20:35], v[84:87], v[126:129], v[20:35]
	global_load_dwordx4 v[84:87], v[94:95], off offset:1664
	global_load_dwordx4 v[138:141], v[96:97], off offset:1664
	global_load_dwordx4 v[142:145], v[98:99], off offset:1664
	v_mfma_f32_32x32x16_bf16 v[4:19], v[134:137], v[126:129], v[4:19]
	global_load_dwordx4 v[126:129], v[100:101], off offset:1664
	global_load_dwordx4 v[134:137], v[92:93], off offset:1664
	s_waitcnt vmcnt(10)
	ds_write_b128 v105, v[76:79]
	global_load_dwordx4 v[76:79], v[102:103], off offset:1664
	s_waitcnt vmcnt(10)
	ds_write_b128 v105, v[122:125] offset:9216
	s_waitcnt vmcnt(9)
	ds_write_b128 v105, v[130:133] offset:18432
	s_waitcnt vmcnt(8)
	ds_write_b128 v105, v[88:91] offset:27648
	s_waitcnt vmcnt(7)
	ds_write_b128 v105, v[118:121] offset:36864
	s_waitcnt vmcnt(6)
	ds_write_b128 v105, v[80:83] offset:46080
	s_waitcnt lgkmcnt(0)
	s_barrier
; #define MFMA32(a, b, c) __builtin_amdgcn_mfma_f32_32x32x16_bf16((a), (b), (c), 0, 0, 0)
; template <bool SWAP, class Epi>
; DI void gemm_tile(const u16* __restrict__ A, int lda, const u16* __restrict__ Bw, int ldb, int K, char* lds, Epi epi) {
;     ...
;   auto compute = [&](int st) {
;     const char* as = lds + st * GEMM_STAGE;
;     const char* bs = as + 36864;
; #pragma unroll
;     for (int ks = 0; ks < 4; ++ks) {
;       bf16x8 af[2], bfr[2];
; #pragma unroll
;       for (int mi = 0; mi < 2; ++mi) af[mi] = *(const bf16x8*)(as + ((wm * 64 + mi * 32 + r) * 72 + ks * 16 + 8 * h) * 2);
; #pragma unroll
;       for (int ni = 0; ni < 2; ++ni) bfr[ni] = *(const bf16x8*)(bs + ((wn * 64 + ni * 32 + r) * 72 + ks * 16 + 8 * h) * 2);
; #pragma unroll
;       for (int mi = 0; mi < 2; ++mi)
; #pragma unroll
;         for (int ni = 0; ni < 2; ++ni) {
;           if (SWAP) acc[mi][ni] = MFMA32(bfr[ni], af[mi], acc[mi][ni]);
;           else acc[mi][ni] = MFMA32(af[mi], bfr[ni], acc[mi][ni]);
;         }
;     }
;   };
;   gload(0, ra0, rb0);
;   lstore(0, ra0, rb0);
;   gload(1, ra1, rb1);
;   __syncthreads();
;   for (int kt = 0; kt < nk; kt += 2) {
;     if (kt + 2 < nk) gload(kt + 2, ra0, rb0);
;     compute(0);
;     lstore(1, ra1, rb1);
;     __syncthreads();
;     if (kt + 3 < nk) gload(kt + 3, ra1, rb1);
;     compute(1);
;     if (kt + 2 < nk) lstore(0, ra0, rb0);
;     __syncthreads();
	ds_read_b128 v[80:83], v111 offset:36864
	ds_read_b128 v[88:91], v2
	ds_read_b128 v[118:121], v111 offset:41472
	s_waitcnt lgkmcnt(1)
	v_mfma_f32_32x32x16_bf16 v[52:67], v[80:83], v[88:91], v[52:67]
	s_waitcnt lgkmcnt(0)
	v_mfma_f32_32x32x16_bf16 v[36:51], v[118:121], v[88:91], v[36:51]
	ds_read_b128 v[88:91], v2 offset:4608
	s_waitcnt lgkmcnt(0)
	v_mfma_f32_32x32x16_bf16 v[20:35], v[80:83], v[88:91], v[20:35]
	v_mfma_f32_32x32x16_bf16 v[4:19], v[118:121], v[88:91], v[4:19]
	ds_read_b128 v[80:83], v111 offset:36896
	ds_read_b128 v[88:91], v2 offset:32
	ds_read_b128 v[118:121], v113 offset:41472
	s_waitcnt lgkmcnt(1)
	v_mfma_f32_32x32x16_bf16 v[52:67], v[80:83], v[88:91], v[52:67]
	s_waitcnt lgkmcnt(0)
	v_mfma_f32_32x32x16_bf16 v[36:51], v[118:121], v[88:91], v[36:51]
	ds_read_b128 v[88:91], v110 offset:4608
	s_waitcnt lgkmcnt(0)
	v_mfma_f32_32x32x16_bf16 v[20:35], v[80:83], v[88:91], v[20:35]
	v_mfma_f32_32x32x16_bf16 v[4:19], v[118:121], v[88:91], v[4:19]
	ds_read_b128 v[80:83], v111 offset:36928
	ds_read_b128 v[88:91], v2 offset:64
	ds_read_b128 v[118:121], v114 offset:41472
	s_waitcnt lgkmcnt(1)
	v_mfma_f32_32x32x16_bf16 v[52:67], v[80:83], v[88:91], v[52:67]
	s_waitcnt lgkmcnt(0)
	v_mfma_f32_32x32x16_bf16 v[36:51], v[118:121], v[88:91], v[36:51]
	ds_read_b128 v[88:91], v109 offset:4608
	s_waitcnt lgkmcnt(0)
	v_mfma_f32_32x32x16_bf16 v[20:35], v[80:83], v[88:91], v[20:35]
	v_mfma_f32_32x32x16_bf16 v[4:19], v[118:121], v[88:91], v[4:19]
	ds_read_b128 v[80:83], v111 offset:36960
	ds_read_b128 v[88:91], v2 offset:96
	ds_read_b128 v[118:121], v115 offset:41472
	s_waitcnt lgkmcnt(1)
	v_mfma_f32_32x32x16_bf16 v[52:67], v[80:83], v[88:91], v[52:67]
	s_waitcnt lgkmcnt(0)
	v_mfma_f32_32x32x16_bf16 v[36:51], v[118:121], v[88:91], v[36:51]
	ds_read_b128 v[88:91], v112 offset:4608
	s_waitcnt lgkmcnt(0)
	v_mfma_f32_32x32x16_bf16 v[20:35], v[80:83], v[88:91], v[20:35]
	global_load_dwordx4 v[80:83], v[94:95], off offset:1792
	global_load_dwordx4 v[122:125], v[96:97], off offset:1792
	global_load_dwordx4 v[130:133], v[98:99], off offset:1792
	v_mfma_f32_32x32x16_bf16 v[4:19], v[118:121], v[88:91], v[4:19]
	global_load_dwordx4 v[88:91], v[100:101], off offset:1792
	global_load_dwordx4 v[118:121], v[92:93], off offset:1792
	s_waitcnt vmcnt(10)
	ds_write_b128 v105, v[84:87] offset:55296
	global_load_dwordx4 v[84:87], v[102:103], off offset:1792
	s_waitcnt vmcnt(10)
	ds_write_b128 v105, v[138:141] offset:64512
	s_waitcnt vmcnt(9)
	ds_write_b128 v117, v[142:145] offset:18432
	s_waitcnt vmcnt(8)
	ds_write_b128 v117, v[126:129] offset:27648
	s_waitcnt vmcnt(7)
	ds_write_b128 v116, v[134:137]
	s_waitcnt vmcnt(6)
	ds_write_b128 v116, v[76:79] offset:9216
	s_waitcnt lgkmcnt(0)
	s_barrier
	ds_read_b128 v[76:79], v104
	ds_read_b128 v[126:129], v2 offset:55296
	ds_read_b128 v[134:137], v68
	s_waitcnt lgkmcnt(1)
	v_mfma_f32_32x32x16_bf16 v[52:67], v[76:79], v[126:129], v[52:67]
	s_waitcnt lgkmcnt(0)
	v_mfma_f32_32x32x16_bf16 v[36:51], v[134:137], v[126:129], v[36:51]
	ds_read_b128 v[126:129], v2 offset:59904
	s_waitcnt lgkmcnt(0)
	v_mfma_f32_32x32x16_bf16 v[20:35], v[76:79], v[126:129], v[20:35]
	v_mfma_f32_32x32x16_bf16 v[4:19], v[134:137], v[126:129], v[4:19]
	ds_read_b128 v[76:79], v70
	ds_read_b128 v[126:129], v2 offset:55328
	ds_read_b128 v[134:137], v71
	s_waitcnt lgkmcnt(1)
	v_mfma_f32_32x32x16_bf16 v[52:67], v[76:79], v[126:129], v[52:67]
	s_waitcnt lgkmcnt(0)
	v_mfma_f32_32x32x16_bf16 v[36:51], v[134:137], v[126:129], v[36:51]
	ds_read_b128 v[126:129], v110 offset:59904
	s_waitcnt lgkmcnt(0)
	v_mfma_f32_32x32x16_bf16 v[20:35], v[76:79], v[126:129], v[20:35]
	v_mfma_f32_32x32x16_bf16 v[4:19], v[134:137], v[126:129], v[4:19]
	ds_read_b128 v[76:79], v72
	ds_read_b128 v[126:129], v2 offset:55360
	ds_read_b128 v[134:137], v69
	s_waitcnt lgkmcnt(1)
	v_mfma_f32_32x32x16_bf16 v[52:67], v[76:79], v[126:129], v[52:67]
	s_waitcnt lgkmcnt(0)
	v_mfma_f32_32x32x16_bf16 v[36:51], v[134:137], v[126:129], v[36:51]
	ds_read_b128 v[126:129], v109 offset:59904
	s_waitcnt lgkmcnt(0)
	v_mfma_f32_32x32x16_bf16 v[20:35], v[76:79], v[126:129], v[20:35]
	v_mfma_f32_32x32x16_bf16 v[4:19], v[134:137], v[126:129], v[4:19]
	ds_read_b128 v[76:79], v73
	ds_read_b128 v[126:129], v2 offset:55392
	ds_read_b128 v[134:137], v74
	s_waitcnt lgkmcnt(1)
	v_mfma_f32_32x32x16_bf16 v[52:67], v[76:79], v[126:129], v[52:67]
	s_waitcnt lgkmcnt(0)
	v_mfma_f32_32x32x16_bf16 v[36:51], v[134:137], v[126:129], v[36:51]
	ds_read_b128 v[126:129], v112 offset:59904
	s_waitcnt lgkmcnt(0)
	v_mfma_f32_32x32x16_bf16 v[20:35], v[76:79], v[126:129], v[20:35]
	global_load_dwordx4 v[76:79], v[94:95], off offset:1920
	s_nop 0
	global_load_dwordx4 v[94:97], v[96:97], off offset:1920
	s_nop 0
	global_load_dwordx4 v[138:141], v[98:99], off offset:1920
	s_nop 0
	global_load_dwordx4 v[98:101], v[100:101], off offset:1920
	s_nop 0
	global_load_dwordx4 v[142:145], v[92:93], off offset:1920
	global_load_dwordx4 v[146:149], v[102:103], off offset:1920
	s_waitcnt vmcnt(11)
	ds_write_b128 v105, v[80:83]
	s_waitcnt vmcnt(10)
	ds_write_b128 v105, v[122:125] offset:9216
	s_waitcnt vmcnt(9)
	ds_write_b128 v105, v[130:133] offset:18432
	s_waitcnt vmcnt(8)
	ds_write_b128 v105, v[88:91] offset:27648
	s_waitcnt vmcnt(7)
	ds_write_b128 v105, v[118:121] offset:36864
	s_waitcnt vmcnt(6)
	ds_write_b128 v105, v[84:87] offset:46080
	s_waitcnt lgkmcnt(0)
	s_barrier
; DI unsigned pk2(float a, float b) { f32x2 v = {a, b}; return __builtin_bit_cast(unsigned, __builtin_convertvector(v, bf2_t)); }
; template <bool SWAP, class Epi>
; DI void gemm_tile(const u16* __restrict__ A, int lda, const u16* __restrict__ Bw, int ldb, int K, char* lds, Epi epi) {
;     ...
;   for (int kt = 0; kt < nk; kt += 2) {
;     if (kt + 2 < nk) gload(kt + 2, ra0, rb0);
;     compute(0);
;     lstore(1, ra1, rb1);
;     __syncthreads();
;     if (kt + 3 < nk) gload(kt + 3, ra1, rb1);
;     compute(1);
;     if (kt + 2 < nk) lstore(0, ra0, rb0);
;     __syncthreads();
; DI void store_rowmajor(u16* dst, const f32x16& a, int h, float sc) {
; #pragma unroll
;   for (int kp = 0; kp < 2; ++kp) {
;     const int g = 2 * kp;
;     unsigned ax = pk2(a[4 * g] * sc, a[4 * g + 1] * sc), ay = pk2(a[4 * g + 2] * sc, a[4 * g + 3] * sc);
;     unsigned bx = pk2(a[4 * g + 4] * sc, a[4 * g + 5] * sc), by = pk2(a[4 * g + 6] * sc, a[4 * g + 7] * sc);
;     const u32x2 rx = __builtin_amdgcn_permlane32_swap(ax, bx, false, false);
;     const u32x2 ry = __builtin_amdgcn_permlane32_swap(ay, by, false, false);
;     const u32x4 v = {rx[0], ry[0], rx[1], ry[1]};
;     *(u32x4*)(dst + 8 * (g + h)) = v;
;   }
; }
; DI void inproj_tile(const Params& p, int l, int mt, int nt, char* lds) {
;     ...
;     gemm_tile<true>(A, DM, Bw, DM, DM, lds, [&](int mi, int ni, const f32x16& a) {
;       const int tok = m0 + wm * 64 + mi * 32 + r;
;       const int b = tok / PP, t = tok - b * PP;
;       const int sub = wn * 2 + ni;
;       if (sub == 0) {
;         store_rope(p.Kpe + (size_t)tok * 32, a, h, 1.f, p.ROPE + (size_t)t * 32);
;       } else if (sub == 1) {
;         store_rowmajor(p.IK + (size_t)tok * 64, a, h, 1.f);
;       } else if (sub == 2) {
;         store_rowmajor(p.IK + (size_t)tok * 64 + 32, a, h, 1.f);
	ds_read_b128 v[80:83], v111 offset:36864
	ds_read_b128 v[84:87], v2
	ds_read_b128 v[88:91], v111 offset:41472
	v_mfma_f32_32x32x16_bf16 v[4:19], v[134:137], v[126:129], v[4:19]
	s_waitcnt lgkmcnt(1)
	v_mfma_f32_32x32x16_bf16 v[52:67], v[80:83], v[84:87], v[52:67]
	s_waitcnt lgkmcnt(0)
	v_mfma_f32_32x32x16_bf16 v[36:51], v[88:91], v[84:87], v[36:51]
	ds_read_b128 v[84:87], v2 offset:4608
	s_waitcnt lgkmcnt(0)
	v_mfma_f32_32x32x16_bf16 v[20:35], v[80:83], v[84:87], v[20:35]
	v_mfma_f32_32x32x16_bf16 v[4:19], v[88:91], v[84:87], v[4:19]
	ds_read_b128 v[80:83], v111 offset:36896
	ds_read_b128 v[84:87], v2 offset:32
	ds_read_b128 v[88:91], v113 offset:41472
	s_waitcnt lgkmcnt(1)
	v_mfma_f32_32x32x16_bf16 v[52:67], v[80:83], v[84:87], v[52:67]
	s_waitcnt lgkmcnt(0)
	v_mfma_f32_32x32x16_bf16 v[36:51], v[88:91], v[84:87], v[36:51]
	ds_read_b128 v[84:87], v110 offset:4608
	s_waitcnt lgkmcnt(0)
	v_mfma_f32_32x32x16_bf16 v[20:35], v[80:83], v[84:87], v[20:35]
	v_mfma_f32_32x32x16_bf16 v[4:19], v[88:91], v[84:87], v[4:19]
	ds_read_b128 v[80:83], v111 offset:36928
	ds_read_b128 v[84:87], v2 offset:64
	ds_read_b128 v[88:91], v114 offset:41472
	s_waitcnt lgkmcnt(1)
	v_mfma_f32_32x32x16_bf16 v[52:67], v[80:83], v[84:87], v[52:67]
	s_waitcnt lgkmcnt(0)
	v_mfma_f32_32x32x16_bf16 v[36:51], v[88:91], v[84:87], v[36:51]
	ds_read_b128 v[84:87], v109 offset:4608
	s_waitcnt lgkmcnt(0)
	v_mfma_f32_32x32x16_bf16 v[20:35], v[80:83], v[84:87], v[20:35]
	v_mfma_f32_32x32x16_bf16 v[4:19], v[88:91], v[84:87], v[4:19]
	ds_read_b128 v[80:83], v111 offset:36960
	ds_read_b128 v[84:87], v2 offset:96
	ds_read_b128 v[88:91], v115 offset:41472
	s_waitcnt lgkmcnt(1)
	v_mfma_f32_32x32x16_bf16 v[52:67], v[80:83], v[84:87], v[52:67]
	s_waitcnt lgkmcnt(0)
	v_mfma_f32_32x32x16_bf16 v[36:51], v[88:91], v[84:87], v[36:51]
	ds_read_b128 v[84:87], v112 offset:4608
	s_waitcnt vmcnt(5)
	ds_write_b128 v105, v[76:79] offset:55296
	s_waitcnt vmcnt(4)
	ds_write_b128 v105, v[94:97] offset:64512
	s_waitcnt vmcnt(3)
	ds_write_b128 v117, v[138:141] offset:18432
	s_waitcnt vmcnt(2)
	ds_write_b128 v117, v[98:101] offset:27648
	s_waitcnt vmcnt(1)
	ds_write_b128 v116, v[142:145]
	s_waitcnt vmcnt(0)
	ds_write_b128 v116, v[146:149] offset:9216
	s_waitcnt lgkmcnt(0)
	s_barrier
	v_mfma_f32_32x32x16_bf16 v[20:35], v[80:83], v[84:87], v[20:35]
	ds_read_b128 v[76:79], v104
	ds_read_b128 v[80:83], v2 offset:55296
	v_mfma_f32_32x32x16_bf16 v[4:19], v[88:91], v[84:87], v[4:19]
	ds_read_b128 v[84:87], v68
	s_waitcnt lgkmcnt(1)
	v_mfma_f32_32x32x16_bf16 v[52:67], v[76:79], v[80:83], v[52:67]
	s_waitcnt lgkmcnt(0)
	v_mfma_f32_32x32x16_bf16 v[36:51], v[84:87], v[80:83], v[36:51]
	ds_read_b128 v[80:83], v2 offset:59904
	s_waitcnt lgkmcnt(0)
	v_mfma_f32_32x32x16_bf16 v[20:35], v[76:79], v[80:83], v[20:35]
	v_mfma_f32_32x32x16_bf16 v[4:19], v[84:87], v[80:83], v[4:19]
	ds_read_b128 v[76:79], v70
	ds_read_b128 v[80:83], v2 offset:55328
	ds_read_b128 v[84:87], v71
	s_waitcnt lgkmcnt(1)
	v_mfma_f32_32x32x16_bf16 v[52:67], v[76:79], v[80:83], v[52:67]
	s_waitcnt lgkmcnt(0)
	v_mfma_f32_32x32x16_bf16 v[36:51], v[84:87], v[80:83], v[36:51]
	ds_read_b128 v[80:83], v110 offset:59904
	s_waitcnt lgkmcnt(0)
	v_mfma_f32_32x32x16_bf16 v[20:35], v[76:79], v[80:83], v[20:35]
	v_mfma_f32_32x32x16_bf16 v[4:19], v[84:87], v[80:83], v[4:19]
	ds_read_b128 v[76:79], v72
	ds_read_b128 v[80:83], v2 offset:55360
	ds_read_b128 v[68:71], v69
	s_waitcnt lgkmcnt(1)
	v_mfma_f32_32x32x16_bf16 v[52:67], v[76:79], v[80:83], v[52:67]
	s_waitcnt lgkmcnt(0)
	v_mfma_f32_32x32x16_bf16 v[36:51], v[68:71], v[80:83], v[36:51]
	ds_read_b128 v[80:83], v109 offset:59904
	s_waitcnt lgkmcnt(0)
	v_mfma_f32_32x32x16_bf16 v[20:35], v[76:79], v[80:83], v[20:35]
	v_mfma_f32_32x32x16_bf16 v[4:19], v[68:71], v[80:83], v[4:19]
	ds_read_b128 v[68:71], v73
	ds_read_b128 v[76:79], v2 offset:55392
	ds_read_b128 v[72:75], v74
	v_lshlrev_b32_e32 v2, 6, v108
	s_waitcnt lgkmcnt(1)
	v_mfma_f32_32x32x16_bf16 v[52:67], v[68:71], v[76:79], v[52:67]
	s_waitcnt lgkmcnt(0)
	v_mfma_f32_32x32x16_bf16 v[36:51], v[72:75], v[76:79], v[36:51]
	ds_read_b128 v[76:79], v112 offset:59904
	s_waitcnt lgkmcnt(0)
	s_barrier
	v_mfma_f32_32x32x16_bf16 v[20:35], v[68:71], v[76:79], v[20:35]
	v_or3_b32 v70, v2, s4, v107
	v_mfma_f32_32x32x16_bf16 v[4:19], v[72:75], v[76:79], v[4:19]
	s_and_saveexec_b64 s[0:1], vcc
	s_xor_b64 s[0:1], exec, s[0:1]
	s_cbranch_execz .LBB0_332
	v_cmp_eq_u32_e32 vcc, 1, v0
	s_mov_b64 s[14:15], -1
	s_and_saveexec_b64 s[12:13], vcc
	s_cbranch_execz .LBB0_331
	v_ashrrev_i32_e32 v71, 31, v70
	v_readlane_b32 s64, v240, 1
	v_lshlrev_b64 v[68:69], 7, v[70:71]
	v_readlane_b32 s74, v240, 11
	v_readlane_b32 s75, v240, 12
	v_cvt_pk_bf16_f32 v72, v52, v53
	v_cvt_pk_bf16_f32 v73, v54, v55
	v_lshl_add_u64 v[68:69], s[74:75], 0, v[68:69]
	v_cvt_pk_bf16_f32 v74, v56, v57
	v_cvt_pk_bf16_f32 v75, v58, v59
	v_lshlrev_b32_e32 v2, 4, v106
	v_permlane32_swap_b32_e32 v72, v74
	v_permlane32_swap_b32_e32 v73, v75
	v_lshl_add_u64 v[68:69], v[68:69], 0, v[2:3]
	global_store_dwordx4 v[68:69], v[72:75], off offset:64
	v_readlane_b32 s65, v240, 2
	v_readlane_b32 s66, v240, 3
	v_cvt_pk_bf16_f32 v72, v60, v61
	v_cvt_pk_bf16_f32 v73, v62, v63
	v_cvt_pk_bf16_f32 v74, v64, v65
	v_cvt_pk_bf16_f32 v75, v66, v67
	s_nop 0
	v_permlane32_swap_b32_e32 v72, v74
	v_permlane32_swap_b32_e32 v73, v75
	v_readlane_b32 s67, v240, 4
	global_store_dwordx4 v[68:69], v[72:75], off offset:96
	s_xor_b64 s[14:15], exec, -1

; DI unsigned pk2(float a, float b) { f32x2 v = {a, b}; return __builtin_bit_cast(unsigned, __builtin_convertvector(v, bf2_t)); }
; DI void store_rope(u16* dst, const f32x16& a, int h, float sc, const float* rp) {
; #pragma unroll
;   for (int g = 0; g < 2; ++g) {
;     f32x4 cs = *(const f32x4*)(rp + 8 * g + 4 * h);
;     f32x4 sn = *(const f32x4*)(rp + 16 + 8 * g + 4 * h);
;     float o1[4], o2[4];
; #pragma unroll
;     for (int e = 0; e < 4; ++e) {
;       float x1 = a[4 * g + e] * sc, x2 = a[8 + 4 * g + e] * sc;
;       o1[e] = x1 * cs[e] - x2 * sn[e];
;       o2[e] = x1 * sn[e] + x2 * cs[e];
;     }
;     u32x2 v1 = {pk2(o1[0], o1[1]), pk2(o1[2], o1[3])};
;     u32x2 v2 = {pk2(o2[0], o2[1]), pk2(o2[2], o2[3])};
;     *(u32x2*)(dst + 8 * g + 4 * h) = v1;
;     *(u32x2*)(dst + 16 + 8 * g + 4 * h) = v2;
;   }
; DI void inproj_tile(const Params& p, int l, int mt, int nt, char* lds) {
;     ...
; #pragma unroll
;         for (int e = 0; e < 4; ++e) {
;           const int hd = e + 4 * h;
;           float xv = a[e] + p.b_f[l * 8 + hd];
;           float lf = fminf(xv, 0.f) - log1pf(expf(-fabsf(xv)));
;           p.LOGF[(size_t)(b * 8 + hd) * PP + t] = lf;
;           p.IW[(size_t)tok * 8 + hd] = a[4 + e];
;         }
.LBB0_336:
	s_or_b64 exec, exec, s[12:13]
	s_and_saveexec_b64 s[0:1], s[10:11]
	s_cbranch_execz .LBB0_338
	v_readlane_b32 s64, v240, 1
	v_lshlrev_b64 v[76:77], 7, v[72:73]
	v_readlane_b32 s46, v241, 38
	v_readlane_b32 s47, v241, 39
	v_lshlrev_b64 v[74:75], 6, v[70:71]
	v_readlane_b32 s72, v240, 9
	v_readlane_b32 s73, v240, 10
	v_lshl_add_u64 v[76:77], s[46:47], 0, v[76:77]
	v_lshlrev_b32_e32 v78, 4, v106
	v_mov_b32_e32 v79, v3
	v_lshl_add_u64 v[74:75], s[72:73], 0, v[74:75]
	v_lshl_add_u64 v[84:85], v[76:77], 0, v[78:79]
	v_lshlrev_b32_e32 v76, 3, v106
	v_mov_b32_e32 v77, v3
	v_lshl_add_u64 v[86:87], v[74:75], 0, v[76:77]
	global_load_dwordx4 v[74:77], v[84:85], off
	global_load_dwordx4 v[78:81], v[84:85], off offset:64
	v_readlane_b32 s65, v240, 2
	v_readlane_b32 s66, v240, 3
	v_readlane_b32 s67, v240, 4
	s_waitcnt vmcnt(0)
	v_pk_mul_f32 v[88:89], v[60:61], v[78:79]
	s_nop 0
	v_pk_fma_f32 v[88:89], v[52:53], v[74:75], v[88:89] neg_lo:[0,0,1] neg_hi:[0,0,1]
	v_pk_mul_f32 v[52:53], v[52:53], v[78:79]
	s_nop 0
	v_pk_fma_f32 v[52:53], v[60:61], v[74:75], v[52:53]
	v_pk_mul_f32 v[60:61], v[62:63], v[80:81]
	v_cvt_pk_bf16_f32 v52, v52, v53
	v_pk_fma_f32 v[60:61], v[54:55], v[76:77], v[60:61] neg_lo:[0,0,1] neg_hi:[0,0,1]
	v_pk_mul_f32 v[54:55], v[54:55], v[80:81]
	s_nop 0
	v_pk_fma_f32 v[54:55], v[62:63], v[76:77], v[54:55]
	v_cvt_pk_bf16_f32 v62, v88, v89
	v_cvt_pk_bf16_f32 v63, v60, v61
	v_cvt_pk_bf16_f32 v53, v54, v55
	global_store_dwordx2 v[86:87], v[62:63], off
	global_store_dwordx2 v[86:87], v[52:53], off offset:32
	global_load_dwordx4 v[52:55], v[84:85], off offset:32
	s_nop 0
	global_load_dwordx4 v[60:63], v[84:85], off offset:96
	s_waitcnt vmcnt(0)
	v_pk_mul_f32 v[74:75], v[64:65], v[60:61]
	s_nop 0
	v_pk_fma_f32 v[74:75], v[56:57], v[52:53], v[74:75] neg_lo:[0,0,1] neg_hi:[0,0,1]
	v_pk_mul_f32 v[56:57], v[56:57], v[60:61]
	s_nop 0
	v_pk_fma_f32 v[52:53], v[64:65], v[52:53], v[56:57]
	v_pk_mul_f32 v[56:57], v[66:67], v[62:63]
	v_cvt_pk_bf16_f32 v52, v52, v53
	v_pk_fma_f32 v[56:57], v[58:59], v[54:55], v[56:57] neg_lo:[0,0,1] neg_hi:[0,0,1]
	v_pk_mul_f32 v[58:59], v[58:59], v[62:63]
	s_nop 0
	v_pk_fma_f32 v[54:55], v[66:67], v[54:55], v[58:59]
	v_cvt_pk_bf16_f32 v58, v74, v75
	v_cvt_pk_bf16_f32 v59, v56, v57
	v_cvt_pk_bf16_f32 v53, v54, v55
	global_store_dwordx2 v[86:87], v[58:59], off offset:16
	global_store_dwordx2 v[86:87], v[52:53], off offset:48
.LBB0_338:
	s_or_b64 exec, exec, s[0:1]
	s_movk_i32 s0, 0xff
	v_cmp_lt_u32_e64 s[40:41], s0, v1
	s_and_saveexec_b64 s[0:1], s[40:41]
	s_xor_b64 s[10:11], exec, s[0:1]
	s_cbranch_execz .LBB0_340
	v_readlane_b32 s64, v241, 32
	v_readlane_b32 s68, v241, 36
	v_readlane_b32 s69, v241, 37
	s_nop 0
	s_nop 0
	v_lshlrev_b64 v[46:47], 5, v[70:71]
	v_lshl_add_u64 v[46:47], s[68:69], 0, v[46:47]
	v_readlane_b32 s76, v241, 8
	v_readlane_b32 s77, v241, 9
	v_readlane_b32 s78, v241, 10
	v_readlane_b32 s79, v241, 11
	v_readlane_b32 s80, v241, 12
	v_readlane_b32 s81, v241, 13
	v_readlane_b32 s82, v241, 14
	v_readlane_b32 s83, v241, 15
	s_mov_b64 s[68:69], s[76:77]
	s_mov_b64 s[72:73], s[80:81]
	v_lshl_add_u64 v[48:49], v[2:3], 2, s[72:73]
	global_load_dword v48, v[48:49], off
	s_mov_b32 s3, 0xbfb8aa3b
	s_mov_b32 s5, 0xb2a5705f
	s_mov_b32 s12, 0x42ce8ed0
	s_mov_b32 s13, 0xc2b17218
	s_mov_b32 s14, 0x3f2aaaab
	s_mov_b32 s15, 0x3f317218
	s_mov_b32 s16, 0x33800000
	v_readlane_b32 s65, v241, 33
	v_mov_b32_e32 v69, v3
	v_readlane_b32 s66, v241, 34
	v_lshl_add_u64 v[44:45], v[72:73], 2, s[64:65]
	v_readlane_b32 s67, v241, 35
	s_mov_b64 s[70:71], s[78:79]
	s_mov_b64 s[74:75], s[82:83]
	s_waitcnt vmcnt(0)
	v_add_f32_e32 v36, v36, v48
	v_mul_f32_e64 v48, |v36|, s3
	v_fma_f32 v49, |v36|, s3, -v48
	v_rndne_f32_e32 v51, v48
	v_fma_f32 v49, |v36|, s5, v49
	v_sub_f32_e32 v48, v48, v51
	v_add_f32_e32 v48, v48, v49
	v_exp_f32_e32 v48, v48
	v_cvt_i32_f32_e32 v49, v51
	v_cmp_ngt_f32_e64 s[0:1], |v36|, s12
	v_min_f32_e32 v50, 0, v36
	v_ldexp_f32 v48, v48, v49
	v_cndmask_b32_e64 v48, 0, v48, s[0:1]
	v_cmp_nlt_f32_e64 s[0:1], |v36|, s13
	s_nop 1
	v_cndmask_b32_e64 v36, v197, v48, s[0:1]
	v_add_f32_e32 v51, 1.0, v36
	v_add_f32_e32 v48, -1.0, v51
	v_sub_f32_e32 v49, v48, v51
	v_add_f32_e32 v49, 1.0, v49
	v_sub_f32_e32 v48, v36, v48
	v_add_f32_e32 v52, v48, v49
	v_frexp_mant_f32_e32 v48, v51
	v_cmp_gt_f32_e64 s[0:1], s14, v48
	v_cvt_f64_f32_e32 v[48:49], v51
	v_frexp_exp_i32_f64_e32 v48, v[48:49]
	v_subbrev_co_u32_e64 v48, s[0:1], 0, v48, s[0:1]
	v_sub_u32_e32 v49, 0, v48
	v_ldexp_f32 v51, v51, v49
	v_ldexp_f32 v49, v52, v49
	v_add_f32_e32 v52, -1.0, v51
	v_add_f32_e32 v53, 1.0, v52
	v_sub_f32_e32 v53, v51, v53
	v_add_f32_e32 v53, v49, v53
	v_add_f32_e32 v54, v52, v53
	v_sub_f32_e32 v52, v52, v54
	v_add_f32_e32 v52, v53, v52
	v_add_f32_e32 v53, 1.0, v51
	v_add_f32_e32 v55, -1.0, v53
	v_sub_f32_e32 v51, v51, v55
	v_add_f32_e32 v49, v49, v51
	v_add_f32_e32 v51, v53, v49
	v_sub_f32_e32 v53, v53, v51
	v_add_f32_e32 v49, v49, v53
	v_rcp_f32_e32 v53, v51
	v_cvt_f32_i32_e32 v48, v48
	v_cmp_neq_f32_e64 s[0:1], s89, v36
	v_mul_f32_e32 v55, v54, v53
	v_mul_f32_e32 v56, v51, v55
	v_fma_f32 v57, v55, v51, -v56
	v_fmac_f32_e32 v57, v55, v49
	v_add_f32_e32 v58, v56, v57
	v_sub_f32_e32 v59, v54, v58
	v_sub_f32_e32 v54, v54, v59
	v_sub_f32_e32 v56, v58, v56
	v_sub_f32_e32 v54, v54, v58
	v_add_f32_e32 v52, v52, v54
	v_sub_f32_e32 v54, v56, v57
	v_add_f32_e32 v52, v54, v52
	v_add_f32_e32 v54, v59, v52
	v_mul_f32_e32 v56, v53, v54
	v_mul_f32_e32 v57, v51, v56
	v_fma_f32 v51, v56, v51, -v57
	v_fmac_f32_e32 v51, v56, v49
	v_sub_f32_e32 v49, v59, v54
	v_add_f32_e32 v49, v52, v49
	v_add_f32_e32 v52, v57, v51
	v_sub_f32_e32 v58, v54, v52
; DI void inproj_tile(const Params& p, int l, int mt, int nt, char* lds) {
;     ...
; #pragma unroll
;         for (int e = 0; e < 4; ++e) {
;           const int hd = e + 4 * h;
;           float xv = a[e] + p.b_f[l * 8 + hd];
;           float lf = fminf(xv, 0.f) - log1pf(expf(-fabsf(xv)));
;           p.LOGF[(size_t)(b * 8 + hd) * PP + t] = lf;
;           p.IW[(size_t)tok * 8 + hd] = a[4 + e];
;         }
	v_sub_f32_e32 v54, v54, v58
	v_sub_f32_e32 v57, v52, v57
	v_sub_f32_e32 v52, v54, v52
	v_add_f32_e32 v49, v49, v52
	v_sub_f32_e32 v51, v57, v51
	v_add_f32_e32 v49, v51, v49
	v_add_f32_e32 v51, v55, v56
	v_add_f32_e32 v49, v58, v49
	v_sub_f32_e32 v52, v51, v55
	v_mul_f32_e32 v49, v53, v49
	v_sub_f32_e32 v52, v56, v52
	v_add_f32_e32 v49, v52, v49
	v_mul_f32_e32 v55, 0x3f317218, v48
	v_add_f32_e32 v52, v51, v49
	v_fma_f32 v56, v48, s15, -v55
	v_mul_f32_e32 v53, v52, v52
	v_fmac_f32_e32 v56, 0xb102e308, v48
	v_sub_f32_e32 v48, v52, v51
	v_fmamk_f32 v54, v53, 0x3e9b6dac, v192
	v_sub_f32_e32 v48, v49, v48
	v_add_f32_e32 v49, v55, v56
	v_fmaak_f32 v54, v53, v54, 0x3f2aaada
	v_sub_f32_e32 v51, v49, v55
	v_ldexp_f32 v55, v52, 1
	v_mul_f32_e32 v52, v52, v53
	v_mul_f32_e32 v52, v52, v54
	v_add_f32_e32 v53, v55, v52
	v_sub_f32_e32 v54, v53, v55
	v_ldexp_f32 v48, v48, 1
	v_sub_f32_e32 v52, v52, v54
	v_add_f32_e32 v48, v48, v52
	v_add_f32_e32 v52, v53, v48
	v_sub_f32_e32 v53, v52, v53
	v_sub_f32_e32 v48, v48, v53
	v_add_f32_e32 v53, v49, v52
	v_sub_f32_e32 v54, v53, v49
	v_sub_f32_e32 v55, v53, v54
	v_sub_f32_e32 v51, v56, v51
	v_sub_f32_e32 v49, v49, v55
	v_sub_f32_e32 v52, v52, v54
	v_add_f32_e32 v49, v52, v49
	v_add_f32_e32 v52, v51, v48
	v_sub_f32_e32 v54, v52, v51
	v_sub_f32_e32 v55, v52, v54
	v_sub_f32_e32 v51, v51, v55
	v_sub_f32_e32 v48, v48, v54
	v_add_f32_e32 v49, v52, v49
	v_add_f32_e32 v48, v48, v51
	v_add_f32_e32 v51, v53, v49
	v_sub_f32_e32 v52, v51, v53
	v_sub_f32_e32 v49, v49, v52
	v_add_f32_e32 v48, v48, v49
	v_add_f32_e32 v48, v51, v48
	v_cndmask_b32_e64 v48, v197, v48, s[0:1]
	v_cmp_lt_f32_e64 s[0:1], |v36|, s16
	v_mul_hi_i32_i24_e32 v49, 0x8400, v83
	s_nop 0
	v_cndmask_b32_e64 v36, v48, v36, s[0:1]
	v_mul_i32_i24_e32 v48, 0x8400, v83
	v_sub_f32_e32 v36, v50, v36
	v_lshl_add_u64 v[48:49], v[44:45], 0, v[48:49]
	global_store_dword v[48:49], v36, off
	v_lshlrev_b32_e32 v48, 4, v106
	v_mov_b32_e32 v49, v3
	v_lshl_add_u64 v[46:47], v[46:47], 0, v[48:49]
	global_store_dword v[46:47], v40, off
	v_lshl_add_u64 v[48:49], v[68:69], 2, s[72:73]
	global_load_dword v36, v[48:49], off offset:4
	s_waitcnt vmcnt(0)
	v_add_f32_e32 v36, v37, v36
	v_mul_f32_e64 v37, |v36|, s3
	v_fma_f32 v50, |v36|, s3, -v37
	v_rndne_f32_e32 v51, v37
	v_fma_f32 v50, |v36|, s5, v50
	v_sub_f32_e32 v37, v37, v51
	v_add_f32_e32 v37, v37, v50
	v_exp_f32_e32 v37, v37
	v_cvt_i32_f32_e32 v50, v51
	v_cmp_ngt_f32_e64 s[0:1], |v36|, s12
	v_min_f32_e32 v40, 0, v36
	v_ldexp_f32 v37, v37, v50
	v_cndmask_b32_e64 v37, 0, v37, s[0:1]
	v_cmp_nlt_f32_e64 s[0:1], |v36|, s13
	s_nop 1
	v_cndmask_b32_e64 v50, v197, v37, s[0:1]
	v_add_f32_e32 v51, 1.0, v50
	v_add_f32_e32 v36, -1.0, v51
	v_sub_f32_e32 v37, v36, v51
	v_add_f32_e32 v37, 1.0, v37
	v_sub_f32_e32 v36, v50, v36
	v_add_f32_e32 v52, v36, v37
	v_frexp_mant_f32_e32 v36, v51
	v_cmp_gt_f32_e64 s[0:1], s14, v36
	v_cvt_f64_f32_e32 v[36:37], v51
	v_frexp_exp_i32_f64_e32 v36, v[36:37]
	v_subbrev_co_u32_e64 v36, s[0:1], 0, v36, s[0:1]
	v_sub_u32_e32 v37, 0, v36
	v_ldexp_f32 v51, v51, v37
	v_ldexp_f32 v37, v52, v37
	v_add_f32_e32 v52, -1.0, v51
	v_add_f32_e32 v53, 1.0, v52
	v_sub_f32_e32 v53, v51, v53
	v_add_f32_e32 v53, v37, v53
	v_add_f32_e32 v54, v52, v53
	v_sub_f32_e32 v52, v52, v54
	v_add_f32_e32 v52, v53, v52
	v_add_f32_e32 v53, 1.0, v51
	v_add_f32_e32 v55, -1.0, v53
	v_sub_f32_e32 v51, v51, v55
	v_add_f32_e32 v37, v37, v51
	v_add_f32_e32 v51, v53, v37
	v_sub_f32_e32 v53, v53, v51
	v_add_f32_e32 v37, v37, v53
	v_rcp_f32_e32 v53, v51
	v_cvt_f32_i32_e32 v36, v36
	v_cmp_neq_f32_e64 s[0:1], s89, v50
	v_mul_f32_e32 v55, v54, v53
	v_mul_f32_e32 v56, v51, v55
	v_fma_f32 v57, v55, v51, -v56
	v_fmac_f32_e32 v57, v55, v37
	v_add_f32_e32 v58, v56, v57
	v_sub_f32_e32 v59, v54, v58
	v_sub_f32_e32 v54, v54, v59
	v_sub_f32_e32 v56, v58, v56
	v_sub_f32_e32 v54, v54, v58
	v_add_f32_e32 v52, v52, v54
	v_sub_f32_e32 v54, v56, v57
	v_add_f32_e32 v52, v54, v52
	v_add_f32_e32 v54, v59, v52
	v_mul_f32_e32 v56, v53, v54
	v_mul_f32_e32 v57, v51, v56
	v_fma_f32 v51, v56, v51, -v57
	v_fmac_f32_e32 v51, v56, v37
	v_sub_f32_e32 v37, v59, v54
	v_add_f32_e32 v37, v52, v37
	v_add_f32_e32 v52, v57, v51
	v_sub_f32_e32 v58, v54, v52
	v_sub_f32_e32 v54, v54, v58
	v_sub_f32_e32 v57, v52, v57
	v_sub_f32_e32 v52, v54, v52
	v_add_f32_e32 v37, v37, v52
	v_sub_f32_e32 v51, v57, v51
	v_add_f32_e32 v37, v51, v37
	v_add_f32_e32 v51, v55, v56
	v_add_f32_e32 v37, v58, v37
	v_sub_f32_e32 v52, v51, v55
	v_mul_f32_e32 v37, v53, v37
	v_sub_f32_e32 v52, v56, v52
	v_add_f32_e32 v37, v52, v37
	v_mul_f32_e32 v55, 0x3f317218, v36
	v_add_f32_e32 v52, v51, v37
	v_fma_f32 v56, v36, s15, -v55
	v_mul_f32_e32 v53, v52, v52
	v_fmac_f32_e32 v56, 0xb102e308, v36
	v_sub_f32_e32 v36, v52, v51
	v_fmamk_f32 v54, v53, 0x3e9b6dac, v192
	v_sub_f32_e32 v36, v37, v36
	v_add_f32_e32 v37, v55, v56
	v_fmaak_f32 v54, v53, v54, 0x3f2aaada
	v_sub_f32_e32 v51, v37, v55
	v_ldexp_f32 v55, v52, 1
	v_mul_f32_e32 v52, v52, v53
	v_mul_f32_e32 v52, v52, v54
	v_add_f32_e32 v53, v55, v52
	v_sub_f32_e32 v54, v53, v55
	v_ldexp_f32 v36, v36, 1
	v_sub_f32_e32 v52, v52, v54
	v_add_f32_e32 v36, v36, v52
	v_add_f32_e32 v52, v53, v36
	v_sub_f32_e32 v53, v52, v53
	v_sub_f32_e32 v36, v36, v53
	v_add_f32_e32 v53, v37, v52
	v_sub_f32_e32 v54, v53, v37
	v_sub_f32_e32 v55, v53, v54
	v_sub_f32_e32 v51, v56, v51
	v_sub_f32_e32 v37, v37, v55
	v_sub_f32_e32 v52, v52, v54
	v_add_f32_e32 v37, v52, v37
	v_add_f32_e32 v52, v51, v36
	v_sub_f32_e32 v54, v52, v51
	v_sub_f32_e32 v55, v52, v54
	v_sub_f32_e32 v51, v51, v55
	v_sub_f32_e32 v36, v36, v54
	v_add_f32_e32 v37, v52, v37
	v_add_f32_e32 v36, v36, v51
	v_add_f32_e32 v51, v53, v37
	v_sub_f32_e32 v52, v51, v53
	v_sub_f32_e32 v37, v37, v52
	v_add_f32_e32 v36, v36, v37
	v_add_f32_e32 v36, v51, v36
	v_cndmask_b32_e64 v36, v197, v36, s[0:1]
	v_cmp_lt_f32_e64 s[0:1], |v50|, s16
	s_nop 1
	v_cndmask_b32_e64 v36, v36, v50, s[0:1]
	v_sub_f32_e32 v40, v40, v36
	v_or_b32_e32 v36, 1, v83
	v_mul_hi_i32_i24_e32 v37, 0x8400, v36
	v_mul_i32_i24_e32 v36, 0x8400, v36
	v_lshl_add_u64 v[36:37], v[44:45], 0, v[36:37]
	global_store_dword v[36:37], v40, off
	global_store_dword v[46:47], v41, off offset:4
	global_load_dword v36, v[48:49], off offset:8
	s_waitcnt vmcnt(0)
; DI void inproj_tile(const Params& p, int l, int mt, int nt, char* lds) {
;     ...
; #pragma unroll
;         for (int e = 0; e < 4; ++e) {
;           const int hd = e + 4 * h;
;           float xv = a[e] + p.b_f[l * 8 + hd];
;           float lf = fminf(xv, 0.f) - log1pf(expf(-fabsf(xv)));
;           p.LOGF[(size_t)(b * 8 + hd) * PP + t] = lf;
;           p.IW[(size_t)tok * 8 + hd] = a[4 + e];
;         }
	v_add_f32_e32 v36, v38, v36
	v_mul_f32_e64 v37, |v36|, s3
	v_fma_f32 v40, |v36|, s3, -v37
	v_rndne_f32_e32 v41, v37
	v_fma_f32 v40, |v36|, s5, v40
	v_sub_f32_e32 v37, v37, v41
	v_add_f32_e32 v37, v37, v40
	v_exp_f32_e32 v37, v37
	v_cvt_i32_f32_e32 v40, v41
	v_cmp_ngt_f32_e64 s[0:1], |v36|, s12
	v_min_f32_e32 v38, 0, v36
	v_ldexp_f32 v37, v37, v40
	v_cndmask_b32_e64 v37, 0, v37, s[0:1]
	v_cmp_nlt_f32_e64 s[0:1], |v36|, s13
	s_nop 1
	v_cndmask_b32_e64 v40, v197, v37, s[0:1]
	v_add_f32_e32 v41, 1.0, v40
	v_add_f32_e32 v36, -1.0, v41
	v_sub_f32_e32 v37, v36, v41
	v_add_f32_e32 v37, 1.0, v37
	v_sub_f32_e32 v36, v40, v36
	v_add_f32_e32 v50, v36, v37
	v_frexp_mant_f32_e32 v36, v41
	v_cmp_gt_f32_e64 s[0:1], s14, v36
	v_cvt_f64_f32_e32 v[36:37], v41
	v_frexp_exp_i32_f64_e32 v36, v[36:37]
	v_subbrev_co_u32_e64 v36, s[0:1], 0, v36, s[0:1]
	v_sub_u32_e32 v37, 0, v36
	v_ldexp_f32 v41, v41, v37
	v_ldexp_f32 v37, v50, v37
	v_add_f32_e32 v50, -1.0, v41
	v_add_f32_e32 v51, 1.0, v50
	v_sub_f32_e32 v51, v41, v51
	v_add_f32_e32 v51, v37, v51
	v_add_f32_e32 v52, v50, v51
	v_sub_f32_e32 v50, v50, v52
	v_add_f32_e32 v50, v51, v50
	v_add_f32_e32 v51, 1.0, v41
	v_add_f32_e32 v53, -1.0, v51
	v_sub_f32_e32 v41, v41, v53
	v_add_f32_e32 v37, v37, v41
	v_add_f32_e32 v41, v51, v37
	v_sub_f32_e32 v51, v51, v41
	v_add_f32_e32 v37, v37, v51
	v_rcp_f32_e32 v51, v41
	v_cvt_f32_i32_e32 v36, v36
	v_cmp_neq_f32_e64 s[0:1], s89, v40
	v_mul_f32_e32 v53, v52, v51
	v_mul_f32_e32 v54, v41, v53
	v_fma_f32 v55, v53, v41, -v54
	v_fmac_f32_e32 v55, v53, v37
	v_add_f32_e32 v56, v54, v55
	v_sub_f32_e32 v57, v52, v56
	v_sub_f32_e32 v52, v52, v57
	v_sub_f32_e32 v54, v56, v54
	v_sub_f32_e32 v52, v52, v56
	v_add_f32_e32 v50, v50, v52
	v_sub_f32_e32 v52, v54, v55
	v_add_f32_e32 v50, v52, v50
	v_add_f32_e32 v52, v57, v50
	v_mul_f32_e32 v54, v51, v52
	v_mul_f32_e32 v55, v41, v54
	v_fma_f32 v41, v54, v41, -v55
	v_fmac_f32_e32 v41, v54, v37
	v_sub_f32_e32 v37, v57, v52
	v_add_f32_e32 v37, v50, v37
	v_add_f32_e32 v50, v55, v41
	v_sub_f32_e32 v56, v52, v50
	v_sub_f32_e32 v52, v52, v56
	v_sub_f32_e32 v55, v50, v55
	v_sub_f32_e32 v50, v52, v50
	v_add_f32_e32 v37, v37, v50
	v_sub_f32_e32 v41, v55, v41
	v_add_f32_e32 v37, v41, v37
	v_add_f32_e32 v41, v53, v54
	v_add_f32_e32 v37, v56, v37
	v_sub_f32_e32 v50, v41, v53
	v_mul_f32_e32 v37, v51, v37
	v_sub_f32_e32 v50, v54, v50
	v_add_f32_e32 v37, v50, v37
	v_mul_f32_e32 v53, 0x3f317218, v36
	v_add_f32_e32 v50, v41, v37
	v_fma_f32 v54, v36, s15, -v53
	v_mul_f32_e32 v51, v50, v50
	v_fmac_f32_e32 v54, 0xb102e308, v36
	v_sub_f32_e32 v36, v50, v41
	v_fmamk_f32 v52, v51, 0x3e9b6dac, v192
	v_sub_f32_e32 v36, v37, v36
	v_add_f32_e32 v37, v53, v54
	v_fmaak_f32 v52, v51, v52, 0x3f2aaada
	v_sub_f32_e32 v41, v37, v53
	v_ldexp_f32 v53, v50, 1
	v_mul_f32_e32 v50, v50, v51
	v_mul_f32_e32 v50, v50, v52
	v_add_f32_e32 v51, v53, v50
	v_sub_f32_e32 v52, v51, v53
	v_ldexp_f32 v36, v36, 1
	v_sub_f32_e32 v50, v50, v52
	v_add_f32_e32 v36, v36, v50
	v_add_f32_e32 v50, v51, v36
	v_sub_f32_e32 v51, v50, v51
	v_sub_f32_e32 v36, v36, v51
	v_add_f32_e32 v51, v37, v50
	v_sub_f32_e32 v52, v51, v37
	v_sub_f32_e32 v53, v51, v52
	v_sub_f32_e32 v41, v54, v41
	v_sub_f32_e32 v37, v37, v53
	v_sub_f32_e32 v50, v50, v52
	v_add_f32_e32 v37, v50, v37
	v_add_f32_e32 v50, v41, v36
	v_sub_f32_e32 v52, v50, v41
	v_sub_f32_e32 v53, v50, v52
	v_sub_f32_e32 v41, v41, v53
	v_sub_f32_e32 v36, v36, v52
	v_add_f32_e32 v37, v50, v37
	v_add_f32_e32 v36, v36, v41
	v_add_f32_e32 v41, v51, v37
	v_sub_f32_e32 v50, v41, v51
	v_sub_f32_e32 v37, v37, v50
	v_add_f32_e32 v36, v36, v37
	v_add_f32_e32 v36, v41, v36
	v_cndmask_b32_e64 v36, v197, v36, s[0:1]
	v_cmp_lt_f32_e64 s[0:1], |v40|, s16
	s_nop 1
	v_cndmask_b32_e64 v36, v36, v40, s[0:1]
	v_sub_f32_e32 v38, v38, v36
	v_or_b32_e32 v36, 2, v83
	v_mul_hi_i32_i24_e32 v37, 0x8400, v36
	v_mul_i32_i24_e32 v36, 0x8400, v36
	v_lshl_add_u64 v[36:37], v[44:45], 0, v[36:37]
	global_store_dword v[36:37], v38, off
	global_store_dword v[46:47], v42, off offset:8
	global_load_dword v36, v[48:49], off offset:12
	s_waitcnt vmcnt(0)
; DI unsigned pk2(float a, float b) { f32x2 v = {a, b}; return __builtin_bit_cast(unsigned, __builtin_convertvector(v, bf2_t)); }
; DI void store_rowmajor(u16* dst, const f32x16& a, int h, float sc) {
; #pragma unroll
;   for (int kp = 0; kp < 2; ++kp) {
;     const int g = 2 * kp;
;     unsigned ax = pk2(a[4 * g] * sc, a[4 * g + 1] * sc), ay = pk2(a[4 * g + 2] * sc, a[4 * g + 3] * sc);
;     unsigned bx = pk2(a[4 * g + 4] * sc, a[4 * g + 5] * sc), by = pk2(a[4 * g + 6] * sc, a[4 * g + 7] * sc);
;     const u32x2 rx = __builtin_amdgcn_permlane32_swap(ax, bx, false, false);
;     const u32x2 ry = __builtin_amdgcn_permlane32_swap(ay, by, false, false);
;     const u32x4 v = {rx[0], ry[0], rx[1], ry[1]};
;     *(u32x4*)(dst + 8 * (g + h)) = v;
;   }
; }
; DI void inproj_tile(const Params& p, int l, int mt, int nt, char* lds) {
;     ...
;       const int tok = m0 + wm * 64 + mi * 32 + r;
;       const int b = tok / PP, t = tok - b * PP;
;       const int sub = wn * 2 + ni;
;       if (sub == 0) {
;         store_rope(p.Kpe + (size_t)tok * 32, a, h, 1.f, p.ROPE + (size_t)t * 32);
;       } else if (sub == 1) {
;         store_rowmajor(p.IK + (size_t)tok * 64, a, h, 1.f);
;       } else if (sub == 2) {
;         store_rowmajor(p.IK + (size_t)tok * 64 + 32, a, h, 1.f);
;       } else {
; #pragma unroll
;         for (int e = 0; e < 4; ++e) {
;           const int hd = e + 4 * h;
;           float xv = a[e] + p.b_f[l * 8 + hd];
;           float lf = fminf(xv, 0.f) - log1pf(expf(-fabsf(xv)));
;           p.LOGF[(size_t)(b * 8 + hd) * PP + t] = lf;
;           p.IW[(size_t)tok * 8 + hd] = a[4 + e];
;         }
	v_add_f32_e32 v36, v39, v36
	v_mul_f32_e64 v37, |v36|, s3
	v_fma_f32 v39, |v36|, s3, -v37
	v_rndne_f32_e32 v40, v37
	v_fma_f32 v39, |v36|, s5, v39
	v_sub_f32_e32 v37, v37, v40
	v_add_f32_e32 v37, v37, v39
	v_exp_f32_e32 v37, v37
	v_cvt_i32_f32_e32 v39, v40
	v_cmp_ngt_f32_e64 s[0:1], |v36|, s12
	v_min_f32_e32 v38, 0, v36
	v_ldexp_f32 v37, v37, v39
	v_cndmask_b32_e64 v37, 0, v37, s[0:1]
	v_cmp_nlt_f32_e64 s[0:1], |v36|, s13
	s_nop 1
	v_cndmask_b32_e64 v39, v197, v37, s[0:1]
	v_add_f32_e32 v40, 1.0, v39
	v_add_f32_e32 v36, -1.0, v40
	v_sub_f32_e32 v37, v36, v40
	v_add_f32_e32 v37, 1.0, v37
	v_sub_f32_e32 v36, v39, v36
	v_add_f32_e32 v41, v36, v37
	v_frexp_mant_f32_e32 v36, v40
	v_cmp_gt_f32_e64 s[0:1], s14, v36
	v_cvt_f64_f32_e32 v[36:37], v40
	v_frexp_exp_i32_f64_e32 v36, v[36:37]
	v_subbrev_co_u32_e64 v36, s[0:1], 0, v36, s[0:1]
	v_sub_u32_e32 v37, 0, v36
	v_ldexp_f32 v40, v40, v37
	v_ldexp_f32 v37, v41, v37
	v_add_f32_e32 v41, -1.0, v40
	v_add_f32_e32 v42, 1.0, v41
	v_sub_f32_e32 v42, v40, v42
	v_add_f32_e32 v42, v37, v42
	v_add_f32_e32 v48, v41, v42
	v_sub_f32_e32 v41, v41, v48
	v_add_f32_e32 v41, v42, v41
	v_add_f32_e32 v42, 1.0, v40
	v_add_f32_e32 v49, -1.0, v42
	v_sub_f32_e32 v40, v40, v49
	v_add_f32_e32 v37, v37, v40
	v_add_f32_e32 v40, v42, v37
	v_sub_f32_e32 v42, v42, v40
	v_add_f32_e32 v37, v37, v42
	v_rcp_f32_e32 v42, v40
	v_cvt_f32_i32_e32 v36, v36
	v_cmp_neq_f32_e64 s[0:1], s89, v39
	v_mul_f32_e32 v49, v48, v42
	v_mul_f32_e32 v50, v40, v49
	v_fma_f32 v51, v49, v40, -v50
	v_fmac_f32_e32 v51, v49, v37
	v_add_f32_e32 v52, v50, v51
	v_sub_f32_e32 v53, v48, v52
	v_sub_f32_e32 v48, v48, v53
	v_sub_f32_e32 v50, v52, v50
	v_sub_f32_e32 v48, v48, v52
	v_add_f32_e32 v41, v41, v48
	v_sub_f32_e32 v48, v50, v51
	v_add_f32_e32 v41, v48, v41
	v_add_f32_e32 v48, v53, v41
	v_mul_f32_e32 v50, v42, v48
	v_mul_f32_e32 v51, v40, v50
	v_fma_f32 v40, v50, v40, -v51
	v_fmac_f32_e32 v40, v50, v37
	v_sub_f32_e32 v37, v53, v48
	v_add_f32_e32 v37, v41, v37
	v_add_f32_e32 v41, v51, v40
	v_sub_f32_e32 v52, v48, v41
	v_sub_f32_e32 v48, v48, v52
	v_sub_f32_e32 v51, v41, v51
	v_sub_f32_e32 v41, v48, v41
	v_add_f32_e32 v37, v37, v41
	v_sub_f32_e32 v40, v51, v40
	v_add_f32_e32 v37, v40, v37
	v_add_f32_e32 v40, v49, v50
	v_add_f32_e32 v37, v52, v37
	v_sub_f32_e32 v41, v40, v49
	v_mul_f32_e32 v37, v42, v37
	v_sub_f32_e32 v41, v50, v41
	v_add_f32_e32 v37, v41, v37
	v_mul_f32_e32 v49, 0x3f317218, v36
	v_add_f32_e32 v41, v40, v37
	v_fma_f32 v50, v36, s15, -v49
	v_mul_f32_e32 v42, v41, v41
	v_fmac_f32_e32 v50, 0xb102e308, v36
	v_sub_f32_e32 v36, v41, v40
	v_fmamk_f32 v48, v42, 0x3e9b6dac, v192
	v_sub_f32_e32 v36, v37, v36
	v_add_f32_e32 v37, v49, v50
	v_fmaak_f32 v48, v42, v48, 0x3f2aaada
	v_sub_f32_e32 v40, v37, v49
	v_ldexp_f32 v49, v41, 1
	v_mul_f32_e32 v41, v41, v42
	v_mul_f32_e32 v41, v41, v48
	v_add_f32_e32 v42, v49, v41
	v_sub_f32_e32 v48, v42, v49
	v_ldexp_f32 v36, v36, 1
	v_sub_f32_e32 v41, v41, v48
	v_add_f32_e32 v36, v36, v41
	v_add_f32_e32 v41, v42, v36
	v_sub_f32_e32 v42, v41, v42
	v_sub_f32_e32 v36, v36, v42
	v_add_f32_e32 v42, v37, v41
	v_sub_f32_e32 v48, v42, v37
	v_sub_f32_e32 v49, v42, v48
	v_sub_f32_e32 v40, v50, v40
	v_sub_f32_e32 v37, v37, v49
	v_sub_f32_e32 v41, v41, v48
	v_add_f32_e32 v37, v41, v37
	v_add_f32_e32 v41, v40, v36
	v_sub_f32_e32 v48, v41, v40
	v_sub_f32_e32 v49, v41, v48
	v_sub_f32_e32 v40, v40, v49
	v_sub_f32_e32 v36, v36, v48
	v_add_f32_e32 v37, v41, v37
	v_add_f32_e32 v36, v36, v40
	v_add_f32_e32 v40, v42, v37
	v_sub_f32_e32 v41, v40, v42
	v_sub_f32_e32 v37, v37, v41
	v_add_f32_e32 v36, v36, v37
	v_add_f32_e32 v36, v40, v36
	v_cndmask_b32_e64 v36, v197, v36, s[0:1]
	v_cmp_lt_f32_e64 s[0:1], |v39|, s16
	s_nop 1
	v_cndmask_b32_e64 v36, v36, v39, s[0:1]
	v_sub_f32_e32 v38, v38, v36
	v_or_b32_e32 v36, 3, v83
	v_mul_hi_i32_i24_e32 v37, 0x8400, v36
	v_mul_i32_i24_e32 v36, 0x8400, v36
	v_lshl_add_u64 v[36:37], v[44:45], 0, v[36:37]
	global_store_dword v[36:37], v38, off
	global_store_dword v[46:47], v43, off offset:12
.LBB0_340:
	s_andn2_saveexec_b64 s[0:1], s[10:11]
	s_cbranch_execz .LBB0_342
	v_readlane_b32 s64, v240, 1
	v_lshlrev_b64 v[52:53], 7, v[70:71]
	v_readlane_b32 s74, v240, 11
	v_readlane_b32 s75, v240, 12
	v_cvt_pk_bf16_f32 v36, v36, v37
	v_cvt_pk_bf16_f32 v37, v38, v39
	v_lshl_add_u64 v[52:53], s[74:75], 0, v[52:53]
	v_cvt_pk_bf16_f32 v38, v40, v41
	v_cvt_pk_bf16_f32 v39, v42, v43
	v_lshlrev_b32_e32 v40, 4, v106
	v_mov_b32_e32 v41, v3
	v_permlane32_swap_b32_e32 v36, v38
	v_permlane32_swap_b32_e32 v37, v39
	v_lshl_add_u64 v[40:41], v[52:53], 0, v[40:41]
	global_store_dwordx4 v[40:41], v[36:39], off
	v_readlane_b32 s65, v240, 2
	v_readlane_b32 s66, v240, 3
	v_cvt_pk_bf16_f32 v36, v44, v45
	v_cvt_pk_bf16_f32 v37, v46, v47
	v_cvt_pk_bf16_f32 v38, v48, v49
	v_cvt_pk_bf16_f32 v39, v50, v51
	s_nop 0
	v_permlane32_swap_b32_e32 v36, v38
	v_permlane32_swap_b32_e32 v37, v39
	v_readlane_b32 s67, v240, 4
	global_store_dwordx4 v[40:41], v[36:39], off offset:32
.LBB0_342:
	s_or_b64 exec, exec, s[0:1]
	s_nop 0
	v_or_b32_e32 v36, 32, v70
	v_cmp_lt_i32_e64 s[0:1], 0, v0
	s_mov_b64 s[10:11], 0
	s_mov_b64 s[14:15], 0
	s_and_saveexec_b64 s[12:13], s[0:1]
	s_xor_b64 s[12:13], exec, s[12:13]
	s_cbranch_execz .LBB0_346
	v_cmp_eq_u32_e64 s[0:1], 1, v0
	s_mov_b64 s[16:17], -1
	s_and_saveexec_b64 s[14:15], s[0:1]
	s_cbranch_execz .LBB0_345
	v_ashrrev_i32_e32 v37, 31, v36
	v_readlane_b32 s64, v240, 1
	v_lshlrev_b64 v[38:39], 7, v[36:37]
	v_readlane_b32 s74, v240, 11
	v_readlane_b32 s75, v240, 12
	v_cvt_pk_bf16_f32 v40, v24, v25
	v_cvt_pk_bf16_f32 v41, v26, v27
	v_lshl_add_u64 v[42:43], s[74:75], 0, v[38:39]
	v_cvt_pk_bf16_f32 v38, v20, v21
	v_cvt_pk_bf16_f32 v39, v22, v23
	v_lshlrev_b32_e32 v44, 4, v106
	v_mov_b32_e32 v45, v3
	v_permlane32_swap_b32_e32 v38, v40
	v_permlane32_swap_b32_e32 v39, v41
	v_lshl_add_u64 v[42:43], v[42:43], 0, v[44:45]
	global_store_dwordx4 v[42:43], v[38:41], off offset:64
	v_readlane_b32 s65, v240, 2
	v_readlane_b32 s66, v240, 3
	v_cvt_pk_bf16_f32 v38, v28, v29
	v_cvt_pk_bf16_f32 v39, v30, v31
	v_cvt_pk_bf16_f32 v40, v32, v33
	v_cvt_pk_bf16_f32 v41, v34, v35
	s_nop 0
	v_permlane32_swap_b32_e32 v38, v40
	v_permlane32_swap_b32_e32 v39, v41
	v_readlane_b32 s67, v240, 4
	global_store_dwordx4 v[42:43], v[38:41], off offset:96
	s_xor_b64 s[16:17], exec, -1

; DI void inproj_tile(const Params& p, int l, int mt, int nt, char* lds) {
;     ...
;       const int tok = m0 + wm * 64 + mi * 32 + r;
;       const int b = tok / PP, t = tok - b * PP;
;       const int sub = wn * 2 + ni;
;       if (sub == 0) {
;         store_rope(p.Kpe + (size_t)tok * 32, a, h, 1.f, p.ROPE + (size_t)t * 32);
;       } else if (sub == 1) {
;         store_rowmajor(p.IK + (size_t)tok * 64, a, h, 1.f);
;       } else if (sub == 2) {
;         store_rowmajor(p.IK + (size_t)tok * 64 + 32, a, h, 1.f);
;       } else {
; #pragma unroll
;         for (int e = 0; e < 4; ++e) {
;           const int hd = e + 4 * h;
;           float xv = a[e] + p.b_f[l * 8 + hd];
;           float lf = fminf(xv, 0.f) - log1pf(expf(-fabsf(xv)));
;           p.LOGF[(size_t)(b * 8 + hd) * PP + t] = lf;
;           p.IW[(size_t)tok * 8 + hd] = a[4 + e];
;         }
.LBB0_346:
	s_andn2_saveexec_b64 s[0:1], s[12:13]
	s_andn2_b64 s[10:11], s[14:15], exec
	s_and_b64 s[12:13], vcc, exec
	s_or_b64 s[14:15], s[10:11], s[12:13]
	s_mov_b64 s[10:11], exec
	s_or_b64 exec, exec, s[0:1]
	s_mov_b32 s0, 0x3e0f83e1
	v_mul_hi_i32 v37, v36, s0
	v_lshrrev_b32_e32 v38, 31, v37
	v_ashrrev_i32_e32 v37, 11, v37
	v_add_u32_e32 v40, v37, v38
	s_movk_i32 s0, 0xdf00
	v_mad_i32_i24 v38, v40, s0, v36
	v_ashrrev_i32_e32 v39, 31, v38
	v_ashrrev_i32_e32 v37, 31, v36
	v_lshl_or_b32 v48, v40, 3, v82
	s_and_saveexec_b64 s[0:1], s[14:15]
	s_xor_b64 s[0:1], exec, s[0:1]
	s_cbranch_execz .LBB0_352
	v_readlane_b32 s64, v241, 32
	v_readlane_b32 s68, v241, 36
	v_readlane_b32 s69, v241, 37
	s_nop 0
	s_nop 0
	v_lshlrev_b64 v[42:43], 5, v[36:37]
	v_lshl_add_u64 v[42:43], s[68:69], 0, v[42:43]
	v_readlane_b32 s76, v241, 8
	v_readlane_b32 s77, v241, 9
	v_readlane_b32 s78, v241, 10
	v_readlane_b32 s79, v241, 11
	v_readlane_b32 s80, v241, 12
	v_readlane_b32 s81, v241, 13
	v_readlane_b32 s82, v241, 14
	v_readlane_b32 s83, v241, 15
	s_mov_b64 s[68:69], s[76:77]
	s_mov_b64 s[72:73], s[80:81]
	v_lshl_add_u64 v[44:45], v[2:3], 2, s[72:73]
	global_load_dword v44, v[44:45], off
	s_mov_b32 s3, 0xbfb8aa3b
	s_mov_b32 s5, 0xb2a5705f
	s_mov_b32 s12, 0x42ce8ed0
	s_mov_b32 s13, 0xc2b17218
	s_mov_b32 s14, 0x3f2aaaab
	s_mov_b32 s15, 0x3f317218
	s_mov_b32 s16, 0x33800000
	v_readlane_b32 s65, v241, 33
	v_mov_b32_e32 v69, v3
	s_andn2_b64 s[10:11], s[10:11], exec
	v_lshl_add_u64 v[40:41], v[38:39], 2, s[64:65]
	v_readlane_b32 s66, v241, 34
	v_readlane_b32 s67, v241, 35
	s_mov_b64 s[70:71], s[78:79]
	s_mov_b64 s[74:75], s[82:83]
	s_waitcnt vmcnt(0)
	v_add_f32_e32 v44, v20, v44
	v_mul_f32_e64 v45, |v44|, s3
	v_fma_f32 v47, |v44|, s3, -v45
	v_rndne_f32_e32 v49, v45
	v_fma_f32 v47, |v44|, s5, v47
	v_sub_f32_e32 v45, v45, v49
	v_add_f32_e32 v45, v45, v47
	v_exp_f32_e32 v45, v45
	v_cvt_i32_f32_e32 v47, v49
	v_cmp_ngt_f32_e64 vcc, |v44|, s12
	v_min_f32_e32 v46, 0, v44
	v_ldexp_f32 v45, v45, v47
	v_cndmask_b32_e32 v45, 0, v45, vcc
	v_cmp_nlt_f32_e64 vcc, |v44|, s13
	s_nop 1
	v_cndmask_b32_e32 v47, v197, v45, vcc
	v_add_f32_e32 v49, 1.0, v47
	v_add_f32_e32 v44, -1.0, v49
	v_sub_f32_e32 v45, v44, v49
	v_add_f32_e32 v45, 1.0, v45
	v_sub_f32_e32 v44, v47, v44
	v_add_f32_e32 v50, v44, v45
	v_frexp_mant_f32_e32 v44, v49
	v_cmp_gt_f32_e32 vcc, s14, v44
	v_cvt_f64_f32_e32 v[44:45], v49
	v_frexp_exp_i32_f64_e32 v44, v[44:45]
	v_subbrev_co_u32_e32 v44, vcc, 0, v44, vcc
	v_sub_u32_e32 v45, 0, v44
	v_ldexp_f32 v49, v49, v45
	v_ldexp_f32 v45, v50, v45
	v_add_f32_e32 v50, -1.0, v49
	v_add_f32_e32 v51, 1.0, v50
	v_sub_f32_e32 v51, v49, v51
	v_add_f32_e32 v51, v45, v51
	v_add_f32_e32 v52, v50, v51
	v_sub_f32_e32 v50, v50, v52
	v_add_f32_e32 v50, v51, v50
	v_add_f32_e32 v51, 1.0, v49
	v_add_f32_e32 v53, -1.0, v51
	v_sub_f32_e32 v49, v49, v53
	v_add_f32_e32 v45, v45, v49
	v_add_f32_e32 v49, v51, v45
	v_sub_f32_e32 v51, v51, v49
	v_add_f32_e32 v45, v45, v51
	v_rcp_f32_e32 v51, v49
	v_cvt_f32_i32_e32 v44, v44
	v_cmp_neq_f32_e32 vcc, s89, v47
	v_mul_f32_e32 v53, v52, v51
	v_mul_f32_e32 v54, v49, v53
	v_fma_f32 v55, v53, v49, -v54
	v_fmac_f32_e32 v55, v53, v45
	v_add_f32_e32 v56, v54, v55
	v_sub_f32_e32 v57, v52, v56
	v_sub_f32_e32 v52, v52, v57
	v_sub_f32_e32 v54, v56, v54
	v_sub_f32_e32 v52, v52, v56
	v_add_f32_e32 v50, v50, v52
	v_sub_f32_e32 v52, v54, v55
	v_add_f32_e32 v50, v52, v50
	v_add_f32_e32 v52, v57, v50
	v_mul_f32_e32 v54, v51, v52
	v_mul_f32_e32 v55, v49, v54
	v_fma_f32 v49, v54, v49, -v55
	v_fmac_f32_e32 v49, v54, v45
	v_sub_f32_e32 v45, v57, v52
	v_add_f32_e32 v45, v50, v45
	v_add_f32_e32 v50, v55, v49
	v_sub_f32_e32 v56, v52, v50
	v_sub_f32_e32 v52, v52, v56
	v_sub_f32_e32 v55, v50, v55
	v_sub_f32_e32 v50, v52, v50
	v_add_f32_e32 v45, v45, v50
	v_sub_f32_e32 v49, v55, v49
	v_add_f32_e32 v45, v49, v45
	v_add_f32_e32 v49, v53, v54
	v_add_f32_e32 v45, v56, v45
	v_sub_f32_e32 v50, v49, v53
	v_mul_f32_e32 v45, v51, v45
	v_sub_f32_e32 v50, v54, v50
	v_add_f32_e32 v45, v50, v45
	v_mul_f32_e32 v53, 0x3f317218, v44
	v_add_f32_e32 v50, v49, v45
	v_fma_f32 v54, v44, s15, -v53
	v_mul_f32_e32 v51, v50, v50
	v_fmac_f32_e32 v54, 0xb102e308, v44
	v_sub_f32_e32 v44, v50, v49
	v_fmamk_f32 v52, v51, 0x3e9b6dac, v192
	v_sub_f32_e32 v44, v45, v44
	v_add_f32_e32 v45, v53, v54
	v_fmaak_f32 v52, v51, v52, 0x3f2aaada
	v_sub_f32_e32 v49, v45, v53
	v_ldexp_f32 v53, v50, 1
	v_mul_f32_e32 v50, v50, v51
	v_mul_f32_e32 v50, v50, v52
	v_add_f32_e32 v51, v53, v50
	v_sub_f32_e32 v52, v51, v53
	v_ldexp_f32 v44, v44, 1
	v_sub_f32_e32 v50, v50, v52
	v_add_f32_e32 v44, v44, v50
	v_add_f32_e32 v50, v51, v44
	v_sub_f32_e32 v51, v50, v51
	v_sub_f32_e32 v44, v44, v51
	v_add_f32_e32 v51, v45, v50
	v_sub_f32_e32 v52, v51, v45
	v_sub_f32_e32 v53, v51, v52
	v_sub_f32_e32 v49, v54, v49
	v_sub_f32_e32 v45, v45, v53
	v_sub_f32_e32 v50, v50, v52
	v_add_f32_e32 v45, v50, v45
	v_add_f32_e32 v50, v49, v44
	v_sub_f32_e32 v52, v50, v49
	v_sub_f32_e32 v53, v50, v52
	v_sub_f32_e32 v49, v49, v53
	v_sub_f32_e32 v44, v44, v52
	v_add_f32_e32 v45, v50, v45
	v_add_f32_e32 v44, v44, v49
	v_add_f32_e32 v49, v51, v45
	v_sub_f32_e32 v50, v49, v51
	v_sub_f32_e32 v45, v45, v50
	v_add_f32_e32 v44, v44, v45
	v_add_f32_e32 v44, v49, v44
	v_cndmask_b32_e32 v44, v197, v44, vcc
	v_cmp_lt_f32_e64 vcc, |v47|, s16
	v_mov_b32_e32 v45, v3
	s_nop 0
	v_cndmask_b32_e32 v44, v44, v47, vcc
	v_sub_f32_e32 v44, v46, v44
	v_mul_hi_i32_i24_e32 v47, 0x8400, v48
	v_mul_i32_i24_e32 v46, 0x8400, v48
	v_lshl_add_u64 v[46:47], v[40:41], 0, v[46:47]
	global_store_dword v[46:47], v44, off
	v_lshlrev_b32_e32 v44, 4, v106
	v_lshl_add_u64 v[42:43], v[42:43], 0, v[44:45]
	global_store_dword v[42:43], v24, off
	v_lshl_add_u64 v[44:45], v[68:69], 2, s[72:73]
	global_load_dword v46, v[44:45], off offset:4
	s_waitcnt vmcnt(0)
; DI void inproj_tile(const Params& p, int l, int mt, int nt, char* lds) {
;     ...
; #pragma unroll
;         for (int e = 0; e < 4; ++e) {
;           const int hd = e + 4 * h;
;           float xv = a[e] + p.b_f[l * 8 + hd];
;           float lf = fminf(xv, 0.f) - log1pf(expf(-fabsf(xv)));
;           p.LOGF[(size_t)(b * 8 + hd) * PP + t] = lf;
;           p.IW[(size_t)tok * 8 + hd] = a[4 + e];
;         }
	v_add_f32_e32 v46, v21, v46
	v_mul_f32_e64 v47, |v46|, s3
	v_fma_f32 v50, |v46|, s3, -v47
	v_rndne_f32_e32 v51, v47
	v_fma_f32 v50, |v46|, s5, v50
	v_sub_f32_e32 v47, v47, v51
	v_add_f32_e32 v47, v47, v50
	v_exp_f32_e32 v47, v47
	v_cvt_i32_f32_e32 v50, v51
	v_cmp_ngt_f32_e64 vcc, |v46|, s12
	v_min_f32_e32 v49, 0, v46
	v_ldexp_f32 v47, v47, v50
	v_cndmask_b32_e32 v47, 0, v47, vcc
	v_cmp_nlt_f32_e64 vcc, |v46|, s13
	s_nop 1
	v_cndmask_b32_e32 v50, v197, v47, vcc
	v_add_f32_e32 v51, 1.0, v50
	v_add_f32_e32 v46, -1.0, v51
	v_sub_f32_e32 v47, v46, v51
	v_add_f32_e32 v47, 1.0, v47
	v_sub_f32_e32 v46, v50, v46
	v_add_f32_e32 v52, v46, v47
	v_frexp_mant_f32_e32 v46, v51
	v_cmp_gt_f32_e32 vcc, s14, v46
	v_cvt_f64_f32_e32 v[46:47], v51
	v_frexp_exp_i32_f64_e32 v46, v[46:47]
	v_subbrev_co_u32_e32 v46, vcc, 0, v46, vcc
	v_sub_u32_e32 v47, 0, v46
	v_ldexp_f32 v51, v51, v47
	v_ldexp_f32 v47, v52, v47
	v_add_f32_e32 v52, -1.0, v51
	v_add_f32_e32 v53, 1.0, v52
	v_sub_f32_e32 v53, v51, v53
	v_add_f32_e32 v53, v47, v53
	v_add_f32_e32 v54, v52, v53
	v_sub_f32_e32 v52, v52, v54
	v_add_f32_e32 v52, v53, v52
	v_add_f32_e32 v53, 1.0, v51
	v_add_f32_e32 v55, -1.0, v53
	v_sub_f32_e32 v51, v51, v55
	v_add_f32_e32 v47, v47, v51
	v_add_f32_e32 v51, v53, v47
	v_sub_f32_e32 v53, v53, v51
	v_add_f32_e32 v47, v47, v53
	v_rcp_f32_e32 v53, v51
	v_cvt_f32_i32_e32 v46, v46
	v_cmp_neq_f32_e32 vcc, s89, v50
	v_mul_f32_e32 v55, v54, v53
	v_mul_f32_e32 v56, v51, v55
	v_fma_f32 v57, v55, v51, -v56
	v_fmac_f32_e32 v57, v55, v47
	v_add_f32_e32 v58, v56, v57
	v_sub_f32_e32 v59, v54, v58
	v_sub_f32_e32 v54, v54, v59
	v_sub_f32_e32 v56, v58, v56
	v_sub_f32_e32 v54, v54, v58
	v_add_f32_e32 v52, v52, v54
	v_sub_f32_e32 v54, v56, v57
	v_add_f32_e32 v52, v54, v52
	v_add_f32_e32 v54, v59, v52
	v_mul_f32_e32 v56, v53, v54
	v_mul_f32_e32 v57, v51, v56
	v_fma_f32 v51, v56, v51, -v57
	v_fmac_f32_e32 v51, v56, v47
	v_sub_f32_e32 v47, v59, v54
	v_add_f32_e32 v47, v52, v47
	v_add_f32_e32 v52, v57, v51
	v_sub_f32_e32 v58, v54, v52
	v_sub_f32_e32 v54, v54, v58
	v_sub_f32_e32 v57, v52, v57
	v_sub_f32_e32 v52, v54, v52
	v_add_f32_e32 v47, v47, v52
	v_sub_f32_e32 v51, v57, v51
	v_add_f32_e32 v47, v51, v47
	v_add_f32_e32 v51, v55, v56
	v_add_f32_e32 v47, v58, v47
	v_sub_f32_e32 v52, v51, v55
	v_mul_f32_e32 v47, v53, v47
	v_sub_f32_e32 v52, v56, v52
	v_add_f32_e32 v47, v52, v47
	v_mul_f32_e32 v55, 0x3f317218, v46
	v_add_f32_e32 v52, v51, v47
	v_fma_f32 v56, v46, s15, -v55
	v_mul_f32_e32 v53, v52, v52
	v_fmac_f32_e32 v56, 0xb102e308, v46
	v_sub_f32_e32 v46, v52, v51
	v_fmamk_f32 v54, v53, 0x3e9b6dac, v192
	v_sub_f32_e32 v46, v47, v46
	v_add_f32_e32 v47, v55, v56
	v_fmaak_f32 v54, v53, v54, 0x3f2aaada
	v_sub_f32_e32 v51, v47, v55
	v_ldexp_f32 v55, v52, 1
	v_mul_f32_e32 v52, v52, v53
	v_mul_f32_e32 v52, v52, v54
	v_add_f32_e32 v53, v55, v52
	v_sub_f32_e32 v54, v53, v55
	v_ldexp_f32 v46, v46, 1
	v_sub_f32_e32 v52, v52, v54
	v_add_f32_e32 v46, v46, v52
	v_add_f32_e32 v52, v53, v46
	v_sub_f32_e32 v53, v52, v53
	v_sub_f32_e32 v46, v46, v53
	v_add_f32_e32 v53, v47, v52
	v_sub_f32_e32 v54, v53, v47
	v_sub_f32_e32 v55, v53, v54
	v_sub_f32_e32 v51, v56, v51
	v_sub_f32_e32 v47, v47, v55
	v_sub_f32_e32 v52, v52, v54
	v_add_f32_e32 v47, v52, v47
	v_add_f32_e32 v52, v51, v46
	v_sub_f32_e32 v54, v52, v51
	v_sub_f32_e32 v55, v52, v54
	v_sub_f32_e32 v51, v51, v55
	v_sub_f32_e32 v46, v46, v54
	v_add_f32_e32 v47, v52, v47
	v_add_f32_e32 v46, v46, v51
	v_add_f32_e32 v51, v53, v47
	v_sub_f32_e32 v52, v51, v53
	v_sub_f32_e32 v47, v47, v52
	v_add_f32_e32 v46, v46, v47
	v_add_f32_e32 v46, v51, v46
	v_cndmask_b32_e32 v46, v197, v46, vcc
	v_cmp_lt_f32_e64 vcc, |v50|, s16
	s_nop 1
	v_cndmask_b32_e32 v46, v46, v50, vcc
	v_sub_f32_e32 v49, v49, v46
	v_or_b32_e32 v46, 1, v48
	v_mul_hi_i32_i24_e32 v47, 0x8400, v46
	v_mul_i32_i24_e32 v46, 0x8400, v46
	v_lshl_add_u64 v[46:47], v[40:41], 0, v[46:47]
	global_store_dword v[46:47], v49, off
	global_store_dword v[42:43], v25, off offset:4
	global_load_dword v46, v[44:45], off offset:8
	s_waitcnt vmcnt(0)
	v_add_f32_e32 v46, v22, v46
	v_mul_f32_e64 v47, |v46|, s3
	v_fma_f32 v50, |v46|, s3, -v47
	v_rndne_f32_e32 v51, v47
	v_fma_f32 v50, |v46|, s5, v50
	v_sub_f32_e32 v47, v47, v51
	v_add_f32_e32 v47, v47, v50
	v_exp_f32_e32 v47, v47
	v_cvt_i32_f32_e32 v50, v51
	v_cmp_ngt_f32_e64 vcc, |v46|, s12
	v_min_f32_e32 v49, 0, v46
	v_ldexp_f32 v47, v47, v50
	v_cndmask_b32_e32 v47, 0, v47, vcc
	v_cmp_nlt_f32_e64 vcc, |v46|, s13
	s_nop 1
	v_cndmask_b32_e32 v50, v197, v47, vcc
	v_add_f32_e32 v51, 1.0, v50
	v_add_f32_e32 v46, -1.0, v51
	v_sub_f32_e32 v47, v46, v51
	v_add_f32_e32 v47, 1.0, v47
	v_sub_f32_e32 v46, v50, v46
	v_add_f32_e32 v52, v46, v47
	v_frexp_mant_f32_e32 v46, v51
	v_cmp_gt_f32_e32 vcc, s14, v46
	v_cvt_f64_f32_e32 v[46:47], v51
	v_frexp_exp_i32_f64_e32 v46, v[46:47]
	v_subbrev_co_u32_e32 v46, vcc, 0, v46, vcc
	v_sub_u32_e32 v47, 0, v46
	v_ldexp_f32 v51, v51, v47
	v_ldexp_f32 v47, v52, v47
	v_add_f32_e32 v52, -1.0, v51
	v_add_f32_e32 v53, 1.0, v52
	v_sub_f32_e32 v53, v51, v53
	v_add_f32_e32 v53, v47, v53
	v_add_f32_e32 v54, v52, v53
	v_sub_f32_e32 v52, v52, v54
	v_add_f32_e32 v52, v53, v52
	v_add_f32_e32 v53, 1.0, v51
	v_add_f32_e32 v55, -1.0, v53
	v_sub_f32_e32 v51, v51, v55
	v_add_f32_e32 v47, v47, v51
	v_add_f32_e32 v51, v53, v47
	v_sub_f32_e32 v53, v53, v51
	v_add_f32_e32 v47, v47, v53
	v_rcp_f32_e32 v53, v51
	v_cvt_f32_i32_e32 v46, v46
	v_cmp_neq_f32_e32 vcc, s89, v50
	v_mul_f32_e32 v55, v54, v53
	v_mul_f32_e32 v56, v51, v55
	v_fma_f32 v57, v55, v51, -v56
	v_fmac_f32_e32 v57, v55, v47
	v_add_f32_e32 v58, v56, v57
	v_sub_f32_e32 v59, v54, v58
	v_sub_f32_e32 v54, v54, v59
; DI void inproj_tile(const Params& p, int l, int mt, int nt, char* lds) {
;     ...
; #pragma unroll
;         for (int e = 0; e < 4; ++e) {
;           const int hd = e + 4 * h;
;           float xv = a[e] + p.b_f[l * 8 + hd];
;           float lf = fminf(xv, 0.f) - log1pf(expf(-fabsf(xv)));
;           p.LOGF[(size_t)(b * 8 + hd) * PP + t] = lf;
;           p.IW[(size_t)tok * 8 + hd] = a[4 + e];
;         }
	v_sub_f32_e32 v56, v58, v56
	v_sub_f32_e32 v54, v54, v58
	v_add_f32_e32 v52, v52, v54
	v_sub_f32_e32 v54, v56, v57
	v_add_f32_e32 v52, v54, v52
	v_add_f32_e32 v54, v59, v52
	v_mul_f32_e32 v56, v53, v54
	v_mul_f32_e32 v57, v51, v56
	v_fma_f32 v51, v56, v51, -v57
	v_fmac_f32_e32 v51, v56, v47
	v_sub_f32_e32 v47, v59, v54
	v_add_f32_e32 v47, v52, v47
	v_add_f32_e32 v52, v57, v51
	v_sub_f32_e32 v58, v54, v52
	v_sub_f32_e32 v54, v54, v58
	v_sub_f32_e32 v57, v52, v57
	v_sub_f32_e32 v52, v54, v52
	v_add_f32_e32 v47, v47, v52
	v_sub_f32_e32 v51, v57, v51
	v_add_f32_e32 v47, v51, v47
	v_add_f32_e32 v51, v55, v56
	v_add_f32_e32 v47, v58, v47
	v_sub_f32_e32 v52, v51, v55
	v_mul_f32_e32 v47, v53, v47
	v_sub_f32_e32 v52, v56, v52
	v_add_f32_e32 v47, v52, v47
	v_mul_f32_e32 v55, 0x3f317218, v46
	v_add_f32_e32 v52, v51, v47
	v_fma_f32 v56, v46, s15, -v55
	v_mul_f32_e32 v53, v52, v52
	v_fmac_f32_e32 v56, 0xb102e308, v46
	v_sub_f32_e32 v46, v52, v51
	v_fmamk_f32 v54, v53, 0x3e9b6dac, v192
	v_sub_f32_e32 v46, v47, v46
	v_add_f32_e32 v47, v55, v56
	v_fmaak_f32 v54, v53, v54, 0x3f2aaada
	v_sub_f32_e32 v51, v47, v55
	v_ldexp_f32 v55, v52, 1
	v_mul_f32_e32 v52, v52, v53
	v_mul_f32_e32 v52, v52, v54
	v_add_f32_e32 v53, v55, v52
	v_sub_f32_e32 v54, v53, v55
	v_ldexp_f32 v46, v46, 1
	v_sub_f32_e32 v52, v52, v54
	v_add_f32_e32 v46, v46, v52
	v_add_f32_e32 v52, v53, v46
	v_sub_f32_e32 v53, v52, v53
	v_sub_f32_e32 v46, v46, v53
	v_add_f32_e32 v53, v47, v52
	v_sub_f32_e32 v54, v53, v47
	v_sub_f32_e32 v55, v53, v54
	v_sub_f32_e32 v51, v56, v51
	v_sub_f32_e32 v47, v47, v55
	v_sub_f32_e32 v52, v52, v54
	v_add_f32_e32 v47, v52, v47
	v_add_f32_e32 v52, v51, v46
	v_sub_f32_e32 v54, v52, v51
	v_sub_f32_e32 v55, v52, v54
	v_sub_f32_e32 v51, v51, v55
	v_sub_f32_e32 v46, v46, v54
	v_add_f32_e32 v47, v52, v47
	v_add_f32_e32 v46, v46, v51
	v_add_f32_e32 v51, v53, v47
	v_sub_f32_e32 v52, v51, v53
	v_sub_f32_e32 v47, v47, v52
	v_add_f32_e32 v46, v46, v47
	v_add_f32_e32 v46, v51, v46
	v_cndmask_b32_e32 v46, v197, v46, vcc
	v_cmp_lt_f32_e64 vcc, |v50|, s16
	s_nop 1
	v_cndmask_b32_e32 v46, v46, v50, vcc
	v_sub_f32_e32 v49, v49, v46
	v_or_b32_e32 v46, 2, v48
	v_mul_hi_i32_i24_e32 v47, 0x8400, v46
	v_mul_i32_i24_e32 v46, 0x8400, v46
	v_lshl_add_u64 v[46:47], v[40:41], 0, v[46:47]
	global_store_dword v[46:47], v49, off
	global_store_dword v[42:43], v26, off offset:8
	global_load_dword v44, v[44:45], off offset:12
	s_waitcnt vmcnt(0)
	v_add_f32_e32 v44, v23, v44
	v_mul_f32_e64 v45, |v44|, s3
	v_fma_f32 v47, |v44|, s3, -v45
	v_rndne_f32_e32 v49, v45
	v_fma_f32 v47, |v44|, s5, v47
	v_sub_f32_e32 v45, v45, v49
	v_add_f32_e32 v45, v45, v47
	v_exp_f32_e32 v45, v45
	v_cvt_i32_f32_e32 v47, v49
	v_cmp_ngt_f32_e64 vcc, |v44|, s12
	v_min_f32_e32 v46, 0, v44
	v_ldexp_f32 v45, v45, v47
	v_cndmask_b32_e32 v45, 0, v45, vcc
	v_cmp_nlt_f32_e64 vcc, |v44|, s13
	s_nop 1
	v_cndmask_b32_e32 v47, v197, v45, vcc
	v_add_f32_e32 v49, 1.0, v47
	v_add_f32_e32 v44, -1.0, v49
	v_sub_f32_e32 v45, v44, v49
	v_add_f32_e32 v45, 1.0, v45
	v_sub_f32_e32 v44, v47, v44
	v_add_f32_e32 v50, v44, v45
	v_frexp_mant_f32_e32 v44, v49
	v_cmp_gt_f32_e32 vcc, s14, v44
	v_cvt_f64_f32_e32 v[44:45], v49
	v_frexp_exp_i32_f64_e32 v44, v[44:45]
	v_subbrev_co_u32_e32 v44, vcc, 0, v44, vcc
	v_sub_u32_e32 v45, 0, v44
	v_ldexp_f32 v49, v49, v45
	v_ldexp_f32 v45, v50, v45
	v_add_f32_e32 v50, -1.0, v49
	v_add_f32_e32 v51, 1.0, v50
	v_sub_f32_e32 v51, v49, v51
	v_add_f32_e32 v51, v45, v51
	v_add_f32_e32 v52, v50, v51
	v_sub_f32_e32 v50, v50, v52
	v_add_f32_e32 v50, v51, v50
	v_add_f32_e32 v51, 1.0, v49
	v_add_f32_e32 v53, -1.0, v51
	v_sub_f32_e32 v49, v49, v53
	v_add_f32_e32 v45, v45, v49
	v_add_f32_e32 v49, v51, v45
	v_sub_f32_e32 v51, v51, v49
	v_add_f32_e32 v45, v45, v51
	v_rcp_f32_e32 v51, v49
	v_cvt_f32_i32_e32 v44, v44
	v_cmp_neq_f32_e32 vcc, s89, v47
	v_mul_f32_e32 v53, v52, v51
	v_mul_f32_e32 v54, v49, v53
	v_fma_f32 v55, v53, v49, -v54
	v_fmac_f32_e32 v55, v53, v45
	v_add_f32_e32 v56, v54, v55
	v_sub_f32_e32 v57, v52, v56
	v_sub_f32_e32 v52, v52, v57
	v_sub_f32_e32 v54, v56, v54
	v_sub_f32_e32 v52, v52, v56
	v_add_f32_e32 v50, v50, v52
	v_sub_f32_e32 v52, v54, v55
	v_add_f32_e32 v50, v52, v50
	v_add_f32_e32 v52, v57, v50
	v_mul_f32_e32 v54, v51, v52
	v_mul_f32_e32 v55, v49, v54
	v_fma_f32 v49, v54, v49, -v55
	v_fmac_f32_e32 v49, v54, v45
	v_sub_f32_e32 v45, v57, v52
	v_add_f32_e32 v45, v50, v45
	v_add_f32_e32 v50, v55, v49
	v_sub_f32_e32 v56, v52, v50
	v_sub_f32_e32 v52, v52, v56
	v_sub_f32_e32 v55, v50, v55
	v_sub_f32_e32 v50, v52, v50
	v_add_f32_e32 v45, v45, v50
	v_sub_f32_e32 v49, v55, v49
	v_add_f32_e32 v45, v49, v45
	v_add_f32_e32 v49, v53, v54
	v_add_f32_e32 v45, v56, v45
	v_sub_f32_e32 v50, v49, v53
	v_mul_f32_e32 v45, v51, v45
	v_sub_f32_e32 v50, v54, v50
	v_add_f32_e32 v45, v50, v45
	v_mul_f32_e32 v53, 0x3f317218, v44
	v_add_f32_e32 v50, v49, v45
	v_fma_f32 v54, v44, s15, -v53
	v_mul_f32_e32 v51, v50, v50
	v_fmac_f32_e32 v54, 0xb102e308, v44
	v_sub_f32_e32 v44, v50, v49
	v_fmamk_f32 v52, v51, 0x3e9b6dac, v192
	v_sub_f32_e32 v44, v45, v44
	v_add_f32_e32 v45, v53, v54
	v_fmaak_f32 v52, v51, v52, 0x3f2aaada
	v_sub_f32_e32 v49, v45, v53
	v_ldexp_f32 v53, v50, 1
	v_mul_f32_e32 v50, v50, v51
	v_mul_f32_e32 v50, v50, v52
	v_add_f32_e32 v51, v53, v50
	v_sub_f32_e32 v52, v51, v53
	v_ldexp_f32 v44, v44, 1
	v_sub_f32_e32 v50, v50, v52
	v_add_f32_e32 v44, v44, v50
	v_add_f32_e32 v50, v51, v44
	v_sub_f32_e32 v51, v50, v51
	v_sub_f32_e32 v44, v44, v51
	v_add_f32_e32 v51, v45, v50
	v_sub_f32_e32 v52, v51, v45
	v_sub_f32_e32 v53, v51, v52
	v_sub_f32_e32 v49, v54, v49
	v_sub_f32_e32 v45, v45, v53
	v_sub_f32_e32 v50, v50, v52
	v_add_f32_e32 v45, v50, v45
	v_add_f32_e32 v50, v49, v44
	v_sub_f32_e32 v52, v50, v49
	v_sub_f32_e32 v53, v50, v52
	v_sub_f32_e32 v49, v49, v53
	v_sub_f32_e32 v44, v44, v52
	v_add_f32_e32 v45, v50, v45
	v_add_f32_e32 v44, v44, v49
	v_add_f32_e32 v49, v51, v45
	v_sub_f32_e32 v50, v49, v51
	v_sub_f32_e32 v45, v45, v50
	v_add_f32_e32 v44, v44, v45
	v_add_f32_e32 v44, v49, v44
	v_cndmask_b32_e32 v44, v197, v44, vcc
	v_cmp_lt_f32_e64 vcc, |v47|, s16
	v_or_b32_e32 v45, 3, v48
	s_nop 0
	v_cndmask_b32_e32 v44, v44, v47, vcc
	v_sub_f32_e32 v44, v46, v44
	v_mul_hi_i32_i24_e32 v47, 0x8400, v45
	v_mul_i32_i24_e32 v46, 0x8400, v45
	v_lshl_add_u64 v[40:41], v[40:41], 0, v[46:47]
	global_store_dword v[40:41], v44, off
	global_store_dword v[42:43], v27, off offset:12
	s_or_b64 exec, exec, s[0:1]
	s_and_saveexec_b64 s[0:1], s[10:11]
	s_cbranch_execnz .LBB0_353

; DI unsigned pk2(float a, float b) { f32x2 v = {a, b}; return __builtin_bit_cast(unsigned, __builtin_convertvector(v, bf2_t)); }
; DI void store_rope(u16* dst, const f32x16& a, int h, float sc, const float* rp) {
; #pragma unroll
;   for (int g = 0; g < 2; ++g) {
;     f32x4 cs = *(const f32x4*)(rp + 8 * g + 4 * h);
;     f32x4 sn = *(const f32x4*)(rp + 16 + 8 * g + 4 * h);
;     float o1[4], o2[4];
; #pragma unroll
;     for (int e = 0; e < 4; ++e) {
;       float x1 = a[4 * g + e] * sc, x2 = a[8 + 4 * g + e] * sc;
;       o1[e] = x1 * cs[e] - x2 * sn[e];
;       o2[e] = x1 * sn[e] + x2 * cs[e];
;     }
;     u32x2 v1 = {pk2(o1[0], o1[1]), pk2(o1[2], o1[3])};
;     u32x2 v2 = {pk2(o2[0], o2[1]), pk2(o2[2], o2[3])};
;     *(u32x2*)(dst + 8 * g + 4 * h) = v1;
;     *(u32x2*)(dst + 16 + 8 * g + 4 * h) = v2;
;   }
.LBB0_353:
	v_readlane_b32 s64, v241, 32
	v_lshlrev_b64 v[42:43], 7, v[38:39]
	v_readlane_b32 s70, v241, 38
	v_readlane_b32 s71, v241, 39
	v_lshlrev_b64 v[40:41], 6, v[36:37]
	v_readlane_b32 s72, v240, 9
	v_readlane_b32 s73, v240, 10
	v_lshl_add_u64 v[42:43], s[70:71], 0, v[42:43]
	v_lshlrev_b32_e32 v44, 4, v106
	v_mov_b32_e32 v45, v3
	v_lshl_add_u64 v[40:41], s[72:73], 0, v[40:41]
	v_lshl_add_u64 v[50:51], v[42:43], 0, v[44:45]
	v_lshlrev_b32_e32 v42, 3, v106
	v_mov_b32_e32 v43, v3
	v_lshl_add_u64 v[52:53], v[40:41], 0, v[42:43]
	global_load_dwordx4 v[40:43], v[50:51], off
	global_load_dwordx4 v[44:47], v[50:51], off offset:64
	v_readlane_b32 s65, v241, 33
	v_readlane_b32 s66, v241, 34
	v_readlane_b32 s67, v241, 35
	s_waitcnt vmcnt(0)
	v_pk_mul_f32 v[54:55], v[28:29], v[44:45]
	s_nop 0
	v_pk_fma_f32 v[54:55], v[20:21], v[40:41], v[54:55] neg_lo:[0,0,1] neg_hi:[0,0,1]
	v_pk_mul_f32 v[20:21], v[20:21], v[44:45]
	s_nop 0
	v_pk_fma_f32 v[20:21], v[28:29], v[40:41], v[20:21]
	v_pk_mul_f32 v[28:29], v[30:31], v[46:47]
	v_cvt_pk_bf16_f32 v20, v20, v21
	v_pk_fma_f32 v[28:29], v[22:23], v[42:43], v[28:29] neg_lo:[0,0,1] neg_hi:[0,0,1]
	v_pk_mul_f32 v[22:23], v[22:23], v[46:47]
	s_nop 0
	v_pk_fma_f32 v[22:23], v[30:31], v[42:43], v[22:23]
	v_cvt_pk_bf16_f32 v30, v54, v55
	v_cvt_pk_bf16_f32 v31, v28, v29
	v_cvt_pk_bf16_f32 v21, v22, v23
	global_store_dwordx2 v[52:53], v[30:31], off
	global_store_dwordx2 v[52:53], v[20:21], off offset:32
	global_load_dwordx4 v[20:23], v[50:51], off offset:32
	s_nop 0
	global_load_dwordx4 v[28:31], v[50:51], off offset:96
	s_waitcnt vmcnt(0)
	v_pk_mul_f32 v[40:41], v[32:33], v[28:29]
	s_nop 0
	v_pk_fma_f32 v[40:41], v[24:25], v[20:21], v[40:41] neg_lo:[0,0,1] neg_hi:[0,0,1]
	v_pk_mul_f32 v[24:25], v[24:25], v[28:29]
	s_nop 0
	v_pk_fma_f32 v[20:21], v[32:33], v[20:21], v[24:25]
	v_pk_mul_f32 v[24:25], v[34:35], v[30:31]
	v_cvt_pk_bf16_f32 v20, v20, v21
	v_pk_fma_f32 v[24:25], v[26:27], v[22:23], v[24:25] neg_lo:[0,0,1] neg_hi:[0,0,1]
	v_pk_mul_f32 v[26:27], v[26:27], v[30:31]
	s_nop 0
	v_pk_fma_f32 v[22:23], v[34:35], v[22:23], v[26:27]
	v_cvt_pk_bf16_f32 v26, v40, v41
	v_cvt_pk_bf16_f32 v27, v24, v25
	v_cvt_pk_bf16_f32 v21, v22, v23
	global_store_dwordx2 v[52:53], v[26:27], off offset:16
	global_store_dwordx2 v[52:53], v[20:21], off offset:48
	s_or_b64 exec, exec, s[0:1]
	s_and_saveexec_b64 s[0:1], s[40:41]
	s_xor_b64 s[0:1], exec, s[0:1]
	s_cbranch_execnz .LBB0_351

; DI unsigned pk2(float a, float b) { f32x2 v = {a, b}; return __builtin_bit_cast(unsigned, __builtin_convertvector(v, bf2_t)); }
; DI void store_rowmajor(u16* dst, const f32x16& a, int h, float sc) {
; #pragma unroll
;   for (int kp = 0; kp < 2; ++kp) {
;     const int g = 2 * kp;
;     unsigned ax = pk2(a[4 * g] * sc, a[4 * g + 1] * sc), ay = pk2(a[4 * g + 2] * sc, a[4 * g + 3] * sc);
;     unsigned bx = pk2(a[4 * g + 4] * sc, a[4 * g + 5] * sc), by = pk2(a[4 * g + 6] * sc, a[4 * g + 7] * sc);
;     const u32x2 rx = __builtin_amdgcn_permlane32_swap(ax, bx, false, false);
;     const u32x2 ry = __builtin_amdgcn_permlane32_swap(ay, by, false, false);
;     const u32x4 v = {rx[0], ry[0], rx[1], ry[1]};
;     *(u32x4*)(dst + 8 * (g + h)) = v;
;   }
; }
.LBB0_355:
	v_readlane_b32 s64, v240, 1
	v_lshlrev_b64 v[20:21], 7, v[36:37]
	v_readlane_b32 s74, v240, 11
	v_readlane_b32 s75, v240, 12
	v_cvt_pk_bf16_f32 v4, v4, v5
	v_cvt_pk_bf16_f32 v5, v6, v7
	v_lshl_add_u64 v[20:21], s[74:75], 0, v[20:21]
	v_cvt_pk_bf16_f32 v6, v8, v9
	v_cvt_pk_bf16_f32 v7, v10, v11
	v_lshlrev_b32_e32 v2, 4, v106
	v_permlane32_swap_b32_e32 v4, v6
	v_permlane32_swap_b32_e32 v5, v7
	v_lshl_add_u64 v[8:9], v[20:21], 0, v[2:3]
	global_store_dwordx4 v[8:9], v[4:7], off
	v_readlane_b32 s65, v240, 2
	v_readlane_b32 s66, v240, 3
	v_cvt_pk_bf16_f32 v4, v12, v13
	v_cvt_pk_bf16_f32 v5, v14, v15
	v_cvt_pk_bf16_f32 v6, v16, v17
	v_cvt_pk_bf16_f32 v7, v18, v19
	s_nop 0
	v_permlane32_swap_b32_e32 v4, v6
	v_permlane32_swap_b32_e32 v5, v7
	v_readlane_b32 s67, v240, 4
	global_store_dwordx4 v[8:9], v[4:7], off offset:32

; DI int opaque_tid() { int t = threadIdx.x; asm volatile("" : "+v"(t)); return t; }
; DI void topk_job(const Params& p, int b, int t0, char* lds) {
;   const int tid = opaque_tid(), lane = tid & 63, w = tid >> 6, r = lane & 31, h = lane >> 5;
;   const int cmax = (t0 + 3) >> 6;
;   unsigned sc[17][4];
;   {
;     const u16* iqp = p.H + (size_t)(b * PP + t0 + (r >> 3)) * LDH + HIQ_C + (r & 7) * 64 + 8 * h;
;     bf16x8 af[4];
; #pragma unroll
;     for (int ks = 0; ks < 4; ++ks) af[ks] = *(const bf16x8*)(iqp + ks * 16);
;     f32x4 iw[4];
; #pragma unroll
;     for (int qi = 0; qi < 4; ++qi) iw[qi] = *(const f32x4*)(p.IW + (size_t)(b * PP + t0 + qi) * 8 + 4 * h);
;     char* wb = lds + 16384 + w * 9216;
;     const int lrow = lane >> 3, lpc = lane & 7;
;     const u16* ikb = p.IK + ((size_t)(b * PP) + lrow) * 64 + lpc * 8;
;     u32x4 st[8];
;     if (1 + w <= cmax) {
;       const u16* kp = ikb + (size_t)(1 + w) * 64 * 64;
; #pragma unroll
;       for (int j = 0; j < 8; ++j) st[j] = *(const u32x4*)(kp + (size_t)j * 8 * 64);
; #pragma unroll
;       for (int j = 0; j < 8; ++j) *(u32x4*)(wb + (lrow + 8 * j) * 144 + lpc * 16) = st[j];
;     }
.LBB0_649:
	s_and_b64 vcc, exec, s[0:1]
	s_cbranch_vccz .LBB0_778
	v_mov_b32_e32 v100, v152
	v_and_b32_e32 v101, 63, v100
	v_lshrrev_b32_e32 v0, 6, v100
	s_lshl_b32 s0, s87, 1
	s_and_b32 s0, s0, 0x3ffc
	s_sub_i32 s4, 0x209c, s0
	s_bitcmp1_b32 s87, 0
	s_cselect_b32 s5, 0x2100, 0
	s_add_i32 s6, s4, s5
	s_add_i32 s90, s4, 3
	s_lshr_b32 s90, s90, 6
	s_mov_b32 s3, s90
	v_readfirstlane_b32 s2, v0
	s_add_i32 s44, s4, 0
	s_add_i32 s45, s4, 1
	s_add_i32 s46, s4, 2
	s_add_i32 s47, s4, 3
	s_brev_b32 s31, 1
	s_movk_i32 s30, 0x70
	s_add_i32 s0, s2, 9
	s_cmp_ge_u32 s90, s0
	s_cselect_b64 s[0:1], -1, 0
	s_nop 3
	v_writelane_b32 v238, s0, 62
	v_writelane_b32 v238, s1, 63
	v_writelane_b32 v237, s36, 2
	s_add_i32 s28, s2, 1
	s_cmp_gt_u32 s28, s3
	s_cbranch_scc1 .Lsc_z0
	v_readlane_b32 s8, v240, 11
	v_readlane_b32 s9, v240, 12
	v_readlane_b32 s12, v241, 24
	v_readlane_b32 s13, v241, 25
	v_readlane_b32 s14, v241, 36
	v_readlane_b32 s15, v241, 37
	s_lshl_b32 s0, s5, 7
	s_lshl_b32 s1, s28, 13
	s_add_u32 s0, s0, s1
	s_add_u32 s10, s8, s0
	s_addc_u32 s11, s9, 0
	s_lshl_b32 s0, s6, 5
	s_add_u32 s16, s14, s0
	s_addc_u32 s17, s15, 0
	s_lshl_b32 s0, s2, 14
	s_add_i32 s40, s0, 0x4000
	s_add_i32 s41, s40, 0x1000
	s_add_i32 s42, s40, 0x2000
	s_add_i32 s43, s40, 0x3000
	v_bfe_u32 v0, v101, 3, 2
	v_add_u32_e32 v0, s6, v0
	v_mul_u32_u24_e32 v0, 0x2a00, v0
	v_and_b32_e32 v1, 7, v101
	v_lshlrev_b32_e32 v1, 7, v1
	v_lshrrev_b32_e32 v2, 5, v101
	v_lshlrev_b32_e32 v2, 4, v2
	v_add3_u32 v0, v0, v1, v2
	v_add_u32_e32 v0, 0x1900, v0
	global_load_dwordx4 v[84:87], v0, s[12:13]
	global_load_dwordx4 v[88:91], v0, s[12:13] offset:32
	global_load_dwordx4 v[92:95], v0, s[12:13] offset:64
	global_load_dwordx4 v[96:99], v0, s[12:13] offset:96
	global_load_dwordx4 v[212:215], v2, s[16:17]
	global_load_dwordx4 v[216:219], v2, s[16:17] offset:32
	global_load_dwordx4 v[220:223], v2, s[16:17] offset:64
	global_load_dwordx4 v[224:227], v2, s[16:17] offset:96
	v_lshrrev_b32_e32 v1, 4, v101
	v_and_b32_e32 v4, 7, v101
	v_xor_b32_e32 v1, v1, v4
	v_lshlrev_b32_e32 v1, 4, v1
	v_lshrrev_b32_e32 v4, 3, v101
	v_lshlrev_b32_e32 v4, 7, v4
	v_add_u32_e32 v102, v1, v4
	v_xor_b32_e32 v104, 64, v102
	v_add_u32_e32 v106, 0x1000, v102
	v_add_u32_e32 v108, 0x1000, v104
	s_mov_b32 m0, s40
	s_nop 0
	global_load_lds_dwordx4 v102, s[10:11]
	global_load_lds_dwordx4 v104, s[10:11] offset:1024
	global_load_lds_dwordx4 v102, s[10:11] offset:2048
	global_load_lds_dwordx4 v104, s[10:11] offset:3072
	s_mov_b32 m0, s41
	s_nop 0
	global_load_lds_dwordx4 v106, s[10:11]
	global_load_lds_dwordx4 v108, s[10:11] offset:1024
	global_load_lds_dwordx4 v106, s[10:11] offset:2048
	global_load_lds_dwordx4 v108, s[10:11] offset:3072
	s_add_u32 s10, s10, 0x10000
	s_addc_u32 s11, s11, 0
	s_add_i32 s29, s28, 8
	s_cmp_gt_u32 s29, s3
	s_cbranch_scc1 .Lsc_pro
	s_mov_b32 m0, s42
	s_nop 0
	global_load_lds_dwordx4 v102, s[10:11]
	global_load_lds_dwordx4 v104, s[10:11] offset:1024
	global_load_lds_dwordx4 v102, s[10:11] offset:2048
	global_load_lds_dwordx4 v104, s[10:11] offset:3072
	s_mov_b32 m0, s43
	s_nop 0
	global_load_lds_dwordx4 v106, s[10:11]
	global_load_lds_dwordx4 v108, s[10:11] offset:1024
	global_load_lds_dwordx4 v106, s[10:11] offset:2048
	global_load_lds_dwordx4 v108, s[10:11] offset:3072
	s_add_u32 s10, s10, 0x10000
	s_addc_u32 s11, s11, 0
.Lsc_pro:
	v_and_b32_e32 v1, 31, v101
	v_lshrrev_b32_e32 v4, 1, v1
	v_and_b32_e32 v4, 7, v4
	v_lshrrev_b32_e32 v5, 5, v101
	v_xor_b32_e32 v4, v4, v5
	v_lshlrev_b32_e32 v1, 7, v1
	v_add_u32_e32 v1, s40, v1
	v_lshl_add_u32 v110, v4, 4, v1
	v_xor_b32_e32 v5, 2, v4
	v_lshl_add_u32 v112, v5, 4, v1
	v_xor_b32_e32 v5, 4, v4
	v_lshl_add_u32 v114, v5, 4, v1
	v_xor_b32_e32 v5, 6, v4
	v_lshl_add_u32 v116, v5, 4, v1
	s_add_i32 s29, s28, 8
	s_cmp_gt_u32 s29, s3
	s_cbranch_scc1 .Lsc_w0
	s_waitcnt vmcnt(8)
	s_branch .Lsc_r0

; #define MFMA32(a, b, c) __builtin_amdgcn_mfma_f32_32x32x16_bf16((a), (b), (c), 0, 0, 0)
; DI void topk_job(const Params& p, int b, int t0, char* lds) {
;     ...
;     for (int i = 0; i < 17; ++i) {
;       const int c = 1 + w + 8 * i;
;       if (c <= cmax) {
;         const bool more = c + 8 <= cmax;
;         if (more) {
;           const u16* kp = ikb + (size_t)(c + 8) * 64 * 64;
; #pragma unroll
;           for (int j = 0; j < 8; ++j) st[j] = *(const u32x4*)(kp + (size_t)j * 8 * 64);
;         }
;         bf16x8 b0[4], b1[4];
; #pragma unroll
;         for (int ks = 0; ks < 4; ++ks) {
;           b0[ks] = *(const bf16x8*)(wb + r * 144 + ks * 32 + h * 16);
;           b1[ks] = *(const bf16x8*)(wb + (32 + r) * 144 + ks * 32 + h * 16);
;         }
;         __builtin_amdgcn_sched_barrier(0);
;         f32x16 a0, a1;
; #pragma unroll
;         for (int e = 0; e < 16; ++e) { a0[e] = 0.f; a1[e] = 0.f; }
; #pragma unroll
;         for (int ks = 0; ks < 4; ++ks) { a0 = MFMA32(af[ks], b0[ks], a0); a1 = MFMA32(af[ks], b1[ks], a1); }
;         const int key = c * 64 + lane;
; #pragma unroll
;         for (int qi = 0; qi < 4; ++qi) {
;           f32x2 pp2 = {0.f, 0.f};
; #pragma unroll
;           for (int e = 0; e < 4; ++e) {
;             const f32x2 rl = {fmaxf(a0[4 * qi + e], 0.f), fmaxf(a1[4 * qi + e], 0.f)};
;             const f32x2 wv = {iw[qi][e], iw[qi][e]};
;             pp2 += rl * wv;
;           }
;           const float p0 = pp2[0], p1 = pp2[1];
;           const u32x2 sw = __builtin_amdgcn_permlane32_swap(__float_as_uint(p0), __float_as_uint(p1), false, false);
;           float mine = __uint_as_float(sw[0]) + __uint_as_float(sw[1]);
;           mine += 0.0f;
;           unsigned u = __float_as_uint(mine);
;           u = (u & 0x80000000u) ? ~u : (u | 0x80000000u);
;           if (key > t0 + qi || key < LEAD) u = 0u;
;           sc[i][qi] = u;
;         }
.Lsc_r0:
	ds_read_b128 v[20:23], v110
	ds_read_b128 v[24:27], v110 offset:4096
	ds_read_b128 v[28:31], v112
	ds_read_b128 v[32:35], v112 offset:4096
	ds_read_b128 v[36:39], v114
	ds_read_b128 v[40:43], v114 offset:4096
	ds_read_b128 v[44:47], v116
	ds_read_b128 v[48:51], v116 offset:4096
	s_waitcnt lgkmcnt(7)
	v_mfma_f32_32x32x16_bf16 v[52:67], v[84:87], v[20:23], 0
	s_waitcnt lgkmcnt(6)
	v_mfma_f32_32x32x16_bf16 v[68:83], v[84:87], v[24:27], 0
	s_waitcnt lgkmcnt(5)
	v_mfma_f32_32x32x16_bf16 v[52:67], v[88:91], v[28:31], v[52:67]
	s_waitcnt lgkmcnt(4)
	v_mfma_f32_32x32x16_bf16 v[68:83], v[88:91], v[32:35], v[68:83]
	s_waitcnt lgkmcnt(3)
	v_mfma_f32_32x32x16_bf16 v[52:67], v[92:95], v[36:39], v[52:67]
	s_waitcnt lgkmcnt(2)
	v_mfma_f32_32x32x16_bf16 v[68:83], v[92:95], v[40:43], v[68:83]
	s_waitcnt lgkmcnt(1)
	v_mfma_f32_32x32x16_bf16 v[52:67], v[96:99], v[44:47], v[52:67]
	s_waitcnt lgkmcnt(0)
	v_mfma_f32_32x32x16_bf16 v[68:83], v[96:99], v[48:51], v[68:83]
	s_add_i32 s29, s28, 16
	s_cmp_gt_u32 s29, s3
	s_cbranch_scc1 .Lsc_e0
	s_mov_b32 m0, s40
	s_nop 0
	global_load_lds_dwordx4 v102, s[10:11]
	global_load_lds_dwordx4 v104, s[10:11] offset:1024
	global_load_lds_dwordx4 v102, s[10:11] offset:2048
	global_load_lds_dwordx4 v104, s[10:11] offset:3072
	s_mov_b32 m0, s41
	s_nop 0
	global_load_lds_dwordx4 v106, s[10:11]
	global_load_lds_dwordx4 v108, s[10:11] offset:1024
	global_load_lds_dwordx4 v106, s[10:11] offset:2048
	global_load_lds_dwordx4 v108, s[10:11] offset:3072
	s_add_u32 s10, s10, 0x10000
	s_addc_u32 s11, s11, 0
.Lsc_e0:
	s_nop 7
	s_nop 3
	v_max_f32_e32 v4, 0, v52
	v_max_f32_e32 v5, 0, v68
	v_max_f32_e32 v6, 0, v56
	v_max_f32_e32 v7, 0, v72
	v_max_f32_e32 v8, 0, v60
	v_max_f32_e32 v9, 0, v76
	v_max_f32_e32 v10, 0, v64
	v_max_f32_e32 v11, 0, v80
	v_pk_fma_f32 v[12:13], v[212:213], v[4:5], 0 op_sel_hi:[0,1,0]
	v_pk_fma_f32 v[14:15], v[216:217], v[6:7], 0 op_sel_hi:[0,1,0]
	v_pk_fma_f32 v[228:229], v[220:221], v[8:9], 0 op_sel_hi:[0,1,0]
	v_pk_fma_f32 v[230:231], v[224:225], v[10:11], 0 op_sel_hi:[0,1,0]
	v_max_f32_e32 v4, 0, v53
	v_max_f32_e32 v5, 0, v69
	v_max_f32_e32 v6, 0, v57
	v_max_f32_e32 v7, 0, v73
	v_max_f32_e32 v8, 0, v61
	v_max_f32_e32 v9, 0, v77
	v_max_f32_e32 v10, 0, v65
	v_max_f32_e32 v11, 0, v81
	v_pk_fma_f32 v[12:13], v[212:213], v[4:5], v[12:13] op_sel:[1,0,0]
	v_pk_fma_f32 v[14:15], v[216:217], v[6:7], v[14:15] op_sel:[1,0,0]
	v_pk_fma_f32 v[228:229], v[220:221], v[8:9], v[228:229] op_sel:[1,0,0]
	v_pk_fma_f32 v[230:231], v[224:225], v[10:11], v[230:231] op_sel:[1,0,0]
	v_max_f32_e32 v4, 0, v54
	v_max_f32_e32 v5, 0, v70
	v_max_f32_e32 v6, 0, v58
	v_max_f32_e32 v7, 0, v74
	v_max_f32_e32 v8, 0, v62
	v_max_f32_e32 v9, 0, v78
	v_max_f32_e32 v10, 0, v66
	v_max_f32_e32 v11, 0, v82
	v_pk_fma_f32 v[12:13], v[214:215], v[4:5], v[12:13] op_sel_hi:[0,1,1]
	v_pk_fma_f32 v[14:15], v[218:219], v[6:7], v[14:15] op_sel_hi:[0,1,1]
	v_pk_fma_f32 v[228:229], v[222:223], v[8:9], v[228:229] op_sel_hi:[0,1,1]
	v_pk_fma_f32 v[230:231], v[226:227], v[10:11], v[230:231] op_sel_hi:[0,1,1]
	v_max_f32_e32 v4, 0, v55
	v_max_f32_e32 v5, 0, v71
	v_max_f32_e32 v6, 0, v59
	v_max_f32_e32 v7, 0, v75
	v_max_f32_e32 v8, 0, v63
	v_max_f32_e32 v9, 0, v79
	v_max_f32_e32 v10, 0, v67
	v_max_f32_e32 v11, 0, v83
	v_pk_fma_f32 v[12:13], v[214:215], v[4:5], v[12:13] op_sel:[1,0,0]
	v_pk_fma_f32 v[14:15], v[218:219], v[6:7], v[14:15] op_sel:[1,0,0]
	v_pk_fma_f32 v[228:229], v[222:223], v[8:9], v[228:229] op_sel:[1,0,0]
	v_pk_fma_f32 v[230:231], v[226:227], v[10:11], v[230:231] op_sel:[1,0,0]
	s_nop 1
	v_permlane32_swap_b32_e32 v12, v13
	v_permlane32_swap_b32_e32 v14, v15
	v_permlane32_swap_b32_e32 v228, v229
	v_permlane32_swap_b32_e32 v230, v231
	v_add_f32_e32 v4, v12, v13
	v_add_f32_e32 v6, v14, v15
	v_add_f32_e32 v8, v228, v229
	v_add_f32_e32 v10, v230, v231
	v_ashrrev_i32_e32 v5, 31, v4
	v_ashrrev_i32_e32 v7, 31, v6
	v_ashrrev_i32_e32 v9, 31, v8
	v_ashrrev_i32_e32 v11, 31, v10
	v_or_b32_e32 v5, s31, v5
	v_or_b32_e32 v7, s31, v7
	v_or_b32_e32 v9, s31, v9
	v_or_b32_e32 v11, s31, v11
	v_xor_b32_e32 v208, v4, v5
	v_xor_b32_e32 v175, v6, v7
	v_xor_b32_e32 v161, v8, v9
	v_xor_b32_e32 v138, v10, v11
	v_lshl_add_u32 v118, s28, 6, v101
	v_cmp_gt_i32_e64 s[0:1], s30, v118
	v_cmp_lt_i32_e32 vcc, s44, v118
	s_or_b64 vcc, vcc, s[0:1]
	s_nop 0
	v_cndmask_b32_e64 v208, v208, 0, vcc
	v_cmp_lt_i32_e32 vcc, s45, v118
	s_or_b64 vcc, vcc, s[0:1]
	s_nop 0
	v_cndmask_b32_e64 v175, v175, 0, vcc
	v_cmp_lt_i32_e32 vcc, s46, v118
	s_or_b64 vcc, vcc, s[0:1]
	s_nop 0
	v_cndmask_b32_e64 v161, v161, 0, vcc
	v_cmp_lt_i32_e32 vcc, s47, v118
	s_or_b64 vcc, vcc, s[0:1]
	s_nop 0
	v_cndmask_b32_e64 v138, v138, 0, vcc
	s_add_i32 s28, s28, 8
	s_cmp_gt_u32 s28, s3
	s_cbranch_scc1 .Lsc_z1
	s_add_i32 s29, s28, 8
	s_cmp_gt_u32 s29, s3
	s_cbranch_scc1 .Lsc_w1
	s_waitcnt vmcnt(8)
	s_branch .Lsc_r1

; #define MFMA32(a, b, c) __builtin_amdgcn_mfma_f32_32x32x16_bf16((a), (b), (c), 0, 0, 0)
; DI void topk_job(const Params& p, int b, int t0, char* lds) {
;     ...
;     for (int i = 0; i < 17; ++i) {
;       const int c = 1 + w + 8 * i;
;       if (c <= cmax) {
;         const bool more = c + 8 <= cmax;
;         if (more) {
;           const u16* kp = ikb + (size_t)(c + 8) * 64 * 64;
; #pragma unroll
;           for (int j = 0; j < 8; ++j) st[j] = *(const u32x4*)(kp + (size_t)j * 8 * 64);
;         }
;         bf16x8 b0[4], b1[4];
; #pragma unroll
;         for (int ks = 0; ks < 4; ++ks) {
;           b0[ks] = *(const bf16x8*)(wb + r * 144 + ks * 32 + h * 16);
;           b1[ks] = *(const bf16x8*)(wb + (32 + r) * 144 + ks * 32 + h * 16);
;         }
;         __builtin_amdgcn_sched_barrier(0);
;         f32x16 a0, a1;
; #pragma unroll
;         for (int e = 0; e < 16; ++e) { a0[e] = 0.f; a1[e] = 0.f; }
; #pragma unroll
;         for (int ks = 0; ks < 4; ++ks) { a0 = MFMA32(af[ks], b0[ks], a0); a1 = MFMA32(af[ks], b1[ks], a1); }
;         const int key = c * 64 + lane;
; #pragma unroll
;         for (int qi = 0; qi < 4; ++qi) {
;           f32x2 pp2 = {0.f, 0.f};
; #pragma unroll
;           for (int e = 0; e < 4; ++e) {
;             const f32x2 rl = {fmaxf(a0[4 * qi + e], 0.f), fmaxf(a1[4 * qi + e], 0.f)};
;             const f32x2 wv = {iw[qi][e], iw[qi][e]};
;             pp2 += rl * wv;
;           }
;           const float p0 = pp2[0], p1 = pp2[1];
;           const u32x2 sw = __builtin_amdgcn_permlane32_swap(__float_as_uint(p0), __float_as_uint(p1), false, false);
;           float mine = __uint_as_float(sw[0]) + __uint_as_float(sw[1]);
;           mine += 0.0f;
;           unsigned u = __float_as_uint(mine);
;           u = (u & 0x80000000u) ? ~u : (u | 0x80000000u);
;           if (key > t0 + qi || key < LEAD) u = 0u;
;           sc[i][qi] = u;
;         }
;         if (more) {
; #pragma unroll
;           for (int j = 0; j < 8; ++j) *(u32x4*)(wb + (lrow + 8 * j) * 144 + lpc * 16) = st[j];
;         }
.Lsc_r1:
	ds_read_b128 v[20:23], v110 offset:8192
	ds_read_b128 v[24:27], v110 offset:12288
	ds_read_b128 v[28:31], v112 offset:8192
	ds_read_b128 v[32:35], v112 offset:12288
	ds_read_b128 v[36:39], v114 offset:8192
	ds_read_b128 v[40:43], v114 offset:12288
	ds_read_b128 v[44:47], v116 offset:8192
	ds_read_b128 v[48:51], v116 offset:12288
	s_waitcnt lgkmcnt(7)
	v_mfma_f32_32x32x16_bf16 v[52:67], v[84:87], v[20:23], 0
	s_waitcnt lgkmcnt(6)
	v_mfma_f32_32x32x16_bf16 v[68:83], v[84:87], v[24:27], 0
	s_waitcnt lgkmcnt(5)
	v_mfma_f32_32x32x16_bf16 v[52:67], v[88:91], v[28:31], v[52:67]
	s_waitcnt lgkmcnt(4)
	v_mfma_f32_32x32x16_bf16 v[68:83], v[88:91], v[32:35], v[68:83]
	s_waitcnt lgkmcnt(3)
	v_mfma_f32_32x32x16_bf16 v[52:67], v[92:95], v[36:39], v[52:67]
	s_waitcnt lgkmcnt(2)
	v_mfma_f32_32x32x16_bf16 v[68:83], v[92:95], v[40:43], v[68:83]
	s_waitcnt lgkmcnt(1)
	v_mfma_f32_32x32x16_bf16 v[52:67], v[96:99], v[44:47], v[52:67]
	s_waitcnt lgkmcnt(0)
	v_mfma_f32_32x32x16_bf16 v[68:83], v[96:99], v[48:51], v[68:83]
	s_add_i32 s29, s28, 16
	s_cmp_gt_u32 s29, s3
	s_cbranch_scc1 .Lsc_e1
	s_mov_b32 m0, s42
	s_nop 0
	global_load_lds_dwordx4 v102, s[10:11]
	global_load_lds_dwordx4 v104, s[10:11] offset:1024
	global_load_lds_dwordx4 v102, s[10:11] offset:2048
	global_load_lds_dwordx4 v104, s[10:11] offset:3072
	s_mov_b32 m0, s43
	s_nop 0
	global_load_lds_dwordx4 v106, s[10:11]
	global_load_lds_dwordx4 v108, s[10:11] offset:1024
	global_load_lds_dwordx4 v106, s[10:11] offset:2048
	global_load_lds_dwordx4 v108, s[10:11] offset:3072
	s_add_u32 s10, s10, 0x10000
	s_addc_u32 s11, s11, 0
.Lsc_e1:
	s_nop 7
	s_nop 3
	v_max_f32_e32 v4, 0, v52
	v_max_f32_e32 v5, 0, v68
	v_max_f32_e32 v6, 0, v56
	v_max_f32_e32 v7, 0, v72
	v_max_f32_e32 v8, 0, v60
	v_max_f32_e32 v9, 0, v76
	v_max_f32_e32 v10, 0, v64
	v_max_f32_e32 v11, 0, v80
	v_pk_fma_f32 v[12:13], v[212:213], v[4:5], 0 op_sel_hi:[0,1,0]
	v_pk_fma_f32 v[14:15], v[216:217], v[6:7], 0 op_sel_hi:[0,1,0]
	v_pk_fma_f32 v[228:229], v[220:221], v[8:9], 0 op_sel_hi:[0,1,0]
	v_pk_fma_f32 v[230:231], v[224:225], v[10:11], 0 op_sel_hi:[0,1,0]
	v_max_f32_e32 v4, 0, v53
	v_max_f32_e32 v5, 0, v69
	v_max_f32_e32 v6, 0, v57
	v_max_f32_e32 v7, 0, v73
	v_max_f32_e32 v8, 0, v61
	v_max_f32_e32 v9, 0, v77
	v_max_f32_e32 v10, 0, v65
	v_max_f32_e32 v11, 0, v81
	v_pk_fma_f32 v[12:13], v[212:213], v[4:5], v[12:13] op_sel:[1,0,0]
	v_pk_fma_f32 v[14:15], v[216:217], v[6:7], v[14:15] op_sel:[1,0,0]
	v_pk_fma_f32 v[228:229], v[220:221], v[8:9], v[228:229] op_sel:[1,0,0]
	v_pk_fma_f32 v[230:231], v[224:225], v[10:11], v[230:231] op_sel:[1,0,0]
	v_max_f32_e32 v4, 0, v54
	v_max_f32_e32 v5, 0, v70
	v_max_f32_e32 v6, 0, v58
	v_max_f32_e32 v7, 0, v74
	v_max_f32_e32 v8, 0, v62
	v_max_f32_e32 v9, 0, v78
	v_max_f32_e32 v10, 0, v66
	v_max_f32_e32 v11, 0, v82
	v_pk_fma_f32 v[12:13], v[214:215], v[4:5], v[12:13] op_sel_hi:[0,1,1]
	v_pk_fma_f32 v[14:15], v[218:219], v[6:7], v[14:15] op_sel_hi:[0,1,1]
	v_pk_fma_f32 v[228:229], v[222:223], v[8:9], v[228:229] op_sel_hi:[0,1,1]
	v_pk_fma_f32 v[230:231], v[226:227], v[10:11], v[230:231] op_sel_hi:[0,1,1]
	v_max_f32_e32 v4, 0, v55
	v_max_f32_e32 v5, 0, v71
	v_max_f32_e32 v6, 0, v59
	v_max_f32_e32 v7, 0, v75
	v_max_f32_e32 v8, 0, v63
	v_max_f32_e32 v9, 0, v79
	v_max_f32_e32 v10, 0, v67
	v_max_f32_e32 v11, 0, v83
	v_pk_fma_f32 v[12:13], v[214:215], v[4:5], v[12:13] op_sel:[1,0,0]
	v_pk_fma_f32 v[14:15], v[218:219], v[6:7], v[14:15] op_sel:[1,0,0]
	v_pk_fma_f32 v[228:229], v[222:223], v[8:9], v[228:229] op_sel:[1,0,0]
	v_pk_fma_f32 v[230:231], v[226:227], v[10:11], v[230:231] op_sel:[1,0,0]
	s_nop 1
	v_permlane32_swap_b32_e32 v12, v13
	v_permlane32_swap_b32_e32 v14, v15
	v_permlane32_swap_b32_e32 v228, v229
	v_permlane32_swap_b32_e32 v230, v231
	v_add_f32_e32 v4, v12, v13
	v_add_f32_e32 v6, v14, v15
	v_add_f32_e32 v8, v228, v229
	v_add_f32_e32 v10, v230, v231
	v_ashrrev_i32_e32 v5, 31, v4
	v_ashrrev_i32_e32 v7, 31, v6
	v_ashrrev_i32_e32 v9, 31, v8
	v_ashrrev_i32_e32 v11, 31, v10
	v_or_b32_e32 v5, s31, v5
	v_or_b32_e32 v7, s31, v7
	v_or_b32_e32 v9, s31, v9
	v_or_b32_e32 v11, s31, v11
	v_xor_b32_e32 v207, v4, v5
	v_xor_b32_e32 v173, v6, v7
	v_xor_b32_e32 v159, v8, v9
	v_xor_b32_e32 v135, v10, v11
	s_cmp_lt_u32 s28, s3
	s_cbranch_scc1 .Lsc_n1
	v_lshl_add_u32 v118, s28, 6, v101
	v_cmp_lt_i32_e32 vcc, s44, v118
	s_nop 1
	v_cndmask_b32_e64 v207, v207, 0, vcc
	v_cmp_lt_i32_e32 vcc, s45, v118
	s_nop 1
	v_cndmask_b32_e64 v173, v173, 0, vcc
	v_cmp_lt_i32_e32 vcc, s46, v118
	s_nop 1
	v_cndmask_b32_e64 v159, v159, 0, vcc
	v_cmp_lt_i32_e32 vcc, s47, v118
	s_nop 1
	v_cndmask_b32_e64 v135, v135, 0, vcc
.Lsc_n1:
	s_add_i32 s28, s28, 8
	s_cmp_gt_u32 s28, s3
	s_cbranch_scc1 .Lsc_z2
	s_add_i32 s29, s28, 8
	s_cmp_gt_u32 s29, s3
	s_cbranch_scc1 .Lsc_w2
	s_waitcnt vmcnt(8)
	s_branch .Lsc_r2

; DI void topk_job(const Params& p, int b, int t0, char* lds) {
;     ...
;         const int key = c * 64 + lane;
; #pragma unroll
;         for (int qi = 0; qi < 4; ++qi) {
;           f32x2 pp2 = {0.f, 0.f};
; #pragma unroll
;           for (int e = 0; e < 4; ++e) {
;             const f32x2 rl = {fmaxf(a0[4 * qi + e], 0.f), fmaxf(a1[4 * qi + e], 0.f)};
;             const f32x2 wv = {iw[qi][e], iw[qi][e]};
;             pp2 += rl * wv;
;           }
;           const float p0 = pp2[0], p1 = pp2[1];
;           const u32x2 sw = __builtin_amdgcn_permlane32_swap(__float_as_uint(p0), __float_as_uint(p1), false, false);
;           float mine = __uint_as_float(sw[0]) + __uint_as_float(sw[1]);
;           mine += 0.0f;
;           unsigned u = __float_as_uint(mine);
;           u = (u & 0x80000000u) ? ~u : (u | 0x80000000u);
;           if (key > t0 + qi || key < LEAD) u = 0u;
;           sc[i][qi] = u;
;         }
.Lsc_e2:
	s_nop 7
	s_nop 3
	v_max_f32_e32 v4, 0, v52
	v_max_f32_e32 v5, 0, v68
	v_max_f32_e32 v6, 0, v56
	v_max_f32_e32 v7, 0, v72
	v_max_f32_e32 v8, 0, v60
	v_max_f32_e32 v9, 0, v76
	v_max_f32_e32 v10, 0, v64
	v_max_f32_e32 v11, 0, v80
	v_pk_fma_f32 v[12:13], v[212:213], v[4:5], 0 op_sel_hi:[0,1,0]
	v_pk_fma_f32 v[14:15], v[216:217], v[6:7], 0 op_sel_hi:[0,1,0]
	v_pk_fma_f32 v[228:229], v[220:221], v[8:9], 0 op_sel_hi:[0,1,0]
	v_pk_fma_f32 v[230:231], v[224:225], v[10:11], 0 op_sel_hi:[0,1,0]
	v_max_f32_e32 v4, 0, v53
	v_max_f32_e32 v5, 0, v69
	v_max_f32_e32 v6, 0, v57
	v_max_f32_e32 v7, 0, v73
	v_max_f32_e32 v8, 0, v61
	v_max_f32_e32 v9, 0, v77
	v_max_f32_e32 v10, 0, v65
	v_max_f32_e32 v11, 0, v81
	v_pk_fma_f32 v[12:13], v[212:213], v[4:5], v[12:13] op_sel:[1,0,0]
	v_pk_fma_f32 v[14:15], v[216:217], v[6:7], v[14:15] op_sel:[1,0,0]
	v_pk_fma_f32 v[228:229], v[220:221], v[8:9], v[228:229] op_sel:[1,0,0]
	v_pk_fma_f32 v[230:231], v[224:225], v[10:11], v[230:231] op_sel:[1,0,0]
	v_max_f32_e32 v4, 0, v54
	v_max_f32_e32 v5, 0, v70
	v_max_f32_e32 v6, 0, v58
	v_max_f32_e32 v7, 0, v74
	v_max_f32_e32 v8, 0, v62
	v_max_f32_e32 v9, 0, v78
	v_max_f32_e32 v10, 0, v66
	v_max_f32_e32 v11, 0, v82
	v_pk_fma_f32 v[12:13], v[214:215], v[4:5], v[12:13] op_sel_hi:[0,1,1]
	v_pk_fma_f32 v[14:15], v[218:219], v[6:7], v[14:15] op_sel_hi:[0,1,1]
	v_pk_fma_f32 v[228:229], v[222:223], v[8:9], v[228:229] op_sel_hi:[0,1,1]
	v_pk_fma_f32 v[230:231], v[226:227], v[10:11], v[230:231] op_sel_hi:[0,1,1]
	v_max_f32_e32 v4, 0, v55
	v_max_f32_e32 v5, 0, v71
	v_max_f32_e32 v6, 0, v59
	v_max_f32_e32 v7, 0, v75
	v_max_f32_e32 v8, 0, v63
	v_max_f32_e32 v9, 0, v79
	v_max_f32_e32 v10, 0, v67
	v_max_f32_e32 v11, 0, v83
	v_pk_fma_f32 v[12:13], v[214:215], v[4:5], v[12:13] op_sel:[1,0,0]
	v_pk_fma_f32 v[14:15], v[218:219], v[6:7], v[14:15] op_sel:[1,0,0]
	v_pk_fma_f32 v[228:229], v[222:223], v[8:9], v[228:229] op_sel:[1,0,0]
	v_pk_fma_f32 v[230:231], v[226:227], v[10:11], v[230:231] op_sel:[1,0,0]
	s_nop 1
	v_permlane32_swap_b32_e32 v12, v13
	v_permlane32_swap_b32_e32 v14, v15
	v_permlane32_swap_b32_e32 v228, v229
	v_permlane32_swap_b32_e32 v230, v231
	v_add_f32_e32 v4, v12, v13
	v_add_f32_e32 v6, v14, v15
	v_add_f32_e32 v8, v228, v229
	v_add_f32_e32 v10, v230, v231
	v_ashrrev_i32_e32 v5, 31, v4
	v_ashrrev_i32_e32 v7, 31, v6
	v_ashrrev_i32_e32 v9, 31, v8
	v_ashrrev_i32_e32 v11, 31, v10
	v_or_b32_e32 v5, s31, v5
	v_or_b32_e32 v7, s31, v7
	v_or_b32_e32 v9, s31, v9
	v_or_b32_e32 v11, s31, v11
	v_xor_b32_e32 v187, v4, v5
	v_xor_b32_e32 v172, v6, v7
	v_xor_b32_e32 v158, v8, v9
	v_xor_b32_e32 v133, v10, v11
	s_cmp_lt_u32 s28, s3
	s_cbranch_scc1 .Lsc_n2
	v_lshl_add_u32 v118, s28, 6, v101
	v_cmp_lt_i32_e32 vcc, s44, v118
	s_nop 1
	v_cndmask_b32_e64 v187, v187, 0, vcc
	v_cmp_lt_i32_e32 vcc, s45, v118
	s_nop 1
	v_cndmask_b32_e64 v172, v172, 0, vcc
	v_cmp_lt_i32_e32 vcc, s46, v118
	s_nop 1
	v_cndmask_b32_e64 v158, v158, 0, vcc
	v_cmp_lt_i32_e32 vcc, s47, v118
	s_nop 1
	v_cndmask_b32_e64 v133, v133, 0, vcc

; DI void topk_job(const Params& p, int b, int t0, char* lds) {
;     ...
;         const int key = c * 64 + lane;
; #pragma unroll
;         for (int qi = 0; qi < 4; ++qi) {
;           f32x2 pp2 = {0.f, 0.f};
; #pragma unroll
;           for (int e = 0; e < 4; ++e) {
;             const f32x2 rl = {fmaxf(a0[4 * qi + e], 0.f), fmaxf(a1[4 * qi + e], 0.f)};
;             const f32x2 wv = {iw[qi][e], iw[qi][e]};
;             pp2 += rl * wv;
;           }
;           const float p0 = pp2[0], p1 = pp2[1];
;           const u32x2 sw = __builtin_amdgcn_permlane32_swap(__float_as_uint(p0), __float_as_uint(p1), false, false);
;           float mine = __uint_as_float(sw[0]) + __uint_as_float(sw[1]);
;           mine += 0.0f;
;           unsigned u = __float_as_uint(mine);
;           u = (u & 0x80000000u) ? ~u : (u | 0x80000000u);
;           if (key > t0 + qi || key < LEAD) u = 0u;
;           sc[i][qi] = u;
;         }
.Lsc_e3:
	s_nop 7
	s_nop 3
	v_max_f32_e32 v4, 0, v52
	v_max_f32_e32 v5, 0, v68
	v_max_f32_e32 v6, 0, v56
	v_max_f32_e32 v7, 0, v72
	v_max_f32_e32 v8, 0, v60
	v_max_f32_e32 v9, 0, v76
	v_max_f32_e32 v10, 0, v64
	v_max_f32_e32 v11, 0, v80
	v_pk_fma_f32 v[12:13], v[212:213], v[4:5], 0 op_sel_hi:[0,1,0]
	v_pk_fma_f32 v[14:15], v[216:217], v[6:7], 0 op_sel_hi:[0,1,0]
	v_pk_fma_f32 v[228:229], v[220:221], v[8:9], 0 op_sel_hi:[0,1,0]
	v_pk_fma_f32 v[230:231], v[224:225], v[10:11], 0 op_sel_hi:[0,1,0]
	v_max_f32_e32 v4, 0, v53
	v_max_f32_e32 v5, 0, v69
	v_max_f32_e32 v6, 0, v57
	v_max_f32_e32 v7, 0, v73
	v_max_f32_e32 v8, 0, v61
	v_max_f32_e32 v9, 0, v77
	v_max_f32_e32 v10, 0, v65
	v_max_f32_e32 v11, 0, v81
	v_pk_fma_f32 v[12:13], v[212:213], v[4:5], v[12:13] op_sel:[1,0,0]
	v_pk_fma_f32 v[14:15], v[216:217], v[6:7], v[14:15] op_sel:[1,0,0]
	v_pk_fma_f32 v[228:229], v[220:221], v[8:9], v[228:229] op_sel:[1,0,0]
	v_pk_fma_f32 v[230:231], v[224:225], v[10:11], v[230:231] op_sel:[1,0,0]
	v_max_f32_e32 v4, 0, v54
	v_max_f32_e32 v5, 0, v70
	v_max_f32_e32 v6, 0, v58
	v_max_f32_e32 v7, 0, v74
	v_max_f32_e32 v8, 0, v62
	v_max_f32_e32 v9, 0, v78
	v_max_f32_e32 v10, 0, v66
	v_max_f32_e32 v11, 0, v82
	v_pk_fma_f32 v[12:13], v[214:215], v[4:5], v[12:13] op_sel_hi:[0,1,1]
	v_pk_fma_f32 v[14:15], v[218:219], v[6:7], v[14:15] op_sel_hi:[0,1,1]
	v_pk_fma_f32 v[228:229], v[222:223], v[8:9], v[228:229] op_sel_hi:[0,1,1]
	v_pk_fma_f32 v[230:231], v[226:227], v[10:11], v[230:231] op_sel_hi:[0,1,1]
	v_max_f32_e32 v4, 0, v55
	v_max_f32_e32 v5, 0, v71
	v_max_f32_e32 v6, 0, v59
	v_max_f32_e32 v7, 0, v75
	v_max_f32_e32 v8, 0, v63
	v_max_f32_e32 v9, 0, v79
	v_max_f32_e32 v10, 0, v67
	v_max_f32_e32 v11, 0, v83
	v_pk_fma_f32 v[12:13], v[214:215], v[4:5], v[12:13] op_sel:[1,0,0]
	v_pk_fma_f32 v[14:15], v[218:219], v[6:7], v[14:15] op_sel:[1,0,0]
	v_pk_fma_f32 v[228:229], v[222:223], v[8:9], v[228:229] op_sel:[1,0,0]
	v_pk_fma_f32 v[230:231], v[226:227], v[10:11], v[230:231] op_sel:[1,0,0]
	s_nop 1
	v_permlane32_swap_b32_e32 v12, v13
	v_permlane32_swap_b32_e32 v14, v15
	v_permlane32_swap_b32_e32 v228, v229
	v_permlane32_swap_b32_e32 v230, v231
	v_add_f32_e32 v4, v12, v13
	v_add_f32_e32 v6, v14, v15
	v_add_f32_e32 v8, v228, v229
	v_add_f32_e32 v10, v230, v231
	v_ashrrev_i32_e32 v5, 31, v4
	v_ashrrev_i32_e32 v7, 31, v6
	v_ashrrev_i32_e32 v9, 31, v8
	v_ashrrev_i32_e32 v11, 31, v10
	v_or_b32_e32 v5, s31, v5
	v_or_b32_e32 v7, s31, v7
	v_or_b32_e32 v9, s31, v9
	v_or_b32_e32 v11, s31, v11
	v_xor_b32_e32 v186, v4, v5
	v_xor_b32_e32 v171, v6, v7
	v_xor_b32_e32 v153, v8, v9
	v_xor_b32_e32 v129, v10, v11
	s_cmp_lt_u32 s28, s3
	s_cbranch_scc1 .Lsc_n3
	v_lshl_add_u32 v118, s28, 6, v101
	v_cmp_lt_i32_e32 vcc, s44, v118
	s_nop 1
	v_cndmask_b32_e64 v186, v186, 0, vcc
	v_cmp_lt_i32_e32 vcc, s45, v118
	s_nop 1
	v_cndmask_b32_e64 v171, v171, 0, vcc
	v_cmp_lt_i32_e32 vcc, s46, v118
	s_nop 1
	v_cndmask_b32_e64 v153, v153, 0, vcc
	v_cmp_lt_i32_e32 vcc, s47, v118
	s_nop 1
	v_cndmask_b32_e64 v129, v129, 0, vcc

; DI void topk_job(const Params& p, int b, int t0, char* lds) {
;     ...
;         const int key = c * 64 + lane;
; #pragma unroll
;         for (int qi = 0; qi < 4; ++qi) {
;           f32x2 pp2 = {0.f, 0.f};
; #pragma unroll
;           for (int e = 0; e < 4; ++e) {
;             const f32x2 rl = {fmaxf(a0[4 * qi + e], 0.f), fmaxf(a1[4 * qi + e], 0.f)};
;             const f32x2 wv = {iw[qi][e], iw[qi][e]};
;             pp2 += rl * wv;
;           }
;           const float p0 = pp2[0], p1 = pp2[1];
;           const u32x2 sw = __builtin_amdgcn_permlane32_swap(__float_as_uint(p0), __float_as_uint(p1), false, false);
;           float mine = __uint_as_float(sw[0]) + __uint_as_float(sw[1]);
;           mine += 0.0f;
;           unsigned u = __float_as_uint(mine);
;           u = (u & 0x80000000u) ? ~u : (u | 0x80000000u);
;           if (key > t0 + qi || key < LEAD) u = 0u;
;           sc[i][qi] = u;
;         }
.Lsc_e4:
	s_nop 7
	s_nop 3
	v_max_f32_e32 v4, 0, v52
	v_max_f32_e32 v5, 0, v68
	v_max_f32_e32 v6, 0, v56
	v_max_f32_e32 v7, 0, v72
	v_max_f32_e32 v8, 0, v60
	v_max_f32_e32 v9, 0, v76
	v_max_f32_e32 v10, 0, v64
	v_max_f32_e32 v11, 0, v80
	v_pk_fma_f32 v[12:13], v[212:213], v[4:5], 0 op_sel_hi:[0,1,0]
	v_pk_fma_f32 v[14:15], v[216:217], v[6:7], 0 op_sel_hi:[0,1,0]
	v_pk_fma_f32 v[228:229], v[220:221], v[8:9], 0 op_sel_hi:[0,1,0]
	v_pk_fma_f32 v[230:231], v[224:225], v[10:11], 0 op_sel_hi:[0,1,0]
	v_max_f32_e32 v4, 0, v53
	v_max_f32_e32 v5, 0, v69
	v_max_f32_e32 v6, 0, v57
	v_max_f32_e32 v7, 0, v73
	v_max_f32_e32 v8, 0, v61
	v_max_f32_e32 v9, 0, v77
	v_max_f32_e32 v10, 0, v65
	v_max_f32_e32 v11, 0, v81
	v_pk_fma_f32 v[12:13], v[212:213], v[4:5], v[12:13] op_sel:[1,0,0]
	v_pk_fma_f32 v[14:15], v[216:217], v[6:7], v[14:15] op_sel:[1,0,0]
	v_pk_fma_f32 v[228:229], v[220:221], v[8:9], v[228:229] op_sel:[1,0,0]
	v_pk_fma_f32 v[230:231], v[224:225], v[10:11], v[230:231] op_sel:[1,0,0]
	v_max_f32_e32 v4, 0, v54
	v_max_f32_e32 v5, 0, v70
	v_max_f32_e32 v6, 0, v58
	v_max_f32_e32 v7, 0, v74
	v_max_f32_e32 v8, 0, v62
	v_max_f32_e32 v9, 0, v78
	v_max_f32_e32 v10, 0, v66
	v_max_f32_e32 v11, 0, v82
	v_pk_fma_f32 v[12:13], v[214:215], v[4:5], v[12:13] op_sel_hi:[0,1,1]
	v_pk_fma_f32 v[14:15], v[218:219], v[6:7], v[14:15] op_sel_hi:[0,1,1]
	v_pk_fma_f32 v[228:229], v[222:223], v[8:9], v[228:229] op_sel_hi:[0,1,1]
	v_pk_fma_f32 v[230:231], v[226:227], v[10:11], v[230:231] op_sel_hi:[0,1,1]
	v_max_f32_e32 v4, 0, v55
	v_max_f32_e32 v5, 0, v71
	v_max_f32_e32 v6, 0, v59
	v_max_f32_e32 v7, 0, v75
	v_max_f32_e32 v8, 0, v63
	v_max_f32_e32 v9, 0, v79
	v_max_f32_e32 v10, 0, v67
	v_max_f32_e32 v11, 0, v83
	v_pk_fma_f32 v[12:13], v[214:215], v[4:5], v[12:13] op_sel:[1,0,0]
	v_pk_fma_f32 v[14:15], v[218:219], v[6:7], v[14:15] op_sel:[1,0,0]
	v_pk_fma_f32 v[228:229], v[222:223], v[8:9], v[228:229] op_sel:[1,0,0]
	v_pk_fma_f32 v[230:231], v[226:227], v[10:11], v[230:231] op_sel:[1,0,0]
	s_nop 1
	v_permlane32_swap_b32_e32 v12, v13
	v_permlane32_swap_b32_e32 v14, v15
	v_permlane32_swap_b32_e32 v228, v229
	v_permlane32_swap_b32_e32 v230, v231
	v_add_f32_e32 v4, v12, v13
	v_add_f32_e32 v6, v14, v15
	v_add_f32_e32 v8, v228, v229
	v_add_f32_e32 v10, v230, v231
	v_ashrrev_i32_e32 v5, 31, v4
	v_ashrrev_i32_e32 v7, 31, v6
	v_ashrrev_i32_e32 v9, 31, v8
	v_ashrrev_i32_e32 v11, 31, v10
	v_or_b32_e32 v5, s31, v5
	v_or_b32_e32 v7, s31, v7
	v_or_b32_e32 v9, s31, v9
	v_or_b32_e32 v11, s31, v11
	v_xor_b32_e32 v185, v4, v5
	v_xor_b32_e32 v170, v6, v7
	v_xor_b32_e32 v150, v8, v9
	v_xor_b32_e32 v127, v10, v11
	s_cmp_lt_u32 s28, s3
	s_cbranch_scc1 .Lsc_n4
	v_lshl_add_u32 v118, s28, 6, v101
	v_cmp_lt_i32_e32 vcc, s44, v118
	s_nop 1
	v_cndmask_b32_e64 v185, v185, 0, vcc
	v_cmp_lt_i32_e32 vcc, s45, v118
	s_nop 1
	v_cndmask_b32_e64 v170, v170, 0, vcc
	v_cmp_lt_i32_e32 vcc, s46, v118
	s_nop 1
	v_cndmask_b32_e64 v150, v150, 0, vcc
	v_cmp_lt_i32_e32 vcc, s47, v118
	s_nop 1
	v_cndmask_b32_e64 v127, v127, 0, vcc

; DI void topk_job(const Params& p, int b, int t0, char* lds) {
;     ...
;         const int key = c * 64 + lane;
; #pragma unroll
;         for (int qi = 0; qi < 4; ++qi) {
;           f32x2 pp2 = {0.f, 0.f};
; #pragma unroll
;           for (int e = 0; e < 4; ++e) {
;             const f32x2 rl = {fmaxf(a0[4 * qi + e], 0.f), fmaxf(a1[4 * qi + e], 0.f)};
;             const f32x2 wv = {iw[qi][e], iw[qi][e]};
;             pp2 += rl * wv;
;           }
;           const float p0 = pp2[0], p1 = pp2[1];
;           const u32x2 sw = __builtin_amdgcn_permlane32_swap(__float_as_uint(p0), __float_as_uint(p1), false, false);
;           float mine = __uint_as_float(sw[0]) + __uint_as_float(sw[1]);
;           mine += 0.0f;
;           unsigned u = __float_as_uint(mine);
;           u = (u & 0x80000000u) ? ~u : (u | 0x80000000u);
;           if (key > t0 + qi || key < LEAD) u = 0u;
;           sc[i][qi] = u;
;         }
.Lsc_e5:
	s_nop 7
	s_nop 3
	v_max_f32_e32 v4, 0, v52
	v_max_f32_e32 v5, 0, v68
	v_max_f32_e32 v6, 0, v56
	v_max_f32_e32 v7, 0, v72
	v_max_f32_e32 v8, 0, v60
	v_max_f32_e32 v9, 0, v76
	v_max_f32_e32 v10, 0, v64
	v_max_f32_e32 v11, 0, v80
	v_pk_fma_f32 v[12:13], v[212:213], v[4:5], 0 op_sel_hi:[0,1,0]
	v_pk_fma_f32 v[14:15], v[216:217], v[6:7], 0 op_sel_hi:[0,1,0]
	v_pk_fma_f32 v[228:229], v[220:221], v[8:9], 0 op_sel_hi:[0,1,0]
	v_pk_fma_f32 v[230:231], v[224:225], v[10:11], 0 op_sel_hi:[0,1,0]
	v_max_f32_e32 v4, 0, v53
	v_max_f32_e32 v5, 0, v69
	v_max_f32_e32 v6, 0, v57
	v_max_f32_e32 v7, 0, v73
	v_max_f32_e32 v8, 0, v61
	v_max_f32_e32 v9, 0, v77
	v_max_f32_e32 v10, 0, v65
	v_max_f32_e32 v11, 0, v81
	v_pk_fma_f32 v[12:13], v[212:213], v[4:5], v[12:13] op_sel:[1,0,0]
	v_pk_fma_f32 v[14:15], v[216:217], v[6:7], v[14:15] op_sel:[1,0,0]
	v_pk_fma_f32 v[228:229], v[220:221], v[8:9], v[228:229] op_sel:[1,0,0]
	v_pk_fma_f32 v[230:231], v[224:225], v[10:11], v[230:231] op_sel:[1,0,0]
	v_max_f32_e32 v4, 0, v54
	v_max_f32_e32 v5, 0, v70
	v_max_f32_e32 v6, 0, v58
	v_max_f32_e32 v7, 0, v74
	v_max_f32_e32 v8, 0, v62
	v_max_f32_e32 v9, 0, v78
	v_max_f32_e32 v10, 0, v66
	v_max_f32_e32 v11, 0, v82
	v_pk_fma_f32 v[12:13], v[214:215], v[4:5], v[12:13] op_sel_hi:[0,1,1]
	v_pk_fma_f32 v[14:15], v[218:219], v[6:7], v[14:15] op_sel_hi:[0,1,1]
	v_pk_fma_f32 v[228:229], v[222:223], v[8:9], v[228:229] op_sel_hi:[0,1,1]
	v_pk_fma_f32 v[230:231], v[226:227], v[10:11], v[230:231] op_sel_hi:[0,1,1]
	v_max_f32_e32 v4, 0, v55
	v_max_f32_e32 v5, 0, v71
	v_max_f32_e32 v6, 0, v59
	v_max_f32_e32 v7, 0, v75
	v_max_f32_e32 v8, 0, v63
	v_max_f32_e32 v9, 0, v79
	v_max_f32_e32 v10, 0, v67
	v_max_f32_e32 v11, 0, v83
	v_pk_fma_f32 v[12:13], v[214:215], v[4:5], v[12:13] op_sel:[1,0,0]
	v_pk_fma_f32 v[14:15], v[218:219], v[6:7], v[14:15] op_sel:[1,0,0]
	v_pk_fma_f32 v[228:229], v[222:223], v[8:9], v[228:229] op_sel:[1,0,0]
	v_pk_fma_f32 v[230:231], v[226:227], v[10:11], v[230:231] op_sel:[1,0,0]
	s_nop 1
	v_permlane32_swap_b32_e32 v12, v13
	v_permlane32_swap_b32_e32 v14, v15
	v_permlane32_swap_b32_e32 v228, v229
	v_permlane32_swap_b32_e32 v230, v231
	v_add_f32_e32 v4, v12, v13
	v_add_f32_e32 v6, v14, v15
	v_add_f32_e32 v8, v228, v229
	v_add_f32_e32 v10, v230, v231
	v_ashrrev_i32_e32 v5, 31, v4
	v_ashrrev_i32_e32 v7, 31, v6
	v_ashrrev_i32_e32 v9, 31, v8
	v_ashrrev_i32_e32 v11, 31, v10
	v_or_b32_e32 v5, s31, v5
	v_or_b32_e32 v7, s31, v7
	v_or_b32_e32 v9, s31, v9
	v_or_b32_e32 v11, s31, v11
	v_xor_b32_e32 v184, v4, v5
	v_xor_b32_e32 v168, v6, v7
	v_xor_b32_e32 v149, v8, v9
	v_xor_b32_e32 v125, v10, v11
	s_cmp_lt_u32 s28, s3
	s_cbranch_scc1 .Lsc_n5
	v_lshl_add_u32 v118, s28, 6, v101
	v_cmp_lt_i32_e32 vcc, s44, v118
	s_nop 1
	v_cndmask_b32_e64 v184, v184, 0, vcc
	v_cmp_lt_i32_e32 vcc, s45, v118
	s_nop 1
	v_cndmask_b32_e64 v168, v168, 0, vcc
	v_cmp_lt_i32_e32 vcc, s46, v118
	s_nop 1
	v_cndmask_b32_e64 v149, v149, 0, vcc
	v_cmp_lt_i32_e32 vcc, s47, v118
	s_nop 1
	v_cndmask_b32_e64 v125, v125, 0, vcc

; DI void topk_job(const Params& p, int b, int t0, char* lds) {
;     ...
;         const int key = c * 64 + lane;
; #pragma unroll
;         for (int qi = 0; qi < 4; ++qi) {
;           f32x2 pp2 = {0.f, 0.f};
; #pragma unroll
;           for (int e = 0; e < 4; ++e) {
;             const f32x2 rl = {fmaxf(a0[4 * qi + e], 0.f), fmaxf(a1[4 * qi + e], 0.f)};
;             const f32x2 wv = {iw[qi][e], iw[qi][e]};
;             pp2 += rl * wv;
;           }
;           const float p0 = pp2[0], p1 = pp2[1];
;           const u32x2 sw = __builtin_amdgcn_permlane32_swap(__float_as_uint(p0), __float_as_uint(p1), false, false);
;           float mine = __uint_as_float(sw[0]) + __uint_as_float(sw[1]);
;           mine += 0.0f;
;           unsigned u = __float_as_uint(mine);
;           u = (u & 0x80000000u) ? ~u : (u | 0x80000000u);
;           if (key > t0 + qi || key < LEAD) u = 0u;
;           sc[i][qi] = u;
;         }
.Lsc_e6:
	s_nop 7
	s_nop 3
	v_max_f32_e32 v4, 0, v52
	v_max_f32_e32 v5, 0, v68
	v_max_f32_e32 v6, 0, v56
	v_max_f32_e32 v7, 0, v72
	v_max_f32_e32 v8, 0, v60
	v_max_f32_e32 v9, 0, v76
	v_max_f32_e32 v10, 0, v64
	v_max_f32_e32 v11, 0, v80
	v_pk_fma_f32 v[12:13], v[212:213], v[4:5], 0 op_sel_hi:[0,1,0]
	v_pk_fma_f32 v[14:15], v[216:217], v[6:7], 0 op_sel_hi:[0,1,0]
	v_pk_fma_f32 v[228:229], v[220:221], v[8:9], 0 op_sel_hi:[0,1,0]
	v_pk_fma_f32 v[230:231], v[224:225], v[10:11], 0 op_sel_hi:[0,1,0]
	v_max_f32_e32 v4, 0, v53
	v_max_f32_e32 v5, 0, v69
	v_max_f32_e32 v6, 0, v57
	v_max_f32_e32 v7, 0, v73
	v_max_f32_e32 v8, 0, v61
	v_max_f32_e32 v9, 0, v77
	v_max_f32_e32 v10, 0, v65
	v_max_f32_e32 v11, 0, v81
	v_pk_fma_f32 v[12:13], v[212:213], v[4:5], v[12:13] op_sel:[1,0,0]
	v_pk_fma_f32 v[14:15], v[216:217], v[6:7], v[14:15] op_sel:[1,0,0]
	v_pk_fma_f32 v[228:229], v[220:221], v[8:9], v[228:229] op_sel:[1,0,0]
	v_pk_fma_f32 v[230:231], v[224:225], v[10:11], v[230:231] op_sel:[1,0,0]
	v_max_f32_e32 v4, 0, v54
	v_max_f32_e32 v5, 0, v70
	v_max_f32_e32 v6, 0, v58
	v_max_f32_e32 v7, 0, v74
	v_max_f32_e32 v8, 0, v62
	v_max_f32_e32 v9, 0, v78
	v_max_f32_e32 v10, 0, v66
	v_max_f32_e32 v11, 0, v82
	v_pk_fma_f32 v[12:13], v[214:215], v[4:5], v[12:13] op_sel_hi:[0,1,1]
	v_pk_fma_f32 v[14:15], v[218:219], v[6:7], v[14:15] op_sel_hi:[0,1,1]
	v_pk_fma_f32 v[228:229], v[222:223], v[8:9], v[228:229] op_sel_hi:[0,1,1]
	v_pk_fma_f32 v[230:231], v[226:227], v[10:11], v[230:231] op_sel_hi:[0,1,1]
	v_max_f32_e32 v4, 0, v55
	v_max_f32_e32 v5, 0, v71
	v_max_f32_e32 v6, 0, v59
	v_max_f32_e32 v7, 0, v75
	v_max_f32_e32 v8, 0, v63
	v_max_f32_e32 v9, 0, v79
	v_max_f32_e32 v10, 0, v67
	v_max_f32_e32 v11, 0, v83
	v_pk_fma_f32 v[12:13], v[214:215], v[4:5], v[12:13] op_sel:[1,0,0]
	v_pk_fma_f32 v[14:15], v[218:219], v[6:7], v[14:15] op_sel:[1,0,0]
	v_pk_fma_f32 v[228:229], v[222:223], v[8:9], v[228:229] op_sel:[1,0,0]
	v_pk_fma_f32 v[230:231], v[226:227], v[10:11], v[230:231] op_sel:[1,0,0]
	s_nop 1
	v_permlane32_swap_b32_e32 v12, v13
	v_permlane32_swap_b32_e32 v14, v15
	v_permlane32_swap_b32_e32 v228, v229
	v_permlane32_swap_b32_e32 v230, v231
	v_add_f32_e32 v4, v12, v13
	v_add_f32_e32 v6, v14, v15
	v_add_f32_e32 v8, v228, v229
	v_add_f32_e32 v10, v230, v231
	v_ashrrev_i32_e32 v5, 31, v4
	v_ashrrev_i32_e32 v7, 31, v6
	v_ashrrev_i32_e32 v9, 31, v8
	v_ashrrev_i32_e32 v11, 31, v10
	v_or_b32_e32 v5, s31, v5
	v_or_b32_e32 v7, s31, v7
	v_or_b32_e32 v9, s31, v9
	v_or_b32_e32 v11, s31, v11
	v_xor_b32_e32 v183, v4, v5
	v_xor_b32_e32 v167, v6, v7
	v_xor_b32_e32 v147, v8, v9
	v_xor_b32_e32 v123, v10, v11
	s_cmp_lt_u32 s28, s3
	s_cbranch_scc1 .Lsc_n6
	v_lshl_add_u32 v118, s28, 6, v101
	v_cmp_lt_i32_e32 vcc, s44, v118
	s_nop 1
	v_cndmask_b32_e64 v183, v183, 0, vcc
	v_cmp_lt_i32_e32 vcc, s45, v118
	s_nop 1
	v_cndmask_b32_e64 v167, v167, 0, vcc
	v_cmp_lt_i32_e32 vcc, s46, v118
	s_nop 1
	v_cndmask_b32_e64 v147, v147, 0, vcc
	v_cmp_lt_i32_e32 vcc, s47, v118
	s_nop 1
	v_cndmask_b32_e64 v123, v123, 0, vcc

; DI void topk_job(const Params& p, int b, int t0, char* lds) {
;     ...
;         const int key = c * 64 + lane;
; #pragma unroll
;         for (int qi = 0; qi < 4; ++qi) {
;           f32x2 pp2 = {0.f, 0.f};
; #pragma unroll
;           for (int e = 0; e < 4; ++e) {
;             const f32x2 rl = {fmaxf(a0[4 * qi + e], 0.f), fmaxf(a1[4 * qi + e], 0.f)};
;             const f32x2 wv = {iw[qi][e], iw[qi][e]};
;             pp2 += rl * wv;
;           }
;           const float p0 = pp2[0], p1 = pp2[1];
;           const u32x2 sw = __builtin_amdgcn_permlane32_swap(__float_as_uint(p0), __float_as_uint(p1), false, false);
;           float mine = __uint_as_float(sw[0]) + __uint_as_float(sw[1]);
;           mine += 0.0f;
;           unsigned u = __float_as_uint(mine);
;           u = (u & 0x80000000u) ? ~u : (u | 0x80000000u);
;           if (key > t0 + qi || key < LEAD) u = 0u;
;           sc[i][qi] = u;
;         }
.Lsc_e7:
	s_nop 7
	s_nop 3
	v_max_f32_e32 v4, 0, v52
	v_max_f32_e32 v5, 0, v68
	v_max_f32_e32 v6, 0, v56
	v_max_f32_e32 v7, 0, v72
	v_max_f32_e32 v8, 0, v60
	v_max_f32_e32 v9, 0, v76
	v_max_f32_e32 v10, 0, v64
	v_max_f32_e32 v11, 0, v80
	v_pk_fma_f32 v[12:13], v[212:213], v[4:5], 0 op_sel_hi:[0,1,0]
	v_pk_fma_f32 v[14:15], v[216:217], v[6:7], 0 op_sel_hi:[0,1,0]
	v_pk_fma_f32 v[228:229], v[220:221], v[8:9], 0 op_sel_hi:[0,1,0]
	v_pk_fma_f32 v[230:231], v[224:225], v[10:11], 0 op_sel_hi:[0,1,0]
	v_max_f32_e32 v4, 0, v53
	v_max_f32_e32 v5, 0, v69
	v_max_f32_e32 v6, 0, v57
	v_max_f32_e32 v7, 0, v73
	v_max_f32_e32 v8, 0, v61
	v_max_f32_e32 v9, 0, v77
	v_max_f32_e32 v10, 0, v65
	v_max_f32_e32 v11, 0, v81
	v_pk_fma_f32 v[12:13], v[212:213], v[4:5], v[12:13] op_sel:[1,0,0]
	v_pk_fma_f32 v[14:15], v[216:217], v[6:7], v[14:15] op_sel:[1,0,0]
	v_pk_fma_f32 v[228:229], v[220:221], v[8:9], v[228:229] op_sel:[1,0,0]
	v_pk_fma_f32 v[230:231], v[224:225], v[10:11], v[230:231] op_sel:[1,0,0]
	v_max_f32_e32 v4, 0, v54
	v_max_f32_e32 v5, 0, v70
	v_max_f32_e32 v6, 0, v58
	v_max_f32_e32 v7, 0, v74
	v_max_f32_e32 v8, 0, v62
	v_max_f32_e32 v9, 0, v78
	v_max_f32_e32 v10, 0, v66
	v_max_f32_e32 v11, 0, v82
	v_pk_fma_f32 v[12:13], v[214:215], v[4:5], v[12:13] op_sel_hi:[0,1,1]
	v_pk_fma_f32 v[14:15], v[218:219], v[6:7], v[14:15] op_sel_hi:[0,1,1]
	v_pk_fma_f32 v[228:229], v[222:223], v[8:9], v[228:229] op_sel_hi:[0,1,1]
	v_pk_fma_f32 v[230:231], v[226:227], v[10:11], v[230:231] op_sel_hi:[0,1,1]
	v_max_f32_e32 v4, 0, v55
	v_max_f32_e32 v5, 0, v71
	v_max_f32_e32 v6, 0, v59
	v_max_f32_e32 v7, 0, v75
	v_max_f32_e32 v8, 0, v63
	v_max_f32_e32 v9, 0, v79
	v_max_f32_e32 v10, 0, v67
	v_max_f32_e32 v11, 0, v83
	v_pk_fma_f32 v[12:13], v[214:215], v[4:5], v[12:13] op_sel:[1,0,0]
	v_pk_fma_f32 v[14:15], v[218:219], v[6:7], v[14:15] op_sel:[1,0,0]
	v_pk_fma_f32 v[228:229], v[222:223], v[8:9], v[228:229] op_sel:[1,0,0]
	v_pk_fma_f32 v[230:231], v[226:227], v[10:11], v[230:231] op_sel:[1,0,0]
	s_nop 1
	v_permlane32_swap_b32_e32 v12, v13
	v_permlane32_swap_b32_e32 v14, v15
	v_permlane32_swap_b32_e32 v228, v229
	v_permlane32_swap_b32_e32 v230, v231
	v_add_f32_e32 v4, v12, v13
	v_add_f32_e32 v6, v14, v15
	v_add_f32_e32 v8, v228, v229
	v_add_f32_e32 v10, v230, v231
	v_ashrrev_i32_e32 v5, 31, v4
	v_ashrrev_i32_e32 v7, 31, v6
	v_ashrrev_i32_e32 v9, 31, v8
	v_ashrrev_i32_e32 v11, 31, v10
	v_or_b32_e32 v5, s31, v5
	v_or_b32_e32 v7, s31, v7
	v_or_b32_e32 v9, s31, v9
	v_or_b32_e32 v11, s31, v11
	v_xor_b32_e32 v182, v4, v5
	v_xor_b32_e32 v166, v6, v7
	v_xor_b32_e32 v146, v8, v9
	v_xor_b32_e32 v121, v10, v11
	s_cmp_lt_u32 s28, s3
	s_cbranch_scc1 .Lsc_n7
	v_lshl_add_u32 v118, s28, 6, v101
	v_cmp_lt_i32_e32 vcc, s44, v118
	s_nop 1
	v_cndmask_b32_e64 v182, v182, 0, vcc
	v_cmp_lt_i32_e32 vcc, s45, v118
	s_nop 1
	v_cndmask_b32_e64 v166, v166, 0, vcc
	v_cmp_lt_i32_e32 vcc, s46, v118
	s_nop 1
	v_cndmask_b32_e64 v146, v146, 0, vcc
	v_cmp_lt_i32_e32 vcc, s47, v118
	s_nop 1
	v_cndmask_b32_e64 v121, v121, 0, vcc

; DI void topk_job(const Params& p, int b, int t0, char* lds) {
;     ...
;         const int key = c * 64 + lane;
; #pragma unroll
;         for (int qi = 0; qi < 4; ++qi) {
;           f32x2 pp2 = {0.f, 0.f};
; #pragma unroll
;           for (int e = 0; e < 4; ++e) {
;             const f32x2 rl = {fmaxf(a0[4 * qi + e], 0.f), fmaxf(a1[4 * qi + e], 0.f)};
;             const f32x2 wv = {iw[qi][e], iw[qi][e]};
;             pp2 += rl * wv;
;           }
;           const float p0 = pp2[0], p1 = pp2[1];
;           const u32x2 sw = __builtin_amdgcn_permlane32_swap(__float_as_uint(p0), __float_as_uint(p1), false, false);
;           float mine = __uint_as_float(sw[0]) + __uint_as_float(sw[1]);
;           mine += 0.0f;
;           unsigned u = __float_as_uint(mine);
;           u = (u & 0x80000000u) ? ~u : (u | 0x80000000u);
;           if (key > t0 + qi || key < LEAD) u = 0u;
;           sc[i][qi] = u;
;         }
.Lsc_e8:
	s_nop 7
	s_nop 3
	v_max_f32_e32 v4, 0, v52
	v_max_f32_e32 v5, 0, v68
	v_max_f32_e32 v6, 0, v56
	v_max_f32_e32 v7, 0, v72
	v_max_f32_e32 v8, 0, v60
	v_max_f32_e32 v9, 0, v76
	v_max_f32_e32 v10, 0, v64
	v_max_f32_e32 v11, 0, v80
	v_pk_fma_f32 v[12:13], v[212:213], v[4:5], 0 op_sel_hi:[0,1,0]
	v_pk_fma_f32 v[14:15], v[216:217], v[6:7], 0 op_sel_hi:[0,1,0]
	v_pk_fma_f32 v[228:229], v[220:221], v[8:9], 0 op_sel_hi:[0,1,0]
	v_pk_fma_f32 v[230:231], v[224:225], v[10:11], 0 op_sel_hi:[0,1,0]
	v_max_f32_e32 v4, 0, v53
	v_max_f32_e32 v5, 0, v69
	v_max_f32_e32 v6, 0, v57
	v_max_f32_e32 v7, 0, v73
	v_max_f32_e32 v8, 0, v61
	v_max_f32_e32 v9, 0, v77
	v_max_f32_e32 v10, 0, v65
	v_max_f32_e32 v11, 0, v81
	v_pk_fma_f32 v[12:13], v[212:213], v[4:5], v[12:13] op_sel:[1,0,0]
	v_pk_fma_f32 v[14:15], v[216:217], v[6:7], v[14:15] op_sel:[1,0,0]
	v_pk_fma_f32 v[228:229], v[220:221], v[8:9], v[228:229] op_sel:[1,0,0]
	v_pk_fma_f32 v[230:231], v[224:225], v[10:11], v[230:231] op_sel:[1,0,0]
	v_max_f32_e32 v4, 0, v54
	v_max_f32_e32 v5, 0, v70
	v_max_f32_e32 v6, 0, v58
	v_max_f32_e32 v7, 0, v74
	v_max_f32_e32 v8, 0, v62
	v_max_f32_e32 v9, 0, v78
	v_max_f32_e32 v10, 0, v66
	v_max_f32_e32 v11, 0, v82
	v_pk_fma_f32 v[12:13], v[214:215], v[4:5], v[12:13] op_sel_hi:[0,1,1]
	v_pk_fma_f32 v[14:15], v[218:219], v[6:7], v[14:15] op_sel_hi:[0,1,1]
	v_pk_fma_f32 v[228:229], v[222:223], v[8:9], v[228:229] op_sel_hi:[0,1,1]
	v_pk_fma_f32 v[230:231], v[226:227], v[10:11], v[230:231] op_sel_hi:[0,1,1]
	v_max_f32_e32 v4, 0, v55
	v_max_f32_e32 v5, 0, v71
	v_max_f32_e32 v6, 0, v59
	v_max_f32_e32 v7, 0, v75
	v_max_f32_e32 v8, 0, v63
	v_max_f32_e32 v9, 0, v79
	v_max_f32_e32 v10, 0, v67
	v_max_f32_e32 v11, 0, v83
	v_pk_fma_f32 v[12:13], v[214:215], v[4:5], v[12:13] op_sel:[1,0,0]
	v_pk_fma_f32 v[14:15], v[218:219], v[6:7], v[14:15] op_sel:[1,0,0]
	v_pk_fma_f32 v[228:229], v[222:223], v[8:9], v[228:229] op_sel:[1,0,0]
	v_pk_fma_f32 v[230:231], v[226:227], v[10:11], v[230:231] op_sel:[1,0,0]
	s_nop 1
	v_permlane32_swap_b32_e32 v12, v13
	v_permlane32_swap_b32_e32 v14, v15
	v_permlane32_swap_b32_e32 v228, v229
	v_permlane32_swap_b32_e32 v230, v231
	v_add_f32_e32 v4, v12, v13
	v_add_f32_e32 v6, v14, v15
	v_add_f32_e32 v8, v228, v229
	v_add_f32_e32 v10, v230, v231
	v_ashrrev_i32_e32 v5, 31, v4
	v_ashrrev_i32_e32 v7, 31, v6
	v_ashrrev_i32_e32 v9, 31, v8
	v_ashrrev_i32_e32 v11, 31, v10
	v_or_b32_e32 v5, s31, v5
	v_or_b32_e32 v7, s31, v7
	v_or_b32_e32 v9, s31, v9
	v_or_b32_e32 v11, s31, v11
	v_xor_b32_e32 v181, v4, v5
	v_xor_b32_e32 v165, v6, v7
	v_xor_b32_e32 v145, v8, v9
	v_xor_b32_e32 v119, v10, v11
	s_cmp_lt_u32 s28, s3
	s_cbranch_scc1 .Lsc_n8
	v_lshl_add_u32 v118, s28, 6, v101
	v_cmp_lt_i32_e32 vcc, s44, v118
	s_nop 1
	v_cndmask_b32_e64 v181, v181, 0, vcc
	v_cmp_lt_i32_e32 vcc, s45, v118
	s_nop 1
	v_cndmask_b32_e64 v165, v165, 0, vcc
	v_cmp_lt_i32_e32 vcc, s46, v118
	s_nop 1
	v_cndmask_b32_e64 v145, v145, 0, vcc
	v_cmp_lt_i32_e32 vcc, s47, v118
	s_nop 1
	v_cndmask_b32_e64 v119, v119, 0, vcc

; DI void topk_job(const Params& p, int b, int t0, char* lds) {
;     ...
;         const int key = c * 64 + lane;
; #pragma unroll
;         for (int qi = 0; qi < 4; ++qi) {
;           f32x2 pp2 = {0.f, 0.f};
; #pragma unroll
;           for (int e = 0; e < 4; ++e) {
;             const f32x2 rl = {fmaxf(a0[4 * qi + e], 0.f), fmaxf(a1[4 * qi + e], 0.f)};
;             const f32x2 wv = {iw[qi][e], iw[qi][e]};
;             pp2 += rl * wv;
;           }
;           const float p0 = pp2[0], p1 = pp2[1];
;           const u32x2 sw = __builtin_amdgcn_permlane32_swap(__float_as_uint(p0), __float_as_uint(p1), false, false);
;           float mine = __uint_as_float(sw[0]) + __uint_as_float(sw[1]);
;           mine += 0.0f;
;           unsigned u = __float_as_uint(mine);
;           u = (u & 0x80000000u) ? ~u : (u | 0x80000000u);
;           if (key > t0 + qi || key < LEAD) u = 0u;
;           sc[i][qi] = u;
;         }
.Lsc_e9:
	s_nop 7
	s_nop 3
	v_max_f32_e32 v4, 0, v52
	v_max_f32_e32 v5, 0, v68
	v_max_f32_e32 v6, 0, v56
	v_max_f32_e32 v7, 0, v72
	v_max_f32_e32 v8, 0, v60
	v_max_f32_e32 v9, 0, v76
	v_max_f32_e32 v10, 0, v64
	v_max_f32_e32 v11, 0, v80
	v_pk_fma_f32 v[12:13], v[212:213], v[4:5], 0 op_sel_hi:[0,1,0]
	v_pk_fma_f32 v[14:15], v[216:217], v[6:7], 0 op_sel_hi:[0,1,0]
	v_pk_fma_f32 v[228:229], v[220:221], v[8:9], 0 op_sel_hi:[0,1,0]
	v_pk_fma_f32 v[230:231], v[224:225], v[10:11], 0 op_sel_hi:[0,1,0]
	v_max_f32_e32 v4, 0, v53
	v_max_f32_e32 v5, 0, v69
	v_max_f32_e32 v6, 0, v57
	v_max_f32_e32 v7, 0, v73
	v_max_f32_e32 v8, 0, v61
	v_max_f32_e32 v9, 0, v77
	v_max_f32_e32 v10, 0, v65
	v_max_f32_e32 v11, 0, v81
	v_pk_fma_f32 v[12:13], v[212:213], v[4:5], v[12:13] op_sel:[1,0,0]
	v_pk_fma_f32 v[14:15], v[216:217], v[6:7], v[14:15] op_sel:[1,0,0]
	v_pk_fma_f32 v[228:229], v[220:221], v[8:9], v[228:229] op_sel:[1,0,0]
	v_pk_fma_f32 v[230:231], v[224:225], v[10:11], v[230:231] op_sel:[1,0,0]
	v_max_f32_e32 v4, 0, v54
	v_max_f32_e32 v5, 0, v70
	v_max_f32_e32 v6, 0, v58
	v_max_f32_e32 v7, 0, v74
	v_max_f32_e32 v8, 0, v62
	v_max_f32_e32 v9, 0, v78
	v_max_f32_e32 v10, 0, v66
	v_max_f32_e32 v11, 0, v82
	v_pk_fma_f32 v[12:13], v[214:215], v[4:5], v[12:13] op_sel_hi:[0,1,1]
	v_pk_fma_f32 v[14:15], v[218:219], v[6:7], v[14:15] op_sel_hi:[0,1,1]
	v_pk_fma_f32 v[228:229], v[222:223], v[8:9], v[228:229] op_sel_hi:[0,1,1]
	v_pk_fma_f32 v[230:231], v[226:227], v[10:11], v[230:231] op_sel_hi:[0,1,1]
	v_max_f32_e32 v4, 0, v55
	v_max_f32_e32 v5, 0, v71
	v_max_f32_e32 v6, 0, v59
	v_max_f32_e32 v7, 0, v75
	v_max_f32_e32 v8, 0, v63
	v_max_f32_e32 v9, 0, v79
	v_max_f32_e32 v10, 0, v67
	v_max_f32_e32 v11, 0, v83
	v_pk_fma_f32 v[12:13], v[214:215], v[4:5], v[12:13] op_sel:[1,0,0]
	v_pk_fma_f32 v[14:15], v[218:219], v[6:7], v[14:15] op_sel:[1,0,0]
	v_pk_fma_f32 v[228:229], v[222:223], v[8:9], v[228:229] op_sel:[1,0,0]
	v_pk_fma_f32 v[230:231], v[226:227], v[10:11], v[230:231] op_sel:[1,0,0]
	s_nop 1
	v_permlane32_swap_b32_e32 v12, v13
	v_permlane32_swap_b32_e32 v14, v15
	v_permlane32_swap_b32_e32 v228, v229
	v_permlane32_swap_b32_e32 v230, v231
	v_add_f32_e32 v4, v12, v13
	v_add_f32_e32 v6, v14, v15
	v_add_f32_e32 v8, v228, v229
	v_add_f32_e32 v10, v230, v231
	v_ashrrev_i32_e32 v5, 31, v4
	v_ashrrev_i32_e32 v7, 31, v6
	v_ashrrev_i32_e32 v9, 31, v8
	v_ashrrev_i32_e32 v11, 31, v10
	v_or_b32_e32 v5, s31, v5
	v_or_b32_e32 v7, s31, v7
	v_or_b32_e32 v9, s31, v9
	v_or_b32_e32 v11, s31, v11
	v_xor_b32_e32 v180, v4, v5
	v_xor_b32_e32 v164, v6, v7
	v_xor_b32_e32 v143, v8, v9
	v_xor_b32_e32 v115, v10, v11
	s_cmp_lt_u32 s28, s3
	s_cbranch_scc1 .Lsc_n9
	v_lshl_add_u32 v118, s28, 6, v101
	v_cmp_lt_i32_e32 vcc, s44, v118
	s_nop 1
	v_cndmask_b32_e64 v180, v180, 0, vcc
	v_cmp_lt_i32_e32 vcc, s45, v118
	s_nop 1
	v_cndmask_b32_e64 v164, v164, 0, vcc
	v_cmp_lt_i32_e32 vcc, s46, v118
	s_nop 1
	v_cndmask_b32_e64 v143, v143, 0, vcc
	v_cmp_lt_i32_e32 vcc, s47, v118
	s_nop 1
	v_cndmask_b32_e64 v115, v115, 0, vcc

; DI void topk_job(const Params& p, int b, int t0, char* lds) {
;     ...
;         const int key = c * 64 + lane;
; #pragma unroll
;         for (int qi = 0; qi < 4; ++qi) {
;           f32x2 pp2 = {0.f, 0.f};
; #pragma unroll
;           for (int e = 0; e < 4; ++e) {
;             const f32x2 rl = {fmaxf(a0[4 * qi + e], 0.f), fmaxf(a1[4 * qi + e], 0.f)};
;             const f32x2 wv = {iw[qi][e], iw[qi][e]};
;             pp2 += rl * wv;
;           }
;           const float p0 = pp2[0], p1 = pp2[1];
;           const u32x2 sw = __builtin_amdgcn_permlane32_swap(__float_as_uint(p0), __float_as_uint(p1), false, false);
;           float mine = __uint_as_float(sw[0]) + __uint_as_float(sw[1]);
;           mine += 0.0f;
;           unsigned u = __float_as_uint(mine);
;           u = (u & 0x80000000u) ? ~u : (u | 0x80000000u);
;           if (key > t0 + qi || key < LEAD) u = 0u;
;           sc[i][qi] = u;
;         }
.Lsc_e10:
	s_nop 7
	s_nop 3
	v_max_f32_e32 v4, 0, v52
	v_max_f32_e32 v5, 0, v68
	v_max_f32_e32 v6, 0, v56
	v_max_f32_e32 v7, 0, v72
	v_max_f32_e32 v8, 0, v60
	v_max_f32_e32 v9, 0, v76
	v_max_f32_e32 v10, 0, v64
	v_max_f32_e32 v11, 0, v80
	v_pk_fma_f32 v[12:13], v[212:213], v[4:5], 0 op_sel_hi:[0,1,0]
	v_pk_fma_f32 v[14:15], v[216:217], v[6:7], 0 op_sel_hi:[0,1,0]
	v_pk_fma_f32 v[228:229], v[220:221], v[8:9], 0 op_sel_hi:[0,1,0]
	v_pk_fma_f32 v[230:231], v[224:225], v[10:11], 0 op_sel_hi:[0,1,0]
	v_max_f32_e32 v4, 0, v53
	v_max_f32_e32 v5, 0, v69
	v_max_f32_e32 v6, 0, v57
	v_max_f32_e32 v7, 0, v73
	v_max_f32_e32 v8, 0, v61
	v_max_f32_e32 v9, 0, v77
	v_max_f32_e32 v10, 0, v65
	v_max_f32_e32 v11, 0, v81
	v_pk_fma_f32 v[12:13], v[212:213], v[4:5], v[12:13] op_sel:[1,0,0]
	v_pk_fma_f32 v[14:15], v[216:217], v[6:7], v[14:15] op_sel:[1,0,0]
	v_pk_fma_f32 v[228:229], v[220:221], v[8:9], v[228:229] op_sel:[1,0,0]
	v_pk_fma_f32 v[230:231], v[224:225], v[10:11], v[230:231] op_sel:[1,0,0]
	v_max_f32_e32 v4, 0, v54
	v_max_f32_e32 v5, 0, v70
	v_max_f32_e32 v6, 0, v58
	v_max_f32_e32 v7, 0, v74
	v_max_f32_e32 v8, 0, v62
	v_max_f32_e32 v9, 0, v78
	v_max_f32_e32 v10, 0, v66
	v_max_f32_e32 v11, 0, v82
	v_pk_fma_f32 v[12:13], v[214:215], v[4:5], v[12:13] op_sel_hi:[0,1,1]
	v_pk_fma_f32 v[14:15], v[218:219], v[6:7], v[14:15] op_sel_hi:[0,1,1]
	v_pk_fma_f32 v[228:229], v[222:223], v[8:9], v[228:229] op_sel_hi:[0,1,1]
	v_pk_fma_f32 v[230:231], v[226:227], v[10:11], v[230:231] op_sel_hi:[0,1,1]
	v_max_f32_e32 v4, 0, v55
	v_max_f32_e32 v5, 0, v71
	v_max_f32_e32 v6, 0, v59
	v_max_f32_e32 v7, 0, v75
	v_max_f32_e32 v8, 0, v63
	v_max_f32_e32 v9, 0, v79
	v_max_f32_e32 v10, 0, v67
	v_max_f32_e32 v11, 0, v83
	v_pk_fma_f32 v[12:13], v[214:215], v[4:5], v[12:13] op_sel:[1,0,0]
	v_pk_fma_f32 v[14:15], v[218:219], v[6:7], v[14:15] op_sel:[1,0,0]
	v_pk_fma_f32 v[228:229], v[222:223], v[8:9], v[228:229] op_sel:[1,0,0]
	v_pk_fma_f32 v[230:231], v[226:227], v[10:11], v[230:231] op_sel:[1,0,0]
	s_nop 1
	v_permlane32_swap_b32_e32 v12, v13
	v_permlane32_swap_b32_e32 v14, v15
	v_permlane32_swap_b32_e32 v228, v229
	v_permlane32_swap_b32_e32 v230, v231
	v_add_f32_e32 v4, v12, v13
	v_add_f32_e32 v6, v14, v15
	v_add_f32_e32 v8, v228, v229
	v_add_f32_e32 v10, v230, v231
	v_ashrrev_i32_e32 v5, 31, v4
	v_ashrrev_i32_e32 v7, 31, v6
	v_ashrrev_i32_e32 v9, 31, v8
	v_ashrrev_i32_e32 v11, 31, v10
	v_or_b32_e32 v5, s31, v5
	v_or_b32_e32 v7, s31, v7
	v_or_b32_e32 v9, s31, v9
	v_or_b32_e32 v11, s31, v11
	v_xor_b32_e32 v179, v4, v5
	v_xor_b32_e32 v163, v6, v7
	v_xor_b32_e32 v142, v8, v9
	v_xor_b32_e32 v113, v10, v11
	s_cmp_lt_u32 s28, s3
	s_cbranch_scc1 .Lsc_n10
	v_lshl_add_u32 v118, s28, 6, v101
	v_cmp_lt_i32_e32 vcc, s44, v118
	s_nop 1
	v_cndmask_b32_e64 v179, v179, 0, vcc
	v_cmp_lt_i32_e32 vcc, s45, v118
	s_nop 1
	v_cndmask_b32_e64 v163, v163, 0, vcc
	v_cmp_lt_i32_e32 vcc, s46, v118
	s_nop 1
	v_cndmask_b32_e64 v142, v142, 0, vcc
	v_cmp_lt_i32_e32 vcc, s47, v118
	s_nop 1
	v_cndmask_b32_e64 v113, v113, 0, vcc

; DI void topk_job(const Params& p, int b, int t0, char* lds) {
;     ...
;         const int key = c * 64 + lane;
; #pragma unroll
;         for (int qi = 0; qi < 4; ++qi) {
;           f32x2 pp2 = {0.f, 0.f};
; #pragma unroll
;           for (int e = 0; e < 4; ++e) {
;             const f32x2 rl = {fmaxf(a0[4 * qi + e], 0.f), fmaxf(a1[4 * qi + e], 0.f)};
;             const f32x2 wv = {iw[qi][e], iw[qi][e]};
;             pp2 += rl * wv;
;           }
;           const float p0 = pp2[0], p1 = pp2[1];
;           const u32x2 sw = __builtin_amdgcn_permlane32_swap(__float_as_uint(p0), __float_as_uint(p1), false, false);
;           float mine = __uint_as_float(sw[0]) + __uint_as_float(sw[1]);
;           mine += 0.0f;
;           unsigned u = __float_as_uint(mine);
;           u = (u & 0x80000000u) ? ~u : (u | 0x80000000u);
;           if (key > t0 + qi || key < LEAD) u = 0u;
;           sc[i][qi] = u;
;         }
.Lsc_e11:
	s_nop 7
	s_nop 3
	v_max_f32_e32 v4, 0, v52
	v_max_f32_e32 v5, 0, v68
	v_max_f32_e32 v6, 0, v56
	v_max_f32_e32 v7, 0, v72
	v_max_f32_e32 v8, 0, v60
	v_max_f32_e32 v9, 0, v76
	v_max_f32_e32 v10, 0, v64
	v_max_f32_e32 v11, 0, v80
	v_pk_fma_f32 v[12:13], v[212:213], v[4:5], 0 op_sel_hi:[0,1,0]
	v_pk_fma_f32 v[14:15], v[216:217], v[6:7], 0 op_sel_hi:[0,1,0]
	v_pk_fma_f32 v[228:229], v[220:221], v[8:9], 0 op_sel_hi:[0,1,0]
	v_pk_fma_f32 v[230:231], v[224:225], v[10:11], 0 op_sel_hi:[0,1,0]
	v_max_f32_e32 v4, 0, v53
	v_max_f32_e32 v5, 0, v69
	v_max_f32_e32 v6, 0, v57
	v_max_f32_e32 v7, 0, v73
	v_max_f32_e32 v8, 0, v61
	v_max_f32_e32 v9, 0, v77
	v_max_f32_e32 v10, 0, v65
	v_max_f32_e32 v11, 0, v81
	v_pk_fma_f32 v[12:13], v[212:213], v[4:5], v[12:13] op_sel:[1,0,0]
	v_pk_fma_f32 v[14:15], v[216:217], v[6:7], v[14:15] op_sel:[1,0,0]
	v_pk_fma_f32 v[228:229], v[220:221], v[8:9], v[228:229] op_sel:[1,0,0]
	v_pk_fma_f32 v[230:231], v[224:225], v[10:11], v[230:231] op_sel:[1,0,0]
	v_max_f32_e32 v4, 0, v54
	v_max_f32_e32 v5, 0, v70
	v_max_f32_e32 v6, 0, v58
	v_max_f32_e32 v7, 0, v74
	v_max_f32_e32 v8, 0, v62
	v_max_f32_e32 v9, 0, v78
	v_max_f32_e32 v10, 0, v66
	v_max_f32_e32 v11, 0, v82
	v_pk_fma_f32 v[12:13], v[214:215], v[4:5], v[12:13] op_sel_hi:[0,1,1]
	v_pk_fma_f32 v[14:15], v[218:219], v[6:7], v[14:15] op_sel_hi:[0,1,1]
	v_pk_fma_f32 v[228:229], v[222:223], v[8:9], v[228:229] op_sel_hi:[0,1,1]
	v_pk_fma_f32 v[230:231], v[226:227], v[10:11], v[230:231] op_sel_hi:[0,1,1]
	v_max_f32_e32 v4, 0, v55
	v_max_f32_e32 v5, 0, v71
	v_max_f32_e32 v6, 0, v59
	v_max_f32_e32 v7, 0, v75
	v_max_f32_e32 v8, 0, v63
	v_max_f32_e32 v9, 0, v79
	v_max_f32_e32 v10, 0, v67
	v_max_f32_e32 v11, 0, v83
	v_pk_fma_f32 v[12:13], v[214:215], v[4:5], v[12:13] op_sel:[1,0,0]
	v_pk_fma_f32 v[14:15], v[218:219], v[6:7], v[14:15] op_sel:[1,0,0]
	v_pk_fma_f32 v[228:229], v[222:223], v[8:9], v[228:229] op_sel:[1,0,0]
	v_pk_fma_f32 v[230:231], v[226:227], v[10:11], v[230:231] op_sel:[1,0,0]
	s_nop 1
	v_permlane32_swap_b32_e32 v12, v13
	v_permlane32_swap_b32_e32 v14, v15
	v_permlane32_swap_b32_e32 v228, v229
	v_permlane32_swap_b32_e32 v230, v231
	v_add_f32_e32 v4, v12, v13
	v_add_f32_e32 v6, v14, v15
	v_add_f32_e32 v8, v228, v229
	v_add_f32_e32 v10, v230, v231
	v_ashrrev_i32_e32 v5, 31, v4
	v_ashrrev_i32_e32 v7, 31, v6
	v_ashrrev_i32_e32 v9, 31, v8
	v_ashrrev_i32_e32 v11, 31, v10
	v_or_b32_e32 v5, s31, v5
	v_or_b32_e32 v7, s31, v7
	v_or_b32_e32 v9, s31, v9
	v_or_b32_e32 v11, s31, v11
	v_xor_b32_e32 v178, v4, v5
	v_xor_b32_e32 v162, v6, v7
	v_xor_b32_e32 v141, v8, v9
	v_xor_b32_e32 v111, v10, v11
	s_cmp_lt_u32 s28, s3
	s_cbranch_scc1 .Lsc_n11
	v_lshl_add_u32 v118, s28, 6, v101
	v_cmp_lt_i32_e32 vcc, s44, v118
	s_nop 1
	v_cndmask_b32_e64 v178, v178, 0, vcc
	v_cmp_lt_i32_e32 vcc, s45, v118
	s_nop 1
	v_cndmask_b32_e64 v162, v162, 0, vcc
	v_cmp_lt_i32_e32 vcc, s46, v118
	s_nop 1
	v_cndmask_b32_e64 v141, v141, 0, vcc
	v_cmp_lt_i32_e32 vcc, s47, v118
	s_nop 1
	v_cndmask_b32_e64 v111, v111, 0, vcc

; DI void topk_job(const Params& p, int b, int t0, char* lds) {
;     ...
;         const int key = c * 64 + lane;
; #pragma unroll
;         for (int qi = 0; qi < 4; ++qi) {
;           f32x2 pp2 = {0.f, 0.f};
; #pragma unroll
;           for (int e = 0; e < 4; ++e) {
;             const f32x2 rl = {fmaxf(a0[4 * qi + e], 0.f), fmaxf(a1[4 * qi + e], 0.f)};
;             const f32x2 wv = {iw[qi][e], iw[qi][e]};
;             pp2 += rl * wv;
;           }
;           const float p0 = pp2[0], p1 = pp2[1];
;           const u32x2 sw = __builtin_amdgcn_permlane32_swap(__float_as_uint(p0), __float_as_uint(p1), false, false);
;           float mine = __uint_as_float(sw[0]) + __uint_as_float(sw[1]);
;           mine += 0.0f;
;           unsigned u = __float_as_uint(mine);
;           u = (u & 0x80000000u) ? ~u : (u | 0x80000000u);
;           if (key > t0 + qi || key < LEAD) u = 0u;
;           sc[i][qi] = u;
;         }
.Lsc_e12:
	s_nop 7
	s_nop 3
	v_max_f32_e32 v4, 0, v52
	v_max_f32_e32 v5, 0, v68
	v_max_f32_e32 v6, 0, v56
	v_max_f32_e32 v7, 0, v72
	v_max_f32_e32 v8, 0, v60
	v_max_f32_e32 v9, 0, v76
	v_max_f32_e32 v10, 0, v64
	v_max_f32_e32 v11, 0, v80
	v_pk_fma_f32 v[12:13], v[212:213], v[4:5], 0 op_sel_hi:[0,1,0]
	v_pk_fma_f32 v[14:15], v[216:217], v[6:7], 0 op_sel_hi:[0,1,0]
	v_pk_fma_f32 v[228:229], v[220:221], v[8:9], 0 op_sel_hi:[0,1,0]
	v_pk_fma_f32 v[230:231], v[224:225], v[10:11], 0 op_sel_hi:[0,1,0]
	v_max_f32_e32 v4, 0, v53
	v_max_f32_e32 v5, 0, v69
	v_max_f32_e32 v6, 0, v57
	v_max_f32_e32 v7, 0, v73
	v_max_f32_e32 v8, 0, v61
	v_max_f32_e32 v9, 0, v77
	v_max_f32_e32 v10, 0, v65
	v_max_f32_e32 v11, 0, v81
	v_pk_fma_f32 v[12:13], v[212:213], v[4:5], v[12:13] op_sel:[1,0,0]
	v_pk_fma_f32 v[14:15], v[216:217], v[6:7], v[14:15] op_sel:[1,0,0]
	v_pk_fma_f32 v[228:229], v[220:221], v[8:9], v[228:229] op_sel:[1,0,0]
	v_pk_fma_f32 v[230:231], v[224:225], v[10:11], v[230:231] op_sel:[1,0,0]
	v_max_f32_e32 v4, 0, v54
	v_max_f32_e32 v5, 0, v70
	v_max_f32_e32 v6, 0, v58
	v_max_f32_e32 v7, 0, v74
	v_max_f32_e32 v8, 0, v62
	v_max_f32_e32 v9, 0, v78
	v_max_f32_e32 v10, 0, v66
	v_max_f32_e32 v11, 0, v82
	v_pk_fma_f32 v[12:13], v[214:215], v[4:5], v[12:13] op_sel_hi:[0,1,1]
	v_pk_fma_f32 v[14:15], v[218:219], v[6:7], v[14:15] op_sel_hi:[0,1,1]
	v_pk_fma_f32 v[228:229], v[222:223], v[8:9], v[228:229] op_sel_hi:[0,1,1]
	v_pk_fma_f32 v[230:231], v[226:227], v[10:11], v[230:231] op_sel_hi:[0,1,1]
	v_max_f32_e32 v4, 0, v55
	v_max_f32_e32 v5, 0, v71
	v_max_f32_e32 v6, 0, v59
	v_max_f32_e32 v7, 0, v75
	v_max_f32_e32 v8, 0, v63
	v_max_f32_e32 v9, 0, v79
	v_max_f32_e32 v10, 0, v67
	v_max_f32_e32 v11, 0, v83
	v_pk_fma_f32 v[12:13], v[214:215], v[4:5], v[12:13] op_sel:[1,0,0]
	v_pk_fma_f32 v[14:15], v[218:219], v[6:7], v[14:15] op_sel:[1,0,0]
	v_pk_fma_f32 v[228:229], v[222:223], v[8:9], v[228:229] op_sel:[1,0,0]
	v_pk_fma_f32 v[230:231], v[226:227], v[10:11], v[230:231] op_sel:[1,0,0]
	s_nop 1
	v_permlane32_swap_b32_e32 v12, v13
	v_permlane32_swap_b32_e32 v14, v15
	v_permlane32_swap_b32_e32 v228, v229
	v_permlane32_swap_b32_e32 v230, v231
	v_add_f32_e32 v4, v12, v13
	v_add_f32_e32 v6, v14, v15
	v_add_f32_e32 v8, v228, v229
	v_add_f32_e32 v10, v230, v231
	v_ashrrev_i32_e32 v5, 31, v4
	v_ashrrev_i32_e32 v7, 31, v6
	v_ashrrev_i32_e32 v9, 31, v8
	v_ashrrev_i32_e32 v11, 31, v10
	v_or_b32_e32 v5, s31, v5
	v_or_b32_e32 v7, s31, v7
	v_or_b32_e32 v9, s31, v9
	v_or_b32_e32 v11, s31, v11
	v_xor_b32_e32 v177, v4, v5
	v_xor_b32_e32 v160, v6, v7
	v_xor_b32_e32 v140, v8, v9
	v_xor_b32_e32 v109, v10, v11
	s_cmp_lt_u32 s28, s3
	s_cbranch_scc1 .Lsc_n12
	v_lshl_add_u32 v118, s28, 6, v101
	v_cmp_lt_i32_e32 vcc, s44, v118
	s_nop 1
	v_cndmask_b32_e64 v177, v177, 0, vcc
	v_cmp_lt_i32_e32 vcc, s45, v118
	s_nop 1
	v_cndmask_b32_e64 v160, v160, 0, vcc
	v_cmp_lt_i32_e32 vcc, s46, v118
	s_nop 1
	v_cndmask_b32_e64 v140, v140, 0, vcc
	v_cmp_lt_i32_e32 vcc, s47, v118
	s_nop 1
	v_cndmask_b32_e64 v109, v109, 0, vcc

; DI void topk_job(const Params& p, int b, int t0, char* lds) {
;     ...
;         const int key = c * 64 + lane;
; #pragma unroll
;         for (int qi = 0; qi < 4; ++qi) {
;           f32x2 pp2 = {0.f, 0.f};
; #pragma unroll
;           for (int e = 0; e < 4; ++e) {
;             const f32x2 rl = {fmaxf(a0[4 * qi + e], 0.f), fmaxf(a1[4 * qi + e], 0.f)};
;             const f32x2 wv = {iw[qi][e], iw[qi][e]};
;             pp2 += rl * wv;
;           }
;           const float p0 = pp2[0], p1 = pp2[1];
;           const u32x2 sw = __builtin_amdgcn_permlane32_swap(__float_as_uint(p0), __float_as_uint(p1), false, false);
;           float mine = __uint_as_float(sw[0]) + __uint_as_float(sw[1]);
;           mine += 0.0f;
;           unsigned u = __float_as_uint(mine);
;           u = (u & 0x80000000u) ? ~u : (u | 0x80000000u);
;           if (key > t0 + qi || key < LEAD) u = 0u;
;           sc[i][qi] = u;
;         }
.Lsc_e13:
	s_nop 7
	s_nop 3
	v_max_f32_e32 v4, 0, v52
	v_max_f32_e32 v5, 0, v68
	v_max_f32_e32 v6, 0, v56
	v_max_f32_e32 v7, 0, v72
	v_max_f32_e32 v8, 0, v60
	v_max_f32_e32 v9, 0, v76
	v_max_f32_e32 v10, 0, v64
	v_max_f32_e32 v11, 0, v80
	v_pk_fma_f32 v[12:13], v[212:213], v[4:5], 0 op_sel_hi:[0,1,0]
	v_pk_fma_f32 v[14:15], v[216:217], v[6:7], 0 op_sel_hi:[0,1,0]
	v_pk_fma_f32 v[228:229], v[220:221], v[8:9], 0 op_sel_hi:[0,1,0]
	v_pk_fma_f32 v[230:231], v[224:225], v[10:11], 0 op_sel_hi:[0,1,0]
	v_max_f32_e32 v4, 0, v53
	v_max_f32_e32 v5, 0, v69
	v_max_f32_e32 v6, 0, v57
	v_max_f32_e32 v7, 0, v73
	v_max_f32_e32 v8, 0, v61
	v_max_f32_e32 v9, 0, v77
	v_max_f32_e32 v10, 0, v65
	v_max_f32_e32 v11, 0, v81
	v_pk_fma_f32 v[12:13], v[212:213], v[4:5], v[12:13] op_sel:[1,0,0]
	v_pk_fma_f32 v[14:15], v[216:217], v[6:7], v[14:15] op_sel:[1,0,0]
	v_pk_fma_f32 v[228:229], v[220:221], v[8:9], v[228:229] op_sel:[1,0,0]
	v_pk_fma_f32 v[230:231], v[224:225], v[10:11], v[230:231] op_sel:[1,0,0]
	v_max_f32_e32 v4, 0, v54
	v_max_f32_e32 v5, 0, v70
	v_max_f32_e32 v6, 0, v58
	v_max_f32_e32 v7, 0, v74
	v_max_f32_e32 v8, 0, v62
	v_max_f32_e32 v9, 0, v78
	v_max_f32_e32 v10, 0, v66
	v_max_f32_e32 v11, 0, v82
	v_pk_fma_f32 v[12:13], v[214:215], v[4:5], v[12:13] op_sel_hi:[0,1,1]
	v_pk_fma_f32 v[14:15], v[218:219], v[6:7], v[14:15] op_sel_hi:[0,1,1]
	v_pk_fma_f32 v[228:229], v[222:223], v[8:9], v[228:229] op_sel_hi:[0,1,1]
	v_pk_fma_f32 v[230:231], v[226:227], v[10:11], v[230:231] op_sel_hi:[0,1,1]
	v_max_f32_e32 v4, 0, v55
	v_max_f32_e32 v5, 0, v71
	v_max_f32_e32 v6, 0, v59
	v_max_f32_e32 v7, 0, v75
	v_max_f32_e32 v8, 0, v63
	v_max_f32_e32 v9, 0, v79
	v_max_f32_e32 v10, 0, v67
	v_max_f32_e32 v11, 0, v83
	v_pk_fma_f32 v[12:13], v[214:215], v[4:5], v[12:13] op_sel:[1,0,0]
	v_pk_fma_f32 v[14:15], v[218:219], v[6:7], v[14:15] op_sel:[1,0,0]
	v_pk_fma_f32 v[228:229], v[222:223], v[8:9], v[228:229] op_sel:[1,0,0]
	v_pk_fma_f32 v[230:231], v[226:227], v[10:11], v[230:231] op_sel:[1,0,0]
	s_nop 1
	v_permlane32_swap_b32_e32 v12, v13
	v_permlane32_swap_b32_e32 v14, v15
	v_permlane32_swap_b32_e32 v228, v229
	v_permlane32_swap_b32_e32 v230, v231
	v_add_f32_e32 v4, v12, v13
	v_add_f32_e32 v6, v14, v15
	v_add_f32_e32 v8, v228, v229
	v_add_f32_e32 v10, v230, v231
	v_ashrrev_i32_e32 v5, 31, v4
	v_ashrrev_i32_e32 v7, 31, v6
	v_ashrrev_i32_e32 v9, 31, v8
	v_ashrrev_i32_e32 v11, 31, v10
	v_or_b32_e32 v5, s31, v5
	v_or_b32_e32 v7, s31, v7
	v_or_b32_e32 v9, s31, v9
	v_or_b32_e32 v11, s31, v11
	v_xor_b32_e32 v176, v4, v5
	v_xor_b32_e32 v151, v6, v7
	v_xor_b32_e32 v139, v8, v9
	v_xor_b32_e32 v107, v10, v11
	s_cmp_lt_u32 s28, s3
	s_cbranch_scc1 .Lsc_n13
	v_lshl_add_u32 v118, s28, 6, v101
	v_cmp_lt_i32_e32 vcc, s44, v118
	s_nop 1
	v_cndmask_b32_e64 v176, v176, 0, vcc
	v_cmp_lt_i32_e32 vcc, s45, v118
	s_nop 1
	v_cndmask_b32_e64 v151, v151, 0, vcc
	v_cmp_lt_i32_e32 vcc, s46, v118
	s_nop 1
	v_cndmask_b32_e64 v139, v139, 0, vcc
	v_cmp_lt_i32_e32 vcc, s47, v118
	s_nop 1
	v_cndmask_b32_e64 v107, v107, 0, vcc

; DI void topk_job(const Params& p, int b, int t0, char* lds) {
;     ...
;         const int key = c * 64 + lane;
; #pragma unroll
;         for (int qi = 0; qi < 4; ++qi) {
;           f32x2 pp2 = {0.f, 0.f};
; #pragma unroll
;           for (int e = 0; e < 4; ++e) {
;             const f32x2 rl = {fmaxf(a0[4 * qi + e], 0.f), fmaxf(a1[4 * qi + e], 0.f)};
;             const f32x2 wv = {iw[qi][e], iw[qi][e]};
;             pp2 += rl * wv;
;           }
;           const float p0 = pp2[0], p1 = pp2[1];
;           const u32x2 sw = __builtin_amdgcn_permlane32_swap(__float_as_uint(p0), __float_as_uint(p1), false, false);
;           float mine = __uint_as_float(sw[0]) + __uint_as_float(sw[1]);
;           mine += 0.0f;
;           unsigned u = __float_as_uint(mine);
;           u = (u & 0x80000000u) ? ~u : (u | 0x80000000u);
;           if (key > t0 + qi || key < LEAD) u = 0u;
;           sc[i][qi] = u;
;         }
.Lsc_e14:
	s_nop 7
	s_nop 3
	v_max_f32_e32 v4, 0, v52
	v_max_f32_e32 v5, 0, v68
	v_max_f32_e32 v6, 0, v56
	v_max_f32_e32 v7, 0, v72
	v_max_f32_e32 v8, 0, v60
	v_max_f32_e32 v9, 0, v76
	v_max_f32_e32 v10, 0, v64
	v_max_f32_e32 v11, 0, v80
	v_pk_fma_f32 v[12:13], v[212:213], v[4:5], 0 op_sel_hi:[0,1,0]
	v_pk_fma_f32 v[14:15], v[216:217], v[6:7], 0 op_sel_hi:[0,1,0]
	v_pk_fma_f32 v[228:229], v[220:221], v[8:9], 0 op_sel_hi:[0,1,0]
	v_pk_fma_f32 v[230:231], v[224:225], v[10:11], 0 op_sel_hi:[0,1,0]
	v_max_f32_e32 v4, 0, v53
	v_max_f32_e32 v5, 0, v69
	v_max_f32_e32 v6, 0, v57
	v_max_f32_e32 v7, 0, v73
	v_max_f32_e32 v8, 0, v61
	v_max_f32_e32 v9, 0, v77
	v_max_f32_e32 v10, 0, v65
	v_max_f32_e32 v11, 0, v81
	v_pk_fma_f32 v[12:13], v[212:213], v[4:5], v[12:13] op_sel:[1,0,0]
	v_pk_fma_f32 v[14:15], v[216:217], v[6:7], v[14:15] op_sel:[1,0,0]
	v_pk_fma_f32 v[228:229], v[220:221], v[8:9], v[228:229] op_sel:[1,0,0]
	v_pk_fma_f32 v[230:231], v[224:225], v[10:11], v[230:231] op_sel:[1,0,0]
	v_max_f32_e32 v4, 0, v54
	v_max_f32_e32 v5, 0, v70
	v_max_f32_e32 v6, 0, v58
	v_max_f32_e32 v7, 0, v74
	v_max_f32_e32 v8, 0, v62
	v_max_f32_e32 v9, 0, v78
	v_max_f32_e32 v10, 0, v66
	v_max_f32_e32 v11, 0, v82
	v_pk_fma_f32 v[12:13], v[214:215], v[4:5], v[12:13] op_sel_hi:[0,1,1]
	v_pk_fma_f32 v[14:15], v[218:219], v[6:7], v[14:15] op_sel_hi:[0,1,1]
	v_pk_fma_f32 v[228:229], v[222:223], v[8:9], v[228:229] op_sel_hi:[0,1,1]
	v_pk_fma_f32 v[230:231], v[226:227], v[10:11], v[230:231] op_sel_hi:[0,1,1]
	v_max_f32_e32 v4, 0, v55
	v_max_f32_e32 v5, 0, v71
	v_max_f32_e32 v6, 0, v59
	v_max_f32_e32 v7, 0, v75
	v_max_f32_e32 v8, 0, v63
	v_max_f32_e32 v9, 0, v79
	v_max_f32_e32 v10, 0, v67
	v_max_f32_e32 v11, 0, v83
	v_pk_fma_f32 v[12:13], v[214:215], v[4:5], v[12:13] op_sel:[1,0,0]
	v_pk_fma_f32 v[14:15], v[218:219], v[6:7], v[14:15] op_sel:[1,0,0]
	v_pk_fma_f32 v[228:229], v[222:223], v[8:9], v[228:229] op_sel:[1,0,0]
	v_pk_fma_f32 v[230:231], v[226:227], v[10:11], v[230:231] op_sel:[1,0,0]
	s_nop 1
	v_permlane32_swap_b32_e32 v12, v13
	v_permlane32_swap_b32_e32 v14, v15
	v_permlane32_swap_b32_e32 v228, v229
	v_permlane32_swap_b32_e32 v230, v231
	v_add_f32_e32 v4, v12, v13
	v_add_f32_e32 v6, v14, v15
	v_add_f32_e32 v8, v228, v229
	v_add_f32_e32 v10, v230, v231
	v_ashrrev_i32_e32 v5, 31, v4
	v_ashrrev_i32_e32 v7, 31, v6
	v_ashrrev_i32_e32 v9, 31, v8
	v_ashrrev_i32_e32 v11, 31, v10
	v_or_b32_e32 v5, s31, v5
	v_or_b32_e32 v7, s31, v7
	v_or_b32_e32 v9, s31, v9
	v_or_b32_e32 v11, s31, v11
	v_xor_b32_e32 v174, v4, v5
	v_xor_b32_e32 v148, v6, v7
	v_xor_b32_e32 v131, v8, v9
	v_xor_b32_e32 v105, v10, v11
	s_cmp_lt_u32 s28, s3
	s_cbranch_scc1 .Lsc_n14
	v_lshl_add_u32 v118, s28, 6, v101
	v_cmp_lt_i32_e32 vcc, s44, v118
	s_nop 1
	v_cndmask_b32_e64 v174, v174, 0, vcc
	v_cmp_lt_i32_e32 vcc, s45, v118
	s_nop 1
	v_cndmask_b32_e64 v148, v148, 0, vcc
	v_cmp_lt_i32_e32 vcc, s46, v118
	s_nop 1
	v_cndmask_b32_e64 v131, v131, 0, vcc
	v_cmp_lt_i32_e32 vcc, s47, v118
	s_nop 1
	v_cndmask_b32_e64 v105, v105, 0, vcc

; DI void topk_job(const Params& p, int b, int t0, char* lds) {
;     ...
;         const int key = c * 64 + lane;
; #pragma unroll
;         for (int qi = 0; qi < 4; ++qi) {
;           f32x2 pp2 = {0.f, 0.f};
; #pragma unroll
;           for (int e = 0; e < 4; ++e) {
;             const f32x2 rl = {fmaxf(a0[4 * qi + e], 0.f), fmaxf(a1[4 * qi + e], 0.f)};
;             const f32x2 wv = {iw[qi][e], iw[qi][e]};
;             pp2 += rl * wv;
;           }
;           const float p0 = pp2[0], p1 = pp2[1];
;           const u32x2 sw = __builtin_amdgcn_permlane32_swap(__float_as_uint(p0), __float_as_uint(p1), false, false);
;           float mine = __uint_as_float(sw[0]) + __uint_as_float(sw[1]);
;           mine += 0.0f;
;           unsigned u = __float_as_uint(mine);
;           u = (u & 0x80000000u) ? ~u : (u | 0x80000000u);
;           if (key > t0 + qi || key < LEAD) u = 0u;
;           sc[i][qi] = u;
;         }
.Lsc_e15:
	s_nop 7
	s_nop 3
	v_max_f32_e32 v4, 0, v52
	v_max_f32_e32 v5, 0, v68
	v_max_f32_e32 v6, 0, v56
	v_max_f32_e32 v7, 0, v72
	v_max_f32_e32 v8, 0, v60
	v_max_f32_e32 v9, 0, v76
	v_max_f32_e32 v10, 0, v64
	v_max_f32_e32 v11, 0, v80
	v_pk_fma_f32 v[12:13], v[212:213], v[4:5], 0 op_sel_hi:[0,1,0]
	v_pk_fma_f32 v[14:15], v[216:217], v[6:7], 0 op_sel_hi:[0,1,0]
	v_pk_fma_f32 v[228:229], v[220:221], v[8:9], 0 op_sel_hi:[0,1,0]
	v_pk_fma_f32 v[230:231], v[224:225], v[10:11], 0 op_sel_hi:[0,1,0]
	v_max_f32_e32 v4, 0, v53
	v_max_f32_e32 v5, 0, v69
	v_max_f32_e32 v6, 0, v57
	v_max_f32_e32 v7, 0, v73
	v_max_f32_e32 v8, 0, v61
	v_max_f32_e32 v9, 0, v77
	v_max_f32_e32 v10, 0, v65
	v_max_f32_e32 v11, 0, v81
	v_pk_fma_f32 v[12:13], v[212:213], v[4:5], v[12:13] op_sel:[1,0,0]
	v_pk_fma_f32 v[14:15], v[216:217], v[6:7], v[14:15] op_sel:[1,0,0]
	v_pk_fma_f32 v[228:229], v[220:221], v[8:9], v[228:229] op_sel:[1,0,0]
	v_pk_fma_f32 v[230:231], v[224:225], v[10:11], v[230:231] op_sel:[1,0,0]
	v_max_f32_e32 v4, 0, v54
	v_max_f32_e32 v5, 0, v70
	v_max_f32_e32 v6, 0, v58
	v_max_f32_e32 v7, 0, v74
	v_max_f32_e32 v8, 0, v62
	v_max_f32_e32 v9, 0, v78
	v_max_f32_e32 v10, 0, v66
	v_max_f32_e32 v11, 0, v82
	v_pk_fma_f32 v[12:13], v[214:215], v[4:5], v[12:13] op_sel_hi:[0,1,1]
	v_pk_fma_f32 v[14:15], v[218:219], v[6:7], v[14:15] op_sel_hi:[0,1,1]
	v_pk_fma_f32 v[228:229], v[222:223], v[8:9], v[228:229] op_sel_hi:[0,1,1]
	v_pk_fma_f32 v[230:231], v[226:227], v[10:11], v[230:231] op_sel_hi:[0,1,1]
	v_max_f32_e32 v4, 0, v55
	v_max_f32_e32 v5, 0, v71
	v_max_f32_e32 v6, 0, v59
	v_max_f32_e32 v7, 0, v75
	v_max_f32_e32 v8, 0, v63
	v_max_f32_e32 v9, 0, v79
	v_max_f32_e32 v10, 0, v67
	v_max_f32_e32 v11, 0, v83
	v_pk_fma_f32 v[12:13], v[214:215], v[4:5], v[12:13] op_sel:[1,0,0]
	v_pk_fma_f32 v[14:15], v[218:219], v[6:7], v[14:15] op_sel:[1,0,0]
	v_pk_fma_f32 v[228:229], v[222:223], v[8:9], v[228:229] op_sel:[1,0,0]
	v_pk_fma_f32 v[230:231], v[226:227], v[10:11], v[230:231] op_sel:[1,0,0]
	s_nop 1
	v_permlane32_swap_b32_e32 v12, v13
	v_permlane32_swap_b32_e32 v14, v15
	v_permlane32_swap_b32_e32 v228, v229
	v_permlane32_swap_b32_e32 v230, v231
	v_add_f32_e32 v4, v12, v13
	v_add_f32_e32 v6, v14, v15
	v_add_f32_e32 v8, v228, v229
	v_add_f32_e32 v10, v230, v231
	v_ashrrev_i32_e32 v5, 31, v4
	v_ashrrev_i32_e32 v7, 31, v6
	v_ashrrev_i32_e32 v9, 31, v8
	v_ashrrev_i32_e32 v11, 31, v10
	v_or_b32_e32 v5, s31, v5
	v_or_b32_e32 v7, s31, v7
	v_or_b32_e32 v9, s31, v9
	v_or_b32_e32 v11, s31, v11
	v_xor_b32_e32 v169, v4, v5
	v_xor_b32_e32 v144, v6, v7
	v_xor_b32_e32 v117, v8, v9
	v_xor_b32_e32 v103, v10, v11
	s_cmp_lt_u32 s28, s3
	s_cbranch_scc1 .Lsc_n15
	v_lshl_add_u32 v118, s28, 6, v101
	v_cmp_lt_i32_e32 vcc, s44, v118
	s_nop 1
	v_cndmask_b32_e64 v169, v169, 0, vcc
	v_cmp_lt_i32_e32 vcc, s45, v118
	s_nop 1
	v_cndmask_b32_e64 v144, v144, 0, vcc
	v_cmp_lt_i32_e32 vcc, s46, v118
	s_nop 1
	v_cndmask_b32_e64 v117, v117, 0, vcc
	v_cmp_lt_i32_e32 vcc, s47, v118
	s_nop 1
	v_cndmask_b32_e64 v103, v103, 0, vcc

; DI void topk_job(const Params& p, int b, int t0, char* lds) {
;     ...
;         const int key = c * 64 + lane;
; #pragma unroll
;         for (int qi = 0; qi < 4; ++qi) {
;           f32x2 pp2 = {0.f, 0.f};
; #pragma unroll
;           for (int e = 0; e < 4; ++e) {
;             const f32x2 rl = {fmaxf(a0[4 * qi + e], 0.f), fmaxf(a1[4 * qi + e], 0.f)};
;             const f32x2 wv = {iw[qi][e], iw[qi][e]};
;             pp2 += rl * wv;
;           }
;           const float p0 = pp2[0], p1 = pp2[1];
;           const u32x2 sw = __builtin_amdgcn_permlane32_swap(__float_as_uint(p0), __float_as_uint(p1), false, false);
;           float mine = __uint_as_float(sw[0]) + __uint_as_float(sw[1]);
;           mine += 0.0f;
;           unsigned u = __float_as_uint(mine);
;           u = (u & 0x80000000u) ? ~u : (u | 0x80000000u);
;           if (key > t0 + qi || key < LEAD) u = 0u;
;           sc[i][qi] = u;
;         }
.Lsc_e16:
	s_nop 7
	s_nop 3
	v_max_f32_e32 v4, 0, v52
	v_max_f32_e32 v5, 0, v68
	v_max_f32_e32 v6, 0, v56
	v_max_f32_e32 v7, 0, v72
	v_max_f32_e32 v8, 0, v60
	v_max_f32_e32 v9, 0, v76
	v_max_f32_e32 v10, 0, v64
	v_max_f32_e32 v11, 0, v80
	v_pk_fma_f32 v[12:13], v[212:213], v[4:5], 0 op_sel_hi:[0,1,0]
	v_pk_fma_f32 v[14:15], v[216:217], v[6:7], 0 op_sel_hi:[0,1,0]
	v_pk_fma_f32 v[228:229], v[220:221], v[8:9], 0 op_sel_hi:[0,1,0]
	v_pk_fma_f32 v[230:231], v[224:225], v[10:11], 0 op_sel_hi:[0,1,0]
	v_max_f32_e32 v4, 0, v53
	v_max_f32_e32 v5, 0, v69
	v_max_f32_e32 v6, 0, v57
	v_max_f32_e32 v7, 0, v73
	v_max_f32_e32 v8, 0, v61
	v_max_f32_e32 v9, 0, v77
	v_max_f32_e32 v10, 0, v65
	v_max_f32_e32 v11, 0, v81
	v_pk_fma_f32 v[12:13], v[212:213], v[4:5], v[12:13] op_sel:[1,0,0]
	v_pk_fma_f32 v[14:15], v[216:217], v[6:7], v[14:15] op_sel:[1,0,0]
	v_pk_fma_f32 v[228:229], v[220:221], v[8:9], v[228:229] op_sel:[1,0,0]
	v_pk_fma_f32 v[230:231], v[224:225], v[10:11], v[230:231] op_sel:[1,0,0]
	v_max_f32_e32 v4, 0, v54
	v_max_f32_e32 v5, 0, v70
	v_max_f32_e32 v6, 0, v58
	v_max_f32_e32 v7, 0, v74
	v_max_f32_e32 v8, 0, v62
	v_max_f32_e32 v9, 0, v78
	v_max_f32_e32 v10, 0, v66
	v_max_f32_e32 v11, 0, v82
	v_pk_fma_f32 v[12:13], v[214:215], v[4:5], v[12:13] op_sel_hi:[0,1,1]
	v_pk_fma_f32 v[14:15], v[218:219], v[6:7], v[14:15] op_sel_hi:[0,1,1]
	v_pk_fma_f32 v[228:229], v[222:223], v[8:9], v[228:229] op_sel_hi:[0,1,1]
	v_pk_fma_f32 v[230:231], v[226:227], v[10:11], v[230:231] op_sel_hi:[0,1,1]
	v_max_f32_e32 v4, 0, v55
	v_max_f32_e32 v5, 0, v71
	v_max_f32_e32 v6, 0, v59
	v_max_f32_e32 v7, 0, v75
	v_max_f32_e32 v8, 0, v63
	v_max_f32_e32 v9, 0, v79
	v_max_f32_e32 v10, 0, v67
	v_max_f32_e32 v11, 0, v83
	v_pk_fma_f32 v[12:13], v[214:215], v[4:5], v[12:13] op_sel:[1,0,0]
	v_pk_fma_f32 v[14:15], v[218:219], v[6:7], v[14:15] op_sel:[1,0,0]
	v_pk_fma_f32 v[228:229], v[222:223], v[8:9], v[228:229] op_sel:[1,0,0]
	v_pk_fma_f32 v[230:231], v[226:227], v[10:11], v[230:231] op_sel:[1,0,0]
	s_nop 1
	v_permlane32_swap_b32_e32 v12, v13
	v_permlane32_swap_b32_e32 v14, v15
	v_permlane32_swap_b32_e32 v228, v229
	v_permlane32_swap_b32_e32 v230, v231
	v_add_f32_e32 v4, v12, v13
	v_add_f32_e32 v6, v14, v15
	v_add_f32_e32 v8, v228, v229
	v_add_f32_e32 v10, v230, v231
	v_ashrrev_i32_e32 v5, 31, v4
	v_ashrrev_i32_e32 v7, 31, v6
	v_ashrrev_i32_e32 v9, 31, v8
	v_ashrrev_i32_e32 v11, 31, v10
	v_or_b32_e32 v5, s31, v5
	v_or_b32_e32 v7, s31, v7
	v_or_b32_e32 v9, s31, v9
	v_or_b32_e32 v11, s31, v11
	v_xor_b32_e32 v19, v4, v5
	v_xor_b32_e32 v18, v6, v7
	v_xor_b32_e32 v17, v8, v9
	v_xor_b32_e32 v16, v10, v11
	s_cmp_lt_u32 s28, s3
	s_cbranch_scc1 .Lsc_n16
	v_lshl_add_u32 v118, s28, 6, v101
	v_cmp_lt_i32_e32 vcc, s44, v118
	s_nop 1
	v_cndmask_b32_e64 v19, v19, 0, vcc
	v_cmp_lt_i32_e32 vcc, s45, v118
	s_nop 1
	v_cndmask_b32_e64 v18, v18, 0, vcc
	v_cmp_lt_i32_e32 vcc, s46, v118
	s_nop 1
	v_cndmask_b32_e64 v17, v17, 0, vcc
	v_cmp_lt_i32_e32 vcc, s47, v118
	s_nop 1
	v_cndmask_b32_e64 v16, v16, 0, vcc

; DI int next_job(unsigned* ctr, char* lds, int& pending, int njobs, int& par) {
;   int* sj = (int*)(lds + LDS_JOB);
;   if (threadIdx.x == 0) sj[par] = pending;
;   __syncthreads();
;   const int j = sj[par];
;   par ^= 1;
;   if (threadIdx.x == 0 && j < njobs) pending = (int)atomicAdd(ctr, 1u);
; DI void topk_job(const Params& p, int b, int t0, char* lds) {
;     ...
;       } else {
; #pragma unroll
;         for (int qi = 0; qi < 4; ++qi) sc[i][qi] = 0u;
;       }
;     }
;   }
;   int* ng = (int*)(lds + 256);
;   unsigned long long* mg = (unsigned long long*)(lds + 1024);
;   unsigned long long* me = mg + 4 * 132;
;   int* bg = (int*)(me + 4 * 132);
;   int* be = bg + 4 * 132;
;   unsigned T[4];
;   {
;     unsigned* hist = (unsigned*)(lds + 16384);
;     int* sel = (int*)(lds + 512);
;     unsigned pref[4] = {0u, 0u, 0u, 0u};
;     int chi[4] = {0, 0, 0, 0};
;     bool few[4] = {false, false, false, false};
;     __syncthreads();
;     bool small = false;
;     int nb[4] = {0, 0, 0, 0};
; #pragma unroll
;     for (int pass = 0; pass < 3; ++pass) {
;       if (pass == 2) {
;         small = true;
; #pragma unroll
;         for (int q = 0; q < 4; ++q) small = small && (few[q] || nb[q] <= 64);
;         if (small) break;
;       }
;       {
;         const u32x4 z = {0u, 0u, 0u, 0u};
; #pragma unroll
;         for (int j = 0; j < 8; ++j) ((u32x4*)hist)[tid + 512 * j] = z;
;       }
;       __syncthreads();
.Lsc_z0:
	v_mov_b32_e32 v208, 0
	v_mov_b32_e32 v175, 0
	v_mov_b32_e32 v161, 0
	v_mov_b32_e32 v138, 0
.Lsc_z1:
	v_mov_b32_e32 v207, 0
	v_mov_b32_e32 v173, 0
	v_mov_b32_e32 v159, 0
	v_mov_b32_e32 v135, 0
.Lsc_z2:
	v_mov_b32_e32 v187, 0
	v_mov_b32_e32 v172, 0
	v_mov_b32_e32 v158, 0
	v_mov_b32_e32 v133, 0
.Lsc_z3:
	v_mov_b32_e32 v186, 0
	v_mov_b32_e32 v171, 0
	v_mov_b32_e32 v153, 0
	v_mov_b32_e32 v129, 0
.Lsc_z4:
	v_mov_b32_e32 v185, 0
	v_mov_b32_e32 v170, 0
	v_mov_b32_e32 v150, 0
	v_mov_b32_e32 v127, 0
.Lsc_z5:
	v_mov_b32_e32 v184, 0
	v_mov_b32_e32 v168, 0
	v_mov_b32_e32 v149, 0
	v_mov_b32_e32 v125, 0
.Lsc_z6:
	v_mov_b32_e32 v183, 0
	v_mov_b32_e32 v167, 0
	v_mov_b32_e32 v147, 0
	v_mov_b32_e32 v123, 0
.Lsc_z7:
	v_mov_b32_e32 v182, 0
	v_mov_b32_e32 v166, 0
	v_mov_b32_e32 v146, 0
	v_mov_b32_e32 v121, 0
.Lsc_z8:
	v_mov_b32_e32 v181, 0
	v_mov_b32_e32 v165, 0
	v_mov_b32_e32 v145, 0
	v_mov_b32_e32 v119, 0
.Lsc_z9:
	v_mov_b32_e32 v180, 0
	v_mov_b32_e32 v164, 0
	v_mov_b32_e32 v143, 0
	v_mov_b32_e32 v115, 0
.Lsc_z10:
	v_mov_b32_e32 v179, 0
	v_mov_b32_e32 v163, 0
	v_mov_b32_e32 v142, 0
	v_mov_b32_e32 v113, 0
.Lsc_z11:
	v_mov_b32_e32 v178, 0
	v_mov_b32_e32 v162, 0
	v_mov_b32_e32 v141, 0
	v_mov_b32_e32 v111, 0
.Lsc_z12:
	v_mov_b32_e32 v177, 0
	v_mov_b32_e32 v160, 0
	v_mov_b32_e32 v140, 0
	v_mov_b32_e32 v109, 0
.Lsc_z13:
	v_mov_b32_e32 v176, 0
	v_mov_b32_e32 v151, 0
	v_mov_b32_e32 v139, 0
	v_mov_b32_e32 v107, 0
.Lsc_z14:
	v_mov_b32_e32 v174, 0
	v_mov_b32_e32 v148, 0
	v_mov_b32_e32 v131, 0
	v_mov_b32_e32 v105, 0
.Lsc_z15:
	v_mov_b32_e32 v169, 0
	v_mov_b32_e32 v144, 0
	v_mov_b32_e32 v117, 0
	v_mov_b32_e32 v103, 0
.Lsc_z16:
	v_mov_b32_e32 v19, 0
	v_mov_b32_e32 v18, 0
	v_mov_b32_e32 v17, 0
	v_mov_b32_e32 v16, 0
.Lsc_end:
	s_waitcnt vmcnt(0) lgkmcnt(0)
	v_lshrrev_b32_e32 v0, 6, v100
	s_mov_b32 s3, s90
	v_readfirstlane_b32 s2, v0
	s_lshl_b32 s4, s87, 1
	s_and_b32 s4, s4, 0x3ffc
	s_sub_i32 s4, 0x209c, s4
	s_bitcmp1_b32 s87, 0
	s_cselect_b32 s5, 0x2100, 0
	s_add_i32 s4, s4, s5
	v_readlane_b32 s6, v240, 13
	v_readlane_b32 s7, v240, 14
	s_lshl_b32 s5, s4, 9
	s_add_u32 s40, s6, s5
	s_addc_u32 s41, s7, 0
	s_add_u32 s42, s40, 0x200
	s_addc_u32 s43, s41, 0
	s_add_u32 s44, s42, 0x200
	s_addc_u32 s45, s43, 0
	s_add_u32 s46, s44, 0x200
	s_addc_u32 s47, s45, 0
	s_mov_b32 s16, 0x55555555
	s_mov_b32 s17, 0x55555555
	s_mov_b32 s18, 0x33333333
	s_mov_b32 s19, 0x33333333
	s_mov_b32 s20, 0xf0f0f0f
	s_mov_b32 s21, 0xf0f0f0f
	s_mov_b32 s22, 0xff00ff
	s_mov_b32 s23, 0xff00ff
	s_mov_b32 s24, 0xffff
	s_mov_b32 s25, 0xffff
	s_mov_b32 s26, 0xffffffff
	s_mov_b32 s27, 0
	v_mov_b32_e32 v20, 1
	v_and_b32_e32 v0, 3, v101
	v_lshlrev_b32_e32 v0, 12, v0
	v_add_u32_e32 v21, 0x4000, v0
	v_add_u32_e32 v25, 0x14000, v0
	v_mov_b32_e32 v29, 0x4000
	v_add_u32_e32 v22, 0x8000, v0
	v_add_u32_e32 v26, 0x18000, v0
	v_mov_b32_e32 v30, 0x8000
	v_add_u32_e32 v23, 0xc000, v0
	v_add_u32_e32 v27, 0x1c000, v0
	v_mov_b32_e32 v31, 0xc000
	v_add_u32_e32 v24, 0x10000, v0
	v_add_u32_e32 v28, 0x20000, v0
	v_mov_b32_e32 v32, 0x10000
	s_movk_i32 s85, 0x100
	s_mov_b32 s56, 0
	s_mov_b32 s58, 0
	v_cmp_eq_u32_e32 vcc, 0, v100
	s_and_saveexec_b64 s[30:31], vcc
	ds_write_b32 v3, v136 offset:768
	s_mov_b64 exec, s[30:31]
	s_waitcnt lgkmcnt(0)
	v_lshlrev_b32_e32 v75, 2, v100
	v_add_u32_e32 v75, 0x2800, v75
	v_lshlrev_b32_e32 v76, 1, v100
	v_add_u32_e32 v76, 0x800, v76
	s_barrier
	v_mov_b32_e32 v4, 0
	v_mov_b32_e32 v5, 0
	v_mov_b32_e32 v6, 0
	v_mov_b32_e32 v7, 0
	v_lshlrev_b32_e32 v0, 4, v100
	v_add_u32_e32 v0, 0x4000, v0
	v_add_u32_e32 v1, 0x10000, v0
	ds_write_b128 v0, v[4:7]
	ds_write_b128 v0, v[4:7] offset:8192
	ds_write_b128 v0, v[4:7] offset:16384
	ds_write_b128 v0, v[4:7] offset:24576
	ds_write_b128 v0, v[4:7] offset:32768
	ds_write_b128 v0, v[4:7] offset:40960
	ds_write_b128 v0, v[4:7] offset:49152
	ds_write_b128 v0, v[4:7] offset:57344
	v_mov_b32_e32 v2, -1
	v_lshlrev_b32_e32 v0, 2, v100
	ds_write_b32 v0, v2 offset:8192
	s_waitcnt lgkmcnt(0)
	s_barrier
	ds_read_b32 v0, v3 offset:768
	s_waitcnt lgkmcnt(0)
	v_readfirstlane_b32 s63, v0
	s_cmp_lt_u32 s63, 16
	s_cbranch_scc1 .Ltk_pf_end_1
	s_cmpk_gt_u32 s63, 0x1017
	s_cbranch_scc1 .Ltk_pf_end_1
	s_lshl_b32 s4, s63, 1
	s_and_b32 s4, s4, 0x3ffc
	s_sub_i32 s4, 0x209c, s4
	s_bitcmp1_b32 s63, 0
	s_cselect_b32 s5, 0x2100, 0
	s_add_i32 s60, s4, 3
	s_lshr_b32 s60, s60, 6
	s_add_i32 s62, s2, 1
	s_cmp_gt_u32 s62, s60
	s_cbranch_scc1 .Ltk_pf_w_2
	v_readlane_b32 s64, v240, 11
	v_readlane_b32 s65, v240, 12
	s_lshl_b32 s62, s62, 6
	s_add_i32 s62, s62, s5
	v_add_lshl_u32 v0, s62, v101, 7
	s_nop 1
	global_load_dword v242, v0, s[64:65]

; DI float bf_lo(unsigned u) { return __uint_as_float(u << 16); }
; DI float bf_hi(unsigned u) { return __uint_as_float(u & 0xffff0000u); }
; DI float xor32_sum(float v) { const u32x2 r = __builtin_amdgcn_permlane32_swap(__float_as_uint(v), __float_as_uint(v), false, false); return __uint_as_float(r[0]) + __uint_as_float(r[1]); }
; template <int DK, int MODE>
; DI void attn_unit(const Params& p, int l, int b, int head, int qu, char* lds) {
;     ...
;   u32x4 rk, rk2, rv;
;   float re = 0.f;
;   const int srow = tid >> 3, sc8 = tid & 7;
;   auto gload = [&](int kt) {
;     const int k0 = kt * 64;
;     rk = *(const u32x4*)(kptr + (size_t)(k0 + srow) * ldk + sc8 * 8);
;     if (MODE == 1) { if (tid < 256) rk2 = *(const u32x4*)(p.Kpe + ((size_t)b * PP + k0 + (tid >> 2)) * 32 + (tid & 3) * 8); }
;     rv = *(const u32x4*)(vtptr + (size_t)srow * PP + k0 + sc8 * 8);
;     if (MODE == 0) { if (tid < 64) re = (cum[k0 + tid] - cref) * LOG2E; }
;   };
;   auto lstore = [&](int st) {
;     char* base = lds + st * AT_STAGE;
;     *(u32x4*)(base + (srow * KST + sc8 * 8) * 2) = rk;
;     if (MODE == 1) { if (tid < 256) *(u32x4*)(base + ((tid >> 2) * KST + 64 + (tid & 3) * 8) * 2) = rk2; }
;     char* vb = base + 64 * KST * 2;
;     u32x2 lo = {rv[0], rv[1]}, hi = {rv[2], rv[3]};
;     *(u32x2*)(vb + (srow * 68 + sc8 * 8) * 2) = lo;
;     *(u32x2*)(vb + (srow * 68 + sc8 * 8 + 4) * 2) = hi;
;     if (MODE == 0) { if (tid < 64) *(float*)(vb + 64 * 68 * 2 + tid * 4) = re; }
;   };
;   f32x16 o[2];
; #pragma unroll
;   for (int d = 0; d < 2; ++d)
; #pragma unroll
;     for (int i = 0; i < 16; ++i) o[d][i] = 0.f;
;   float m = NEGL, lsum = 0.f;
;   float qn = 0.f, kmx = 0.f;
;   int* stopf = (int*)(lds + 2 * AT_STAGE + 1024);
;   if (MODE == 0) {
; #pragma unroll
;     for (int ks = 0; ks < KS; ++ks) {
;       const u32x4 qq = __builtin_bit_cast(u32x4, qf[ks]);
; #pragma unroll
;       for (int e = 0; e < 4; ++e) { const float a = bf_lo(qq[e]), b2 = bf_hi(qq[e]); qn += a * a + b2 * b2; }
;     }
;     qn = xor32_sum(qn);
;     qn = sqrtf(qn) * 1.01f;
;     kmx = __uint_as_float(p.ctr[64 + l * 16 + b * 8 + head]);
;   }
;   gload(kt_hi); lstore(0);
;   __syncthreads();
.LBB0_2380:
	s_or_b64 exec, exec, s[4:5]
	s_lshl_b32 s22, s17, 6
	s_lshl_b32 s4, s21, 9
	s_or_b32 s4, s4, s22
	s_mulk_i32 s4, 0x4200
	s_add_u32 s4, s70, s4
	s_addc_u32 s5, s71, 0
	v_mov_b64_e32 v[6:7], s[4:5]
	s_movk_i32 s4, 0x4200
	v_lshlrev_b32_e32 v2, 3, v4
	v_mad_i64_i32 v[6:7], s[4:5], v163, s4, v[6:7]
	s_waitcnt vmcnt(15) lgkmcnt(0)
	v_lshl_add_u64 v[10:11], s[60:61], 1, v[6:7]
	v_lshlrev_b32_e32 v2, 1, v2
	v_lshl_add_u64 v[10:11], v[10:11], 0, v[2:3]
	global_load_dwordx4 v[100:103], v[10:11], off
	s_movk_i32 s4, 0xd0
	v_mul_lo_u32 v9, v163, s4
	v_lshl_add_u32 v165, v4, 4, v9
	v_lshlrev_b32_e32 v10, 3, v5
	v_add_u32_e32 v9, 0, v165
	v_and_b32_e32 v4, 24, v10
	s_waitcnt vmcnt(1)
	ds_write_b128 v9, v[92:95]
	s_and_saveexec_b64 s[4:5], vcc
	s_xor_b64 s[4:5], exec, s[4:5]
	v_lshrrev_b32_e32 v0, 2, v5
	v_and_b32_e32 v4, 24, v10
	s_movk_i32 s6, 0x68
	v_mad_u64_u32 v[10:11], s[6:7], v0, s6, v[4:5]
	v_lshl_add_u32 v176, v10, 1, v205
	s_andn2_saveexec_b64 s[4:5], s[4:5]
	s_movk_i32 s6, 0x68
	v_mad_u64_u32 v[10:11], s[6:7], v0, s6, v[4:5]
	v_lshl_add_u32 v176, v10, 1, v205
	v_add_u32_e32 v5, 0, v176
	ds_write_b128 v5, v[96:99]
	s_or_b64 exec, exec, s[4:5]
	s_movk_i32 s4, 0xffb8
	v_lshlrev_b32_e32 v161, 2, v1
	v_mul_lo_u32 v1, v163, s4
	s_movk_i32 s4, 0x3400
	v_add_u32_e32 v177, v165, v1
	v_add3_u32 v1, v9, v1, s4
	v_readlane_b32 s64, v240, 1
	s_waitcnt vmcnt(0)
	ds_write2_b64 v1, v[100:101], v[102:103] offset1:1
	v_lshl_add_u64 v[166:167], s[2:3], 0, v[2:3]
	v_ashrrev_i32_e32 v1, 31, v0
	v_mov_b32_e32 v5, v3
	s_movk_i32 s2, 0xd0
	v_readlane_b32 s72, v240, 9
	v_readlane_b32 s73, v240, 10
	v_mov_b32_e32 v14, v3
	v_mov_b32_e32 v15, v3
	v_lshl_add_u64 v[168:169], v[6:7], 0, v[2:3]
	v_lshl_add_u64 v[170:171], s[8:9], 0, v[0:1]
	v_mul_u32_u24_e32 v179, 0xd0, v8
	v_mad_u32_u24 v180, v8, s2, v206
	v_mul_u32_u24_e32 v181, 0x88, v8
	v_lshl_add_u64 v[172:173], v[4:5], 1, s[72:73]
	s_lshl_b32 s2, s16, 8
	v_mov_b32_e32 v0, v3
	v_mov_b32_e32 v1, v3
	v_mov_b32_e32 v2, v3
	v_mov_b32_e32 v4, v3
	v_mov_b32_e32 v6, v3
	v_mov_b32_e32 v7, v3
	v_mov_b32_e32 v8, v3
	v_mov_b32_e32 v9, v3
	v_mov_b32_e32 v10, v3
	v_mov_b32_e32 v11, v3
	v_mov_b32_e32 v12, v3
	v_mov_b32_e32 v13, v3
	v_mov_b64_e32 v[34:35], v[14:15]
	s_sub_i32 s60, 0x2080, s2
	s_lshl_b32 s2, s16, 2
	v_mov_b64_e32 v[32:33], v[12:13]
	v_mov_b64_e32 v[30:31], v[10:11]
	v_mov_b64_e32 v[28:29], v[8:9]
	v_mov_b64_e32 v[26:27], v[6:7]
	v_mov_b64_e32 v[24:25], v[4:5]
	v_mov_b64_e32 v[22:23], v[2:3]
	v_mov_b64_e32 v[20:21], v[0:1]
	v_mov_b64_e32 v[18:19], v[14:15]
	v_or_b32_e32 v178, 31, v175
	v_mov_b32_e32 v153, v160
	s_sub_i32 s4, 0x84, s2
	v_mov_b32_e32 v182, 0
	v_mov_b32_e32 v183, 0xf149f2ca
	v_mov_b64_e32 v[16:17], v[12:13]
	v_mov_b64_e32 v[14:15], v[10:11]
	v_mov_b64_e32 v[12:13], v[8:9]
	v_mov_b64_e32 v[10:11], v[6:7]
	v_mov_b64_e32 v[8:9], v[4:5]
	v_mov_b64_e32 v[6:7], v[2:3]
	v_mov_b64_e32 v[4:5], v[0:1]
	s_waitcnt lgkmcnt(0)
	s_barrier
	v_readlane_b32 s65, v240, 2
	v_readlane_b32 s66, v240, 3
	v_readlane_b32 s67, v240, 4
